# all 112 GEMM MFMA bursts start on 8-byte instruction addresses (21 s_nop inserted); otherwise as previous
# speedup vs baseline: 1.0029x; 1.0029x over previous
; #define PG8_STAGE(bufoff, gbase, voff) do { _Pragma("unroll") for (int _i = 0; _i < 2; ++_i) \
;         __builtin_amdgcn_global_load_lds((const unsigned*)((const char*)(gbase) + (voff)[_i]), (PG8_LAS unsigned*)(lds + (bufoff) + ldsw + _i * 8192), 16, 0, 0); } while (0)
; #define PG8_LDA(dst, b, h) do { _Pragma("unroll") for (int m = 0; m < 4; ++m) _Pragma("unroll") for (int k = 0; k < 2; ++k) dst[m][k] = *(const PG8_LAS bf16x8*)(lds + PG8_SA(b, h) + aoff + m * 2048 + k * 1024); } while (0)
; #define PG8_LDB(dst, b, h) do { _Pragma("unroll") for (int n = 0; n < 2; ++n) _Pragma("unroll") for (int k = 0; k < 2; ++k) dst[n][k] = *(const PG8_LAS bf16x8*)(lds + PG8_SB(b, h) + boff + n * 2048 + k * 1024); } while (0)
; #define PG8_MMA(ai, bj, At, Bt) do { __builtin_amdgcn_s_setprio(1); _Pragma("unroll") for (int m = 0; m < 4; ++m) _Pragma("unroll") for (int n = 0; n < 2; ++n) _Pragma("unroll") for (int k = 0; k < 2; ++k) \
;         acc[ai][bj][m][n] = __builtin_amdgcn_mfma_f32_16x16x32_bf16(Bt[n][k], At[m][k], acc[ai][bj][m][n], 0, 0, 0); __builtin_amdgcn_s_setprio(0); } while (0)
; #define PG8_WAIT_V(n) asm volatile("s_waitcnt vmcnt(" #n ")" ::: "memory")
; template <class Epi, class Sched, bool ALIGN_EPI = false, bool SP2 = false>
; __device__ __forceinline__ void gemm_phase(PG8_LAS unsigned char* lds, const Gemm g, const Sched& S, const Epi& E, int tid_in) {
;     ...
;         for (int t = 0; t < nt; t += 2) {
;             const bool last = (t == nt - 2);
;             if constexpr (mid_hook<Epi>::value) { if (t == Epi::H1 || t == Epi::H2) E.mid(acc, cur, wr, wc, fr, fq, t == Epi::H2); }
;             const char* a1 = cA + (size_t)(t + 1) * kstep + (t >= jt ? jb : 0);
;             const char* a2 = last ? nA : cA + (size_t)(t + 2) * kstep + (t + 2 >= jt ? jb : 0); const char* b2 = last ? nB : cB + (size_t)(t + 2) * kstep;
;             const char* a3 = a2 + kstep; const char* b3 = b2 + kstep;
;             if (last && has_next) S.a_ready(nxt);
;             if constexpr (SP2) {
;             PG8_LDB(B0, 0, 0); PG8_LDB(B1, 0, 1); PG8_SCHED; PG8_LDA(At, 0, 0); PG8_STAGE(PG8_SA(1, 1), a1 + hsA, voffA);
;             PG8_WAIT_V(8); PG8_WAIT_L(0); PG8_BAR; PG8_MMA(0, 0, At, B0); PG8_MMA(0, 1, At, B1); PG8_BAR; PG8_SCHED;
;             PG8_LDA(At, 0, 1); PG8_STAGE(PG8_SB(0, 0), b2, voffB); PG8_STAGE(PG8_SB(0, 1), b2 + hsB, voffB); PG8_STAGE(PG8_SA(0, 0), a2, voffA);
.LBB0_244:
	s_add_i32 s24, s53, -2
	s_cmp_ge_i32 s24, s28
	s_cselect_b32 s54, s29, 0
	s_cselect_b32 s55, s44, 0
	s_cmp_ge_i32 s53, s28
	s_cselect_b32 s25, s29, 0
	s_cselect_b32 s24, s44, 0
	s_add_u32 s25, s22, s25
	s_addc_u32 s24, s23, s24
	s_add_u32 s58, s25, 0x80
	s_addc_u32 s24, s24, 0
	s_add_i32 s60, 0, 0x10000
	s_cmp_eq_u32 s43, s53
	s_cselect_b32 s25, s5, s24
	s_cselect_b32 s24, s4, s58
	s_cselect_b32 s59, s21, s52
	s_cselect_b32 s58, s20, s51
	s_add_i32 s61, 0, 0x14000
	v_add_u32_e32 v160, s60, v142
	v_add_u32_e32 v176, s61, v142
	ds_read_b128 v[148:151], v160
	ds_read_b128 v[152:155], v160 offset:1024
	ds_read_b128 v[156:159], v160 offset:2048
	ds_read_b128 v[160:163], v160 offset:3072
	ds_read_b128 v[164:167], v176
	ds_read_b128 v[168:171], v176 offset:1024
	ds_read_b128 v[172:175], v176 offset:2048
	ds_read_b128 v[176:179], v176 offset:3072
	v_lshl_add_u64 v[230:231], s[22:23], 0, v[140:141]
	v_lshl_add_u64 v[230:231], v[230:231], 0, s[54:55]
	s_add_i32 m0, s37, 0xc000
	ds_read_b128 v[180:183], v147
	ds_read_b128 v[184:187], v147 offset:1024
	ds_read_b128 v[188:191], v147 offset:2048
	ds_read_b128 v[204:207], v147 offset:3072
	ds_read_b128 v[208:211], v147 offset:4096
	ds_read_b128 v[212:215], v147 offset:5120
	ds_read_b128 v[216:219], v147 offset:6144
	ds_read_b128 v[220:223], v147 offset:7168
	global_load_lds_dwordx4 v[230:231], off
	v_lshl_add_u64 v[230:231], s[22:23], 0, v[138:139]
	v_lshl_add_u64 v[230:231], v[230:231], 0, s[54:55]
	s_add_i32 m0, s37, 0xe000
	s_nop 0
	global_load_lds_dwordx4 v[230:231], off
	s_waitcnt vmcnt(8)
	s_waitcnt lgkmcnt(0)
	s_barrier
	s_setprio 1
	s_waitcnt lgkmcnt(0)
	v_mfma_f32_16x16x32_bf16 v[124:127], v[148:151], v[180:183], v[124:127]
	v_mfma_f32_16x16x32_bf16 v[120:123], v[156:159], v[180:183], v[120:123]
	v_mfma_f32_16x16x32_bf16 v[112:115], v[148:151], v[188:191], v[112:115]
	v_mfma_f32_16x16x32_bf16 v[104:107], v[156:159], v[188:191], v[104:107]
	v_mfma_f32_16x16x32_bf16 v[96:99], v[148:151], v[208:211], v[96:99]
	v_mfma_f32_16x16x32_bf16 v[88:91], v[156:159], v[208:211], v[88:91]
	v_mfma_f32_16x16x32_bf16 v[80:83], v[148:151], v[216:219], v[80:83]
	v_mfma_f32_16x16x32_bf16 v[72:75], v[156:159], v[216:219], v[72:75]
	v_mfma_f32_16x16x32_bf16 v[124:127], v[152:155], v[184:187], v[124:127]
	v_mfma_f32_16x16x32_bf16 v[120:123], v[160:163], v[184:187], v[120:123]
	v_mfma_f32_16x16x32_bf16 v[112:115], v[152:155], v[204:207], v[112:115]
	v_mfma_f32_16x16x32_bf16 v[104:107], v[160:163], v[204:207], v[104:107]
	v_mfma_f32_16x16x32_bf16 v[96:99], v[152:155], v[212:215], v[96:99]
	v_mfma_f32_16x16x32_bf16 v[88:91], v[160:163], v[212:215], v[88:91]
	v_mfma_f32_16x16x32_bf16 v[80:83], v[152:155], v[220:223], v[80:83]
	v_mfma_f32_16x16x32_bf16 v[72:75], v[160:163], v[220:223], v[72:75]
	s_setprio 0
	s_setprio 1
	v_mfma_f32_16x16x32_bf16 v[128:131], v[164:167], v[180:183], v[128:131]
	v_mfma_f32_16x16x32_bf16 v[116:119], v[172:175], v[180:183], v[116:119]
	v_mfma_f32_16x16x32_bf16 v[108:111], v[164:167], v[188:191], v[108:111]
	v_mfma_f32_16x16x32_bf16 v[100:103], v[172:175], v[188:191], v[100:103]
	v_mfma_f32_16x16x32_bf16 v[92:95], v[164:167], v[208:211], v[92:95]
	v_mfma_f32_16x16x32_bf16 v[84:87], v[172:175], v[208:211], v[84:87]
	v_mfma_f32_16x16x32_bf16 v[76:79], v[164:167], v[216:219], v[76:79]
	v_mfma_f32_16x16x32_bf16 v[68:71], v[172:175], v[216:219], v[68:71]
	v_mfma_f32_16x16x32_bf16 v[128:131], v[168:171], v[184:187], v[128:131]
	v_mfma_f32_16x16x32_bf16 v[116:119], v[176:179], v[184:187], v[116:119]
	v_mfma_f32_16x16x32_bf16 v[108:111], v[168:171], v[204:207], v[108:111]
	v_mfma_f32_16x16x32_bf16 v[100:103], v[176:179], v[204:207], v[100:103]
	v_mfma_f32_16x16x32_bf16 v[92:95], v[168:171], v[212:215], v[92:95]
	v_mfma_f32_16x16x32_bf16 v[84:87], v[176:179], v[212:215], v[84:87]
	v_mfma_f32_16x16x32_bf16 v[76:79], v[168:171], v[220:223], v[76:79]
	v_mfma_f32_16x16x32_bf16 v[68:71], v[176:179], v[220:223], v[68:71]
	s_setprio 0
	s_barrier
	s_add_i32 s54, s60, s35
	v_lshl_add_u64 v[230:231], s[58:59], 0, v[134:135]
	s_mov_b32 m0, s54
	ds_read_b128 v[180:183], v147 offset:16384
	ds_read_b128 v[184:187], v147 offset:17408
	ds_read_b128 v[188:191], v147 offset:18432
	ds_read_b128 v[204:207], v147 offset:19456
	ds_read_b128 v[208:211], v147 offset:20480
	ds_read_b128 v[212:215], v147 offset:21504
	ds_read_b128 v[216:219], v147 offset:22528
	ds_read_b128 v[220:223], v147 offset:23552
	global_load_lds_dwordx4 v[230:231], off
	s_add_i32 m0, s54, 0x2000
	s_add_u32 s54, s58, s6
	v_lshl_add_u64 v[232:233], s[58:59], 0, v[0:1]
	s_addc_u32 s55, s59, s7
	s_add_i32 s58, s61, s35
	global_load_lds_dwordx4 v[232:233], off
	v_lshl_add_u64 v[238:239], s[54:55], 0, v[134:135]
	s_mov_b32 m0, s58
	v_lshl_add_u64 v[240:241], s[54:55], 0, v[0:1]
	global_load_lds_dwordx4 v[238:239], off
	s_add_i32 m0, s58, 0x2000
	v_lshl_add_u64 v[242:243], s[24:25], 0, v[136:137]
	global_load_lds_dwordx4 v[240:241], off
	s_mov_b32 m0, s37
	v_lshl_add_u64 v[244:245], s[24:25], 0, v[132:133]
	global_load_lds_dwordx4 v[242:243], off
	s_mov_b32 m0, s38
	s_nop 0
	global_load_lds_dwordx4 v[244:245], off
	s_waitcnt vmcnt(8)
	s_waitcnt lgkmcnt(0)
	s_barrier
; #define PG8_STAGE(bufoff, gbase, voff) do { _Pragma("unroll") for (int _i = 0; _i < 2; ++_i) \
;         __builtin_amdgcn_global_load_lds((const unsigned*)((const char*)(gbase) + (voff)[_i]), (PG8_LAS unsigned*)(lds + (bufoff) + ldsw + _i * 8192), 16, 0, 0); } while (0)
; #define PG8_LDA(dst, b, h) do { _Pragma("unroll") for (int m = 0; m < 4; ++m) _Pragma("unroll") for (int k = 0; k < 2; ++k) dst[m][k] = *(const PG8_LAS bf16x8*)(lds + PG8_SA(b, h) + aoff + m * 2048 + k * 1024); } while (0)
; #define PG8_LDB(dst, b, h) do { _Pragma("unroll") for (int n = 0; n < 2; ++n) _Pragma("unroll") for (int k = 0; k < 2; ++k) dst[n][k] = *(const PG8_LAS bf16x8*)(lds + PG8_SB(b, h) + boff + n * 2048 + k * 1024); } while (0)
; #define PG8_MMA(ai, bj, At, Bt) do { __builtin_amdgcn_s_setprio(1); _Pragma("unroll") for (int m = 0; m < 4; ++m) _Pragma("unroll") for (int n = 0; n < 2; ++n) _Pragma("unroll") for (int k = 0; k < 2; ++k) \
;         acc[ai][bj][m][n] = __builtin_amdgcn_mfma_f32_16x16x32_bf16(Bt[n][k], At[m][k], acc[ai][bj][m][n], 0, 0, 0); __builtin_amdgcn_s_setprio(0); } while (0)
; #define PG8_WAIT_V(n) asm volatile("s_waitcnt vmcnt(" #n ")" ::: "memory")
; #define PG8_WAIT_L(n) asm volatile("s_waitcnt lgkmcnt(" #n ")" ::: "memory")
; #define PG8_BAR __builtin_amdgcn_s_barrier()
; #define PG8_SCHED __builtin_amdgcn_sched_barrier(0)
; template <class Epi, class Sched, bool ALIGN_EPI = false, bool SP2 = false>
; __device__ __forceinline__ void gemm_phase(PG8_LAS unsigned char* lds, const Gemm g, const Sched& S, const Epi& E, int tid_in) {
;     ...
;             PG8_WAIT_V(8); PG8_WAIT_L(0); PG8_BAR; PG8_MMA(1, 0, At, B0); PG8_MMA(1, 1, At, B1); PG8_BAR; PG8_SCHED;
;             PG8_LDB(B0, 1, 0); PG8_LDB(B1, 1, 1); PG8_SCHED; PG8_LDA(At, 1, 0); PG8_STAGE(PG8_SA(0, 1), a2 + hsA, voffA);
;             PG8_WAIT_V(8); PG8_WAIT_L(0); PG8_BAR; PG8_MMA(0, 0, At, B0); PG8_MMA(0, 1, At, B1); PG8_BAR; PG8_SCHED;
;             PG8_LDA(At, 1, 1); PG8_STAGE(PG8_SB(1, 0), b3, voffB); PG8_STAGE(PG8_SB(1, 1), b3 + hsB, voffB); PG8_STAGE(PG8_SA(1, 0), a3, voffA);
	s_setprio 1
	s_waitcnt lgkmcnt(0)
	v_mfma_f32_16x16x32_bf16 v[64:67], v[148:151], v[180:183], v[64:67]
	v_mfma_f32_16x16x32_bf16 v[56:59], v[156:159], v[180:183], v[56:59]
	v_mfma_f32_16x16x32_bf16 v[48:51], v[148:151], v[188:191], v[48:51]
	v_mfma_f32_16x16x32_bf16 v[40:43], v[156:159], v[188:191], v[40:43]
	v_mfma_f32_16x16x32_bf16 v[32:35], v[148:151], v[208:211], v[32:35]
	v_mfma_f32_16x16x32_bf16 v[24:27], v[156:159], v[208:211], v[24:27]
	v_mfma_f32_16x16x32_bf16 v[16:19], v[148:151], v[216:219], v[16:19]
	v_mfma_f32_16x16x32_bf16 v[8:11], v[156:159], v[216:219], v[8:11]
	v_mfma_f32_16x16x32_bf16 v[64:67], v[152:155], v[184:187], v[64:67]
	v_mfma_f32_16x16x32_bf16 v[56:59], v[160:163], v[184:187], v[56:59]
	v_mfma_f32_16x16x32_bf16 v[48:51], v[152:155], v[204:207], v[48:51]
	v_mfma_f32_16x16x32_bf16 v[40:43], v[160:163], v[204:207], v[40:43]
	v_mfma_f32_16x16x32_bf16 v[32:35], v[152:155], v[212:215], v[32:35]
	v_mfma_f32_16x16x32_bf16 v[24:27], v[160:163], v[212:215], v[24:27]
	v_mfma_f32_16x16x32_bf16 v[16:19], v[152:155], v[220:223], v[16:19]
	v_mfma_f32_16x16x32_bf16 v[8:11], v[160:163], v[220:223], v[8:11]
	s_setprio 0
	s_setprio 1
	v_mfma_f32_16x16x32_bf16 v[60:63], v[164:167], v[180:183], v[60:63]
	v_mfma_f32_16x16x32_bf16 v[52:55], v[172:175], v[180:183], v[52:55]
	v_mfma_f32_16x16x32_bf16 v[44:47], v[164:167], v[188:191], v[44:47]
	v_mfma_f32_16x16x32_bf16 v[36:39], v[172:175], v[188:191], v[36:39]
	v_mfma_f32_16x16x32_bf16 v[28:31], v[164:167], v[208:211], v[28:31]
	v_mfma_f32_16x16x32_bf16 v[20:23], v[172:175], v[208:211], v[20:23]
	v_mfma_f32_16x16x32_bf16 v[12:15], v[164:167], v[216:219], v[12:15]
	v_mfma_f32_16x16x32_bf16 v[4:7], v[172:175], v[216:219], v[4:7]
	v_mfma_f32_16x16x32_bf16 v[60:63], v[168:171], v[184:187], v[60:63]
	v_mfma_f32_16x16x32_bf16 v[52:55], v[176:179], v[184:187], v[52:55]
	v_mfma_f32_16x16x32_bf16 v[44:47], v[168:171], v[204:207], v[44:47]
	v_mfma_f32_16x16x32_bf16 v[36:39], v[176:179], v[204:207], v[36:39]
	v_mfma_f32_16x16x32_bf16 v[28:31], v[168:171], v[212:215], v[28:31]
	v_mfma_f32_16x16x32_bf16 v[20:23], v[176:179], v[212:215], v[20:23]
	v_mfma_f32_16x16x32_bf16 v[12:15], v[168:171], v[220:223], v[12:15]
	v_mfma_f32_16x16x32_bf16 v[4:7], v[176:179], v[220:223], v[4:7]
	s_setprio 0
	s_barrier
	s_add_i32 s54, 0, 0x18000
	s_add_i32 s55, 0, 0x1c000
	v_add_u32_e32 v160, s54, v142
	v_add_u32_e32 v176, s55, v142
	ds_read_b128 v[148:151], v160
	ds_read_b128 v[152:155], v160 offset:1024
	ds_read_b128 v[156:159], v160 offset:2048
	ds_read_b128 v[160:163], v160 offset:3072
	ds_read_b128 v[164:167], v176
	ds_read_b128 v[168:171], v176 offset:1024
	ds_read_b128 v[172:175], v176 offset:2048
	ds_read_b128 v[176:179], v176 offset:3072
	s_add_u32 s24, s24, s0
	s_addc_u32 s25, s25, s1
	s_mov_b32 m0, s39
	v_lshl_add_u64 v[246:247], s[24:25], 0, v[136:137]
	ds_read_b128 v[180:183], v147 offset:32768
	ds_read_b128 v[184:187], v147 offset:33792
	ds_read_b128 v[188:191], v147 offset:34816
	ds_read_b128 v[204:207], v147 offset:35840
	ds_read_b128 v[208:211], v147 offset:36864
	ds_read_b128 v[212:215], v147 offset:37888
	ds_read_b128 v[216:219], v147 offset:38912
	ds_read_b128 v[220:223], v147 offset:39936
	global_load_lds_dwordx4 v[246:247], off
	v_lshl_add_u64 v[246:247], s[24:25], 0, v[132:133]
	s_mov_b32 m0, s40
	s_nop 0
	global_load_lds_dwordx4 v[246:247], off
	s_waitcnt vmcnt(8)
	s_waitcnt lgkmcnt(0)
	s_barrier
	s_setprio 1
	s_waitcnt lgkmcnt(0)
	v_mfma_f32_16x16x32_bf16 v[124:127], v[148:151], v[180:183], v[124:127]
	v_mfma_f32_16x16x32_bf16 v[120:123], v[156:159], v[180:183], v[120:123]
	v_mfma_f32_16x16x32_bf16 v[112:115], v[148:151], v[188:191], v[112:115]
	v_mfma_f32_16x16x32_bf16 v[104:107], v[156:159], v[188:191], v[104:107]
	v_mfma_f32_16x16x32_bf16 v[96:99], v[148:151], v[208:211], v[96:99]
	v_mfma_f32_16x16x32_bf16 v[88:91], v[156:159], v[208:211], v[88:91]
	v_mfma_f32_16x16x32_bf16 v[80:83], v[148:151], v[216:219], v[80:83]
	v_mfma_f32_16x16x32_bf16 v[72:75], v[156:159], v[216:219], v[72:75]
	v_mfma_f32_16x16x32_bf16 v[124:127], v[152:155], v[184:187], v[124:127]
	v_mfma_f32_16x16x32_bf16 v[120:123], v[160:163], v[184:187], v[120:123]
	v_mfma_f32_16x16x32_bf16 v[112:115], v[152:155], v[204:207], v[112:115]
	v_mfma_f32_16x16x32_bf16 v[104:107], v[160:163], v[204:207], v[104:107]
	v_mfma_f32_16x16x32_bf16 v[96:99], v[152:155], v[212:215], v[96:99]
	v_mfma_f32_16x16x32_bf16 v[88:91], v[160:163], v[212:215], v[88:91]
	v_mfma_f32_16x16x32_bf16 v[80:83], v[152:155], v[220:223], v[80:83]
	v_mfma_f32_16x16x32_bf16 v[72:75], v[160:163], v[220:223], v[72:75]
	s_setprio 0
	s_setprio 1
	v_mfma_f32_16x16x32_bf16 v[128:131], v[164:167], v[180:183], v[128:131]
	v_mfma_f32_16x16x32_bf16 v[116:119], v[172:175], v[180:183], v[116:119]
	v_mfma_f32_16x16x32_bf16 v[108:111], v[164:167], v[188:191], v[108:111]
	v_mfma_f32_16x16x32_bf16 v[100:103], v[172:175], v[188:191], v[100:103]
	v_mfma_f32_16x16x32_bf16 v[92:95], v[164:167], v[208:211], v[92:95]
	v_mfma_f32_16x16x32_bf16 v[84:87], v[172:175], v[208:211], v[84:87]
	v_mfma_f32_16x16x32_bf16 v[76:79], v[164:167], v[216:219], v[76:79]
	v_mfma_f32_16x16x32_bf16 v[68:71], v[172:175], v[216:219], v[68:71]
	v_mfma_f32_16x16x32_bf16 v[128:131], v[168:171], v[184:187], v[128:131]
	v_mfma_f32_16x16x32_bf16 v[116:119], v[176:179], v[184:187], v[116:119]
	v_mfma_f32_16x16x32_bf16 v[108:111], v[168:171], v[204:207], v[108:111]
	v_mfma_f32_16x16x32_bf16 v[100:103], v[176:179], v[204:207], v[100:103]
	v_mfma_f32_16x16x32_bf16 v[92:95], v[168:171], v[212:215], v[92:95]
	v_mfma_f32_16x16x32_bf16 v[84:87], v[176:179], v[212:215], v[84:87]
	v_mfma_f32_16x16x32_bf16 v[76:79], v[168:171], v[220:223], v[76:79]
	v_mfma_f32_16x16x32_bf16 v[68:71], v[176:179], v[220:223], v[68:71]
	s_setprio 0
	s_barrier
; #define PG8_STAGE(bufoff, gbase, voff) do { _Pragma("unroll") for (int _i = 0; _i < 2; ++_i) \
;         __builtin_amdgcn_global_load_lds((const unsigned*)((const char*)(gbase) + (voff)[_i]), (PG8_LAS unsigned*)(lds + (bufoff) + ldsw + _i * 8192), 16, 0, 0); } while (0)
; #define PG8_LDA(dst, b, h) do { _Pragma("unroll") for (int m = 0; m < 4; ++m) _Pragma("unroll") for (int k = 0; k < 2; ++k) dst[m][k] = *(const PG8_LAS bf16x8*)(lds + PG8_SA(b, h) + aoff + m * 2048 + k * 1024); } while (0)
; #define PG8_MMA(ai, bj, At, Bt) do { __builtin_amdgcn_s_setprio(1); _Pragma("unroll") for (int m = 0; m < 4; ++m) _Pragma("unroll") for (int n = 0; n < 2; ++n) _Pragma("unroll") for (int k = 0; k < 2; ++k) \
;         acc[ai][bj][m][n] = __builtin_amdgcn_mfma_f32_16x16x32_bf16(Bt[n][k], At[m][k], acc[ai][bj][m][n], 0, 0, 0); __builtin_amdgcn_s_setprio(0); } while (0)
; #define PG8_WAIT_V(n) asm volatile("s_waitcnt vmcnt(" #n ")" ::: "memory")
; #define PG8_WAIT_L(n) asm volatile("s_waitcnt lgkmcnt(" #n ")" ::: "memory")
; #define PG8_BAR __builtin_amdgcn_s_barrier()
; #define PG8_SCHED __builtin_amdgcn_sched_barrier(0)
; template <class Epi, class Sched, bool ALIGN_EPI = false, bool SP2 = false>
; __device__ __forceinline__ void gemm_phase(PG8_LAS unsigned char* lds, const Gemm g, const Sched& S, const Epi& E, int tid_in) {
;     ...
;             PG8_LDA(At, 1, 1); PG8_STAGE(PG8_SB(1, 0), b3, voffB); PG8_STAGE(PG8_SB(1, 1), b3 + hsB, voffB); PG8_STAGE(PG8_SA(1, 0), a3, voffA);
;             PG8_WAIT_V(8); PG8_WAIT_L(0); PG8_BAR; PG8_MMA(1, 0, At, B0); PG8_MMA(1, 1, At, B1); PG8_BAR; PG8_SCHED;
	s_add_i32 s24, s54, s35
	v_lshl_add_u64 v[230:231], v[230:231], 0, s[80:81]
	s_mov_b32 m0, s24
	ds_read_b128 v[180:183], v147 offset:49152
	ds_read_b128 v[184:187], v147 offset:50176
	ds_read_b128 v[188:191], v147 offset:51200
	ds_read_b128 v[204:207], v147 offset:52224
	ds_read_b128 v[208:211], v147 offset:53248
	ds_read_b128 v[212:215], v147 offset:54272
	ds_read_b128 v[216:219], v147 offset:55296
	ds_read_b128 v[220:223], v147 offset:56320
	global_load_lds_dwordx4 v[230:231], off
	v_lshl_add_u64 v[230:231], v[232:233], 0, s[80:81]
	s_add_i32 m0, s24, 0x2000
	s_add_i32 s24, s55, s35
	global_load_lds_dwordx4 v[230:231], off
	v_lshl_add_u64 v[230:231], v[238:239], 0, s[80:81]
	s_mov_b32 m0, s24
	s_nop 0
	global_load_lds_dwordx4 v[230:231], off
	v_lshl_add_u64 v[230:231], v[240:241], 0, s[80:81]
	s_add_i32 m0, s24, 0x2000
	s_nop 0
	global_load_lds_dwordx4 v[230:231], off
	v_lshl_add_u64 v[230:231], v[242:243], 0, s[80:81]
	s_mov_b32 m0, s41
	s_nop 0
	global_load_lds_dwordx4 v[230:231], off
	v_lshl_add_u64 v[230:231], v[244:245], 0, s[80:81]
	s_mov_b32 m0, s42
	s_nop 0
	global_load_lds_dwordx4 v[230:231], off
	s_waitcnt vmcnt(8)
	s_waitcnt lgkmcnt(0)
	s_barrier
	s_setprio 1
	s_waitcnt lgkmcnt(0)
	s_nop 0
	v_mfma_f32_16x16x32_bf16 v[64:67], v[148:151], v[180:183], v[64:67]
	v_mfma_f32_16x16x32_bf16 v[56:59], v[156:159], v[180:183], v[56:59]
	v_mfma_f32_16x16x32_bf16 v[48:51], v[148:151], v[188:191], v[48:51]
	v_mfma_f32_16x16x32_bf16 v[40:43], v[156:159], v[188:191], v[40:43]
	v_mfma_f32_16x16x32_bf16 v[32:35], v[148:151], v[208:211], v[32:35]
	v_mfma_f32_16x16x32_bf16 v[24:27], v[156:159], v[208:211], v[24:27]
	v_mfma_f32_16x16x32_bf16 v[16:19], v[148:151], v[216:219], v[16:19]
	v_mfma_f32_16x16x32_bf16 v[8:11], v[156:159], v[216:219], v[8:11]
	v_mfma_f32_16x16x32_bf16 v[64:67], v[152:155], v[184:187], v[64:67]
	v_mfma_f32_16x16x32_bf16 v[56:59], v[160:163], v[184:187], v[56:59]
	v_mfma_f32_16x16x32_bf16 v[48:51], v[152:155], v[204:207], v[48:51]
	v_mfma_f32_16x16x32_bf16 v[40:43], v[160:163], v[204:207], v[40:43]
	v_mfma_f32_16x16x32_bf16 v[32:35], v[152:155], v[212:215], v[32:35]
	v_mfma_f32_16x16x32_bf16 v[24:27], v[160:163], v[212:215], v[24:27]
	v_mfma_f32_16x16x32_bf16 v[16:19], v[152:155], v[220:223], v[16:19]
	v_mfma_f32_16x16x32_bf16 v[8:11], v[160:163], v[220:223], v[8:11]
	s_setprio 0
	s_setprio 1
	v_mfma_f32_16x16x32_bf16 v[60:63], v[164:167], v[180:183], v[60:63]
	v_mfma_f32_16x16x32_bf16 v[52:55], v[172:175], v[180:183], v[52:55]
	v_mfma_f32_16x16x32_bf16 v[44:47], v[164:167], v[188:191], v[44:47]
	v_mfma_f32_16x16x32_bf16 v[36:39], v[172:175], v[188:191], v[36:39]
	v_mfma_f32_16x16x32_bf16 v[28:31], v[164:167], v[208:211], v[28:31]
	v_mfma_f32_16x16x32_bf16 v[20:23], v[172:175], v[208:211], v[20:23]
	v_mfma_f32_16x16x32_bf16 v[12:15], v[164:167], v[216:219], v[12:15]
	v_mfma_f32_16x16x32_bf16 v[4:7], v[172:175], v[216:219], v[4:7]
	v_mfma_f32_16x16x32_bf16 v[60:63], v[168:171], v[184:187], v[60:63]
	v_mfma_f32_16x16x32_bf16 v[52:55], v[176:179], v[184:187], v[52:55]
	v_mfma_f32_16x16x32_bf16 v[44:47], v[168:171], v[204:207], v[44:47]
	v_mfma_f32_16x16x32_bf16 v[36:39], v[176:179], v[204:207], v[36:39]
	v_mfma_f32_16x16x32_bf16 v[28:31], v[168:171], v[212:215], v[28:31]
	v_mfma_f32_16x16x32_bf16 v[20:23], v[176:179], v[212:215], v[20:23]
	v_mfma_f32_16x16x32_bf16 v[12:15], v[168:171], v[220:223], v[12:15]
	v_mfma_f32_16x16x32_bf16 v[4:7], v[176:179], v[220:223], v[4:7]
	s_setprio 0
	s_barrier
	s_add_i32 s24, s53, 2
	s_add_u32 s51, s51, 0x100
	s_addc_u32 s52, s52, 0
	s_add_u32 s22, s22, 0x100
	s_addc_u32 s23, s23, 0
	s_cmp_ge_i32 s53, s43
	s_mov_b32 s53, s24
	s_cbranch_scc0 .LBB0_244

; #define PG8_STAGE(bufoff, gbase, voff) do { _Pragma("unroll") for (int _i = 0; _i < 2; ++_i) \
;         __builtin_amdgcn_global_load_lds((const unsigned*)((const char*)(gbase) + (voff)[_i]), (PG8_LAS unsigned*)(lds + (bufoff) + ldsw + _i * 8192), 16, 0, 0); } while (0)
; #define PG8_LDA(dst, b, h) do { _Pragma("unroll") for (int m = 0; m < 4; ++m) _Pragma("unroll") for (int k = 0; k < 2; ++k) dst[m][k] = *(const PG8_LAS bf16x8*)(lds + PG8_SA(b, h) + aoff + m * 2048 + k * 1024); } while (0)
; #define PG8_LDB(dst, b, h) do { _Pragma("unroll") for (int n = 0; n < 2; ++n) _Pragma("unroll") for (int k = 0; k < 2; ++k) dst[n][k] = *(const PG8_LAS bf16x8*)(lds + PG8_SB(b, h) + boff + n * 2048 + k * 1024); } while (0)
; #define PG8_MMA(ai, bj, At, Bt) do { __builtin_amdgcn_s_setprio(1); _Pragma("unroll") for (int m = 0; m < 4; ++m) _Pragma("unroll") for (int n = 0; n < 2; ++n) _Pragma("unroll") for (int k = 0; k < 2; ++k) \
;         acc[ai][bj][m][n] = __builtin_amdgcn_mfma_f32_16x16x32_bf16(Bt[n][k], At[m][k], acc[ai][bj][m][n], 0, 0, 0); __builtin_amdgcn_s_setprio(0); } while (0)
; #define PG8_WAIT_V(n) asm volatile("s_waitcnt vmcnt(" #n ")" ::: "memory")
; template <class Epi, class Sched, bool ALIGN_EPI = false, bool SP2 = false>
; __device__ __forceinline__ void gemm_phase(PG8_LAS unsigned char* lds, const Gemm g, const Sched& S, const Epi& E, int tid_in) {
;     ...
;         for (int t = 0; t < nt; t += 2) {
;             const bool last = (t == nt - 2);
;             if constexpr (mid_hook<Epi>::value) { if (t == Epi::H1 || t == Epi::H2) E.mid(acc, cur, wr, wc, fr, fq, t == Epi::H2); }
;             const char* a1 = cA + (size_t)(t + 1) * kstep + (t >= jt ? jb : 0);
;             const char* a2 = last ? nA : cA + (size_t)(t + 2) * kstep + (t + 2 >= jt ? jb : 0); const char* b2 = last ? nB : cB + (size_t)(t + 2) * kstep;
;             const char* a3 = a2 + kstep; const char* b3 = b2 + kstep;
;             if (last && has_next) S.a_ready(nxt);
;             if constexpr (SP2) {
;             PG8_LDB(B0, 0, 0); PG8_LDB(B1, 0, 1); PG8_SCHED; PG8_LDA(At, 0, 0); PG8_STAGE(PG8_SA(1, 1), a1 + hsA, voffA);
;             PG8_WAIT_V(8); PG8_WAIT_L(0); PG8_BAR; PG8_MMA(0, 0, At, B0); PG8_MMA(0, 1, At, B1); PG8_BAR; PG8_SCHED;
;             PG8_LDA(At, 0, 1); PG8_STAGE(PG8_SB(0, 0), b2, voffB); PG8_STAGE(PG8_SB(0, 1), b2 + hsB, voffB); PG8_STAGE(PG8_SA(0, 0), a2, voffA);
.LBB0_321:
	s_add_i32 s40, s42, -2
	s_cmp_ge_i32 s40, s33
	s_cselect_b32 s78, s49, 0
	s_cselect_b32 s79, s65, 0
	s_cmp_ge_i32 s42, s33
	s_cselect_b32 s41, s49, 0
	s_cselect_b32 s40, s65, 0
	s_add_u32 s41, s4, s41
	s_addc_u32 s40, s5, s40
	s_add_u32 s43, s41, 0x80
	s_addc_u32 s40, s40, 0
	s_add_i32 s84, 0, 0x10000
	s_cmp_eq_u32 s64, s42
	s_cselect_b32 s41, s37, s40
	s_cselect_b32 s40, s36, s43
	s_cselect_b32 s83, s39, s77
	s_cselect_b32 s82, s38, s76
	s_add_i32 s43, 0, 0x14000
	v_add_u32_e32 v144, s84, v219
	v_add_u32_e32 v170, s43, v219
	ds_read_b128 v[132:135], v144
	ds_read_b128 v[136:139], v144 offset:1024
	ds_read_b128 v[140:143], v144 offset:2048
	ds_read_b128 v[144:147], v144 offset:3072
	ds_read_b128 v[148:151], v170
	ds_read_b128 v[162:165], v170 offset:1024
	ds_read_b128 v[166:169], v170 offset:2048
	ds_read_b128 v[170:173], v170 offset:3072
	v_lshl_add_u64 v[190:191], s[4:5], 0, v[160:161]
	v_lshl_add_u64 v[190:191], v[190:191], 0, s[78:79]
	s_add_i32 m0, s53, 0xc000
	ds_read_b128 v[174:177], v221
	ds_read_b128 v[178:181], v221 offset:1024
	ds_read_b128 v[182:185], v221 offset:2048
	ds_read_b128 v[186:189], v221 offset:3072
	ds_read_b128 v[204:207], v221 offset:4096
	ds_read_b128 v[208:211], v221 offset:5120
	ds_read_b128 v[212:215], v221 offset:6144
	ds_read_b128 v[238:241], v221 offset:7168
	global_load_lds_dwordx4 v[190:191], off
	v_lshl_add_u64 v[190:191], s[4:5], 0, v[158:159]
	v_lshl_add_u64 v[190:191], v[190:191], 0, s[78:79]
	s_add_i32 m0, s53, 0xe000
	s_nop 0
	global_load_lds_dwordx4 v[190:191], off
	s_waitcnt vmcnt(8)
	s_waitcnt lgkmcnt(0)
	s_barrier
	s_setprio 1
	s_waitcnt lgkmcnt(0)
	v_mfma_f32_16x16x32_bf16 v[128:131], v[132:135], v[174:177], v[128:131]
	v_mfma_f32_16x16x32_bf16 v[124:127], v[140:143], v[174:177], v[124:127]
	v_mfma_f32_16x16x32_bf16 v[120:123], v[132:135], v[182:185], v[120:123]
	v_mfma_f32_16x16x32_bf16 v[116:119], v[140:143], v[182:185], v[116:119]
	v_mfma_f32_16x16x32_bf16 v[112:115], v[132:135], v[204:207], v[112:115]
	v_mfma_f32_16x16x32_bf16 v[108:111], v[140:143], v[204:207], v[108:111]
	v_mfma_f32_16x16x32_bf16 v[104:107], v[132:135], v[212:215], v[104:107]
	v_mfma_f32_16x16x32_bf16 v[100:103], v[140:143], v[212:215], v[100:103]
	v_mfma_f32_16x16x32_bf16 v[128:131], v[136:139], v[178:181], v[128:131]
	v_mfma_f32_16x16x32_bf16 v[124:127], v[144:147], v[178:181], v[124:127]
	v_mfma_f32_16x16x32_bf16 v[120:123], v[136:139], v[186:189], v[120:123]
	v_mfma_f32_16x16x32_bf16 v[116:119], v[144:147], v[186:189], v[116:119]
	v_mfma_f32_16x16x32_bf16 v[112:115], v[136:139], v[208:211], v[112:115]
	v_mfma_f32_16x16x32_bf16 v[108:111], v[144:147], v[208:211], v[108:111]
	v_mfma_f32_16x16x32_bf16 v[104:107], v[136:139], v[238:241], v[104:107]
	v_mfma_f32_16x16x32_bf16 v[100:103], v[144:147], v[238:241], v[100:103]
	s_setprio 0
	s_setprio 1
	v_mfma_f32_16x16x32_bf16 v[64:67], v[148:151], v[174:177], v[64:67]
	v_mfma_f32_16x16x32_bf16 v[56:59], v[166:169], v[174:177], v[56:59]
	v_mfma_f32_16x16x32_bf16 v[60:63], v[148:151], v[182:185], v[60:63]
	v_mfma_f32_16x16x32_bf16 v[52:55], v[166:169], v[182:185], v[52:55]
	v_mfma_f32_16x16x32_bf16 v[48:51], v[148:151], v[204:207], v[48:51]
	v_mfma_f32_16x16x32_bf16 v[40:43], v[166:169], v[204:207], v[40:43]
	v_mfma_f32_16x16x32_bf16 v[44:47], v[148:151], v[212:215], v[44:47]
	v_mfma_f32_16x16x32_bf16 v[36:39], v[166:169], v[212:215], v[36:39]
	v_mfma_f32_16x16x32_bf16 v[64:67], v[162:165], v[178:181], v[64:67]
	v_mfma_f32_16x16x32_bf16 v[56:59], v[170:173], v[178:181], v[56:59]
	v_mfma_f32_16x16x32_bf16 v[60:63], v[162:165], v[186:189], v[60:63]
	v_mfma_f32_16x16x32_bf16 v[52:55], v[170:173], v[186:189], v[52:55]
	v_mfma_f32_16x16x32_bf16 v[48:51], v[162:165], v[208:211], v[48:51]
	v_mfma_f32_16x16x32_bf16 v[40:43], v[170:173], v[208:211], v[40:43]
	v_mfma_f32_16x16x32_bf16 v[44:47], v[162:165], v[238:241], v[44:47]
	v_mfma_f32_16x16x32_bf16 v[36:39], v[170:173], v[238:241], v[36:39]
	s_setprio 0
	s_barrier
	s_add_i32 s78, s84, s52
	v_lshl_add_u64 v[190:191], s[82:83], 0, v[152:153]
	s_mov_b32 m0, s78
	ds_read_b128 v[174:177], v221 offset:16384
	ds_read_b128 v[178:181], v221 offset:17408
	ds_read_b128 v[182:185], v221 offset:18432
	ds_read_b128 v[186:189], v221 offset:19456
	ds_read_b128 v[204:207], v221 offset:20480
	ds_read_b128 v[208:211], v221 offset:21504
	ds_read_b128 v[212:215], v221 offset:22528
	ds_read_b128 v[238:241], v221 offset:23552
	global_load_lds_dwordx4 v[190:191], off
	s_add_i32 m0, s78, 0x2000
	s_add_u32 s78, s82, s12
	v_lshl_add_u64 v[216:217], s[82:83], 0, v[156:157]
	s_addc_u32 s79, s83, s13
	s_add_i32 s43, s43, s52
	global_load_lds_dwordx4 v[216:217], off
	v_lshl_add_u64 v[222:223], s[78:79], 0, v[152:153]
	s_mov_b32 m0, s43
	v_lshl_add_u64 v[230:231], s[78:79], 0, v[156:157]
	global_load_lds_dwordx4 v[222:223], off
	s_add_i32 m0, s43, 0x2000
	v_lshl_add_u64 v[232:233], s[40:41], 0, v[0:1]
	global_load_lds_dwordx4 v[230:231], off
	s_mov_b32 m0, s53
	v_lshl_add_u64 v[242:243], s[40:41], 0, v[154:155]
	global_load_lds_dwordx4 v[232:233], off
	s_mov_b32 m0, s54
	s_nop 0
	global_load_lds_dwordx4 v[242:243], off
	s_waitcnt vmcnt(8)
	s_waitcnt lgkmcnt(0)
	s_barrier
; #define PG8_STAGE(bufoff, gbase, voff) do { _Pragma("unroll") for (int _i = 0; _i < 2; ++_i) \
;         __builtin_amdgcn_global_load_lds((const unsigned*)((const char*)(gbase) + (voff)[_i]), (PG8_LAS unsigned*)(lds + (bufoff) + ldsw + _i * 8192), 16, 0, 0); } while (0)
; #define PG8_LDA(dst, b, h) do { _Pragma("unroll") for (int m = 0; m < 4; ++m) _Pragma("unroll") for (int k = 0; k < 2; ++k) dst[m][k] = *(const PG8_LAS bf16x8*)(lds + PG8_SA(b, h) + aoff + m * 2048 + k * 1024); } while (0)
; #define PG8_LDB(dst, b, h) do { _Pragma("unroll") for (int n = 0; n < 2; ++n) _Pragma("unroll") for (int k = 0; k < 2; ++k) dst[n][k] = *(const PG8_LAS bf16x8*)(lds + PG8_SB(b, h) + boff + n * 2048 + k * 1024); } while (0)
; #define PG8_MMA(ai, bj, At, Bt) do { __builtin_amdgcn_s_setprio(1); _Pragma("unroll") for (int m = 0; m < 4; ++m) _Pragma("unroll") for (int n = 0; n < 2; ++n) _Pragma("unroll") for (int k = 0; k < 2; ++k) \
;         acc[ai][bj][m][n] = __builtin_amdgcn_mfma_f32_16x16x32_bf16(Bt[n][k], At[m][k], acc[ai][bj][m][n], 0, 0, 0); __builtin_amdgcn_s_setprio(0); } while (0)
; #define PG8_WAIT_V(n) asm volatile("s_waitcnt vmcnt(" #n ")" ::: "memory")
; #define PG8_WAIT_L(n) asm volatile("s_waitcnt lgkmcnt(" #n ")" ::: "memory")
; #define PG8_BAR __builtin_amdgcn_s_barrier()
; #define PG8_SCHED __builtin_amdgcn_sched_barrier(0)
; template <class Epi, class Sched, bool ALIGN_EPI = false, bool SP2 = false>
; __device__ __forceinline__ void gemm_phase(PG8_LAS unsigned char* lds, const Gemm g, const Sched& S, const Epi& E, int tid_in) {
;     ...
;             PG8_WAIT_V(8); PG8_WAIT_L(0); PG8_BAR; PG8_MMA(1, 0, At, B0); PG8_MMA(1, 1, At, B1); PG8_BAR; PG8_SCHED;
;             PG8_LDB(B0, 1, 0); PG8_LDB(B1, 1, 1); PG8_SCHED; PG8_LDA(At, 1, 0); PG8_STAGE(PG8_SA(0, 1), a2 + hsA, voffA);
;             PG8_WAIT_V(8); PG8_WAIT_L(0); PG8_BAR; PG8_MMA(0, 0, At, B0); PG8_MMA(0, 1, At, B1); PG8_BAR; PG8_SCHED;
;             PG8_LDA(At, 1, 1); PG8_STAGE(PG8_SB(1, 0), b3, voffB); PG8_STAGE(PG8_SB(1, 1), b3 + hsB, voffB); PG8_STAGE(PG8_SA(1, 0), a3, voffA);
	s_setprio 1
	s_waitcnt lgkmcnt(0)
	v_mfma_f32_16x16x32_bf16 v[96:99], v[132:135], v[174:177], v[96:99]
	v_mfma_f32_16x16x32_bf16 v[92:95], v[140:143], v[174:177], v[92:95]
	v_mfma_f32_16x16x32_bf16 v[88:91], v[132:135], v[182:185], v[88:91]
	v_mfma_f32_16x16x32_bf16 v[84:87], v[140:143], v[182:185], v[84:87]
	v_mfma_f32_16x16x32_bf16 v[80:83], v[132:135], v[204:207], v[80:83]
	v_mfma_f32_16x16x32_bf16 v[76:79], v[140:143], v[204:207], v[76:79]
	v_mfma_f32_16x16x32_bf16 v[72:75], v[132:135], v[212:215], v[72:75]
	v_mfma_f32_16x16x32_bf16 v[68:71], v[140:143], v[212:215], v[68:71]
	v_mfma_f32_16x16x32_bf16 v[96:99], v[136:139], v[178:181], v[96:99]
	v_mfma_f32_16x16x32_bf16 v[92:95], v[144:147], v[178:181], v[92:95]
	v_mfma_f32_16x16x32_bf16 v[88:91], v[136:139], v[186:189], v[88:91]
	v_mfma_f32_16x16x32_bf16 v[84:87], v[144:147], v[186:189], v[84:87]
	v_mfma_f32_16x16x32_bf16 v[80:83], v[136:139], v[208:211], v[80:83]
	v_mfma_f32_16x16x32_bf16 v[76:79], v[144:147], v[208:211], v[76:79]
	v_mfma_f32_16x16x32_bf16 v[72:75], v[136:139], v[238:241], v[72:75]
	v_mfma_f32_16x16x32_bf16 v[68:71], v[144:147], v[238:241], v[68:71]
	s_setprio 0
	s_setprio 1
	v_mfma_f32_16x16x32_bf16 v[32:35], v[148:151], v[174:177], v[32:35]
	v_mfma_f32_16x16x32_bf16 v[28:31], v[166:169], v[174:177], v[28:31]
	v_mfma_f32_16x16x32_bf16 v[24:27], v[148:151], v[182:185], v[24:27]
	v_mfma_f32_16x16x32_bf16 v[12:15], v[166:169], v[182:185], v[12:15]
	v_mfma_f32_16x16x32_bf16 v[20:23], v[148:151], v[204:207], v[20:23]
	v_mfma_f32_16x16x32_bf16 v[8:11], v[166:169], v[204:207], v[8:11]
	v_mfma_f32_16x16x32_bf16 v[16:19], v[148:151], v[212:215], v[16:19]
	v_mfma_f32_16x16x32_bf16 v[4:7], v[166:169], v[212:215], v[4:7]
	v_mfma_f32_16x16x32_bf16 v[32:35], v[162:165], v[178:181], v[32:35]
	v_mfma_f32_16x16x32_bf16 v[28:31], v[170:173], v[178:181], v[28:31]
	v_mfma_f32_16x16x32_bf16 v[24:27], v[162:165], v[186:189], v[24:27]
	v_mfma_f32_16x16x32_bf16 v[12:15], v[170:173], v[186:189], v[12:15]
	v_mfma_f32_16x16x32_bf16 v[20:23], v[162:165], v[208:211], v[20:23]
	v_mfma_f32_16x16x32_bf16 v[8:11], v[170:173], v[208:211], v[8:11]
	v_mfma_f32_16x16x32_bf16 v[16:19], v[162:165], v[238:241], v[16:19]
	v_mfma_f32_16x16x32_bf16 v[4:7], v[170:173], v[238:241], v[4:7]
	s_setprio 0
	s_barrier
	s_add_i32 s43, 0, 0x18000
	s_add_i32 s78, 0, 0x1c000
	v_add_u32_e32 v144, s43, v219
	v_add_u32_e32 v170, s78, v219
	ds_read_b128 v[132:135], v144
	ds_read_b128 v[136:139], v144 offset:1024
	ds_read_b128 v[140:143], v144 offset:2048
	ds_read_b128 v[144:147], v144 offset:3072
	ds_read_b128 v[148:151], v170
	ds_read_b128 v[162:165], v170 offset:1024
	ds_read_b128 v[166:169], v170 offset:2048
	ds_read_b128 v[170:173], v170 offset:3072
	s_add_u32 s40, s40, s10
	s_addc_u32 s41, s41, s11
	s_mov_b32 m0, s55
	v_lshl_add_u64 v[244:245], s[40:41], 0, v[0:1]
	ds_read_b128 v[174:177], v221 offset:32768
	ds_read_b128 v[178:181], v221 offset:33792
	ds_read_b128 v[182:185], v221 offset:34816
	ds_read_b128 v[186:189], v221 offset:35840
	ds_read_b128 v[204:207], v221 offset:36864
	ds_read_b128 v[208:211], v221 offset:37888
	ds_read_b128 v[212:215], v221 offset:38912
	ds_read_b128 v[238:241], v221 offset:39936
	global_load_lds_dwordx4 v[244:245], off
	v_lshl_add_u64 v[244:245], s[40:41], 0, v[154:155]
	s_mov_b32 m0, s58
	s_nop 0
	global_load_lds_dwordx4 v[244:245], off
	s_waitcnt vmcnt(8)
	s_waitcnt lgkmcnt(0)
	s_barrier
	s_setprio 1
	s_waitcnt lgkmcnt(0)
	v_mfma_f32_16x16x32_bf16 v[128:131], v[132:135], v[174:177], v[128:131]
	v_mfma_f32_16x16x32_bf16 v[124:127], v[140:143], v[174:177], v[124:127]
	v_mfma_f32_16x16x32_bf16 v[120:123], v[132:135], v[182:185], v[120:123]
	v_mfma_f32_16x16x32_bf16 v[116:119], v[140:143], v[182:185], v[116:119]
	v_mfma_f32_16x16x32_bf16 v[112:115], v[132:135], v[204:207], v[112:115]
	v_mfma_f32_16x16x32_bf16 v[108:111], v[140:143], v[204:207], v[108:111]
	v_mfma_f32_16x16x32_bf16 v[104:107], v[132:135], v[212:215], v[104:107]
	v_mfma_f32_16x16x32_bf16 v[100:103], v[140:143], v[212:215], v[100:103]
	v_mfma_f32_16x16x32_bf16 v[128:131], v[136:139], v[178:181], v[128:131]
	v_mfma_f32_16x16x32_bf16 v[124:127], v[144:147], v[178:181], v[124:127]
	v_mfma_f32_16x16x32_bf16 v[120:123], v[136:139], v[186:189], v[120:123]
	v_mfma_f32_16x16x32_bf16 v[116:119], v[144:147], v[186:189], v[116:119]
	v_mfma_f32_16x16x32_bf16 v[112:115], v[136:139], v[208:211], v[112:115]
	v_mfma_f32_16x16x32_bf16 v[108:111], v[144:147], v[208:211], v[108:111]
	v_mfma_f32_16x16x32_bf16 v[104:107], v[136:139], v[238:241], v[104:107]
	v_mfma_f32_16x16x32_bf16 v[100:103], v[144:147], v[238:241], v[100:103]
	s_setprio 0
	s_setprio 1
	v_mfma_f32_16x16x32_bf16 v[64:67], v[148:151], v[174:177], v[64:67]
	v_mfma_f32_16x16x32_bf16 v[56:59], v[166:169], v[174:177], v[56:59]
	v_mfma_f32_16x16x32_bf16 v[60:63], v[148:151], v[182:185], v[60:63]
	v_mfma_f32_16x16x32_bf16 v[52:55], v[166:169], v[182:185], v[52:55]
	v_mfma_f32_16x16x32_bf16 v[48:51], v[148:151], v[204:207], v[48:51]
	v_mfma_f32_16x16x32_bf16 v[40:43], v[166:169], v[204:207], v[40:43]
	v_mfma_f32_16x16x32_bf16 v[44:47], v[148:151], v[212:215], v[44:47]
	v_mfma_f32_16x16x32_bf16 v[36:39], v[166:169], v[212:215], v[36:39]
	v_mfma_f32_16x16x32_bf16 v[64:67], v[162:165], v[178:181], v[64:67]
	v_mfma_f32_16x16x32_bf16 v[56:59], v[170:173], v[178:181], v[56:59]
	v_mfma_f32_16x16x32_bf16 v[60:63], v[162:165], v[186:189], v[60:63]
	v_mfma_f32_16x16x32_bf16 v[52:55], v[170:173], v[186:189], v[52:55]
	v_mfma_f32_16x16x32_bf16 v[48:51], v[162:165], v[208:211], v[48:51]
	v_mfma_f32_16x16x32_bf16 v[40:43], v[170:173], v[208:211], v[40:43]
	v_mfma_f32_16x16x32_bf16 v[44:47], v[162:165], v[238:241], v[44:47]
	v_mfma_f32_16x16x32_bf16 v[36:39], v[170:173], v[238:241], v[36:39]
	s_setprio 0
	s_barrier
; #define PG8_STAGE(bufoff, gbase, voff) do { _Pragma("unroll") for (int _i = 0; _i < 2; ++_i) \
;         __builtin_amdgcn_global_load_lds((const unsigned*)((const char*)(gbase) + (voff)[_i]), (PG8_LAS unsigned*)(lds + (bufoff) + ldsw + _i * 8192), 16, 0, 0); } while (0)
; #define PG8_LDA(dst, b, h) do { _Pragma("unroll") for (int m = 0; m < 4; ++m) _Pragma("unroll") for (int k = 0; k < 2; ++k) dst[m][k] = *(const PG8_LAS bf16x8*)(lds + PG8_SA(b, h) + aoff + m * 2048 + k * 1024); } while (0)
; #define PG8_MMA(ai, bj, At, Bt) do { __builtin_amdgcn_s_setprio(1); _Pragma("unroll") for (int m = 0; m < 4; ++m) _Pragma("unroll") for (int n = 0; n < 2; ++n) _Pragma("unroll") for (int k = 0; k < 2; ++k) \
;         acc[ai][bj][m][n] = __builtin_amdgcn_mfma_f32_16x16x32_bf16(Bt[n][k], At[m][k], acc[ai][bj][m][n], 0, 0, 0); __builtin_amdgcn_s_setprio(0); } while (0)
; #define PG8_WAIT_V(n) asm volatile("s_waitcnt vmcnt(" #n ")" ::: "memory")
; #define PG8_WAIT_L(n) asm volatile("s_waitcnt lgkmcnt(" #n ")" ::: "memory")
; #define PG8_BAR __builtin_amdgcn_s_barrier()
; #define PG8_SCHED __builtin_amdgcn_sched_barrier(0)
; template <class Epi, class Sched, bool ALIGN_EPI = false, bool SP2 = false>
; __device__ __forceinline__ void gemm_phase(PG8_LAS unsigned char* lds, const Gemm g, const Sched& S, const Epi& E, int tid_in) {
;     ...
;             PG8_LDA(At, 1, 1); PG8_STAGE(PG8_SB(1, 0), b3, voffB); PG8_STAGE(PG8_SB(1, 1), b3 + hsB, voffB); PG8_STAGE(PG8_SA(1, 0), a3, voffA);
;             PG8_WAIT_V(8); PG8_WAIT_L(0); PG8_BAR; PG8_MMA(1, 0, At, B0); PG8_MMA(1, 1, At, B1); PG8_BAR; PG8_SCHED;
	s_add_i32 s40, s43, s52
	v_lshl_add_u64 v[190:191], v[190:191], 0, s[80:81]
	s_mov_b32 m0, s40
	ds_read_b128 v[174:177], v221 offset:49152
	ds_read_b128 v[178:181], v221 offset:50176
	ds_read_b128 v[182:185], v221 offset:51200
	ds_read_b128 v[186:189], v221 offset:52224
	ds_read_b128 v[204:207], v221 offset:53248
	ds_read_b128 v[208:211], v221 offset:54272
	ds_read_b128 v[212:215], v221 offset:55296
	ds_read_b128 v[238:241], v221 offset:56320
	global_load_lds_dwordx4 v[190:191], off
	v_lshl_add_u64 v[190:191], v[216:217], 0, s[80:81]
	s_add_i32 m0, s40, 0x2000
	s_add_i32 s40, s78, s52
	global_load_lds_dwordx4 v[190:191], off
	v_lshl_add_u64 v[190:191], v[222:223], 0, s[80:81]
	s_mov_b32 m0, s40
	s_nop 0
	global_load_lds_dwordx4 v[190:191], off
	v_lshl_add_u64 v[190:191], v[230:231], 0, s[80:81]
	s_add_i32 m0, s40, 0x2000
	s_nop 0
	global_load_lds_dwordx4 v[190:191], off
	v_lshl_add_u64 v[190:191], v[232:233], 0, s[80:81]
	s_mov_b32 m0, s61
	s_nop 0
	global_load_lds_dwordx4 v[190:191], off
	v_lshl_add_u64 v[190:191], v[242:243], 0, s[80:81]
	s_mov_b32 m0, s62
	s_nop 0
	global_load_lds_dwordx4 v[190:191], off
	s_waitcnt vmcnt(8)
	s_waitcnt lgkmcnt(0)
	s_barrier
	s_setprio 1
	s_waitcnt lgkmcnt(0)
	s_nop 0
	v_mfma_f32_16x16x32_bf16 v[96:99], v[132:135], v[174:177], v[96:99]
	v_mfma_f32_16x16x32_bf16 v[92:95], v[140:143], v[174:177], v[92:95]
	v_mfma_f32_16x16x32_bf16 v[88:91], v[132:135], v[182:185], v[88:91]
	v_mfma_f32_16x16x32_bf16 v[84:87], v[140:143], v[182:185], v[84:87]
	v_mfma_f32_16x16x32_bf16 v[80:83], v[132:135], v[204:207], v[80:83]
	v_mfma_f32_16x16x32_bf16 v[76:79], v[140:143], v[204:207], v[76:79]
	v_mfma_f32_16x16x32_bf16 v[72:75], v[132:135], v[212:215], v[72:75]
	v_mfma_f32_16x16x32_bf16 v[68:71], v[140:143], v[212:215], v[68:71]
	v_mfma_f32_16x16x32_bf16 v[96:99], v[136:139], v[178:181], v[96:99]
	v_mfma_f32_16x16x32_bf16 v[92:95], v[144:147], v[178:181], v[92:95]
	v_mfma_f32_16x16x32_bf16 v[88:91], v[136:139], v[186:189], v[88:91]
	v_mfma_f32_16x16x32_bf16 v[84:87], v[144:147], v[186:189], v[84:87]
	v_mfma_f32_16x16x32_bf16 v[80:83], v[136:139], v[208:211], v[80:83]
	v_mfma_f32_16x16x32_bf16 v[76:79], v[144:147], v[208:211], v[76:79]
	v_mfma_f32_16x16x32_bf16 v[72:75], v[136:139], v[238:241], v[72:75]
	v_mfma_f32_16x16x32_bf16 v[68:71], v[144:147], v[238:241], v[68:71]
	s_setprio 0
	s_setprio 1
	v_mfma_f32_16x16x32_bf16 v[32:35], v[148:151], v[174:177], v[32:35]
	v_mfma_f32_16x16x32_bf16 v[28:31], v[166:169], v[174:177], v[28:31]
	v_mfma_f32_16x16x32_bf16 v[24:27], v[148:151], v[182:185], v[24:27]
	v_mfma_f32_16x16x32_bf16 v[12:15], v[166:169], v[182:185], v[12:15]
	v_mfma_f32_16x16x32_bf16 v[20:23], v[148:151], v[204:207], v[20:23]
	v_mfma_f32_16x16x32_bf16 v[8:11], v[166:169], v[204:207], v[8:11]
	v_mfma_f32_16x16x32_bf16 v[16:19], v[148:151], v[212:215], v[16:19]
	v_mfma_f32_16x16x32_bf16 v[4:7], v[166:169], v[212:215], v[4:7]
	v_mfma_f32_16x16x32_bf16 v[32:35], v[162:165], v[178:181], v[32:35]
	v_mfma_f32_16x16x32_bf16 v[28:31], v[170:173], v[178:181], v[28:31]
	v_mfma_f32_16x16x32_bf16 v[24:27], v[162:165], v[186:189], v[24:27]
	v_mfma_f32_16x16x32_bf16 v[12:15], v[170:173], v[186:189], v[12:15]
	v_mfma_f32_16x16x32_bf16 v[20:23], v[162:165], v[208:211], v[20:23]
	v_mfma_f32_16x16x32_bf16 v[8:11], v[170:173], v[208:211], v[8:11]
	v_mfma_f32_16x16x32_bf16 v[16:19], v[162:165], v[238:241], v[16:19]
	v_mfma_f32_16x16x32_bf16 v[4:7], v[170:173], v[238:241], v[4:7]
	s_setprio 0
	s_barrier
	s_add_i32 s40, s42, 2
	s_add_u32 s76, s76, 0x100
	s_addc_u32 s77, s77, 0
	s_add_u32 s4, s4, 0x100
	s_addc_u32 s5, s5, 0
	s_cmp_ge_i32 s42, s64
	s_mov_b32 s42, s40
	s_cbranch_scc0 .LBB0_321
	s_movk_i32 s83, 0x3000

; #define PG8_STAGE(bufoff, gbase, voff) do { _Pragma("unroll") for (int _i = 0; _i < 2; ++_i) \
;         __builtin_amdgcn_global_load_lds((const unsigned*)((const char*)(gbase) + (voff)[_i]), (PG8_LAS unsigned*)(lds + (bufoff) + ldsw + _i * 8192), 16, 0, 0); } while (0)
; #define PG8_LDA(dst, b, h) do { _Pragma("unroll") for (int m = 0; m < 4; ++m) _Pragma("unroll") for (int k = 0; k < 2; ++k) dst[m][k] = *(const PG8_LAS bf16x8*)(lds + PG8_SA(b, h) + aoff + m * 2048 + k * 1024); } while (0)
; #define PG8_LDB(dst, b, h) do { _Pragma("unroll") for (int n = 0; n < 2; ++n) _Pragma("unroll") for (int k = 0; k < 2; ++k) dst[n][k] = *(const PG8_LAS bf16x8*)(lds + PG8_SB(b, h) + boff + n * 2048 + k * 1024); } while (0)
; #define PG8_MMA(ai, bj, At, Bt) do { __builtin_amdgcn_s_setprio(1); _Pragma("unroll") for (int m = 0; m < 4; ++m) _Pragma("unroll") for (int n = 0; n < 2; ++n) _Pragma("unroll") for (int k = 0; k < 2; ++k) \
;         acc[ai][bj][m][n] = __builtin_amdgcn_mfma_f32_16x16x32_bf16(Bt[n][k], At[m][k], acc[ai][bj][m][n], 0, 0, 0); __builtin_amdgcn_s_setprio(0); } while (0)
; #define PG8_WAIT_V(n) asm volatile("s_waitcnt vmcnt(" #n ")" ::: "memory")
; template <class Epi, class Sched, bool ALIGN_EPI = false, bool SP2 = false>
; __device__ __forceinline__ void gemm_phase(PG8_LAS unsigned char* lds, const Gemm g, const Sched& S, const Epi& E, int tid_in) {
;     ...
;         for (int t = 0; t < nt; t += 2) {
;             const bool last = (t == nt - 2);
;             if constexpr (mid_hook<Epi>::value) { if (t == Epi::H1 || t == Epi::H2) E.mid(acc, cur, wr, wc, fr, fq, t == Epi::H2); }
;             const char* a1 = cA + (size_t)(t + 1) * kstep + (t >= jt ? jb : 0);
;             const char* a2 = last ? nA : cA + (size_t)(t + 2) * kstep + (t + 2 >= jt ? jb : 0); const char* b2 = last ? nB : cB + (size_t)(t + 2) * kstep;
;             const char* a3 = a2 + kstep; const char* b3 = b2 + kstep;
;             if (last && has_next) S.a_ready(nxt);
;             if constexpr (SP2) {
;             PG8_LDB(B0, 0, 0); PG8_LDB(B1, 0, 1); PG8_SCHED; PG8_LDA(At, 0, 0); PG8_STAGE(PG8_SA(1, 1), a1 + hsA, voffA);
;             PG8_WAIT_V(8); PG8_WAIT_L(0); PG8_BAR; PG8_MMA(0, 0, At, B0); PG8_MMA(0, 1, At, B1); PG8_BAR; PG8_SCHED;
;             PG8_LDA(At, 0, 1); PG8_STAGE(PG8_SB(0, 0), b2, voffB); PG8_STAGE(PG8_SB(0, 1), b2 + hsB, voffB); PG8_STAGE(PG8_SA(0, 0), a2, voffA);
.LBB0_352:
	s_add_i32 s24, s55, -2
	s_cmp_ge_i32 s24, s26
	s_cselect_b32 s58, s27, 0
	s_cselect_b32 s59, s42, 0
	s_cmp_ge_i32 s55, s26
	s_cselect_b32 s25, s27, 0
	s_cselect_b32 s24, s42, 0
	s_add_u32 s25, s22, s25
	s_addc_u32 s24, s23, s24
	s_add_u32 s60, s25, 0x80
	s_addc_u32 s24, s24, 0
	s_add_i32 s62, 0, 0x10000
	s_cmp_eq_u32 s41, s55
	s_cselect_b32 s25, s5, s24
	s_cselect_b32 s24, s4, s60
	s_cselect_b32 s61, s21, s54
	s_cselect_b32 s60, s20, s53
	s_add_i32 s63, 0, 0x14000
	v_add_u32_e32 v160, s62, v3
	v_add_u32_e32 v176, s63, v3
	ds_read_b128 v[148:151], v160
	ds_read_b128 v[152:155], v160 offset:1024
	ds_read_b128 v[156:159], v160 offset:2048
	ds_read_b128 v[160:163], v160 offset:3072
	ds_read_b128 v[164:167], v176
	ds_read_b128 v[168:171], v176 offset:1024
	ds_read_b128 v[172:175], v176 offset:2048
	ds_read_b128 v[176:179], v176 offset:3072
	v_lshl_add_u64 v[230:231], s[22:23], 0, v[140:141]
	v_lshl_add_u64 v[230:231], v[230:231], 0, s[58:59]
	s_add_i32 m0, s31, 0xc000
	ds_read_b128 v[180:183], v147
	ds_read_b128 v[184:187], v147 offset:1024
	ds_read_b128 v[188:191], v147 offset:2048
	ds_read_b128 v[204:207], v147 offset:3072
	ds_read_b128 v[208:211], v147 offset:4096
	ds_read_b128 v[212:215], v147 offset:5120
	ds_read_b128 v[216:219], v147 offset:6144
	ds_read_b128 v[220:223], v147 offset:7168
	global_load_lds_dwordx4 v[230:231], off
	v_lshl_add_u64 v[230:231], s[22:23], 0, v[138:139]
	v_lshl_add_u64 v[230:231], v[230:231], 0, s[58:59]
	s_add_i32 m0, s31, 0xe000
	s_nop 0
	global_load_lds_dwordx4 v[230:231], off
	s_waitcnt vmcnt(8)
	s_waitcnt lgkmcnt(0)
	s_barrier
	s_setprio 1
	s_waitcnt lgkmcnt(0)
	s_nop 0
	v_mfma_f32_16x16x32_bf16 v[124:127], v[148:151], v[180:183], v[124:127]
	v_mfma_f32_16x16x32_bf16 v[128:131], v[156:159], v[180:183], v[128:131]
	v_mfma_f32_16x16x32_bf16 v[112:115], v[148:151], v[188:191], v[112:115]
	v_mfma_f32_16x16x32_bf16 v[108:111], v[156:159], v[188:191], v[108:111]
	v_mfma_f32_16x16x32_bf16 v[96:99], v[148:151], v[208:211], v[96:99]
	v_mfma_f32_16x16x32_bf16 v[92:95], v[156:159], v[208:211], v[92:95]
	v_mfma_f32_16x16x32_bf16 v[80:83], v[148:151], v[216:219], v[80:83]
	v_mfma_f32_16x16x32_bf16 v[76:79], v[156:159], v[216:219], v[76:79]
	v_mfma_f32_16x16x32_bf16 v[124:127], v[152:155], v[184:187], v[124:127]
	v_mfma_f32_16x16x32_bf16 v[128:131], v[160:163], v[184:187], v[128:131]
	v_mfma_f32_16x16x32_bf16 v[112:115], v[152:155], v[204:207], v[112:115]
	v_mfma_f32_16x16x32_bf16 v[108:111], v[160:163], v[204:207], v[108:111]
	v_mfma_f32_16x16x32_bf16 v[96:99], v[152:155], v[212:215], v[96:99]
	v_mfma_f32_16x16x32_bf16 v[92:95], v[160:163], v[212:215], v[92:95]
	v_mfma_f32_16x16x32_bf16 v[80:83], v[152:155], v[220:223], v[80:83]
	v_mfma_f32_16x16x32_bf16 v[76:79], v[160:163], v[220:223], v[76:79]
	s_setprio 0
	s_setprio 1
	v_mfma_f32_16x16x32_bf16 v[120:123], v[164:167], v[180:183], v[120:123]
	v_mfma_f32_16x16x32_bf16 v[116:119], v[172:175], v[180:183], v[116:119]
	v_mfma_f32_16x16x32_bf16 v[104:107], v[164:167], v[188:191], v[104:107]
	v_mfma_f32_16x16x32_bf16 v[100:103], v[172:175], v[188:191], v[100:103]
	v_mfma_f32_16x16x32_bf16 v[88:91], v[164:167], v[208:211], v[88:91]
	v_mfma_f32_16x16x32_bf16 v[84:87], v[172:175], v[208:211], v[84:87]
	v_mfma_f32_16x16x32_bf16 v[72:75], v[164:167], v[216:219], v[72:75]
	v_mfma_f32_16x16x32_bf16 v[68:71], v[172:175], v[216:219], v[68:71]
	v_mfma_f32_16x16x32_bf16 v[120:123], v[168:171], v[184:187], v[120:123]
	v_mfma_f32_16x16x32_bf16 v[116:119], v[176:179], v[184:187], v[116:119]
	v_mfma_f32_16x16x32_bf16 v[104:107], v[168:171], v[204:207], v[104:107]
	v_mfma_f32_16x16x32_bf16 v[100:103], v[176:179], v[204:207], v[100:103]
	v_mfma_f32_16x16x32_bf16 v[88:91], v[168:171], v[212:215], v[88:91]
	v_mfma_f32_16x16x32_bf16 v[84:87], v[176:179], v[212:215], v[84:87]
	v_mfma_f32_16x16x32_bf16 v[72:75], v[168:171], v[220:223], v[72:75]
	v_mfma_f32_16x16x32_bf16 v[68:71], v[176:179], v[220:223], v[68:71]
	s_setprio 0
	s_barrier
	s_add_i32 s58, s62, s30
	v_lshl_add_u64 v[230:231], s[60:61], 0, v[134:135]
	s_mov_b32 m0, s58
	ds_read_b128 v[180:183], v147 offset:16384
	ds_read_b128 v[184:187], v147 offset:17408
	ds_read_b128 v[188:191], v147 offset:18432
	ds_read_b128 v[204:207], v147 offset:19456
	ds_read_b128 v[208:211], v147 offset:20480
	ds_read_b128 v[212:215], v147 offset:21504
	ds_read_b128 v[216:219], v147 offset:22528
	ds_read_b128 v[220:223], v147 offset:23552
	global_load_lds_dwordx4 v[230:231], off
	s_add_i32 m0, s58, 0x2000
	s_add_u32 s58, s60, s8
	v_lshl_add_u64 v[232:233], s[60:61], 0, v[0:1]
	s_addc_u32 s59, s61, s9
	s_add_i32 s60, s63, s30
	global_load_lds_dwordx4 v[232:233], off
	v_lshl_add_u64 v[238:239], s[58:59], 0, v[134:135]
	s_mov_b32 m0, s60
	v_lshl_add_u64 v[240:241], s[58:59], 0, v[0:1]
	global_load_lds_dwordx4 v[238:239], off
	s_add_i32 m0, s60, 0x2000
	v_lshl_add_u64 v[242:243], s[24:25], 0, v[136:137]
	global_load_lds_dwordx4 v[240:241], off
	s_mov_b32 m0, s31
	v_lshl_add_u64 v[244:245], s[24:25], 0, v[132:133]
	global_load_lds_dwordx4 v[242:243], off
	s_mov_b32 m0, s33
	s_nop 0
	global_load_lds_dwordx4 v[244:245], off
	s_waitcnt vmcnt(8)
	s_waitcnt lgkmcnt(0)
	s_barrier
; #define PG8_STAGE(bufoff, gbase, voff) do { _Pragma("unroll") for (int _i = 0; _i < 2; ++_i) \
;         __builtin_amdgcn_global_load_lds((const unsigned*)((const char*)(gbase) + (voff)[_i]), (PG8_LAS unsigned*)(lds + (bufoff) + ldsw + _i * 8192), 16, 0, 0); } while (0)
; #define PG8_LDA(dst, b, h) do { _Pragma("unroll") for (int m = 0; m < 4; ++m) _Pragma("unroll") for (int k = 0; k < 2; ++k) dst[m][k] = *(const PG8_LAS bf16x8*)(lds + PG8_SA(b, h) + aoff + m * 2048 + k * 1024); } while (0)
; #define PG8_LDB(dst, b, h) do { _Pragma("unroll") for (int n = 0; n < 2; ++n) _Pragma("unroll") for (int k = 0; k < 2; ++k) dst[n][k] = *(const PG8_LAS bf16x8*)(lds + PG8_SB(b, h) + boff + n * 2048 + k * 1024); } while (0)
; #define PG8_MMA(ai, bj, At, Bt) do { __builtin_amdgcn_s_setprio(1); _Pragma("unroll") for (int m = 0; m < 4; ++m) _Pragma("unroll") for (int n = 0; n < 2; ++n) _Pragma("unroll") for (int k = 0; k < 2; ++k) \
;         acc[ai][bj][m][n] = __builtin_amdgcn_mfma_f32_16x16x32_bf16(Bt[n][k], At[m][k], acc[ai][bj][m][n], 0, 0, 0); __builtin_amdgcn_s_setprio(0); } while (0)
; #define PG8_WAIT_V(n) asm volatile("s_waitcnt vmcnt(" #n ")" ::: "memory")
; #define PG8_WAIT_L(n) asm volatile("s_waitcnt lgkmcnt(" #n ")" ::: "memory")
; #define PG8_BAR __builtin_amdgcn_s_barrier()
; #define PG8_SCHED __builtin_amdgcn_sched_barrier(0)
; template <class Epi, class Sched, bool ALIGN_EPI = false, bool SP2 = false>
; __device__ __forceinline__ void gemm_phase(PG8_LAS unsigned char* lds, const Gemm g, const Sched& S, const Epi& E, int tid_in) {
;     ...
;             PG8_WAIT_V(8); PG8_WAIT_L(0); PG8_BAR; PG8_MMA(1, 0, At, B0); PG8_MMA(1, 1, At, B1); PG8_BAR; PG8_SCHED;
;             PG8_LDB(B0, 1, 0); PG8_LDB(B1, 1, 1); PG8_SCHED; PG8_LDA(At, 1, 0); PG8_STAGE(PG8_SA(0, 1), a2 + hsA, voffA);
;             PG8_WAIT_V(8); PG8_WAIT_L(0); PG8_BAR; PG8_MMA(0, 0, At, B0); PG8_MMA(0, 1, At, B1); PG8_BAR; PG8_SCHED;
;             PG8_LDA(At, 1, 1); PG8_STAGE(PG8_SB(1, 0), b3, voffB); PG8_STAGE(PG8_SB(1, 1), b3 + hsB, voffB); PG8_STAGE(PG8_SA(1, 0), a3, voffA);
	s_setprio 1
	s_waitcnt lgkmcnt(0)
	v_mfma_f32_16x16x32_bf16 v[64:67], v[148:151], v[180:183], v[64:67]
	v_mfma_f32_16x16x32_bf16 v[60:63], v[156:159], v[180:183], v[60:63]
	v_mfma_f32_16x16x32_bf16 v[48:51], v[148:151], v[188:191], v[48:51]
	v_mfma_f32_16x16x32_bf16 v[44:47], v[156:159], v[188:191], v[44:47]
	v_mfma_f32_16x16x32_bf16 v[32:35], v[148:151], v[208:211], v[32:35]
	v_mfma_f32_16x16x32_bf16 v[28:31], v[156:159], v[208:211], v[28:31]
	v_mfma_f32_16x16x32_bf16 v[16:19], v[148:151], v[216:219], v[16:19]
	v_mfma_f32_16x16x32_bf16 v[12:15], v[156:159], v[216:219], v[12:15]
	v_mfma_f32_16x16x32_bf16 v[64:67], v[152:155], v[184:187], v[64:67]
	v_mfma_f32_16x16x32_bf16 v[60:63], v[160:163], v[184:187], v[60:63]
	v_mfma_f32_16x16x32_bf16 v[48:51], v[152:155], v[204:207], v[48:51]
	v_mfma_f32_16x16x32_bf16 v[44:47], v[160:163], v[204:207], v[44:47]
	v_mfma_f32_16x16x32_bf16 v[32:35], v[152:155], v[212:215], v[32:35]
	v_mfma_f32_16x16x32_bf16 v[28:31], v[160:163], v[212:215], v[28:31]
	v_mfma_f32_16x16x32_bf16 v[16:19], v[152:155], v[220:223], v[16:19]
	v_mfma_f32_16x16x32_bf16 v[12:15], v[160:163], v[220:223], v[12:15]
	s_setprio 0
	s_setprio 1
	v_mfma_f32_16x16x32_bf16 v[56:59], v[164:167], v[180:183], v[56:59]
	v_mfma_f32_16x16x32_bf16 v[52:55], v[172:175], v[180:183], v[52:55]
	v_mfma_f32_16x16x32_bf16 v[40:43], v[164:167], v[188:191], v[40:43]
	v_mfma_f32_16x16x32_bf16 v[36:39], v[172:175], v[188:191], v[36:39]
	v_mfma_f32_16x16x32_bf16 v[24:27], v[164:167], v[208:211], v[24:27]
	v_mfma_f32_16x16x32_bf16 v[20:23], v[172:175], v[208:211], v[20:23]
	v_mfma_f32_16x16x32_bf16 v[8:11], v[164:167], v[216:219], v[8:11]
	v_mfma_f32_16x16x32_bf16 v[4:7], v[172:175], v[216:219], v[4:7]
	v_mfma_f32_16x16x32_bf16 v[56:59], v[168:171], v[184:187], v[56:59]
	v_mfma_f32_16x16x32_bf16 v[52:55], v[176:179], v[184:187], v[52:55]
	v_mfma_f32_16x16x32_bf16 v[40:43], v[168:171], v[204:207], v[40:43]
	v_mfma_f32_16x16x32_bf16 v[36:39], v[176:179], v[204:207], v[36:39]
	v_mfma_f32_16x16x32_bf16 v[24:27], v[168:171], v[212:215], v[24:27]
	v_mfma_f32_16x16x32_bf16 v[20:23], v[176:179], v[212:215], v[20:23]
	v_mfma_f32_16x16x32_bf16 v[8:11], v[168:171], v[220:223], v[8:11]
	v_mfma_f32_16x16x32_bf16 v[4:7], v[176:179], v[220:223], v[4:7]
	s_setprio 0
	s_barrier
	s_add_i32 s58, 0, 0x18000
	s_add_i32 s59, 0, 0x1c000
	v_add_u32_e32 v160, s58, v3
	v_add_u32_e32 v176, s59, v3
	ds_read_b128 v[148:151], v160
	ds_read_b128 v[152:155], v160 offset:1024
	ds_read_b128 v[156:159], v160 offset:2048
	ds_read_b128 v[160:163], v160 offset:3072
	ds_read_b128 v[164:167], v176
	ds_read_b128 v[168:171], v176 offset:1024
	ds_read_b128 v[172:175], v176 offset:2048
	ds_read_b128 v[176:179], v176 offset:3072
	s_add_u32 s24, s24, s6
	s_addc_u32 s25, s25, s7
	s_mov_b32 m0, s34
	v_lshl_add_u64 v[246:247], s[24:25], 0, v[136:137]
	ds_read_b128 v[180:183], v147 offset:32768
	ds_read_b128 v[184:187], v147 offset:33792
	ds_read_b128 v[188:191], v147 offset:34816
	ds_read_b128 v[204:207], v147 offset:35840
	ds_read_b128 v[208:211], v147 offset:36864
	ds_read_b128 v[212:215], v147 offset:37888
	ds_read_b128 v[216:219], v147 offset:38912
	ds_read_b128 v[220:223], v147 offset:39936
	global_load_lds_dwordx4 v[246:247], off
	v_lshl_add_u64 v[246:247], s[24:25], 0, v[132:133]
	s_mov_b32 m0, s35
	s_nop 0
	global_load_lds_dwordx4 v[246:247], off
	s_waitcnt vmcnt(8)
	s_waitcnt lgkmcnt(0)
	s_barrier
	s_setprio 1
	s_waitcnt lgkmcnt(0)
	v_mfma_f32_16x16x32_bf16 v[124:127], v[148:151], v[180:183], v[124:127]
	v_mfma_f32_16x16x32_bf16 v[128:131], v[156:159], v[180:183], v[128:131]
	v_mfma_f32_16x16x32_bf16 v[112:115], v[148:151], v[188:191], v[112:115]
	v_mfma_f32_16x16x32_bf16 v[108:111], v[156:159], v[188:191], v[108:111]
	v_mfma_f32_16x16x32_bf16 v[96:99], v[148:151], v[208:211], v[96:99]
	v_mfma_f32_16x16x32_bf16 v[92:95], v[156:159], v[208:211], v[92:95]
	v_mfma_f32_16x16x32_bf16 v[80:83], v[148:151], v[216:219], v[80:83]
	v_mfma_f32_16x16x32_bf16 v[76:79], v[156:159], v[216:219], v[76:79]
	v_mfma_f32_16x16x32_bf16 v[124:127], v[152:155], v[184:187], v[124:127]
	v_mfma_f32_16x16x32_bf16 v[128:131], v[160:163], v[184:187], v[128:131]
	v_mfma_f32_16x16x32_bf16 v[112:115], v[152:155], v[204:207], v[112:115]
	v_mfma_f32_16x16x32_bf16 v[108:111], v[160:163], v[204:207], v[108:111]
	v_mfma_f32_16x16x32_bf16 v[96:99], v[152:155], v[212:215], v[96:99]
	v_mfma_f32_16x16x32_bf16 v[92:95], v[160:163], v[212:215], v[92:95]
	v_mfma_f32_16x16x32_bf16 v[80:83], v[152:155], v[220:223], v[80:83]
	v_mfma_f32_16x16x32_bf16 v[76:79], v[160:163], v[220:223], v[76:79]
	s_setprio 0
	s_setprio 1
	v_mfma_f32_16x16x32_bf16 v[120:123], v[164:167], v[180:183], v[120:123]
	v_mfma_f32_16x16x32_bf16 v[116:119], v[172:175], v[180:183], v[116:119]
	v_mfma_f32_16x16x32_bf16 v[104:107], v[164:167], v[188:191], v[104:107]
	v_mfma_f32_16x16x32_bf16 v[100:103], v[172:175], v[188:191], v[100:103]
	v_mfma_f32_16x16x32_bf16 v[88:91], v[164:167], v[208:211], v[88:91]
	v_mfma_f32_16x16x32_bf16 v[84:87], v[172:175], v[208:211], v[84:87]
	v_mfma_f32_16x16x32_bf16 v[72:75], v[164:167], v[216:219], v[72:75]
	v_mfma_f32_16x16x32_bf16 v[68:71], v[172:175], v[216:219], v[68:71]
	v_mfma_f32_16x16x32_bf16 v[120:123], v[168:171], v[184:187], v[120:123]
	v_mfma_f32_16x16x32_bf16 v[116:119], v[176:179], v[184:187], v[116:119]
	v_mfma_f32_16x16x32_bf16 v[104:107], v[168:171], v[204:207], v[104:107]
	v_mfma_f32_16x16x32_bf16 v[100:103], v[176:179], v[204:207], v[100:103]
	v_mfma_f32_16x16x32_bf16 v[88:91], v[168:171], v[212:215], v[88:91]
	v_mfma_f32_16x16x32_bf16 v[84:87], v[176:179], v[212:215], v[84:87]
	v_mfma_f32_16x16x32_bf16 v[72:75], v[168:171], v[220:223], v[72:75]
	v_mfma_f32_16x16x32_bf16 v[68:71], v[176:179], v[220:223], v[68:71]
	s_setprio 0
	s_barrier
; #define PG8_STAGE(bufoff, gbase, voff) do { _Pragma("unroll") for (int _i = 0; _i < 2; ++_i) \
;         __builtin_amdgcn_global_load_lds((const unsigned*)((const char*)(gbase) + (voff)[_i]), (PG8_LAS unsigned*)(lds + (bufoff) + ldsw + _i * 8192), 16, 0, 0); } while (0)
; #define PG8_LDA(dst, b, h) do { _Pragma("unroll") for (int m = 0; m < 4; ++m) _Pragma("unroll") for (int k = 0; k < 2; ++k) dst[m][k] = *(const PG8_LAS bf16x8*)(lds + PG8_SA(b, h) + aoff + m * 2048 + k * 1024); } while (0)
; #define PG8_MMA(ai, bj, At, Bt) do { __builtin_amdgcn_s_setprio(1); _Pragma("unroll") for (int m = 0; m < 4; ++m) _Pragma("unroll") for (int n = 0; n < 2; ++n) _Pragma("unroll") for (int k = 0; k < 2; ++k) \
;         acc[ai][bj][m][n] = __builtin_amdgcn_mfma_f32_16x16x32_bf16(Bt[n][k], At[m][k], acc[ai][bj][m][n], 0, 0, 0); __builtin_amdgcn_s_setprio(0); } while (0)
; #define PG8_WAIT_V(n) asm volatile("s_waitcnt vmcnt(" #n ")" ::: "memory")
; #define PG8_WAIT_L(n) asm volatile("s_waitcnt lgkmcnt(" #n ")" ::: "memory")
; #define PG8_BAR __builtin_amdgcn_s_barrier()
; #define PG8_SCHED __builtin_amdgcn_sched_barrier(0)
; template <class Epi, class Sched, bool ALIGN_EPI = false, bool SP2 = false>
; __device__ __forceinline__ void gemm_phase(PG8_LAS unsigned char* lds, const Gemm g, const Sched& S, const Epi& E, int tid_in) {
;     ...
;             PG8_LDA(At, 1, 1); PG8_STAGE(PG8_SB(1, 0), b3, voffB); PG8_STAGE(PG8_SB(1, 1), b3 + hsB, voffB); PG8_STAGE(PG8_SA(1, 0), a3, voffA);
;             PG8_WAIT_V(8); PG8_WAIT_L(0); PG8_BAR; PG8_MMA(1, 0, At, B0); PG8_MMA(1, 1, At, B1); PG8_BAR; PG8_SCHED;
	s_add_i32 s24, s58, s30
	v_lshl_add_u64 v[230:231], v[230:231], 0, s[80:81]
	s_mov_b32 m0, s24
	ds_read_b128 v[180:183], v147 offset:49152
	ds_read_b128 v[184:187], v147 offset:50176
	ds_read_b128 v[188:191], v147 offset:51200
	ds_read_b128 v[204:207], v147 offset:52224
	ds_read_b128 v[208:211], v147 offset:53248
	ds_read_b128 v[212:215], v147 offset:54272
	ds_read_b128 v[216:219], v147 offset:55296
	ds_read_b128 v[220:223], v147 offset:56320
	global_load_lds_dwordx4 v[230:231], off
	v_lshl_add_u64 v[230:231], v[232:233], 0, s[80:81]
	s_add_i32 m0, s24, 0x2000
	s_add_i32 s24, s59, s30
	global_load_lds_dwordx4 v[230:231], off
	v_lshl_add_u64 v[230:231], v[238:239], 0, s[80:81]
	s_mov_b32 m0, s24
	s_nop 0
	global_load_lds_dwordx4 v[230:231], off
	v_lshl_add_u64 v[230:231], v[240:241], 0, s[80:81]
	s_add_i32 m0, s24, 0x2000
	s_nop 0
	global_load_lds_dwordx4 v[230:231], off
	v_lshl_add_u64 v[230:231], v[242:243], 0, s[80:81]
	s_mov_b32 m0, s38
	s_nop 0
	global_load_lds_dwordx4 v[230:231], off
	v_lshl_add_u64 v[230:231], v[244:245], 0, s[80:81]
	s_mov_b32 m0, s39
	s_nop 0
	global_load_lds_dwordx4 v[230:231], off
	s_waitcnt vmcnt(8)
	s_waitcnt lgkmcnt(0)
	s_barrier
	s_setprio 1
	s_waitcnt lgkmcnt(0)
	s_nop 0
	v_mfma_f32_16x16x32_bf16 v[64:67], v[148:151], v[180:183], v[64:67]
	v_mfma_f32_16x16x32_bf16 v[60:63], v[156:159], v[180:183], v[60:63]
	v_mfma_f32_16x16x32_bf16 v[48:51], v[148:151], v[188:191], v[48:51]
	v_mfma_f32_16x16x32_bf16 v[44:47], v[156:159], v[188:191], v[44:47]
	v_mfma_f32_16x16x32_bf16 v[32:35], v[148:151], v[208:211], v[32:35]
	v_mfma_f32_16x16x32_bf16 v[28:31], v[156:159], v[208:211], v[28:31]
	v_mfma_f32_16x16x32_bf16 v[16:19], v[148:151], v[216:219], v[16:19]
	v_mfma_f32_16x16x32_bf16 v[12:15], v[156:159], v[216:219], v[12:15]
	v_mfma_f32_16x16x32_bf16 v[64:67], v[152:155], v[184:187], v[64:67]
	v_mfma_f32_16x16x32_bf16 v[60:63], v[160:163], v[184:187], v[60:63]
	v_mfma_f32_16x16x32_bf16 v[48:51], v[152:155], v[204:207], v[48:51]
	v_mfma_f32_16x16x32_bf16 v[44:47], v[160:163], v[204:207], v[44:47]
	v_mfma_f32_16x16x32_bf16 v[32:35], v[152:155], v[212:215], v[32:35]
	v_mfma_f32_16x16x32_bf16 v[28:31], v[160:163], v[212:215], v[28:31]
	v_mfma_f32_16x16x32_bf16 v[16:19], v[152:155], v[220:223], v[16:19]
	v_mfma_f32_16x16x32_bf16 v[12:15], v[160:163], v[220:223], v[12:15]
	s_setprio 0
	s_setprio 1
	v_mfma_f32_16x16x32_bf16 v[56:59], v[164:167], v[180:183], v[56:59]
	v_mfma_f32_16x16x32_bf16 v[52:55], v[172:175], v[180:183], v[52:55]
	v_mfma_f32_16x16x32_bf16 v[40:43], v[164:167], v[188:191], v[40:43]
	v_mfma_f32_16x16x32_bf16 v[36:39], v[172:175], v[188:191], v[36:39]
	v_mfma_f32_16x16x32_bf16 v[24:27], v[164:167], v[208:211], v[24:27]
	v_mfma_f32_16x16x32_bf16 v[20:23], v[172:175], v[208:211], v[20:23]
	v_mfma_f32_16x16x32_bf16 v[8:11], v[164:167], v[216:219], v[8:11]
	v_mfma_f32_16x16x32_bf16 v[4:7], v[172:175], v[216:219], v[4:7]
	v_mfma_f32_16x16x32_bf16 v[56:59], v[168:171], v[184:187], v[56:59]
	v_mfma_f32_16x16x32_bf16 v[52:55], v[176:179], v[184:187], v[52:55]
	v_mfma_f32_16x16x32_bf16 v[40:43], v[168:171], v[204:207], v[40:43]
	v_mfma_f32_16x16x32_bf16 v[36:39], v[176:179], v[204:207], v[36:39]
	v_mfma_f32_16x16x32_bf16 v[24:27], v[168:171], v[212:215], v[24:27]
	v_mfma_f32_16x16x32_bf16 v[20:23], v[176:179], v[212:215], v[20:23]
	v_mfma_f32_16x16x32_bf16 v[8:11], v[168:171], v[220:223], v[8:11]
	v_mfma_f32_16x16x32_bf16 v[4:7], v[176:179], v[220:223], v[4:7]
	s_setprio 0
	s_barrier
	s_add_i32 s24, s55, 2
	s_add_u32 s53, s53, 0x100
	s_addc_u32 s54, s54, 0
	s_add_u32 s22, s22, 0x100
	s_addc_u32 s23, s23, 0
	s_cmp_ge_i32 s55, s41
	s_mov_b32 s55, s24
	s_cbranch_scc0 .LBB0_352

; #define PG8_STAGE(bufoff, gbase, voff) do { _Pragma("unroll") for (int _i = 0; _i < 2; ++_i) \
;         __builtin_amdgcn_global_load_lds((const unsigned*)((const char*)(gbase) + (voff)[_i]), (PG8_LAS unsigned*)(lds + (bufoff) + ldsw + _i * 8192), 16, 0, 0); } while (0)
; #define PG8_LDA(dst, b, h) do { _Pragma("unroll") for (int m = 0; m < 4; ++m) _Pragma("unroll") for (int k = 0; k < 2; ++k) dst[m][k] = *(const PG8_LAS bf16x8*)(lds + PG8_SA(b, h) + aoff + m * 2048 + k * 1024); } while (0)
; #define PG8_LDB(dst, b, h) do { _Pragma("unroll") for (int n = 0; n < 2; ++n) _Pragma("unroll") for (int k = 0; k < 2; ++k) dst[n][k] = *(const PG8_LAS bf16x8*)(lds + PG8_SB(b, h) + boff + n * 2048 + k * 1024); } while (0)
; #define PG8_MMA(ai, bj, At, Bt) do { __builtin_amdgcn_s_setprio(1); _Pragma("unroll") for (int m = 0; m < 4; ++m) _Pragma("unroll") for (int n = 0; n < 2; ++n) _Pragma("unroll") for (int k = 0; k < 2; ++k) \
;         acc[ai][bj][m][n] = __builtin_amdgcn_mfma_f32_16x16x32_bf16(Bt[n][k], At[m][k], acc[ai][bj][m][n], 0, 0, 0); __builtin_amdgcn_s_setprio(0); } while (0)
; #define PG8_WAIT_V(n) asm volatile("s_waitcnt vmcnt(" #n ")" ::: "memory")
; template <class Epi, class Sched, bool ALIGN_EPI = false, bool SP2 = false>
; __device__ __forceinline__ void gemm_phase(PG8_LAS unsigned char* lds, const Gemm g, const Sched& S, const Epi& E, int tid_in) {
;     ...
;         for (int t = 0; t < nt; t += 2) {
;             const bool last = (t == nt - 2);
;             if constexpr (mid_hook<Epi>::value) { if (t == Epi::H1 || t == Epi::H2) E.mid(acc, cur, wr, wc, fr, fq, t == Epi::H2); }
;             const char* a1 = cA + (size_t)(t + 1) * kstep + (t >= jt ? jb : 0);
;             const char* a2 = last ? nA : cA + (size_t)(t + 2) * kstep + (t + 2 >= jt ? jb : 0); const char* b2 = last ? nB : cB + (size_t)(t + 2) * kstep;
;             const char* a3 = a2 + kstep; const char* b3 = b2 + kstep;
;             if (last && has_next) S.a_ready(nxt);
;             if constexpr (SP2) {
;             PG8_LDB(B0, 0, 0); PG8_LDB(B1, 0, 1); PG8_SCHED; PG8_LDA(At, 0, 0); PG8_STAGE(PG8_SA(1, 1), a1 + hsA, voffA);
;             PG8_WAIT_V(8); PG8_WAIT_L(0); PG8_BAR; PG8_MMA(0, 0, At, B0); PG8_MMA(0, 1, At, B1); PG8_BAR; PG8_SCHED;
;             PG8_LDA(At, 0, 1); PG8_STAGE(PG8_SB(0, 0), b2, voffB); PG8_STAGE(PG8_SB(0, 1), b2 + hsB, voffB); PG8_STAGE(PG8_SA(0, 0), a2, voffA);
.LBB0_485:
	s_add_i32 s24, s53, -2
	s_cmp_ge_i32 s24, s28
	s_cselect_b32 s54, s29, 0
	s_cselect_b32 s55, s45, 0
	s_cmp_ge_i32 s53, s28
	s_cselect_b32 s25, s29, 0
	s_cselect_b32 s24, s45, 0
	s_add_u32 s25, s22, s25
	s_addc_u32 s24, s23, s24
	s_add_u32 s58, s25, 0x80
	s_addc_u32 s24, s24, 0
	s_add_i32 s60, 0, 0x10000
	s_cmp_eq_u32 s44, s53
	s_cselect_b32 s25, s5, s24
	s_cselect_b32 s24, s4, s58
	v_add_u32_e32 v145, s60, v142
	s_cselect_b32 s59, s21, s52
	s_cselect_b32 s58, s20, s51
	s_add_i32 s61, 0, 0x14000
	ds_read_b128 v[146:149], v145
	ds_read_b128 v[150:153], v145 offset:1024
	ds_read_b128 v[154:157], v145 offset:2048
	ds_read_b128 v[158:161], v145 offset:3072
	v_add_u32_e32 v145, s61, v142
	ds_read_b128 v[162:165], v145
	ds_read_b128 v[166:169], v145 offset:1024
	ds_read_b128 v[170:173], v145 offset:2048
	ds_read_b128 v[174:177], v145 offset:3072
	v_lshl_add_u64 v[190:191], s[22:23], 0, v[140:141]
	v_lshl_add_u64 v[190:191], v[190:191], 0, s[54:55]
	s_add_i32 m0, s37, 0xc000
	ds_read_b128 v[178:181], v144
	ds_read_b128 v[182:185], v144 offset:1024
	ds_read_b128 v[186:189], v144 offset:2048
	ds_read_b128 v[204:207], v144 offset:3072
	ds_read_b128 v[208:211], v144 offset:4096
	ds_read_b128 v[212:215], v144 offset:5120
	ds_read_b128 v[216:219], v144 offset:6144
	ds_read_b128 v[220:223], v144 offset:7168
	global_load_lds_dwordx4 v[190:191], off
	v_lshl_add_u64 v[190:191], s[22:23], 0, v[138:139]
	v_lshl_add_u64 v[190:191], v[190:191], 0, s[54:55]
	s_add_i32 m0, s37, 0xe000
	s_nop 0
	global_load_lds_dwordx4 v[190:191], off
	s_waitcnt vmcnt(8)
	s_waitcnt lgkmcnt(0)
	s_barrier
	s_setprio 1
	s_waitcnt lgkmcnt(0)
	s_nop 0
	v_mfma_f32_16x16x32_bf16 v[124:127], v[146:149], v[178:181], v[124:127]
	v_mfma_f32_16x16x32_bf16 v[128:131], v[154:157], v[178:181], v[128:131]
	v_mfma_f32_16x16x32_bf16 v[112:115], v[146:149], v[186:189], v[112:115]
	v_mfma_f32_16x16x32_bf16 v[108:111], v[154:157], v[186:189], v[108:111]
	v_mfma_f32_16x16x32_bf16 v[96:99], v[146:149], v[208:211], v[96:99]
	v_mfma_f32_16x16x32_bf16 v[92:95], v[154:157], v[208:211], v[92:95]
	v_mfma_f32_16x16x32_bf16 v[80:83], v[146:149], v[216:219], v[80:83]
	v_mfma_f32_16x16x32_bf16 v[76:79], v[154:157], v[216:219], v[76:79]
	v_mfma_f32_16x16x32_bf16 v[124:127], v[150:153], v[182:185], v[124:127]
	v_mfma_f32_16x16x32_bf16 v[128:131], v[158:161], v[182:185], v[128:131]
	v_mfma_f32_16x16x32_bf16 v[112:115], v[150:153], v[204:207], v[112:115]
	v_mfma_f32_16x16x32_bf16 v[108:111], v[158:161], v[204:207], v[108:111]
	v_mfma_f32_16x16x32_bf16 v[96:99], v[150:153], v[212:215], v[96:99]
	v_mfma_f32_16x16x32_bf16 v[92:95], v[158:161], v[212:215], v[92:95]
	v_mfma_f32_16x16x32_bf16 v[80:83], v[150:153], v[220:223], v[80:83]
	v_mfma_f32_16x16x32_bf16 v[76:79], v[158:161], v[220:223], v[76:79]
	s_setprio 0
	s_setprio 1
	v_mfma_f32_16x16x32_bf16 v[120:123], v[162:165], v[178:181], v[120:123]
	v_mfma_f32_16x16x32_bf16 v[116:119], v[170:173], v[178:181], v[116:119]
	v_mfma_f32_16x16x32_bf16 v[104:107], v[162:165], v[186:189], v[104:107]
	v_mfma_f32_16x16x32_bf16 v[100:103], v[170:173], v[186:189], v[100:103]
	v_mfma_f32_16x16x32_bf16 v[88:91], v[162:165], v[208:211], v[88:91]
	v_mfma_f32_16x16x32_bf16 v[84:87], v[170:173], v[208:211], v[84:87]
	v_mfma_f32_16x16x32_bf16 v[72:75], v[162:165], v[216:219], v[72:75]
	v_mfma_f32_16x16x32_bf16 v[68:71], v[170:173], v[216:219], v[68:71]
	v_mfma_f32_16x16x32_bf16 v[120:123], v[166:169], v[182:185], v[120:123]
	v_mfma_f32_16x16x32_bf16 v[116:119], v[174:177], v[182:185], v[116:119]
	v_mfma_f32_16x16x32_bf16 v[104:107], v[166:169], v[204:207], v[104:107]
	v_mfma_f32_16x16x32_bf16 v[100:103], v[174:177], v[204:207], v[100:103]
	v_mfma_f32_16x16x32_bf16 v[88:91], v[166:169], v[212:215], v[88:91]
	v_mfma_f32_16x16x32_bf16 v[84:87], v[174:177], v[212:215], v[84:87]
	v_mfma_f32_16x16x32_bf16 v[72:75], v[166:169], v[220:223], v[72:75]
	v_mfma_f32_16x16x32_bf16 v[68:71], v[174:177], v[220:223], v[68:71]
	s_setprio 0
	s_barrier
	s_add_i32 s54, s60, s35
	v_lshl_add_u64 v[190:191], s[58:59], 0, v[134:135]
	s_mov_b32 m0, s54
	ds_read_b128 v[178:181], v144 offset:16384
	ds_read_b128 v[182:185], v144 offset:17408
	ds_read_b128 v[186:189], v144 offset:18432
	ds_read_b128 v[204:207], v144 offset:19456
	ds_read_b128 v[208:211], v144 offset:20480
	ds_read_b128 v[212:215], v144 offset:21504
	ds_read_b128 v[216:219], v144 offset:22528
	ds_read_b128 v[220:223], v144 offset:23552
	global_load_lds_dwordx4 v[190:191], off
	s_add_i32 m0, s54, 0x2000
	s_add_u32 s54, s58, s8
	v_lshl_add_u64 v[230:231], s[58:59], 0, v[0:1]
	s_addc_u32 s55, s59, s9
	s_add_i32 s58, s61, s35
	global_load_lds_dwordx4 v[230:231], off
	v_lshl_add_u64 v[232:233], s[54:55], 0, v[134:135]
	s_mov_b32 m0, s58
	v_lshl_add_u64 v[238:239], s[54:55], 0, v[0:1]
	global_load_lds_dwordx4 v[232:233], off
	s_add_i32 m0, s58, 0x2000
	v_lshl_add_u64 v[240:241], s[24:25], 0, v[136:137]
	global_load_lds_dwordx4 v[238:239], off
	s_mov_b32 m0, s37
	v_lshl_add_u64 v[242:243], s[24:25], 0, v[132:133]
	global_load_lds_dwordx4 v[240:241], off
	s_mov_b32 m0, s38
	s_nop 0
	global_load_lds_dwordx4 v[242:243], off
	s_waitcnt vmcnt(8)
	s_waitcnt lgkmcnt(0)
	s_barrier
; #define PG8_STAGE(bufoff, gbase, voff) do { _Pragma("unroll") for (int _i = 0; _i < 2; ++_i) \
;         __builtin_amdgcn_global_load_lds((const unsigned*)((const char*)(gbase) + (voff)[_i]), (PG8_LAS unsigned*)(lds + (bufoff) + ldsw + _i * 8192), 16, 0, 0); } while (0)
; #define PG8_LDA(dst, b, h) do { _Pragma("unroll") for (int m = 0; m < 4; ++m) _Pragma("unroll") for (int k = 0; k < 2; ++k) dst[m][k] = *(const PG8_LAS bf16x8*)(lds + PG8_SA(b, h) + aoff + m * 2048 + k * 1024); } while (0)
; #define PG8_LDB(dst, b, h) do { _Pragma("unroll") for (int n = 0; n < 2; ++n) _Pragma("unroll") for (int k = 0; k < 2; ++k) dst[n][k] = *(const PG8_LAS bf16x8*)(lds + PG8_SB(b, h) + boff + n * 2048 + k * 1024); } while (0)
; #define PG8_MMA(ai, bj, At, Bt) do { __builtin_amdgcn_s_setprio(1); _Pragma("unroll") for (int m = 0; m < 4; ++m) _Pragma("unroll") for (int n = 0; n < 2; ++n) _Pragma("unroll") for (int k = 0; k < 2; ++k) \
;         acc[ai][bj][m][n] = __builtin_amdgcn_mfma_f32_16x16x32_bf16(Bt[n][k], At[m][k], acc[ai][bj][m][n], 0, 0, 0); __builtin_amdgcn_s_setprio(0); } while (0)
; #define PG8_WAIT_V(n) asm volatile("s_waitcnt vmcnt(" #n ")" ::: "memory")
; #define PG8_WAIT_L(n) asm volatile("s_waitcnt lgkmcnt(" #n ")" ::: "memory")
; #define PG8_BAR __builtin_amdgcn_s_barrier()
; #define PG8_SCHED __builtin_amdgcn_sched_barrier(0)
; template <class Epi, class Sched, bool ALIGN_EPI = false, bool SP2 = false>
; __device__ __forceinline__ void gemm_phase(PG8_LAS unsigned char* lds, const Gemm g, const Sched& S, const Epi& E, int tid_in) {
;     ...
;             PG8_WAIT_V(8); PG8_WAIT_L(0); PG8_BAR; PG8_MMA(1, 0, At, B0); PG8_MMA(1, 1, At, B1); PG8_BAR; PG8_SCHED;
;             PG8_LDB(B0, 1, 0); PG8_LDB(B1, 1, 1); PG8_SCHED; PG8_LDA(At, 1, 0); PG8_STAGE(PG8_SA(0, 1), a2 + hsA, voffA);
;             PG8_WAIT_V(8); PG8_WAIT_L(0); PG8_BAR; PG8_MMA(0, 0, At, B0); PG8_MMA(0, 1, At, B1); PG8_BAR; PG8_SCHED;
;             PG8_LDA(At, 1, 1); PG8_STAGE(PG8_SB(1, 0), b3, voffB); PG8_STAGE(PG8_SB(1, 1), b3 + hsB, voffB); PG8_STAGE(PG8_SA(1, 0), a3, voffA);
	s_setprio 1
	s_waitcnt lgkmcnt(0)
	v_mfma_f32_16x16x32_bf16 v[64:67], v[146:149], v[178:181], v[64:67]
	v_mfma_f32_16x16x32_bf16 v[60:63], v[154:157], v[178:181], v[60:63]
	v_mfma_f32_16x16x32_bf16 v[48:51], v[146:149], v[186:189], v[48:51]
	v_mfma_f32_16x16x32_bf16 v[44:47], v[154:157], v[186:189], v[44:47]
	v_mfma_f32_16x16x32_bf16 v[32:35], v[146:149], v[208:211], v[32:35]
	v_mfma_f32_16x16x32_bf16 v[28:31], v[154:157], v[208:211], v[28:31]
	v_mfma_f32_16x16x32_bf16 v[16:19], v[146:149], v[216:219], v[16:19]
	v_mfma_f32_16x16x32_bf16 v[12:15], v[154:157], v[216:219], v[12:15]
	v_mfma_f32_16x16x32_bf16 v[64:67], v[150:153], v[182:185], v[64:67]
	v_mfma_f32_16x16x32_bf16 v[60:63], v[158:161], v[182:185], v[60:63]
	v_mfma_f32_16x16x32_bf16 v[48:51], v[150:153], v[204:207], v[48:51]
	v_mfma_f32_16x16x32_bf16 v[44:47], v[158:161], v[204:207], v[44:47]
	v_mfma_f32_16x16x32_bf16 v[32:35], v[150:153], v[212:215], v[32:35]
	v_mfma_f32_16x16x32_bf16 v[28:31], v[158:161], v[212:215], v[28:31]
	v_mfma_f32_16x16x32_bf16 v[16:19], v[150:153], v[220:223], v[16:19]
	v_mfma_f32_16x16x32_bf16 v[12:15], v[158:161], v[220:223], v[12:15]
	s_setprio 0
	s_setprio 1
	v_mfma_f32_16x16x32_bf16 v[56:59], v[162:165], v[178:181], v[56:59]
	v_mfma_f32_16x16x32_bf16 v[52:55], v[170:173], v[178:181], v[52:55]
	v_mfma_f32_16x16x32_bf16 v[40:43], v[162:165], v[186:189], v[40:43]
	v_mfma_f32_16x16x32_bf16 v[36:39], v[170:173], v[186:189], v[36:39]
	v_mfma_f32_16x16x32_bf16 v[24:27], v[162:165], v[208:211], v[24:27]
	v_mfma_f32_16x16x32_bf16 v[20:23], v[170:173], v[208:211], v[20:23]
	v_mfma_f32_16x16x32_bf16 v[8:11], v[162:165], v[216:219], v[8:11]
	v_mfma_f32_16x16x32_bf16 v[4:7], v[170:173], v[216:219], v[4:7]
	v_mfma_f32_16x16x32_bf16 v[56:59], v[166:169], v[182:185], v[56:59]
	v_mfma_f32_16x16x32_bf16 v[52:55], v[174:177], v[182:185], v[52:55]
	v_mfma_f32_16x16x32_bf16 v[40:43], v[166:169], v[204:207], v[40:43]
	v_mfma_f32_16x16x32_bf16 v[36:39], v[174:177], v[204:207], v[36:39]
	v_mfma_f32_16x16x32_bf16 v[24:27], v[166:169], v[212:215], v[24:27]
	v_mfma_f32_16x16x32_bf16 v[20:23], v[174:177], v[212:215], v[20:23]
	v_mfma_f32_16x16x32_bf16 v[8:11], v[166:169], v[220:223], v[8:11]
	v_mfma_f32_16x16x32_bf16 v[4:7], v[174:177], v[220:223], v[4:7]
	s_setprio 0
	s_barrier
	s_add_i32 s54, 0, 0x18000
	v_add_u32_e32 v145, s54, v142
	s_add_i32 s55, 0, 0x1c000
	ds_read_b128 v[146:149], v145
	ds_read_b128 v[150:153], v145 offset:1024
	ds_read_b128 v[154:157], v145 offset:2048
	ds_read_b128 v[158:161], v145 offset:3072
	v_add_u32_e32 v145, s55, v142
	ds_read_b128 v[162:165], v145
	ds_read_b128 v[166:169], v145 offset:1024
	ds_read_b128 v[170:173], v145 offset:2048
	ds_read_b128 v[174:177], v145 offset:3072
	s_add_u32 s24, s24, s6
	s_addc_u32 s25, s25, s7
	s_mov_b32 m0, s39
	v_lshl_add_u64 v[244:245], s[24:25], 0, v[136:137]
	ds_read_b128 v[178:181], v144 offset:32768
	ds_read_b128 v[182:185], v144 offset:33792
	ds_read_b128 v[186:189], v144 offset:34816
	ds_read_b128 v[204:207], v144 offset:35840
	ds_read_b128 v[208:211], v144 offset:36864
	ds_read_b128 v[212:215], v144 offset:37888
	ds_read_b128 v[216:219], v144 offset:38912
	ds_read_b128 v[220:223], v144 offset:39936
	global_load_lds_dwordx4 v[244:245], off
	v_lshl_add_u64 v[244:245], s[24:25], 0, v[132:133]
	s_mov_b32 m0, s40
	s_nop 0
	global_load_lds_dwordx4 v[244:245], off
	s_waitcnt vmcnt(8)
	s_waitcnt lgkmcnt(0)
	s_barrier
	s_setprio 1
	s_waitcnt lgkmcnt(0)
	v_mfma_f32_16x16x32_bf16 v[124:127], v[146:149], v[178:181], v[124:127]
	v_mfma_f32_16x16x32_bf16 v[128:131], v[154:157], v[178:181], v[128:131]
	v_mfma_f32_16x16x32_bf16 v[112:115], v[146:149], v[186:189], v[112:115]
	v_mfma_f32_16x16x32_bf16 v[108:111], v[154:157], v[186:189], v[108:111]
	v_mfma_f32_16x16x32_bf16 v[96:99], v[146:149], v[208:211], v[96:99]
	v_mfma_f32_16x16x32_bf16 v[92:95], v[154:157], v[208:211], v[92:95]
	v_mfma_f32_16x16x32_bf16 v[80:83], v[146:149], v[216:219], v[80:83]
	v_mfma_f32_16x16x32_bf16 v[76:79], v[154:157], v[216:219], v[76:79]
	v_mfma_f32_16x16x32_bf16 v[124:127], v[150:153], v[182:185], v[124:127]
	v_mfma_f32_16x16x32_bf16 v[128:131], v[158:161], v[182:185], v[128:131]
	v_mfma_f32_16x16x32_bf16 v[112:115], v[150:153], v[204:207], v[112:115]
	v_mfma_f32_16x16x32_bf16 v[108:111], v[158:161], v[204:207], v[108:111]
	v_mfma_f32_16x16x32_bf16 v[96:99], v[150:153], v[212:215], v[96:99]
	v_mfma_f32_16x16x32_bf16 v[92:95], v[158:161], v[212:215], v[92:95]
	v_mfma_f32_16x16x32_bf16 v[80:83], v[150:153], v[220:223], v[80:83]
	v_mfma_f32_16x16x32_bf16 v[76:79], v[158:161], v[220:223], v[76:79]
	s_setprio 0
	s_setprio 1
	v_mfma_f32_16x16x32_bf16 v[120:123], v[162:165], v[178:181], v[120:123]
	v_mfma_f32_16x16x32_bf16 v[116:119], v[170:173], v[178:181], v[116:119]
	v_mfma_f32_16x16x32_bf16 v[104:107], v[162:165], v[186:189], v[104:107]
	v_mfma_f32_16x16x32_bf16 v[100:103], v[170:173], v[186:189], v[100:103]
	v_mfma_f32_16x16x32_bf16 v[88:91], v[162:165], v[208:211], v[88:91]
	v_mfma_f32_16x16x32_bf16 v[84:87], v[170:173], v[208:211], v[84:87]
	v_mfma_f32_16x16x32_bf16 v[72:75], v[162:165], v[216:219], v[72:75]
	v_mfma_f32_16x16x32_bf16 v[68:71], v[170:173], v[216:219], v[68:71]
	v_mfma_f32_16x16x32_bf16 v[120:123], v[166:169], v[182:185], v[120:123]
	v_mfma_f32_16x16x32_bf16 v[116:119], v[174:177], v[182:185], v[116:119]
	v_mfma_f32_16x16x32_bf16 v[104:107], v[166:169], v[204:207], v[104:107]
	v_mfma_f32_16x16x32_bf16 v[100:103], v[174:177], v[204:207], v[100:103]
	v_mfma_f32_16x16x32_bf16 v[88:91], v[166:169], v[212:215], v[88:91]
	v_mfma_f32_16x16x32_bf16 v[84:87], v[174:177], v[212:215], v[84:87]
	v_mfma_f32_16x16x32_bf16 v[72:75], v[166:169], v[220:223], v[72:75]
	v_mfma_f32_16x16x32_bf16 v[68:71], v[174:177], v[220:223], v[68:71]
	s_setprio 0
	s_barrier
; #define PG8_STAGE(bufoff, gbase, voff) do { _Pragma("unroll") for (int _i = 0; _i < 2; ++_i) \
;         __builtin_amdgcn_global_load_lds((const unsigned*)((const char*)(gbase) + (voff)[_i]), (PG8_LAS unsigned*)(lds + (bufoff) + ldsw + _i * 8192), 16, 0, 0); } while (0)
; #define PG8_LDA(dst, b, h) do { _Pragma("unroll") for (int m = 0; m < 4; ++m) _Pragma("unroll") for (int k = 0; k < 2; ++k) dst[m][k] = *(const PG8_LAS bf16x8*)(lds + PG8_SA(b, h) + aoff + m * 2048 + k * 1024); } while (0)
; #define PG8_MMA(ai, bj, At, Bt) do { __builtin_amdgcn_s_setprio(1); _Pragma("unroll") for (int m = 0; m < 4; ++m) _Pragma("unroll") for (int n = 0; n < 2; ++n) _Pragma("unroll") for (int k = 0; k < 2; ++k) \
;         acc[ai][bj][m][n] = __builtin_amdgcn_mfma_f32_16x16x32_bf16(Bt[n][k], At[m][k], acc[ai][bj][m][n], 0, 0, 0); __builtin_amdgcn_s_setprio(0); } while (0)
; #define PG8_WAIT_V(n) asm volatile("s_waitcnt vmcnt(" #n ")" ::: "memory")
; #define PG8_WAIT_L(n) asm volatile("s_waitcnt lgkmcnt(" #n ")" ::: "memory")
; #define PG8_BAR __builtin_amdgcn_s_barrier()
; #define PG8_SCHED __builtin_amdgcn_sched_barrier(0)
; template <class Epi, class Sched, bool ALIGN_EPI = false, bool SP2 = false>
; __device__ __forceinline__ void gemm_phase(PG8_LAS unsigned char* lds, const Gemm g, const Sched& S, const Epi& E, int tid_in) {
;     ...
;             PG8_LDA(At, 1, 1); PG8_STAGE(PG8_SB(1, 0), b3, voffB); PG8_STAGE(PG8_SB(1, 1), b3 + hsB, voffB); PG8_STAGE(PG8_SA(1, 0), a3, voffA);
;             PG8_WAIT_V(8); PG8_WAIT_L(0); PG8_BAR; PG8_MMA(1, 0, At, B0); PG8_MMA(1, 1, At, B1); PG8_BAR; PG8_SCHED;
	s_add_i32 s24, s54, s35
	v_lshl_add_u64 v[190:191], v[190:191], 0, s[80:81]
	s_mov_b32 m0, s24
	ds_read_b128 v[178:181], v144 offset:49152
	ds_read_b128 v[182:185], v144 offset:50176
	ds_read_b128 v[186:189], v144 offset:51200
	ds_read_b128 v[204:207], v144 offset:52224
	ds_read_b128 v[208:211], v144 offset:53248
	ds_read_b128 v[212:215], v144 offset:54272
	ds_read_b128 v[216:219], v144 offset:55296
	ds_read_b128 v[220:223], v144 offset:56320
	global_load_lds_dwordx4 v[190:191], off
	v_lshl_add_u64 v[190:191], v[230:231], 0, s[80:81]
	s_add_i32 m0, s24, 0x2000
	s_add_i32 s24, s55, s35
	global_load_lds_dwordx4 v[190:191], off
	v_lshl_add_u64 v[190:191], v[232:233], 0, s[80:81]
	s_mov_b32 m0, s24
	s_nop 0
	global_load_lds_dwordx4 v[190:191], off
	v_lshl_add_u64 v[190:191], v[238:239], 0, s[80:81]
	s_add_i32 m0, s24, 0x2000
	s_nop 0
	global_load_lds_dwordx4 v[190:191], off
	v_lshl_add_u64 v[190:191], v[240:241], 0, s[80:81]
	s_mov_b32 m0, s41
	s_nop 0
	global_load_lds_dwordx4 v[190:191], off
	v_lshl_add_u64 v[190:191], v[242:243], 0, s[80:81]
	s_mov_b32 m0, s42
	s_nop 0
	global_load_lds_dwordx4 v[190:191], off
	s_waitcnt vmcnt(8)
	s_waitcnt lgkmcnt(0)
	s_barrier
	s_setprio 1
	s_waitcnt lgkmcnt(0)
	s_nop 0
	v_mfma_f32_16x16x32_bf16 v[64:67], v[146:149], v[178:181], v[64:67]
	v_mfma_f32_16x16x32_bf16 v[60:63], v[154:157], v[178:181], v[60:63]
	v_mfma_f32_16x16x32_bf16 v[48:51], v[146:149], v[186:189], v[48:51]
	v_mfma_f32_16x16x32_bf16 v[44:47], v[154:157], v[186:189], v[44:47]
	v_mfma_f32_16x16x32_bf16 v[32:35], v[146:149], v[208:211], v[32:35]
	v_mfma_f32_16x16x32_bf16 v[28:31], v[154:157], v[208:211], v[28:31]
	v_mfma_f32_16x16x32_bf16 v[16:19], v[146:149], v[216:219], v[16:19]
	v_mfma_f32_16x16x32_bf16 v[12:15], v[154:157], v[216:219], v[12:15]
	v_mfma_f32_16x16x32_bf16 v[64:67], v[150:153], v[182:185], v[64:67]
	v_mfma_f32_16x16x32_bf16 v[60:63], v[158:161], v[182:185], v[60:63]
	v_mfma_f32_16x16x32_bf16 v[48:51], v[150:153], v[204:207], v[48:51]
	v_mfma_f32_16x16x32_bf16 v[44:47], v[158:161], v[204:207], v[44:47]
	v_mfma_f32_16x16x32_bf16 v[32:35], v[150:153], v[212:215], v[32:35]
	v_mfma_f32_16x16x32_bf16 v[28:31], v[158:161], v[212:215], v[28:31]
	v_mfma_f32_16x16x32_bf16 v[16:19], v[150:153], v[220:223], v[16:19]
	v_mfma_f32_16x16x32_bf16 v[12:15], v[158:161], v[220:223], v[12:15]
	s_setprio 0
	s_setprio 1
	v_mfma_f32_16x16x32_bf16 v[56:59], v[162:165], v[178:181], v[56:59]
	v_mfma_f32_16x16x32_bf16 v[52:55], v[170:173], v[178:181], v[52:55]
	v_mfma_f32_16x16x32_bf16 v[40:43], v[162:165], v[186:189], v[40:43]
	v_mfma_f32_16x16x32_bf16 v[36:39], v[170:173], v[186:189], v[36:39]
	v_mfma_f32_16x16x32_bf16 v[24:27], v[162:165], v[208:211], v[24:27]
	v_mfma_f32_16x16x32_bf16 v[20:23], v[170:173], v[208:211], v[20:23]
	v_mfma_f32_16x16x32_bf16 v[8:11], v[162:165], v[216:219], v[8:11]
	v_mfma_f32_16x16x32_bf16 v[4:7], v[170:173], v[216:219], v[4:7]
	v_mfma_f32_16x16x32_bf16 v[56:59], v[166:169], v[182:185], v[56:59]
	v_mfma_f32_16x16x32_bf16 v[52:55], v[174:177], v[182:185], v[52:55]
	v_mfma_f32_16x16x32_bf16 v[40:43], v[166:169], v[204:207], v[40:43]
	v_mfma_f32_16x16x32_bf16 v[36:39], v[174:177], v[204:207], v[36:39]
	v_mfma_f32_16x16x32_bf16 v[24:27], v[166:169], v[212:215], v[24:27]
	v_mfma_f32_16x16x32_bf16 v[20:23], v[174:177], v[212:215], v[20:23]
	v_mfma_f32_16x16x32_bf16 v[8:11], v[166:169], v[220:223], v[8:11]
	v_mfma_f32_16x16x32_bf16 v[4:7], v[174:177], v[220:223], v[4:7]
	s_setprio 0
	s_barrier
	s_add_i32 s24, s53, 2
	s_add_u32 s51, s51, 0x100
	s_addc_u32 s52, s52, 0
	s_add_u32 s22, s22, 0x100
	s_addc_u32 s23, s23, 0
	s_cmp_ge_i32 s53, s44
	s_mov_b32 s53, s24
	s_cbranch_scc0 .LBB0_485

; #define PG8_STAGE(bufoff, gbase, voff) do { _Pragma("unroll") for (int _i = 0; _i < 2; ++_i) \
;         __builtin_amdgcn_global_load_lds((const unsigned*)((const char*)(gbase) + (voff)[_i]), (PG8_LAS unsigned*)(lds + (bufoff) + ldsw + _i * 8192), 16, 0, 0); } while (0)
; #define PG8_LDA(dst, b, h) do { _Pragma("unroll") for (int m = 0; m < 4; ++m) _Pragma("unroll") for (int k = 0; k < 2; ++k) dst[m][k] = *(const PG8_LAS bf16x8*)(lds + PG8_SA(b, h) + aoff + m * 2048 + k * 1024); } while (0)
; #define PG8_LDB(dst, b, h) do { _Pragma("unroll") for (int n = 0; n < 2; ++n) _Pragma("unroll") for (int k = 0; k < 2; ++k) dst[n][k] = *(const PG8_LAS bf16x8*)(lds + PG8_SB(b, h) + boff + n * 2048 + k * 1024); } while (0)
; #define PG8_MMA(ai, bj, At, Bt) do { __builtin_amdgcn_s_setprio(1); _Pragma("unroll") for (int m = 0; m < 4; ++m) _Pragma("unroll") for (int n = 0; n < 2; ++n) _Pragma("unroll") for (int k = 0; k < 2; ++k) \
;         acc[ai][bj][m][n] = __builtin_amdgcn_mfma_f32_16x16x32_bf16(Bt[n][k], At[m][k], acc[ai][bj][m][n], 0, 0, 0); __builtin_amdgcn_s_setprio(0); } while (0)
; #define PG8_WAIT_V(n) asm volatile("s_waitcnt vmcnt(" #n ")" ::: "memory")
; template <class Epi, class Sched, bool ALIGN_EPI = false, bool SP2 = false>
; __device__ __forceinline__ void gemm_phase(PG8_LAS unsigned char* lds, const Gemm g, const Sched& S, const Epi& E, int tid_in) {
;     ...
;         for (int t = 0; t < nt; t += 2) {
;             const bool last = (t == nt - 2);
;             if constexpr (mid_hook<Epi>::value) { if (t == Epi::H1 || t == Epi::H2) E.mid(acc, cur, wr, wc, fr, fq, t == Epi::H2); }
;             const char* a1 = cA + (size_t)(t + 1) * kstep + (t >= jt ? jb : 0);
;             const char* a2 = last ? nA : cA + (size_t)(t + 2) * kstep + (t + 2 >= jt ? jb : 0); const char* b2 = last ? nB : cB + (size_t)(t + 2) * kstep;
;             const char* a3 = a2 + kstep; const char* b3 = b2 + kstep;
;             if (last && has_next) S.a_ready(nxt);
;             if constexpr (SP2) {
;             PG8_LDB(B0, 0, 0); PG8_LDB(B1, 0, 1); PG8_SCHED; PG8_LDA(At, 0, 0); PG8_STAGE(PG8_SA(1, 1), a1 + hsA, voffA);
;             PG8_WAIT_V(8); PG8_WAIT_L(0); PG8_BAR; PG8_MMA(0, 0, At, B0); PG8_MMA(0, 1, At, B1); PG8_BAR; PG8_SCHED;
;             PG8_LDA(At, 0, 1); PG8_STAGE(PG8_SB(0, 0), b2, voffB); PG8_STAGE(PG8_SB(0, 1), b2 + hsB, voffB); PG8_STAGE(PG8_SA(0, 0), a2, voffA);
.LBB0_667:
	s_add_i32 s24, s55, -2
	s_cmp_ge_i32 s24, s28
	s_cselect_b32 s58, s29, 0
	s_cselect_b32 s59, s47, 0
	s_cmp_ge_i32 s55, s28
	s_cselect_b32 s25, s29, 0
	s_cselect_b32 s24, s47, 0
	s_add_u32 s25, s22, s25
	s_addc_u32 s24, s23, s24
	s_add_u32 s60, s25, 0x80
	s_addc_u32 s24, s24, 0
	s_add_i32 s62, 0, 0x10000
	s_cmp_eq_u32 s46, s55
	s_cselect_b32 s25, s1, s24
	s_cselect_b32 s24, s0, s60
	s_cselect_b32 s61, s5, s54
	s_cselect_b32 s60, s4, s53
	s_add_i32 s63, 0, 0x14000
	v_add_u32_e32 v48, s62, v162
	v_add_u32_e32 v165, s63, v162
	ds_read_b128 v[28:31], v48
	ds_read_b128 v[32:35], v48 offset:1024
	ds_read_b128 v[44:47], v48 offset:2048
	ds_read_b128 v[48:51], v48 offset:3072
	ds_read_b128 v[158:161], v165
	ds_read_b128 v[166:169], v165 offset:1024
	ds_read_b128 v[170:173], v165 offset:2048
	ds_read_b128 v[174:177], v165 offset:3072
	v_lshl_add_u64 v[190:191], s[22:23], 0, v[156:157]
	v_lshl_add_u64 v[190:191], v[190:191], 0, s[58:59]
	s_add_i32 m0, s38, 0xc000
	ds_read_b128 v[178:181], v164
	ds_read_b128 v[182:185], v164 offset:1024
	ds_read_b128 v[186:189], v164 offset:2048
	ds_read_b128 v[204:207], v164 offset:3072
	ds_read_b128 v[208:211], v164 offset:4096
	ds_read_b128 v[212:215], v164 offset:5120
	ds_read_b128 v[216:219], v164 offset:6144
	ds_read_b128 v[220:223], v164 offset:7168
	global_load_lds_dwordx4 v[190:191], off
	v_lshl_add_u64 v[190:191], s[22:23], 0, v[154:155]
	v_lshl_add_u64 v[190:191], v[190:191], 0, s[58:59]
	s_add_i32 m0, s38, 0xe000
	s_nop 0
	global_load_lds_dwordx4 v[190:191], off
	s_waitcnt vmcnt(8)
	s_waitcnt lgkmcnt(0)
	s_barrier
	s_setprio 1
	s_waitcnt lgkmcnt(0)
	v_mfma_f32_16x16x32_bf16 v[140:143], v[28:31], v[178:181], v[140:143]
	v_mfma_f32_16x16x32_bf16 v[144:147], v[44:47], v[178:181], v[144:147]
	v_mfma_f32_16x16x32_bf16 v[128:131], v[28:31], v[186:189], v[128:131]
	v_mfma_f32_16x16x32_bf16 v[124:127], v[44:47], v[186:189], v[124:127]
	v_mfma_f32_16x16x32_bf16 v[112:115], v[28:31], v[208:211], v[112:115]
	v_mfma_f32_16x16x32_bf16 v[108:111], v[44:47], v[208:211], v[108:111]
	v_mfma_f32_16x16x32_bf16 v[96:99], v[28:31], v[216:219], v[96:99]
	v_mfma_f32_16x16x32_bf16 v[92:95], v[44:47], v[216:219], v[92:95]
	v_mfma_f32_16x16x32_bf16 v[140:143], v[32:35], v[182:185], v[140:143]
	v_mfma_f32_16x16x32_bf16 v[144:147], v[48:51], v[182:185], v[144:147]
	v_mfma_f32_16x16x32_bf16 v[128:131], v[32:35], v[204:207], v[128:131]
	v_mfma_f32_16x16x32_bf16 v[124:127], v[48:51], v[204:207], v[124:127]
	v_mfma_f32_16x16x32_bf16 v[112:115], v[32:35], v[212:215], v[112:115]
	v_mfma_f32_16x16x32_bf16 v[108:111], v[48:51], v[212:215], v[108:111]
	v_mfma_f32_16x16x32_bf16 v[96:99], v[32:35], v[220:223], v[96:99]
	v_mfma_f32_16x16x32_bf16 v[92:95], v[48:51], v[220:223], v[92:95]
	s_setprio 0
	s_setprio 1
	v_mfma_f32_16x16x32_bf16 v[136:139], v[158:161], v[178:181], v[136:139]
	v_mfma_f32_16x16x32_bf16 v[132:135], v[170:173], v[178:181], v[132:135]
	v_mfma_f32_16x16x32_bf16 v[120:123], v[158:161], v[186:189], v[120:123]
	v_mfma_f32_16x16x32_bf16 v[116:119], v[170:173], v[186:189], v[116:119]
	v_mfma_f32_16x16x32_bf16 v[104:107], v[158:161], v[208:211], v[104:107]
	v_mfma_f32_16x16x32_bf16 v[100:103], v[170:173], v[208:211], v[100:103]
	v_mfma_f32_16x16x32_bf16 v[88:91], v[158:161], v[216:219], v[88:91]
	v_mfma_f32_16x16x32_bf16 v[84:87], v[170:173], v[216:219], v[84:87]
	v_mfma_f32_16x16x32_bf16 v[136:139], v[166:169], v[182:185], v[136:139]
	v_mfma_f32_16x16x32_bf16 v[132:135], v[174:177], v[182:185], v[132:135]
	v_mfma_f32_16x16x32_bf16 v[120:123], v[166:169], v[204:207], v[120:123]
	v_mfma_f32_16x16x32_bf16 v[116:119], v[174:177], v[204:207], v[116:119]
	v_mfma_f32_16x16x32_bf16 v[104:107], v[166:169], v[212:215], v[104:107]
	v_mfma_f32_16x16x32_bf16 v[100:103], v[174:177], v[212:215], v[100:103]
	v_mfma_f32_16x16x32_bf16 v[88:91], v[166:169], v[220:223], v[88:91]
	v_mfma_f32_16x16x32_bf16 v[84:87], v[174:177], v[220:223], v[84:87]
	s_setprio 0
	s_barrier
	s_add_i32 s58, s62, s36
	v_lshl_add_u64 v[190:191], s[60:61], 0, v[150:151]
	s_mov_b32 m0, s58
	ds_read_b128 v[178:181], v164 offset:16384
	ds_read_b128 v[182:185], v164 offset:17408
	ds_read_b128 v[186:189], v164 offset:18432
	ds_read_b128 v[204:207], v164 offset:19456
	ds_read_b128 v[208:211], v164 offset:20480
	ds_read_b128 v[212:215], v164 offset:21504
	ds_read_b128 v[216:219], v164 offset:22528
	ds_read_b128 v[220:223], v164 offset:23552
	global_load_lds_dwordx4 v[190:191], off
	s_add_i32 m0, s58, 0x2000
	s_add_u32 s58, s60, s8
	v_lshl_add_u64 v[230:231], s[60:61], 0, v[0:1]
	s_addc_u32 s59, s61, s9
	s_add_i32 s60, s63, s36
	global_load_lds_dwordx4 v[230:231], off
	v_lshl_add_u64 v[232:233], s[58:59], 0, v[150:151]
	s_mov_b32 m0, s60
	v_lshl_add_u64 v[238:239], s[58:59], 0, v[0:1]
	global_load_lds_dwordx4 v[232:233], off
	s_add_i32 m0, s60, 0x2000
	v_lshl_add_u64 v[240:241], s[24:25], 0, v[152:153]
	global_load_lds_dwordx4 v[238:239], off
	s_mov_b32 m0, s38
	v_lshl_add_u64 v[242:243], s[24:25], 0, v[148:149]
	global_load_lds_dwordx4 v[240:241], off
	s_mov_b32 m0, s39
	s_nop 0
	global_load_lds_dwordx4 v[242:243], off
	s_waitcnt vmcnt(8)
	s_waitcnt lgkmcnt(0)
	s_barrier
; #define PG8_STAGE(bufoff, gbase, voff) do { _Pragma("unroll") for (int _i = 0; _i < 2; ++_i) \
;         __builtin_amdgcn_global_load_lds((const unsigned*)((const char*)(gbase) + (voff)[_i]), (PG8_LAS unsigned*)(lds + (bufoff) + ldsw + _i * 8192), 16, 0, 0); } while (0)
; #define PG8_LDA(dst, b, h) do { _Pragma("unroll") for (int m = 0; m < 4; ++m) _Pragma("unroll") for (int k = 0; k < 2; ++k) dst[m][k] = *(const PG8_LAS bf16x8*)(lds + PG8_SA(b, h) + aoff + m * 2048 + k * 1024); } while (0)
; #define PG8_LDB(dst, b, h) do { _Pragma("unroll") for (int n = 0; n < 2; ++n) _Pragma("unroll") for (int k = 0; k < 2; ++k) dst[n][k] = *(const PG8_LAS bf16x8*)(lds + PG8_SB(b, h) + boff + n * 2048 + k * 1024); } while (0)
; #define PG8_MMA(ai, bj, At, Bt) do { __builtin_amdgcn_s_setprio(1); _Pragma("unroll") for (int m = 0; m < 4; ++m) _Pragma("unroll") for (int n = 0; n < 2; ++n) _Pragma("unroll") for (int k = 0; k < 2; ++k) \
;         acc[ai][bj][m][n] = __builtin_amdgcn_mfma_f32_16x16x32_bf16(Bt[n][k], At[m][k], acc[ai][bj][m][n], 0, 0, 0); __builtin_amdgcn_s_setprio(0); } while (0)
; #define PG8_WAIT_V(n) asm volatile("s_waitcnt vmcnt(" #n ")" ::: "memory")
; #define PG8_WAIT_L(n) asm volatile("s_waitcnt lgkmcnt(" #n ")" ::: "memory")
; #define PG8_BAR __builtin_amdgcn_s_barrier()
; #define PG8_SCHED __builtin_amdgcn_sched_barrier(0)
; template <class Epi, class Sched, bool ALIGN_EPI = false, bool SP2 = false>
; __device__ __forceinline__ void gemm_phase(PG8_LAS unsigned char* lds, const Gemm g, const Sched& S, const Epi& E, int tid_in) {
;     ...
;             PG8_WAIT_V(8); PG8_WAIT_L(0); PG8_BAR; PG8_MMA(1, 0, At, B0); PG8_MMA(1, 1, At, B1); PG8_BAR; PG8_SCHED;
;             PG8_LDB(B0, 1, 0); PG8_LDB(B1, 1, 1); PG8_SCHED; PG8_LDA(At, 1, 0); PG8_STAGE(PG8_SA(0, 1), a2 + hsA, voffA);
;             PG8_WAIT_V(8); PG8_WAIT_L(0); PG8_BAR; PG8_MMA(0, 0, At, B0); PG8_MMA(0, 1, At, B1); PG8_BAR; PG8_SCHED;
;             PG8_LDA(At, 1, 1); PG8_STAGE(PG8_SB(1, 0), b3, voffB); PG8_STAGE(PG8_SB(1, 1), b3 + hsB, voffB); PG8_STAGE(PG8_SA(1, 0), a3, voffA);
	s_setprio 1
	s_waitcnt lgkmcnt(0)
	v_mfma_f32_16x16x32_bf16 v[80:83], v[28:31], v[178:181], v[80:83]
	v_mfma_f32_16x16x32_bf16 v[76:79], v[44:47], v[178:181], v[76:79]
	v_mfma_f32_16x16x32_bf16 v[64:67], v[28:31], v[186:189], v[64:67]
	v_mfma_f32_16x16x32_bf16 v[60:63], v[44:47], v[186:189], v[60:63]
	v_mfma_f32_16x16x32_bf16 v[40:43], v[28:31], v[208:211], v[40:43]
	v_mfma_f32_16x16x32_bf16 v[36:39], v[44:47], v[208:211], v[36:39]
	v_mfma_f32_16x16x32_bf16 v[16:19], v[28:31], v[216:219], v[16:19]
	v_mfma_f32_16x16x32_bf16 v[12:15], v[44:47], v[216:219], v[12:15]
	v_mfma_f32_16x16x32_bf16 v[80:83], v[32:35], v[182:185], v[80:83]
	v_mfma_f32_16x16x32_bf16 v[76:79], v[48:51], v[182:185], v[76:79]
	v_mfma_f32_16x16x32_bf16 v[64:67], v[32:35], v[204:207], v[64:67]
	v_mfma_f32_16x16x32_bf16 v[60:63], v[48:51], v[204:207], v[60:63]
	v_mfma_f32_16x16x32_bf16 v[40:43], v[32:35], v[212:215], v[40:43]
	v_mfma_f32_16x16x32_bf16 v[36:39], v[48:51], v[212:215], v[36:39]
	v_mfma_f32_16x16x32_bf16 v[16:19], v[32:35], v[220:223], v[16:19]
	v_mfma_f32_16x16x32_bf16 v[12:15], v[48:51], v[220:223], v[12:15]
	s_setprio 0
	s_setprio 1
	v_mfma_f32_16x16x32_bf16 v[24:27], v[158:161], v[208:211], v[24:27]
	v_mfma_f32_16x16x32_bf16 v[20:23], v[170:173], v[208:211], v[20:23]
	v_mfma_f32_16x16x32_bf16 v[8:11], v[158:161], v[216:219], v[8:11]
	v_mfma_f32_16x16x32_bf16 v[4:7], v[170:173], v[216:219], v[4:7]
	v_mfma_f32_16x16x32_bf16 v[28:31], v[158:161], v[178:181], v[72:75]
	v_mfma_f32_16x16x32_bf16 v[32:35], v[170:173], v[178:181], v[68:71]
	v_mfma_f32_16x16x32_bf16 v[44:47], v[158:161], v[186:189], v[56:59]
	v_mfma_f32_16x16x32_bf16 v[48:51], v[170:173], v[186:189], v[52:55]
	v_mfma_f32_16x16x32_bf16 v[24:27], v[166:169], v[212:215], v[24:27]
	v_mfma_f32_16x16x32_bf16 v[20:23], v[174:177], v[212:215], v[20:23]
	v_mfma_f32_16x16x32_bf16 v[8:11], v[166:169], v[220:223], v[8:11]
	v_mfma_f32_16x16x32_bf16 v[4:7], v[174:177], v[220:223], v[4:7]
	v_mfma_f32_16x16x32_bf16 v[28:31], v[166:169], v[182:185], v[28:31]
	v_mfma_f32_16x16x32_bf16 v[32:35], v[174:177], v[182:185], v[32:35]
	v_mfma_f32_16x16x32_bf16 v[44:47], v[166:169], v[204:207], v[44:47]
	v_mfma_f32_16x16x32_bf16 v[48:51], v[174:177], v[204:207], v[48:51]
	s_setprio 0
	s_barrier
	s_add_i32 s58, 0, 0x18000
	s_add_i32 s59, 0, 0x1c000
	v_add_u32_e32 v72, s58, v162
	v_add_u32_e32 v165, s59, v162
	ds_read_b128 v[52:55], v72
	ds_read_b128 v[56:59], v72 offset:1024
	ds_read_b128 v[68:71], v72 offset:2048
	ds_read_b128 v[72:75], v72 offset:3072
	ds_read_b128 v[158:161], v165
	ds_read_b128 v[166:169], v165 offset:1024
	ds_read_b128 v[170:173], v165 offset:2048
	ds_read_b128 v[174:177], v165 offset:3072
	s_add_u32 s24, s24, s6
	s_addc_u32 s25, s25, s7
	s_mov_b32 m0, s40
	v_lshl_add_u64 v[244:245], s[24:25], 0, v[152:153]
	ds_read_b128 v[178:181], v164 offset:32768
	ds_read_b128 v[182:185], v164 offset:33792
	ds_read_b128 v[186:189], v164 offset:34816
	ds_read_b128 v[204:207], v164 offset:35840
	ds_read_b128 v[208:211], v164 offset:36864
	ds_read_b128 v[212:215], v164 offset:37888
	ds_read_b128 v[216:219], v164 offset:38912
	ds_read_b128 v[220:223], v164 offset:39936
	global_load_lds_dwordx4 v[244:245], off
	v_lshl_add_u64 v[244:245], s[24:25], 0, v[148:149]
	s_mov_b32 m0, s41
	s_nop 0
	global_load_lds_dwordx4 v[244:245], off
	s_waitcnt vmcnt(8)
	s_waitcnt lgkmcnt(0)
	s_barrier
	s_setprio 1
	s_waitcnt lgkmcnt(0)
	v_mfma_f32_16x16x32_bf16 v[140:143], v[52:55], v[178:181], v[140:143]
	v_mfma_f32_16x16x32_bf16 v[144:147], v[68:71], v[178:181], v[144:147]
	v_mfma_f32_16x16x32_bf16 v[128:131], v[52:55], v[186:189], v[128:131]
	v_mfma_f32_16x16x32_bf16 v[124:127], v[68:71], v[186:189], v[124:127]
	v_mfma_f32_16x16x32_bf16 v[112:115], v[52:55], v[208:211], v[112:115]
	v_mfma_f32_16x16x32_bf16 v[108:111], v[68:71], v[208:211], v[108:111]
	v_mfma_f32_16x16x32_bf16 v[96:99], v[52:55], v[216:219], v[96:99]
	v_mfma_f32_16x16x32_bf16 v[92:95], v[68:71], v[216:219], v[92:95]
	v_mfma_f32_16x16x32_bf16 v[140:143], v[56:59], v[182:185], v[140:143]
	v_mfma_f32_16x16x32_bf16 v[144:147], v[72:75], v[182:185], v[144:147]
	v_mfma_f32_16x16x32_bf16 v[128:131], v[56:59], v[204:207], v[128:131]
	v_mfma_f32_16x16x32_bf16 v[124:127], v[72:75], v[204:207], v[124:127]
	v_mfma_f32_16x16x32_bf16 v[112:115], v[56:59], v[212:215], v[112:115]
	v_mfma_f32_16x16x32_bf16 v[108:111], v[72:75], v[212:215], v[108:111]
	v_mfma_f32_16x16x32_bf16 v[96:99], v[56:59], v[220:223], v[96:99]
	v_mfma_f32_16x16x32_bf16 v[92:95], v[72:75], v[220:223], v[92:95]
	s_setprio 0
	s_setprio 1
	v_mfma_f32_16x16x32_bf16 v[136:139], v[158:161], v[178:181], v[136:139]
	v_mfma_f32_16x16x32_bf16 v[132:135], v[170:173], v[178:181], v[132:135]
	v_mfma_f32_16x16x32_bf16 v[120:123], v[158:161], v[186:189], v[120:123]
	v_mfma_f32_16x16x32_bf16 v[116:119], v[170:173], v[186:189], v[116:119]
	v_mfma_f32_16x16x32_bf16 v[104:107], v[158:161], v[208:211], v[104:107]
	v_mfma_f32_16x16x32_bf16 v[100:103], v[170:173], v[208:211], v[100:103]
	v_mfma_f32_16x16x32_bf16 v[88:91], v[158:161], v[216:219], v[88:91]
	v_mfma_f32_16x16x32_bf16 v[84:87], v[170:173], v[216:219], v[84:87]
	v_mfma_f32_16x16x32_bf16 v[136:139], v[166:169], v[182:185], v[136:139]
	v_mfma_f32_16x16x32_bf16 v[132:135], v[174:177], v[182:185], v[132:135]
	v_mfma_f32_16x16x32_bf16 v[120:123], v[166:169], v[204:207], v[120:123]
	v_mfma_f32_16x16x32_bf16 v[116:119], v[174:177], v[204:207], v[116:119]
	v_mfma_f32_16x16x32_bf16 v[104:107], v[166:169], v[212:215], v[104:107]
	v_mfma_f32_16x16x32_bf16 v[100:103], v[174:177], v[212:215], v[100:103]
	v_mfma_f32_16x16x32_bf16 v[88:91], v[166:169], v[220:223], v[88:91]
	v_mfma_f32_16x16x32_bf16 v[84:87], v[174:177], v[220:223], v[84:87]
	s_setprio 0
	s_barrier
; #define PG8_STAGE(bufoff, gbase, voff) do { _Pragma("unroll") for (int _i = 0; _i < 2; ++_i) \
;         __builtin_amdgcn_global_load_lds((const unsigned*)((const char*)(gbase) + (voff)[_i]), (PG8_LAS unsigned*)(lds + (bufoff) + ldsw + _i * 8192), 16, 0, 0); } while (0)
; #define PG8_LDA(dst, b, h) do { _Pragma("unroll") for (int m = 0; m < 4; ++m) _Pragma("unroll") for (int k = 0; k < 2; ++k) dst[m][k] = *(const PG8_LAS bf16x8*)(lds + PG8_SA(b, h) + aoff + m * 2048 + k * 1024); } while (0)
; #define PG8_MMA(ai, bj, At, Bt) do { __builtin_amdgcn_s_setprio(1); _Pragma("unroll") for (int m = 0; m < 4; ++m) _Pragma("unroll") for (int n = 0; n < 2; ++n) _Pragma("unroll") for (int k = 0; k < 2; ++k) \
;         acc[ai][bj][m][n] = __builtin_amdgcn_mfma_f32_16x16x32_bf16(Bt[n][k], At[m][k], acc[ai][bj][m][n], 0, 0, 0); __builtin_amdgcn_s_setprio(0); } while (0)
; #define PG8_WAIT_V(n) asm volatile("s_waitcnt vmcnt(" #n ")" ::: "memory")
; #define PG8_WAIT_L(n) asm volatile("s_waitcnt lgkmcnt(" #n ")" ::: "memory")
; #define PG8_BAR __builtin_amdgcn_s_barrier()
; #define PG8_SCHED __builtin_amdgcn_sched_barrier(0)
; template <class Epi, class Sched, bool ALIGN_EPI = false, bool SP2 = false>
; __device__ __forceinline__ void gemm_phase(PG8_LAS unsigned char* lds, const Gemm g, const Sched& S, const Epi& E, int tid_in) {
;     ...
;             PG8_LDA(At, 1, 1); PG8_STAGE(PG8_SB(1, 0), b3, voffB); PG8_STAGE(PG8_SB(1, 1), b3 + hsB, voffB); PG8_STAGE(PG8_SA(1, 0), a3, voffA);
;             PG8_WAIT_V(8); PG8_WAIT_L(0); PG8_BAR; PG8_MMA(1, 0, At, B0); PG8_MMA(1, 1, At, B1); PG8_BAR; PG8_SCHED;
	s_add_i32 s24, s58, s36
	v_lshl_add_u64 v[190:191], v[190:191], 0, s[80:81]
	s_mov_b32 m0, s24
	ds_read_b128 v[178:181], v164 offset:49152
	ds_read_b128 v[182:185], v164 offset:50176
	ds_read_b128 v[186:189], v164 offset:51200
	ds_read_b128 v[204:207], v164 offset:52224
	ds_read_b128 v[208:211], v164 offset:53248
	ds_read_b128 v[212:215], v164 offset:54272
	ds_read_b128 v[216:219], v164 offset:55296
	ds_read_b128 v[220:223], v164 offset:56320
	global_load_lds_dwordx4 v[190:191], off
	v_lshl_add_u64 v[190:191], v[230:231], 0, s[80:81]
	s_add_i32 m0, s24, 0x2000
	s_add_i32 s24, s59, s36
	global_load_lds_dwordx4 v[190:191], off
	v_lshl_add_u64 v[190:191], v[232:233], 0, s[80:81]
	s_mov_b32 m0, s24
	s_nop 0
	global_load_lds_dwordx4 v[190:191], off
	v_lshl_add_u64 v[190:191], v[238:239], 0, s[80:81]
	s_add_i32 m0, s24, 0x2000
	s_nop 0
	global_load_lds_dwordx4 v[190:191], off
	v_lshl_add_u64 v[190:191], v[240:241], 0, s[80:81]
	s_mov_b32 m0, s44
	s_nop 0
	global_load_lds_dwordx4 v[190:191], off
	v_lshl_add_u64 v[190:191], v[242:243], 0, s[80:81]
	s_mov_b32 m0, s45
	s_nop 0
	global_load_lds_dwordx4 v[190:191], off
	s_waitcnt vmcnt(8)
	s_waitcnt lgkmcnt(0)
	s_barrier
	s_setprio 1
	s_waitcnt lgkmcnt(0)
	s_nop 0
	v_mfma_f32_16x16x32_bf16 v[80:83], v[52:55], v[178:181], v[80:83]
	v_mfma_f32_16x16x32_bf16 v[76:79], v[68:71], v[178:181], v[76:79]
	v_mfma_f32_16x16x32_bf16 v[64:67], v[52:55], v[186:189], v[64:67]
	v_mfma_f32_16x16x32_bf16 v[60:63], v[68:71], v[186:189], v[60:63]
	v_mfma_f32_16x16x32_bf16 v[40:43], v[52:55], v[208:211], v[40:43]
	v_mfma_f32_16x16x32_bf16 v[36:39], v[68:71], v[208:211], v[36:39]
	v_mfma_f32_16x16x32_bf16 v[16:19], v[52:55], v[216:219], v[16:19]
	v_mfma_f32_16x16x32_bf16 v[12:15], v[68:71], v[216:219], v[12:15]
	v_mfma_f32_16x16x32_bf16 v[80:83], v[56:59], v[182:185], v[80:83]
	v_mfma_f32_16x16x32_bf16 v[76:79], v[72:75], v[182:185], v[76:79]
	v_mfma_f32_16x16x32_bf16 v[64:67], v[56:59], v[204:207], v[64:67]
	v_mfma_f32_16x16x32_bf16 v[60:63], v[72:75], v[204:207], v[60:63]
	v_mfma_f32_16x16x32_bf16 v[40:43], v[56:59], v[212:215], v[40:43]
	v_mfma_f32_16x16x32_bf16 v[36:39], v[72:75], v[212:215], v[36:39]
	v_mfma_f32_16x16x32_bf16 v[16:19], v[56:59], v[220:223], v[16:19]
	v_mfma_f32_16x16x32_bf16 v[12:15], v[72:75], v[220:223], v[12:15]
	s_setprio 0
	s_setprio 1
	v_mfma_f32_16x16x32_bf16 v[28:31], v[158:161], v[178:181], v[28:31]
	v_mfma_f32_16x16x32_bf16 v[72:75], v[166:169], v[182:185], v[28:31]
	v_mfma_f32_16x16x32_bf16 v[28:31], v[170:173], v[178:181], v[32:35]
	v_mfma_f32_16x16x32_bf16 v[68:71], v[174:177], v[182:185], v[28:31]
	v_mfma_f32_16x16x32_bf16 v[28:31], v[158:161], v[186:189], v[44:47]
	v_mfma_f32_16x16x32_bf16 v[56:59], v[166:169], v[204:207], v[28:31]
	v_mfma_f32_16x16x32_bf16 v[28:31], v[170:173], v[186:189], v[48:51]
	v_mfma_f32_16x16x32_bf16 v[24:27], v[158:161], v[208:211], v[24:27]
	v_mfma_f32_16x16x32_bf16 v[20:23], v[170:173], v[208:211], v[20:23]
	v_mfma_f32_16x16x32_bf16 v[8:11], v[158:161], v[216:219], v[8:11]
	v_mfma_f32_16x16x32_bf16 v[4:7], v[170:173], v[216:219], v[4:7]
	v_mfma_f32_16x16x32_bf16 v[52:55], v[174:177], v[204:207], v[28:31]
	v_mfma_f32_16x16x32_bf16 v[24:27], v[166:169], v[212:215], v[24:27]
	v_mfma_f32_16x16x32_bf16 v[20:23], v[174:177], v[212:215], v[20:23]
	v_mfma_f32_16x16x32_bf16 v[8:11], v[166:169], v[220:223], v[8:11]
	v_mfma_f32_16x16x32_bf16 v[4:7], v[174:177], v[220:223], v[4:7]
	s_setprio 0
	s_barrier
	s_add_i32 s24, s55, 2
	s_add_u32 s53, s53, 0x100
	s_addc_u32 s54, s54, 0
	s_add_u32 s22, s22, 0x100
	s_addc_u32 s23, s23, 0
	s_cmp_ge_i32 s55, s46
	s_mov_b32 s55, s24
	s_cbranch_scc0 .LBB0_667

; #define PG8_STAGE(bufoff, gbase, voff) do { _Pragma("unroll") for (int _i = 0; _i < 2; ++_i) \
;         __builtin_amdgcn_global_load_lds((const unsigned*)((const char*)(gbase) + (voff)[_i]), (PG8_LAS unsigned*)(lds + (bufoff) + ldsw + _i * 8192), 16, 0, 0); } while (0)
; #define PG8_LDA(dst, b, h) do { _Pragma("unroll") for (int m = 0; m < 4; ++m) _Pragma("unroll") for (int k = 0; k < 2; ++k) dst[m][k] = *(const PG8_LAS bf16x8*)(lds + PG8_SA(b, h) + aoff + m * 2048 + k * 1024); } while (0)
; #define PG8_LDB(dst, b, h) do { _Pragma("unroll") for (int n = 0; n < 2; ++n) _Pragma("unroll") for (int k = 0; k < 2; ++k) dst[n][k] = *(const PG8_LAS bf16x8*)(lds + PG8_SB(b, h) + boff + n * 2048 + k * 1024); } while (0)
; #define PG8_MMA(ai, bj, At, Bt) do { __builtin_amdgcn_s_setprio(1); _Pragma("unroll") for (int m = 0; m < 4; ++m) _Pragma("unroll") for (int n = 0; n < 2; ++n) _Pragma("unroll") for (int k = 0; k < 2; ++k) \
;         acc[ai][bj][m][n] = __builtin_amdgcn_mfma_f32_16x16x32_bf16(Bt[n][k], At[m][k], acc[ai][bj][m][n], 0, 0, 0); __builtin_amdgcn_s_setprio(0); } while (0)
; #define PG8_WAIT_V(n) asm volatile("s_waitcnt vmcnt(" #n ")" ::: "memory")
; template <class Epi, class Sched, bool ALIGN_EPI = false, bool SP2 = false>
; __device__ __forceinline__ void gemm_phase(PG8_LAS unsigned char* lds, const Gemm g, const Sched& S, const Epi& E, int tid_in) {
;     ...
;         for (int t = 0; t < nt; t += 2) {
;             const bool last = (t == nt - 2);
;             if constexpr (mid_hook<Epi>::value) { if (t == Epi::H1 || t == Epi::H2) E.mid(acc, cur, wr, wc, fr, fq, t == Epi::H2); }
;             const char* a1 = cA + (size_t)(t + 1) * kstep + (t >= jt ? jb : 0);
;             const char* a2 = last ? nA : cA + (size_t)(t + 2) * kstep + (t + 2 >= jt ? jb : 0); const char* b2 = last ? nB : cB + (size_t)(t + 2) * kstep;
;             const char* a3 = a2 + kstep; const char* b3 = b2 + kstep;
;             if (last && has_next) S.a_ready(nxt);
;             if constexpr (SP2) {
;             PG8_LDB(B0, 0, 0); PG8_LDB(B1, 0, 1); PG8_SCHED; PG8_LDA(At, 0, 0); PG8_STAGE(PG8_SA(1, 1), a1 + hsA, voffA);
;             PG8_WAIT_V(8); PG8_WAIT_L(0); PG8_BAR; PG8_MMA(0, 0, At, B0); PG8_MMA(0, 1, At, B1); PG8_BAR; PG8_SCHED;
;             PG8_LDA(At, 0, 1); PG8_STAGE(PG8_SB(0, 0), b2, voffB); PG8_STAGE(PG8_SB(0, 1), b2 + hsB, voffB); PG8_STAGE(PG8_SA(0, 0), a2, voffA);
.LBB0_688:
	s_add_i32 s24, s55, -2
	s_cmp_ge_i32 s24, s28
	s_cselect_b32 s58, s29, 0
	s_cselect_b32 s59, s46, 0
	s_cmp_ge_i32 s55, s28
	s_cselect_b32 s25, s29, 0
	s_cselect_b32 s24, s46, 0
	s_add_u32 s25, s22, s25
	s_addc_u32 s24, s23, s24
	s_add_u32 s60, s25, 0x80
	s_addc_u32 s24, s24, 0
	s_add_i32 s62, 0, 0x10000
	s_cmp_eq_u32 s45, s55
	s_cselect_b32 s25, s5, s24
	s_cselect_b32 s24, s4, s60
	s_cselect_b32 s61, s21, s54
	s_cselect_b32 s60, s20, s53
	s_add_i32 s63, 0, 0x14000
	v_add_u32_e32 v88, s62, v160
	v_add_u32_e32 v158, s63, v160
	ds_read_b128 v[68:71], v88
	ds_read_b128 v[72:75], v88 offset:1024
	ds_read_b128 v[84:87], v88 offset:2048
	ds_read_b128 v[88:91], v88 offset:3072
	ds_read_b128 v[164:167], v158
	ds_read_b128 v[168:171], v158 offset:1024
	ds_read_b128 v[172:175], v158 offset:2048
	ds_read_b128 v[176:179], v158 offset:3072
	v_lshl_add_u64 v[158:159], s[22:23], 0, v[156:157]
	v_lshl_add_u64 v[158:159], v[158:159], 0, s[58:59]
	s_add_i32 m0, s37, 0xc000
	ds_read_b128 v[180:183], v162
	ds_read_b128 v[184:187], v162 offset:1024
	ds_read_b128 v[188:191], v162 offset:2048
	ds_read_b128 v[204:207], v162 offset:3072
	ds_read_b128 v[208:211], v162 offset:4096
	ds_read_b128 v[212:215], v162 offset:5120
	ds_read_b128 v[216:219], v162 offset:6144
	ds_read_b128 v[220:223], v162 offset:7168
	global_load_lds_dwordx4 v[158:159], off
	v_lshl_add_u64 v[158:159], s[22:23], 0, v[154:155]
	v_lshl_add_u64 v[158:159], v[158:159], 0, s[58:59]
	s_add_i32 m0, s37, 0xe000
	s_nop 0
	global_load_lds_dwordx4 v[158:159], off
	s_waitcnt vmcnt(8)
	s_waitcnt lgkmcnt(0)
	s_barrier
	s_setprio 1
	s_waitcnt lgkmcnt(0)
	s_nop 0
	v_mfma_f32_16x16x32_bf16 v[140:143], v[68:71], v[180:183], v[140:143]
	v_mfma_f32_16x16x32_bf16 v[144:147], v[84:87], v[180:183], v[144:147]
	v_mfma_f32_16x16x32_bf16 v[128:131], v[68:71], v[188:191], v[128:131]
	v_mfma_f32_16x16x32_bf16 v[124:127], v[84:87], v[188:191], v[124:127]
	v_mfma_f32_16x16x32_bf16 v[112:115], v[68:71], v[208:211], v[112:115]
	v_mfma_f32_16x16x32_bf16 v[108:111], v[84:87], v[208:211], v[108:111]
	v_mfma_f32_16x16x32_bf16 v[96:99], v[68:71], v[216:219], v[96:99]
	v_mfma_f32_16x16x32_bf16 v[92:95], v[84:87], v[216:219], v[92:95]
	v_mfma_f32_16x16x32_bf16 v[140:143], v[72:75], v[184:187], v[140:143]
	v_mfma_f32_16x16x32_bf16 v[144:147], v[88:91], v[184:187], v[144:147]
	v_mfma_f32_16x16x32_bf16 v[128:131], v[72:75], v[204:207], v[128:131]
	v_mfma_f32_16x16x32_bf16 v[124:127], v[88:91], v[204:207], v[124:127]
	v_mfma_f32_16x16x32_bf16 v[112:115], v[72:75], v[212:215], v[112:115]
	v_mfma_f32_16x16x32_bf16 v[108:111], v[88:91], v[212:215], v[108:111]
	v_mfma_f32_16x16x32_bf16 v[96:99], v[72:75], v[220:223], v[96:99]
	v_mfma_f32_16x16x32_bf16 v[92:95], v[88:91], v[220:223], v[92:95]
	s_setprio 0
	s_setprio 1
	v_mfma_f32_16x16x32_bf16 v[136:139], v[164:167], v[180:183], v[136:139]
	v_mfma_f32_16x16x32_bf16 v[132:135], v[172:175], v[180:183], v[132:135]
	v_mfma_f32_16x16x32_bf16 v[120:123], v[164:167], v[188:191], v[120:123]
	v_mfma_f32_16x16x32_bf16 v[116:119], v[172:175], v[188:191], v[116:119]
	v_mfma_f32_16x16x32_bf16 v[104:107], v[164:167], v[208:211], v[104:107]
	v_mfma_f32_16x16x32_bf16 v[100:103], v[172:175], v[208:211], v[100:103]
	v_mfma_f32_16x16x32_bf16 v[80:83], v[164:167], v[216:219], v[80:83]
	v_mfma_f32_16x16x32_bf16 v[76:79], v[172:175], v[216:219], v[76:79]
	v_mfma_f32_16x16x32_bf16 v[136:139], v[168:171], v[184:187], v[136:139]
	v_mfma_f32_16x16x32_bf16 v[132:135], v[176:179], v[184:187], v[132:135]
	v_mfma_f32_16x16x32_bf16 v[120:123], v[168:171], v[204:207], v[120:123]
	v_mfma_f32_16x16x32_bf16 v[116:119], v[176:179], v[204:207], v[116:119]
	v_mfma_f32_16x16x32_bf16 v[104:107], v[168:171], v[212:215], v[104:107]
	v_mfma_f32_16x16x32_bf16 v[100:103], v[176:179], v[212:215], v[100:103]
	v_mfma_f32_16x16x32_bf16 v[80:83], v[168:171], v[220:223], v[80:83]
	v_mfma_f32_16x16x32_bf16 v[76:79], v[176:179], v[220:223], v[76:79]
	s_setprio 0
	s_barrier
	s_add_i32 s58, s62, s35
	v_lshl_add_u64 v[158:159], s[60:61], 0, v[150:151]
	s_mov_b32 m0, s58
	ds_read_b128 v[180:183], v162 offset:16384
	ds_read_b128 v[184:187], v162 offset:17408
	ds_read_b128 v[188:191], v162 offset:18432
	ds_read_b128 v[204:207], v162 offset:19456
	ds_read_b128 v[208:211], v162 offset:20480
	ds_read_b128 v[212:215], v162 offset:21504
	ds_read_b128 v[216:219], v162 offset:22528
	ds_read_b128 v[220:223], v162 offset:23552
	global_load_lds_dwordx4 v[158:159], off
	s_add_i32 m0, s58, 0x2000
	s_add_u32 s58, s60, s6
	v_lshl_add_u64 v[230:231], s[60:61], 0, v[0:1]
	s_addc_u32 s59, s61, s7
	s_add_i32 s60, s63, s35
	global_load_lds_dwordx4 v[230:231], off
	v_lshl_add_u64 v[232:233], s[58:59], 0, v[150:151]
	s_mov_b32 m0, s60
	v_lshl_add_u64 v[238:239], s[58:59], 0, v[0:1]
	global_load_lds_dwordx4 v[232:233], off
	s_add_i32 m0, s60, 0x2000
	v_lshl_add_u64 v[240:241], s[24:25], 0, v[152:153]
	global_load_lds_dwordx4 v[238:239], off
	s_mov_b32 m0, s37
	v_lshl_add_u64 v[242:243], s[24:25], 0, v[148:149]
	global_load_lds_dwordx4 v[240:241], off
	s_mov_b32 m0, s38
	s_nop 0
	global_load_lds_dwordx4 v[242:243], off
	s_waitcnt vmcnt(8)
	s_waitcnt lgkmcnt(0)
	s_barrier
; #define PG8_STAGE(bufoff, gbase, voff) do { _Pragma("unroll") for (int _i = 0; _i < 2; ++_i) \
;         __builtin_amdgcn_global_load_lds((const unsigned*)((const char*)(gbase) + (voff)[_i]), (PG8_LAS unsigned*)(lds + (bufoff) + ldsw + _i * 8192), 16, 0, 0); } while (0)
; #define PG8_LDA(dst, b, h) do { _Pragma("unroll") for (int m = 0; m < 4; ++m) _Pragma("unroll") for (int k = 0; k < 2; ++k) dst[m][k] = *(const PG8_LAS bf16x8*)(lds + PG8_SA(b, h) + aoff + m * 2048 + k * 1024); } while (0)
; #define PG8_LDB(dst, b, h) do { _Pragma("unroll") for (int n = 0; n < 2; ++n) _Pragma("unroll") for (int k = 0; k < 2; ++k) dst[n][k] = *(const PG8_LAS bf16x8*)(lds + PG8_SB(b, h) + boff + n * 2048 + k * 1024); } while (0)
; #define PG8_MMA(ai, bj, At, Bt) do { __builtin_amdgcn_s_setprio(1); _Pragma("unroll") for (int m = 0; m < 4; ++m) _Pragma("unroll") for (int n = 0; n < 2; ++n) _Pragma("unroll") for (int k = 0; k < 2; ++k) \
;         acc[ai][bj][m][n] = __builtin_amdgcn_mfma_f32_16x16x32_bf16(Bt[n][k], At[m][k], acc[ai][bj][m][n], 0, 0, 0); __builtin_amdgcn_s_setprio(0); } while (0)
; #define PG8_WAIT_V(n) asm volatile("s_waitcnt vmcnt(" #n ")" ::: "memory")
; #define PG8_WAIT_L(n) asm volatile("s_waitcnt lgkmcnt(" #n ")" ::: "memory")
; #define PG8_BAR __builtin_amdgcn_s_barrier()
; #define PG8_SCHED __builtin_amdgcn_sched_barrier(0)
; template <class Epi, class Sched, bool ALIGN_EPI = false, bool SP2 = false>
; __device__ __forceinline__ void gemm_phase(PG8_LAS unsigned char* lds, const Gemm g, const Sched& S, const Epi& E, int tid_in) {
;     ...
;             PG8_WAIT_V(8); PG8_WAIT_L(0); PG8_BAR; PG8_MMA(1, 0, At, B0); PG8_MMA(1, 1, At, B1); PG8_BAR; PG8_SCHED;
;             PG8_LDB(B0, 1, 0); PG8_LDB(B1, 1, 1); PG8_SCHED; PG8_LDA(At, 1, 0); PG8_STAGE(PG8_SA(0, 1), a2 + hsA, voffA);
;             PG8_WAIT_V(8); PG8_WAIT_L(0); PG8_BAR; PG8_MMA(0, 0, At, B0); PG8_MMA(0, 1, At, B1); PG8_BAR; PG8_SCHED;
;             PG8_LDA(At, 1, 1); PG8_STAGE(PG8_SB(1, 0), b3, voffB); PG8_STAGE(PG8_SB(1, 1), b3 + hsB, voffB); PG8_STAGE(PG8_SA(1, 0), a3, voffA);
	s_setprio 1
	s_waitcnt lgkmcnt(0)
	v_mfma_f32_16x16x32_bf16 v[64:67], v[68:71], v[180:183], v[64:67]
	v_mfma_f32_16x16x32_bf16 v[60:63], v[84:87], v[180:183], v[60:63]
	v_mfma_f32_16x16x32_bf16 v[48:51], v[68:71], v[188:191], v[48:51]
	v_mfma_f32_16x16x32_bf16 v[44:47], v[84:87], v[188:191], v[44:47]
	v_mfma_f32_16x16x32_bf16 v[32:35], v[68:71], v[208:211], v[32:35]
	v_mfma_f32_16x16x32_bf16 v[28:31], v[84:87], v[208:211], v[28:31]
	v_mfma_f32_16x16x32_bf16 v[16:19], v[68:71], v[216:219], v[16:19]
	v_mfma_f32_16x16x32_bf16 v[12:15], v[84:87], v[216:219], v[12:15]
	v_mfma_f32_16x16x32_bf16 v[64:67], v[72:75], v[184:187], v[64:67]
	v_mfma_f32_16x16x32_bf16 v[60:63], v[88:91], v[184:187], v[60:63]
	v_mfma_f32_16x16x32_bf16 v[48:51], v[72:75], v[204:207], v[48:51]
	v_mfma_f32_16x16x32_bf16 v[44:47], v[88:91], v[204:207], v[44:47]
	v_mfma_f32_16x16x32_bf16 v[32:35], v[72:75], v[212:215], v[32:35]
	v_mfma_f32_16x16x32_bf16 v[28:31], v[88:91], v[212:215], v[28:31]
	v_mfma_f32_16x16x32_bf16 v[16:19], v[72:75], v[220:223], v[16:19]
	v_mfma_f32_16x16x32_bf16 v[12:15], v[88:91], v[220:223], v[12:15]
	s_setprio 0
	s_setprio 1
	v_mfma_f32_16x16x32_bf16 v[56:59], v[164:167], v[180:183], v[56:59]
	v_mfma_f32_16x16x32_bf16 v[52:55], v[172:175], v[180:183], v[52:55]
	v_mfma_f32_16x16x32_bf16 v[40:43], v[164:167], v[188:191], v[40:43]
	v_mfma_f32_16x16x32_bf16 v[36:39], v[172:175], v[188:191], v[36:39]
	v_mfma_f32_16x16x32_bf16 v[24:27], v[164:167], v[208:211], v[24:27]
	v_mfma_f32_16x16x32_bf16 v[20:23], v[172:175], v[208:211], v[20:23]
	v_mfma_f32_16x16x32_bf16 v[8:11], v[164:167], v[216:219], v[8:11]
	v_mfma_f32_16x16x32_bf16 v[4:7], v[172:175], v[216:219], v[4:7]
	v_mfma_f32_16x16x32_bf16 v[56:59], v[168:171], v[184:187], v[56:59]
	v_mfma_f32_16x16x32_bf16 v[52:55], v[176:179], v[184:187], v[52:55]
	v_mfma_f32_16x16x32_bf16 v[40:43], v[168:171], v[204:207], v[40:43]
	v_mfma_f32_16x16x32_bf16 v[36:39], v[176:179], v[204:207], v[36:39]
	v_mfma_f32_16x16x32_bf16 v[24:27], v[168:171], v[212:215], v[24:27]
	v_mfma_f32_16x16x32_bf16 v[20:23], v[176:179], v[212:215], v[20:23]
	v_mfma_f32_16x16x32_bf16 v[8:11], v[168:171], v[220:223], v[8:11]
	v_mfma_f32_16x16x32_bf16 v[4:7], v[176:179], v[220:223], v[4:7]
	s_setprio 0
	s_barrier
	s_add_i32 s58, 0, 0x18000
	s_add_i32 s59, 0, 0x1c000
	v_add_u32_e32 v88, s58, v160
	v_add_u32_e32 v163, s59, v160
	ds_read_b128 v[68:71], v88
	ds_read_b128 v[72:75], v88 offset:1024
	ds_read_b128 v[84:87], v88 offset:2048
	ds_read_b128 v[88:91], v88 offset:3072
	ds_read_b128 v[164:167], v163
	ds_read_b128 v[168:171], v163 offset:1024
	ds_read_b128 v[172:175], v163 offset:2048
	ds_read_b128 v[176:179], v163 offset:3072
	s_add_u32 s24, s24, s0
	s_addc_u32 s25, s25, s1
	s_mov_b32 m0, s39
	v_lshl_add_u64 v[244:245], s[24:25], 0, v[152:153]
	ds_read_b128 v[180:183], v162 offset:32768
	ds_read_b128 v[184:187], v162 offset:33792
	ds_read_b128 v[188:191], v162 offset:34816
	ds_read_b128 v[204:207], v162 offset:35840
	ds_read_b128 v[208:211], v162 offset:36864
	ds_read_b128 v[212:215], v162 offset:37888
	ds_read_b128 v[216:219], v162 offset:38912
	ds_read_b128 v[220:223], v162 offset:39936
	global_load_lds_dwordx4 v[244:245], off
	v_lshl_add_u64 v[244:245], s[24:25], 0, v[148:149]
	s_mov_b32 m0, s40
	s_nop 0
	global_load_lds_dwordx4 v[244:245], off
	s_waitcnt vmcnt(8)
	s_waitcnt lgkmcnt(0)
	s_barrier
	s_setprio 1
	s_waitcnt lgkmcnt(0)
	v_mfma_f32_16x16x32_bf16 v[140:143], v[68:71], v[180:183], v[140:143]
	v_mfma_f32_16x16x32_bf16 v[144:147], v[84:87], v[180:183], v[144:147]
	v_mfma_f32_16x16x32_bf16 v[128:131], v[68:71], v[188:191], v[128:131]
	v_mfma_f32_16x16x32_bf16 v[124:127], v[84:87], v[188:191], v[124:127]
	v_mfma_f32_16x16x32_bf16 v[112:115], v[68:71], v[208:211], v[112:115]
	v_mfma_f32_16x16x32_bf16 v[108:111], v[84:87], v[208:211], v[108:111]
	v_mfma_f32_16x16x32_bf16 v[96:99], v[68:71], v[216:219], v[96:99]
	v_mfma_f32_16x16x32_bf16 v[92:95], v[84:87], v[216:219], v[92:95]
	v_mfma_f32_16x16x32_bf16 v[140:143], v[72:75], v[184:187], v[140:143]
	v_mfma_f32_16x16x32_bf16 v[144:147], v[88:91], v[184:187], v[144:147]
	v_mfma_f32_16x16x32_bf16 v[128:131], v[72:75], v[204:207], v[128:131]
	v_mfma_f32_16x16x32_bf16 v[124:127], v[88:91], v[204:207], v[124:127]
	v_mfma_f32_16x16x32_bf16 v[112:115], v[72:75], v[212:215], v[112:115]
	v_mfma_f32_16x16x32_bf16 v[108:111], v[88:91], v[212:215], v[108:111]
	v_mfma_f32_16x16x32_bf16 v[96:99], v[72:75], v[220:223], v[96:99]
	v_mfma_f32_16x16x32_bf16 v[92:95], v[88:91], v[220:223], v[92:95]
	s_setprio 0
	s_setprio 1
	v_mfma_f32_16x16x32_bf16 v[136:139], v[164:167], v[180:183], v[136:139]
	v_mfma_f32_16x16x32_bf16 v[132:135], v[172:175], v[180:183], v[132:135]
	v_mfma_f32_16x16x32_bf16 v[120:123], v[164:167], v[188:191], v[120:123]
	v_mfma_f32_16x16x32_bf16 v[116:119], v[172:175], v[188:191], v[116:119]
	v_mfma_f32_16x16x32_bf16 v[104:107], v[164:167], v[208:211], v[104:107]
	v_mfma_f32_16x16x32_bf16 v[100:103], v[172:175], v[208:211], v[100:103]
	v_mfma_f32_16x16x32_bf16 v[80:83], v[164:167], v[216:219], v[80:83]
	v_mfma_f32_16x16x32_bf16 v[76:79], v[172:175], v[216:219], v[76:79]
	v_mfma_f32_16x16x32_bf16 v[136:139], v[168:171], v[184:187], v[136:139]
	v_mfma_f32_16x16x32_bf16 v[132:135], v[176:179], v[184:187], v[132:135]
	v_mfma_f32_16x16x32_bf16 v[120:123], v[168:171], v[204:207], v[120:123]
	v_mfma_f32_16x16x32_bf16 v[116:119], v[176:179], v[204:207], v[116:119]
	v_mfma_f32_16x16x32_bf16 v[104:107], v[168:171], v[212:215], v[104:107]
	v_mfma_f32_16x16x32_bf16 v[100:103], v[176:179], v[212:215], v[100:103]
	v_mfma_f32_16x16x32_bf16 v[80:83], v[168:171], v[220:223], v[80:83]
	v_mfma_f32_16x16x32_bf16 v[76:79], v[176:179], v[220:223], v[76:79]
	s_setprio 0
	s_barrier
; #define PG8_STAGE(bufoff, gbase, voff) do { _Pragma("unroll") for (int _i = 0; _i < 2; ++_i) \
;         __builtin_amdgcn_global_load_lds((const unsigned*)((const char*)(gbase) + (voff)[_i]), (PG8_LAS unsigned*)(lds + (bufoff) + ldsw + _i * 8192), 16, 0, 0); } while (0)
; #define PG8_LDA(dst, b, h) do { _Pragma("unroll") for (int m = 0; m < 4; ++m) _Pragma("unroll") for (int k = 0; k < 2; ++k) dst[m][k] = *(const PG8_LAS bf16x8*)(lds + PG8_SA(b, h) + aoff + m * 2048 + k * 1024); } while (0)
; #define PG8_MMA(ai, bj, At, Bt) do { __builtin_amdgcn_s_setprio(1); _Pragma("unroll") for (int m = 0; m < 4; ++m) _Pragma("unroll") for (int n = 0; n < 2; ++n) _Pragma("unroll") for (int k = 0; k < 2; ++k) \
;         acc[ai][bj][m][n] = __builtin_amdgcn_mfma_f32_16x16x32_bf16(Bt[n][k], At[m][k], acc[ai][bj][m][n], 0, 0, 0); __builtin_amdgcn_s_setprio(0); } while (0)
; #define PG8_WAIT_V(n) asm volatile("s_waitcnt vmcnt(" #n ")" ::: "memory")
; #define PG8_WAIT_L(n) asm volatile("s_waitcnt lgkmcnt(" #n ")" ::: "memory")
; #define PG8_BAR __builtin_amdgcn_s_barrier()
; #define PG8_SCHED __builtin_amdgcn_sched_barrier(0)
; template <class Epi, class Sched, bool ALIGN_EPI = false, bool SP2 = false>
; __device__ __forceinline__ void gemm_phase(PG8_LAS unsigned char* lds, const Gemm g, const Sched& S, const Epi& E, int tid_in) {
;     ...
;             PG8_LDA(At, 1, 1); PG8_STAGE(PG8_SB(1, 0), b3, voffB); PG8_STAGE(PG8_SB(1, 1), b3 + hsB, voffB); PG8_STAGE(PG8_SA(1, 0), a3, voffA);
;             PG8_WAIT_V(8); PG8_WAIT_L(0); PG8_BAR; PG8_MMA(1, 0, At, B0); PG8_MMA(1, 1, At, B1); PG8_BAR; PG8_SCHED;
	s_add_i32 s24, s58, s35
	v_lshl_add_u64 v[158:159], v[158:159], 0, s[80:81]
	s_mov_b32 m0, s24
	ds_read_b128 v[180:183], v162 offset:49152
	ds_read_b128 v[184:187], v162 offset:50176
	ds_read_b128 v[188:191], v162 offset:51200
	ds_read_b128 v[204:207], v162 offset:52224
	ds_read_b128 v[208:211], v162 offset:53248
	ds_read_b128 v[212:215], v162 offset:54272
	ds_read_b128 v[216:219], v162 offset:55296
	ds_read_b128 v[220:223], v162 offset:56320
	global_load_lds_dwordx4 v[158:159], off
	v_lshl_add_u64 v[158:159], v[230:231], 0, s[80:81]
	s_add_i32 m0, s24, 0x2000
	s_add_i32 s24, s59, s35
	global_load_lds_dwordx4 v[158:159], off
	v_lshl_add_u64 v[158:159], v[232:233], 0, s[80:81]
	s_mov_b32 m0, s24
	s_nop 0
	global_load_lds_dwordx4 v[158:159], off
	v_lshl_add_u64 v[158:159], v[238:239], 0, s[80:81]
	s_add_i32 m0, s24, 0x2000
	s_nop 0
	global_load_lds_dwordx4 v[158:159], off
	v_lshl_add_u64 v[158:159], v[240:241], 0, s[80:81]
	s_mov_b32 m0, s43
	s_nop 0
	global_load_lds_dwordx4 v[158:159], off
	v_lshl_add_u64 v[158:159], v[242:243], 0, s[80:81]
	s_mov_b32 m0, s44
	s_nop 0
	global_load_lds_dwordx4 v[158:159], off
	s_waitcnt vmcnt(8)
	s_waitcnt lgkmcnt(0)
	s_barrier
	s_setprio 1
	s_waitcnt lgkmcnt(0)
	s_nop 0
	v_mfma_f32_16x16x32_bf16 v[64:67], v[68:71], v[180:183], v[64:67]
	v_mfma_f32_16x16x32_bf16 v[60:63], v[84:87], v[180:183], v[60:63]
	v_mfma_f32_16x16x32_bf16 v[48:51], v[68:71], v[188:191], v[48:51]
	v_mfma_f32_16x16x32_bf16 v[44:47], v[84:87], v[188:191], v[44:47]
	v_mfma_f32_16x16x32_bf16 v[32:35], v[68:71], v[208:211], v[32:35]
	v_mfma_f32_16x16x32_bf16 v[28:31], v[84:87], v[208:211], v[28:31]
	v_mfma_f32_16x16x32_bf16 v[16:19], v[68:71], v[216:219], v[16:19]
	v_mfma_f32_16x16x32_bf16 v[12:15], v[84:87], v[216:219], v[12:15]
	v_mfma_f32_16x16x32_bf16 v[64:67], v[72:75], v[184:187], v[64:67]
	v_mfma_f32_16x16x32_bf16 v[60:63], v[88:91], v[184:187], v[60:63]
	v_mfma_f32_16x16x32_bf16 v[48:51], v[72:75], v[204:207], v[48:51]
	v_mfma_f32_16x16x32_bf16 v[44:47], v[88:91], v[204:207], v[44:47]
	v_mfma_f32_16x16x32_bf16 v[32:35], v[72:75], v[212:215], v[32:35]
	v_mfma_f32_16x16x32_bf16 v[28:31], v[88:91], v[212:215], v[28:31]
	v_mfma_f32_16x16x32_bf16 v[16:19], v[72:75], v[220:223], v[16:19]
	v_mfma_f32_16x16x32_bf16 v[12:15], v[88:91], v[220:223], v[12:15]
	s_setprio 0
	s_setprio 1
	v_mfma_f32_16x16x32_bf16 v[56:59], v[164:167], v[180:183], v[56:59]
	v_mfma_f32_16x16x32_bf16 v[52:55], v[172:175], v[180:183], v[52:55]
	v_mfma_f32_16x16x32_bf16 v[40:43], v[164:167], v[188:191], v[40:43]
	v_mfma_f32_16x16x32_bf16 v[36:39], v[172:175], v[188:191], v[36:39]
	v_mfma_f32_16x16x32_bf16 v[24:27], v[164:167], v[208:211], v[24:27]
	v_mfma_f32_16x16x32_bf16 v[20:23], v[172:175], v[208:211], v[20:23]
	v_mfma_f32_16x16x32_bf16 v[8:11], v[164:167], v[216:219], v[8:11]
	v_mfma_f32_16x16x32_bf16 v[4:7], v[172:175], v[216:219], v[4:7]
	v_mfma_f32_16x16x32_bf16 v[56:59], v[168:171], v[184:187], v[56:59]
	v_mfma_f32_16x16x32_bf16 v[52:55], v[176:179], v[184:187], v[52:55]
	v_mfma_f32_16x16x32_bf16 v[40:43], v[168:171], v[204:207], v[40:43]
	v_mfma_f32_16x16x32_bf16 v[36:39], v[176:179], v[204:207], v[36:39]
	v_mfma_f32_16x16x32_bf16 v[24:27], v[168:171], v[212:215], v[24:27]
	v_mfma_f32_16x16x32_bf16 v[20:23], v[176:179], v[212:215], v[20:23]
	v_mfma_f32_16x16x32_bf16 v[8:11], v[168:171], v[220:223], v[8:11]
	v_mfma_f32_16x16x32_bf16 v[4:7], v[176:179], v[220:223], v[4:7]
	s_setprio 0
	s_barrier
	s_add_i32 s24, s55, 2
	s_add_u32 s53, s53, 0x100
	s_addc_u32 s54, s54, 0
	s_add_u32 s22, s22, 0x100
	s_addc_u32 s23, s23, 0
	s_cmp_ge_i32 s55, s45
	s_mov_b32 s55, s24
	s_cbranch_scc0 .LBB0_688

; #define PG8_STAGE(bufoff, gbase, voff) do { _Pragma("unroll") for (int _i = 0; _i < 2; ++_i) \
;         __builtin_amdgcn_global_load_lds((const unsigned*)((const char*)(gbase) + (voff)[_i]), (PG8_LAS unsigned*)(lds + (bufoff) + ldsw + _i * 8192), 16, 0, 0); } while (0)
; #define PG8_LDA(dst, b, h) do { _Pragma("unroll") for (int m = 0; m < 4; ++m) _Pragma("unroll") for (int k = 0; k < 2; ++k) dst[m][k] = *(const PG8_LAS bf16x8*)(lds + PG8_SA(b, h) + aoff + m * 2048 + k * 1024); } while (0)
; #define PG8_LDB(dst, b, h) do { _Pragma("unroll") for (int n = 0; n < 2; ++n) _Pragma("unroll") for (int k = 0; k < 2; ++k) dst[n][k] = *(const PG8_LAS bf16x8*)(lds + PG8_SB(b, h) + boff + n * 2048 + k * 1024); } while (0)
; #define PG8_MMA(ai, bj, At, Bt) do { __builtin_amdgcn_s_setprio(1); _Pragma("unroll") for (int m = 0; m < 4; ++m) _Pragma("unroll") for (int n = 0; n < 2; ++n) _Pragma("unroll") for (int k = 0; k < 2; ++k) \
;         acc[ai][bj][m][n] = __builtin_amdgcn_mfma_f32_16x16x32_bf16(Bt[n][k], At[m][k], acc[ai][bj][m][n], 0, 0, 0); __builtin_amdgcn_s_setprio(0); } while (0)
; #define PG8_WAIT_V(n) asm volatile("s_waitcnt vmcnt(" #n ")" ::: "memory")
; template <class Epi, class Sched, bool ALIGN_EPI = false, bool SP2 = false>
; __device__ __forceinline__ void gemm_phase(PG8_LAS unsigned char* lds, const Gemm g, const Sched& S, const Epi& E, int tid_in) {
;     ...
;         for (int t = 0; t < nt; t += 2) {
;             const bool last = (t == nt - 2);
;             if constexpr (mid_hook<Epi>::value) { if (t == Epi::H1 || t == Epi::H2) E.mid(acc, cur, wr, wc, fr, fq, t == Epi::H2); }
;             const char* a1 = cA + (size_t)(t + 1) * kstep + (t >= jt ? jb : 0);
;             const char* a2 = last ? nA : cA + (size_t)(t + 2) * kstep + (t + 2 >= jt ? jb : 0); const char* b2 = last ? nB : cB + (size_t)(t + 2) * kstep;
;             const char* a3 = a2 + kstep; const char* b3 = b2 + kstep;
;             if (last && has_next) S.a_ready(nxt);
;             if constexpr (SP2) {
;             PG8_LDB(B0, 0, 0); PG8_LDB(B1, 0, 1); PG8_SCHED; PG8_LDA(At, 0, 0); PG8_STAGE(PG8_SA(1, 1), a1 + hsA, voffA);
;             PG8_WAIT_V(8); PG8_WAIT_L(0); PG8_BAR; PG8_MMA(0, 0, At, B0); PG8_MMA(0, 1, At, B1); PG8_BAR; PG8_SCHED;
;             PG8_LDA(At, 0, 1); PG8_STAGE(PG8_SB(0, 0), b2, voffB); PG8_STAGE(PG8_SB(0, 1), b2 + hsB, voffB); PG8_STAGE(PG8_SA(0, 0), a2, voffA);
.LBB0_709:
	s_add_i32 s24, s53, -2
	s_cmp_ge_i32 s24, s28
	s_cselect_b32 s54, s29, 0
	s_cselect_b32 s55, s44, 0
	s_cmp_ge_i32 s53, s28
	s_cselect_b32 s25, s29, 0
	s_cselect_b32 s24, s44, 0
	s_add_u32 s25, s22, s25
	s_addc_u32 s24, s23, s24
	s_add_u32 s58, s25, 0x80
	s_addc_u32 s24, s24, 0
	s_add_i32 s60, 0, 0x10000
	s_cmp_eq_u32 s43, s53
	s_cselect_b32 s25, s5, s24
	s_cselect_b32 s24, s4, s58
	v_add_u32_e32 v145, s60, v142
	s_cselect_b32 s59, s21, s52
	s_cselect_b32 s58, s20, s51
	s_add_i32 s61, 0, 0x14000
	ds_read_b128 v[146:149], v145
	ds_read_b128 v[150:153], v145 offset:1024
	ds_read_b128 v[154:157], v145 offset:2048
	ds_read_b128 v[158:161], v145 offset:3072
	v_add_u32_e32 v145, s61, v142
	ds_read_b128 v[162:165], v145
	ds_read_b128 v[166:169], v145 offset:1024
	ds_read_b128 v[170:173], v145 offset:2048
	ds_read_b128 v[174:177], v145 offset:3072
	v_lshl_add_u64 v[190:191], s[22:23], 0, v[140:141]
	v_lshl_add_u64 v[190:191], v[190:191], 0, s[54:55]
	s_add_i32 m0, s37, 0xc000
	ds_read_b128 v[178:181], v144
	ds_read_b128 v[182:185], v144 offset:1024
	ds_read_b128 v[186:189], v144 offset:2048
	ds_read_b128 v[204:207], v144 offset:3072
	ds_read_b128 v[208:211], v144 offset:4096
	ds_read_b128 v[212:215], v144 offset:5120
	ds_read_b128 v[216:219], v144 offset:6144
	ds_read_b128 v[220:223], v144 offset:7168
	global_load_lds_dwordx4 v[190:191], off
	v_lshl_add_u64 v[190:191], s[22:23], 0, v[138:139]
	v_lshl_add_u64 v[190:191], v[190:191], 0, s[54:55]
	s_add_i32 m0, s37, 0xe000
	s_nop 0
	global_load_lds_dwordx4 v[190:191], off
	s_waitcnt vmcnt(8)
	s_waitcnt lgkmcnt(0)
	s_barrier
	s_setprio 1
	s_waitcnt lgkmcnt(0)
	v_mfma_f32_16x16x32_bf16 v[124:127], v[146:149], v[178:181], v[124:127]
	v_mfma_f32_16x16x32_bf16 v[128:131], v[154:157], v[178:181], v[128:131]
	v_mfma_f32_16x16x32_bf16 v[112:115], v[146:149], v[186:189], v[112:115]
	v_mfma_f32_16x16x32_bf16 v[108:111], v[154:157], v[186:189], v[108:111]
	v_mfma_f32_16x16x32_bf16 v[96:99], v[146:149], v[208:211], v[96:99]
	v_mfma_f32_16x16x32_bf16 v[92:95], v[154:157], v[208:211], v[92:95]
	v_mfma_f32_16x16x32_bf16 v[80:83], v[146:149], v[216:219], v[80:83]
	v_mfma_f32_16x16x32_bf16 v[76:79], v[154:157], v[216:219], v[76:79]
	v_mfma_f32_16x16x32_bf16 v[124:127], v[150:153], v[182:185], v[124:127]
	v_mfma_f32_16x16x32_bf16 v[128:131], v[158:161], v[182:185], v[128:131]
	v_mfma_f32_16x16x32_bf16 v[112:115], v[150:153], v[204:207], v[112:115]
	v_mfma_f32_16x16x32_bf16 v[108:111], v[158:161], v[204:207], v[108:111]
	v_mfma_f32_16x16x32_bf16 v[96:99], v[150:153], v[212:215], v[96:99]
	v_mfma_f32_16x16x32_bf16 v[92:95], v[158:161], v[212:215], v[92:95]
	v_mfma_f32_16x16x32_bf16 v[80:83], v[150:153], v[220:223], v[80:83]
	v_mfma_f32_16x16x32_bf16 v[76:79], v[158:161], v[220:223], v[76:79]
	s_setprio 0
	s_setprio 1
	v_mfma_f32_16x16x32_bf16 v[120:123], v[162:165], v[178:181], v[120:123]
	v_mfma_f32_16x16x32_bf16 v[116:119], v[170:173], v[178:181], v[116:119]
	v_mfma_f32_16x16x32_bf16 v[104:107], v[162:165], v[186:189], v[104:107]
	v_mfma_f32_16x16x32_bf16 v[100:103], v[170:173], v[186:189], v[100:103]
	v_mfma_f32_16x16x32_bf16 v[88:91], v[162:165], v[208:211], v[88:91]
	v_mfma_f32_16x16x32_bf16 v[84:87], v[170:173], v[208:211], v[84:87]
	v_mfma_f32_16x16x32_bf16 v[72:75], v[162:165], v[216:219], v[72:75]
	v_mfma_f32_16x16x32_bf16 v[68:71], v[170:173], v[216:219], v[68:71]
	v_mfma_f32_16x16x32_bf16 v[120:123], v[166:169], v[182:185], v[120:123]
	v_mfma_f32_16x16x32_bf16 v[116:119], v[174:177], v[182:185], v[116:119]
	v_mfma_f32_16x16x32_bf16 v[104:107], v[166:169], v[204:207], v[104:107]
	v_mfma_f32_16x16x32_bf16 v[100:103], v[174:177], v[204:207], v[100:103]
	v_mfma_f32_16x16x32_bf16 v[88:91], v[166:169], v[212:215], v[88:91]
	v_mfma_f32_16x16x32_bf16 v[84:87], v[174:177], v[212:215], v[84:87]
	v_mfma_f32_16x16x32_bf16 v[72:75], v[166:169], v[220:223], v[72:75]
	v_mfma_f32_16x16x32_bf16 v[68:71], v[174:177], v[220:223], v[68:71]
	s_setprio 0
	s_barrier
	s_add_i32 s54, s60, s35
	v_lshl_add_u64 v[190:191], s[58:59], 0, v[134:135]
	s_mov_b32 m0, s54
	ds_read_b128 v[178:181], v144 offset:16384
	ds_read_b128 v[182:185], v144 offset:17408
	ds_read_b128 v[186:189], v144 offset:18432
	ds_read_b128 v[204:207], v144 offset:19456
	ds_read_b128 v[208:211], v144 offset:20480
	ds_read_b128 v[212:215], v144 offset:21504
	ds_read_b128 v[216:219], v144 offset:22528
	ds_read_b128 v[220:223], v144 offset:23552
	global_load_lds_dwordx4 v[190:191], off
	s_add_i32 m0, s54, 0x2000
	s_add_u32 s54, s58, s6
	v_lshl_add_u64 v[230:231], s[58:59], 0, v[0:1]
	s_addc_u32 s55, s59, s7
	s_add_i32 s58, s61, s35
	global_load_lds_dwordx4 v[230:231], off
	v_lshl_add_u64 v[232:233], s[54:55], 0, v[134:135]
	s_mov_b32 m0, s58
	v_lshl_add_u64 v[238:239], s[54:55], 0, v[0:1]
	global_load_lds_dwordx4 v[232:233], off
	s_add_i32 m0, s58, 0x2000
	v_lshl_add_u64 v[240:241], s[24:25], 0, v[136:137]
	global_load_lds_dwordx4 v[238:239], off
	s_mov_b32 m0, s37
	v_lshl_add_u64 v[242:243], s[24:25], 0, v[132:133]
	global_load_lds_dwordx4 v[240:241], off
	s_mov_b32 m0, s38
	s_nop 0
	global_load_lds_dwordx4 v[242:243], off
	s_waitcnt vmcnt(8)
	s_waitcnt lgkmcnt(0)
	s_barrier
; #define PG8_STAGE(bufoff, gbase, voff) do { _Pragma("unroll") for (int _i = 0; _i < 2; ++_i) \
;         __builtin_amdgcn_global_load_lds((const unsigned*)((const char*)(gbase) + (voff)[_i]), (PG8_LAS unsigned*)(lds + (bufoff) + ldsw + _i * 8192), 16, 0, 0); } while (0)
; #define PG8_LDA(dst, b, h) do { _Pragma("unroll") for (int m = 0; m < 4; ++m) _Pragma("unroll") for (int k = 0; k < 2; ++k) dst[m][k] = *(const PG8_LAS bf16x8*)(lds + PG8_SA(b, h) + aoff + m * 2048 + k * 1024); } while (0)
; #define PG8_LDB(dst, b, h) do { _Pragma("unroll") for (int n = 0; n < 2; ++n) _Pragma("unroll") for (int k = 0; k < 2; ++k) dst[n][k] = *(const PG8_LAS bf16x8*)(lds + PG8_SB(b, h) + boff + n * 2048 + k * 1024); } while (0)
; #define PG8_MMA(ai, bj, At, Bt) do { __builtin_amdgcn_s_setprio(1); _Pragma("unroll") for (int m = 0; m < 4; ++m) _Pragma("unroll") for (int n = 0; n < 2; ++n) _Pragma("unroll") for (int k = 0; k < 2; ++k) \
;         acc[ai][bj][m][n] = __builtin_amdgcn_mfma_f32_16x16x32_bf16(Bt[n][k], At[m][k], acc[ai][bj][m][n], 0, 0, 0); __builtin_amdgcn_s_setprio(0); } while (0)
; #define PG8_WAIT_V(n) asm volatile("s_waitcnt vmcnt(" #n ")" ::: "memory")
; #define PG8_WAIT_L(n) asm volatile("s_waitcnt lgkmcnt(" #n ")" ::: "memory")
; #define PG8_BAR __builtin_amdgcn_s_barrier()
; #define PG8_SCHED __builtin_amdgcn_sched_barrier(0)
; template <class Epi, class Sched, bool ALIGN_EPI = false, bool SP2 = false>
; __device__ __forceinline__ void gemm_phase(PG8_LAS unsigned char* lds, const Gemm g, const Sched& S, const Epi& E, int tid_in) {
;     ...
;             PG8_WAIT_V(8); PG8_WAIT_L(0); PG8_BAR; PG8_MMA(1, 0, At, B0); PG8_MMA(1, 1, At, B1); PG8_BAR; PG8_SCHED;
;             PG8_LDB(B0, 1, 0); PG8_LDB(B1, 1, 1); PG8_SCHED; PG8_LDA(At, 1, 0); PG8_STAGE(PG8_SA(0, 1), a2 + hsA, voffA);
;             PG8_WAIT_V(8); PG8_WAIT_L(0); PG8_BAR; PG8_MMA(0, 0, At, B0); PG8_MMA(0, 1, At, B1); PG8_BAR; PG8_SCHED;
;             PG8_LDA(At, 1, 1); PG8_STAGE(PG8_SB(1, 0), b3, voffB); PG8_STAGE(PG8_SB(1, 1), b3 + hsB, voffB); PG8_STAGE(PG8_SA(1, 0), a3, voffA);
	s_setprio 1
	s_waitcnt lgkmcnt(0)
	v_mfma_f32_16x16x32_bf16 v[64:67], v[146:149], v[178:181], v[64:67]
	v_mfma_f32_16x16x32_bf16 v[60:63], v[154:157], v[178:181], v[60:63]
	v_mfma_f32_16x16x32_bf16 v[48:51], v[146:149], v[186:189], v[48:51]
	v_mfma_f32_16x16x32_bf16 v[44:47], v[154:157], v[186:189], v[44:47]
	v_mfma_f32_16x16x32_bf16 v[32:35], v[146:149], v[208:211], v[32:35]
	v_mfma_f32_16x16x32_bf16 v[28:31], v[154:157], v[208:211], v[28:31]
	v_mfma_f32_16x16x32_bf16 v[16:19], v[146:149], v[216:219], v[16:19]
	v_mfma_f32_16x16x32_bf16 v[12:15], v[154:157], v[216:219], v[12:15]
	v_mfma_f32_16x16x32_bf16 v[64:67], v[150:153], v[182:185], v[64:67]
	v_mfma_f32_16x16x32_bf16 v[60:63], v[158:161], v[182:185], v[60:63]
	v_mfma_f32_16x16x32_bf16 v[48:51], v[150:153], v[204:207], v[48:51]
	v_mfma_f32_16x16x32_bf16 v[44:47], v[158:161], v[204:207], v[44:47]
	v_mfma_f32_16x16x32_bf16 v[32:35], v[150:153], v[212:215], v[32:35]
	v_mfma_f32_16x16x32_bf16 v[28:31], v[158:161], v[212:215], v[28:31]
	v_mfma_f32_16x16x32_bf16 v[16:19], v[150:153], v[220:223], v[16:19]
	v_mfma_f32_16x16x32_bf16 v[12:15], v[158:161], v[220:223], v[12:15]
	s_setprio 0
	s_setprio 1
	v_mfma_f32_16x16x32_bf16 v[56:59], v[162:165], v[178:181], v[56:59]
	v_mfma_f32_16x16x32_bf16 v[52:55], v[170:173], v[178:181], v[52:55]
	v_mfma_f32_16x16x32_bf16 v[40:43], v[162:165], v[186:189], v[40:43]
	v_mfma_f32_16x16x32_bf16 v[36:39], v[170:173], v[186:189], v[36:39]
	v_mfma_f32_16x16x32_bf16 v[24:27], v[162:165], v[208:211], v[24:27]
	v_mfma_f32_16x16x32_bf16 v[20:23], v[170:173], v[208:211], v[20:23]
	v_mfma_f32_16x16x32_bf16 v[8:11], v[162:165], v[216:219], v[8:11]
	v_mfma_f32_16x16x32_bf16 v[4:7], v[170:173], v[216:219], v[4:7]
	v_mfma_f32_16x16x32_bf16 v[56:59], v[166:169], v[182:185], v[56:59]
	v_mfma_f32_16x16x32_bf16 v[52:55], v[174:177], v[182:185], v[52:55]
	v_mfma_f32_16x16x32_bf16 v[40:43], v[166:169], v[204:207], v[40:43]
	v_mfma_f32_16x16x32_bf16 v[36:39], v[174:177], v[204:207], v[36:39]
	v_mfma_f32_16x16x32_bf16 v[24:27], v[166:169], v[212:215], v[24:27]
	v_mfma_f32_16x16x32_bf16 v[20:23], v[174:177], v[212:215], v[20:23]
	v_mfma_f32_16x16x32_bf16 v[8:11], v[166:169], v[220:223], v[8:11]
	v_mfma_f32_16x16x32_bf16 v[4:7], v[174:177], v[220:223], v[4:7]
	s_setprio 0
	s_barrier
	s_add_i32 s54, 0, 0x18000
	v_add_u32_e32 v145, s54, v142
	s_add_i32 s55, 0, 0x1c000
	ds_read_b128 v[146:149], v145
	ds_read_b128 v[150:153], v145 offset:1024
	ds_read_b128 v[154:157], v145 offset:2048
	ds_read_b128 v[158:161], v145 offset:3072
	v_add_u32_e32 v145, s55, v142
	ds_read_b128 v[162:165], v145
	ds_read_b128 v[166:169], v145 offset:1024
	ds_read_b128 v[170:173], v145 offset:2048
	ds_read_b128 v[174:177], v145 offset:3072
	s_add_u32 s24, s24, s0
	s_addc_u32 s25, s25, s1
	s_mov_b32 m0, s39
	v_lshl_add_u64 v[244:245], s[24:25], 0, v[136:137]
	ds_read_b128 v[178:181], v144 offset:32768
	ds_read_b128 v[182:185], v144 offset:33792
	ds_read_b128 v[186:189], v144 offset:34816
	ds_read_b128 v[204:207], v144 offset:35840
	ds_read_b128 v[208:211], v144 offset:36864
	ds_read_b128 v[212:215], v144 offset:37888
	ds_read_b128 v[216:219], v144 offset:38912
	ds_read_b128 v[220:223], v144 offset:39936
	global_load_lds_dwordx4 v[244:245], off
	v_lshl_add_u64 v[244:245], s[24:25], 0, v[132:133]
	s_mov_b32 m0, s40
	s_nop 0
	global_load_lds_dwordx4 v[244:245], off
	s_waitcnt vmcnt(8)
	s_waitcnt lgkmcnt(0)
	s_barrier
	s_setprio 1
	s_waitcnt lgkmcnt(0)
	v_mfma_f32_16x16x32_bf16 v[124:127], v[146:149], v[178:181], v[124:127]
	v_mfma_f32_16x16x32_bf16 v[128:131], v[154:157], v[178:181], v[128:131]
	v_mfma_f32_16x16x32_bf16 v[112:115], v[146:149], v[186:189], v[112:115]
	v_mfma_f32_16x16x32_bf16 v[108:111], v[154:157], v[186:189], v[108:111]
	v_mfma_f32_16x16x32_bf16 v[96:99], v[146:149], v[208:211], v[96:99]
	v_mfma_f32_16x16x32_bf16 v[92:95], v[154:157], v[208:211], v[92:95]
	v_mfma_f32_16x16x32_bf16 v[80:83], v[146:149], v[216:219], v[80:83]
	v_mfma_f32_16x16x32_bf16 v[76:79], v[154:157], v[216:219], v[76:79]
	v_mfma_f32_16x16x32_bf16 v[124:127], v[150:153], v[182:185], v[124:127]
	v_mfma_f32_16x16x32_bf16 v[128:131], v[158:161], v[182:185], v[128:131]
	v_mfma_f32_16x16x32_bf16 v[112:115], v[150:153], v[204:207], v[112:115]
	v_mfma_f32_16x16x32_bf16 v[108:111], v[158:161], v[204:207], v[108:111]
	v_mfma_f32_16x16x32_bf16 v[96:99], v[150:153], v[212:215], v[96:99]
	v_mfma_f32_16x16x32_bf16 v[92:95], v[158:161], v[212:215], v[92:95]
	v_mfma_f32_16x16x32_bf16 v[80:83], v[150:153], v[220:223], v[80:83]
	v_mfma_f32_16x16x32_bf16 v[76:79], v[158:161], v[220:223], v[76:79]
	s_setprio 0
	s_setprio 1
	v_mfma_f32_16x16x32_bf16 v[120:123], v[162:165], v[178:181], v[120:123]
	v_mfma_f32_16x16x32_bf16 v[116:119], v[170:173], v[178:181], v[116:119]
	v_mfma_f32_16x16x32_bf16 v[104:107], v[162:165], v[186:189], v[104:107]
	v_mfma_f32_16x16x32_bf16 v[100:103], v[170:173], v[186:189], v[100:103]
	v_mfma_f32_16x16x32_bf16 v[88:91], v[162:165], v[208:211], v[88:91]
	v_mfma_f32_16x16x32_bf16 v[84:87], v[170:173], v[208:211], v[84:87]
	v_mfma_f32_16x16x32_bf16 v[72:75], v[162:165], v[216:219], v[72:75]
	v_mfma_f32_16x16x32_bf16 v[68:71], v[170:173], v[216:219], v[68:71]
	v_mfma_f32_16x16x32_bf16 v[120:123], v[166:169], v[182:185], v[120:123]
	v_mfma_f32_16x16x32_bf16 v[116:119], v[174:177], v[182:185], v[116:119]
	v_mfma_f32_16x16x32_bf16 v[104:107], v[166:169], v[204:207], v[104:107]
	v_mfma_f32_16x16x32_bf16 v[100:103], v[174:177], v[204:207], v[100:103]
	v_mfma_f32_16x16x32_bf16 v[88:91], v[166:169], v[212:215], v[88:91]
	v_mfma_f32_16x16x32_bf16 v[84:87], v[174:177], v[212:215], v[84:87]
	v_mfma_f32_16x16x32_bf16 v[72:75], v[166:169], v[220:223], v[72:75]
	v_mfma_f32_16x16x32_bf16 v[68:71], v[174:177], v[220:223], v[68:71]
	s_setprio 0
	s_barrier
; #define PG8_STAGE(bufoff, gbase, voff) do { _Pragma("unroll") for (int _i = 0; _i < 2; ++_i) \
;         __builtin_amdgcn_global_load_lds((const unsigned*)((const char*)(gbase) + (voff)[_i]), (PG8_LAS unsigned*)(lds + (bufoff) + ldsw + _i * 8192), 16, 0, 0); } while (0)
; #define PG8_LDA(dst, b, h) do { _Pragma("unroll") for (int m = 0; m < 4; ++m) _Pragma("unroll") for (int k = 0; k < 2; ++k) dst[m][k] = *(const PG8_LAS bf16x8*)(lds + PG8_SA(b, h) + aoff + m * 2048 + k * 1024); } while (0)
; #define PG8_MMA(ai, bj, At, Bt) do { __builtin_amdgcn_s_setprio(1); _Pragma("unroll") for (int m = 0; m < 4; ++m) _Pragma("unroll") for (int n = 0; n < 2; ++n) _Pragma("unroll") for (int k = 0; k < 2; ++k) \
;         acc[ai][bj][m][n] = __builtin_amdgcn_mfma_f32_16x16x32_bf16(Bt[n][k], At[m][k], acc[ai][bj][m][n], 0, 0, 0); __builtin_amdgcn_s_setprio(0); } while (0)
; #define PG8_WAIT_V(n) asm volatile("s_waitcnt vmcnt(" #n ")" ::: "memory")
; #define PG8_WAIT_L(n) asm volatile("s_waitcnt lgkmcnt(" #n ")" ::: "memory")
; #define PG8_BAR __builtin_amdgcn_s_barrier()
; #define PG8_SCHED __builtin_amdgcn_sched_barrier(0)
; template <class Epi, class Sched, bool ALIGN_EPI = false, bool SP2 = false>
; __device__ __forceinline__ void gemm_phase(PG8_LAS unsigned char* lds, const Gemm g, const Sched& S, const Epi& E, int tid_in) {
;     ...
;             PG8_LDA(At, 1, 1); PG8_STAGE(PG8_SB(1, 0), b3, voffB); PG8_STAGE(PG8_SB(1, 1), b3 + hsB, voffB); PG8_STAGE(PG8_SA(1, 0), a3, voffA);
;             PG8_WAIT_V(8); PG8_WAIT_L(0); PG8_BAR; PG8_MMA(1, 0, At, B0); PG8_MMA(1, 1, At, B1); PG8_BAR; PG8_SCHED;
	s_add_i32 s24, s54, s35
	v_lshl_add_u64 v[190:191], v[190:191], 0, s[80:81]
	s_mov_b32 m0, s24
	ds_read_b128 v[178:181], v144 offset:49152
	ds_read_b128 v[182:185], v144 offset:50176
	ds_read_b128 v[186:189], v144 offset:51200
	ds_read_b128 v[204:207], v144 offset:52224
	ds_read_b128 v[208:211], v144 offset:53248
	ds_read_b128 v[212:215], v144 offset:54272
	ds_read_b128 v[216:219], v144 offset:55296
	ds_read_b128 v[220:223], v144 offset:56320
	global_load_lds_dwordx4 v[190:191], off
	v_lshl_add_u64 v[190:191], v[230:231], 0, s[80:81]
	s_add_i32 m0, s24, 0x2000
	s_add_i32 s24, s55, s35
	global_load_lds_dwordx4 v[190:191], off
	v_lshl_add_u64 v[190:191], v[232:233], 0, s[80:81]
	s_mov_b32 m0, s24
	s_nop 0
	global_load_lds_dwordx4 v[190:191], off
	v_lshl_add_u64 v[190:191], v[238:239], 0, s[80:81]
	s_add_i32 m0, s24, 0x2000
	s_nop 0
	global_load_lds_dwordx4 v[190:191], off
	v_lshl_add_u64 v[190:191], v[240:241], 0, s[80:81]
	s_mov_b32 m0, s41
	s_nop 0
	global_load_lds_dwordx4 v[190:191], off
	v_lshl_add_u64 v[190:191], v[242:243], 0, s[80:81]
	s_mov_b32 m0, s42
	s_nop 0
	global_load_lds_dwordx4 v[190:191], off
	s_waitcnt vmcnt(8)
	s_waitcnt lgkmcnt(0)
	s_barrier
	s_setprio 1
	s_waitcnt lgkmcnt(0)
	s_nop 0
	v_mfma_f32_16x16x32_bf16 v[64:67], v[146:149], v[178:181], v[64:67]
	v_mfma_f32_16x16x32_bf16 v[60:63], v[154:157], v[178:181], v[60:63]
	v_mfma_f32_16x16x32_bf16 v[48:51], v[146:149], v[186:189], v[48:51]
	v_mfma_f32_16x16x32_bf16 v[44:47], v[154:157], v[186:189], v[44:47]
	v_mfma_f32_16x16x32_bf16 v[32:35], v[146:149], v[208:211], v[32:35]
	v_mfma_f32_16x16x32_bf16 v[28:31], v[154:157], v[208:211], v[28:31]
	v_mfma_f32_16x16x32_bf16 v[16:19], v[146:149], v[216:219], v[16:19]
	v_mfma_f32_16x16x32_bf16 v[12:15], v[154:157], v[216:219], v[12:15]
	v_mfma_f32_16x16x32_bf16 v[64:67], v[150:153], v[182:185], v[64:67]
	v_mfma_f32_16x16x32_bf16 v[60:63], v[158:161], v[182:185], v[60:63]
	v_mfma_f32_16x16x32_bf16 v[48:51], v[150:153], v[204:207], v[48:51]
	v_mfma_f32_16x16x32_bf16 v[44:47], v[158:161], v[204:207], v[44:47]
	v_mfma_f32_16x16x32_bf16 v[32:35], v[150:153], v[212:215], v[32:35]
	v_mfma_f32_16x16x32_bf16 v[28:31], v[158:161], v[212:215], v[28:31]
	v_mfma_f32_16x16x32_bf16 v[16:19], v[150:153], v[220:223], v[16:19]
	v_mfma_f32_16x16x32_bf16 v[12:15], v[158:161], v[220:223], v[12:15]
	s_setprio 0
	s_setprio 1
	v_mfma_f32_16x16x32_bf16 v[56:59], v[162:165], v[178:181], v[56:59]
	v_mfma_f32_16x16x32_bf16 v[52:55], v[170:173], v[178:181], v[52:55]
	v_mfma_f32_16x16x32_bf16 v[40:43], v[162:165], v[186:189], v[40:43]
	v_mfma_f32_16x16x32_bf16 v[36:39], v[170:173], v[186:189], v[36:39]
	v_mfma_f32_16x16x32_bf16 v[24:27], v[162:165], v[208:211], v[24:27]
	v_mfma_f32_16x16x32_bf16 v[20:23], v[170:173], v[208:211], v[20:23]
	v_mfma_f32_16x16x32_bf16 v[8:11], v[162:165], v[216:219], v[8:11]
	v_mfma_f32_16x16x32_bf16 v[4:7], v[170:173], v[216:219], v[4:7]
	v_mfma_f32_16x16x32_bf16 v[56:59], v[166:169], v[182:185], v[56:59]
	v_mfma_f32_16x16x32_bf16 v[52:55], v[174:177], v[182:185], v[52:55]
	v_mfma_f32_16x16x32_bf16 v[40:43], v[166:169], v[204:207], v[40:43]
	v_mfma_f32_16x16x32_bf16 v[36:39], v[174:177], v[204:207], v[36:39]
	v_mfma_f32_16x16x32_bf16 v[24:27], v[166:169], v[212:215], v[24:27]
	v_mfma_f32_16x16x32_bf16 v[20:23], v[174:177], v[212:215], v[20:23]
	v_mfma_f32_16x16x32_bf16 v[8:11], v[166:169], v[220:223], v[8:11]
	v_mfma_f32_16x16x32_bf16 v[4:7], v[174:177], v[220:223], v[4:7]
	s_setprio 0
	s_barrier
	s_add_i32 s24, s53, 2
	s_add_u32 s51, s51, 0x100
	s_addc_u32 s52, s52, 0
	s_add_u32 s22, s22, 0x100
	s_addc_u32 s23, s23, 0
	s_cmp_ge_i32 s53, s43
	s_mov_b32 s53, s24
	s_cbranch_scc0 .LBB0_709

; #define PG8_STAGE(bufoff, gbase, voff) do { _Pragma("unroll") for (int _i = 0; _i < 2; ++_i) \
;         __builtin_amdgcn_global_load_lds((const unsigned*)((const char*)(gbase) + (voff)[_i]), (PG8_LAS unsigned*)(lds + (bufoff) + ldsw + _i * 8192), 16, 0, 0); } while (0)
; #define PG8_LDA(dst, b, h) do { _Pragma("unroll") for (int m = 0; m < 4; ++m) _Pragma("unroll") for (int k = 0; k < 2; ++k) dst[m][k] = *(const PG8_LAS bf16x8*)(lds + PG8_SA(b, h) + aoff + m * 2048 + k * 1024); } while (0)
; #define PG8_LDB(dst, b, h) do { _Pragma("unroll") for (int n = 0; n < 2; ++n) _Pragma("unroll") for (int k = 0; k < 2; ++k) dst[n][k] = *(const PG8_LAS bf16x8*)(lds + PG8_SB(b, h) + boff + n * 2048 + k * 1024); } while (0)
; #define PG8_MMA(ai, bj, At, Bt) do { __builtin_amdgcn_s_setprio(1); _Pragma("unroll") for (int m = 0; m < 4; ++m) _Pragma("unroll") for (int n = 0; n < 2; ++n) _Pragma("unroll") for (int k = 0; k < 2; ++k) \
;         acc[ai][bj][m][n] = __builtin_amdgcn_mfma_f32_16x16x32_bf16(Bt[n][k], At[m][k], acc[ai][bj][m][n], 0, 0, 0); __builtin_amdgcn_s_setprio(0); } while (0)
; #define PG8_WAIT_V(n) asm volatile("s_waitcnt vmcnt(" #n ")" ::: "memory")
; template <class Epi, class Sched, bool ALIGN_EPI = false, bool SP2 = false>
; __device__ __forceinline__ void gemm_phase(PG8_LAS unsigned char* lds, const Gemm g, const Sched& S, const Epi& E, int tid_in) {
;     ...
;         for (int t = 0; t < nt; t += 2) {
;             const bool last = (t == nt - 2);
;             if constexpr (mid_hook<Epi>::value) { if (t == Epi::H1 || t == Epi::H2) E.mid(acc, cur, wr, wc, fr, fq, t == Epi::H2); }
;             const char* a1 = cA + (size_t)(t + 1) * kstep + (t >= jt ? jb : 0);
;             const char* a2 = last ? nA : cA + (size_t)(t + 2) * kstep + (t + 2 >= jt ? jb : 0); const char* b2 = last ? nB : cB + (size_t)(t + 2) * kstep;
;             const char* a3 = a2 + kstep; const char* b3 = b2 + kstep;
;             if (last && has_next) S.a_ready(nxt);
;             if constexpr (SP2) {
;             PG8_LDB(B0, 0, 0); PG8_LDB(B1, 0, 1); PG8_SCHED; PG8_LDA(At, 0, 0); PG8_STAGE(PG8_SA(1, 1), a1 + hsA, voffA);
;             PG8_WAIT_V(8); PG8_WAIT_L(0); PG8_BAR; PG8_MMA(0, 0, At, B0); PG8_MMA(0, 1, At, B1); PG8_BAR; PG8_SCHED;
;             PG8_LDA(At, 0, 1); PG8_STAGE(PG8_SB(0, 0), b2, voffB); PG8_STAGE(PG8_SB(0, 1), b2 + hsB, voffB); PG8_STAGE(PG8_SA(0, 0), a2, voffA);
.LBB0_924:
	s_add_i32 s24, s58, -2
	s_cmp_ge_i32 s24, s29
	s_cselect_b32 s60, s30, 0
	s_cselect_b32 s61, s47, 0
	s_cmp_ge_i32 s58, s29
	s_cselect_b32 s25, s30, 0
	s_cselect_b32 s24, s47, 0
	s_add_u32 s25, s22, s25
	s_addc_u32 s24, s23, s24
	s_add_u32 s59, s25, 0x80
	s_addc_u32 s24, s24, 0
	s_add_i32 s64, 0, 0x10000
	s_cmp_eq_u32 s46, s58
	s_cselect_b32 s25, s5, s24
	s_cselect_b32 s24, s4, s59
	v_add_u32_e32 v142, s64, v144
	s_cselect_b32 s63, s21, s55
	s_cselect_b32 s62, s20, s54
	s_add_i32 s59, 0, 0x14000
	ds_read_b128 v[148:151], v142
	ds_read_b128 v[152:155], v142 offset:1024
	ds_read_b128 v[156:159], v142 offset:2048
	ds_read_b128 v[160:163], v142 offset:3072
	v_add_u32_e32 v142, s59, v144
	ds_read_b128 v[164:167], v142
	ds_read_b128 v[168:171], v142 offset:1024
	ds_read_b128 v[172:175], v142 offset:2048
	ds_read_b128 v[176:179], v142 offset:3072
	v_lshl_add_u64 v[142:143], s[22:23], 0, v[140:141]
	v_lshl_add_u64 v[142:143], v[142:143], 0, s[60:61]
	s_add_i32 m0, s40, 0xc000
	ds_read_b128 v[180:183], v146
	ds_read_b128 v[184:187], v146 offset:1024
	ds_read_b128 v[188:191], v146 offset:2048
	ds_read_b128 v[204:207], v146 offset:3072
	ds_read_b128 v[208:211], v146 offset:4096
	ds_read_b128 v[212:215], v146 offset:5120
	ds_read_b128 v[216:219], v146 offset:6144
	ds_read_b128 v[220:223], v146 offset:7168
	global_load_lds_dwordx4 v[142:143], off
	v_lshl_add_u64 v[142:143], s[22:23], 0, v[138:139]
	v_lshl_add_u64 v[142:143], v[142:143], 0, s[60:61]
	s_add_i32 m0, s40, 0xe000
	s_nop 0
	global_load_lds_dwordx4 v[142:143], off
	s_waitcnt vmcnt(8)
	s_waitcnt lgkmcnt(0)
	s_barrier
	s_setprio 1
	s_waitcnt lgkmcnt(0)
	v_mfma_f32_16x16x32_bf16 v[128:131], v[148:151], v[180:183], v[128:131]
	v_mfma_f32_16x16x32_bf16 v[124:127], v[156:159], v[180:183], v[124:127]
	v_mfma_f32_16x16x32_bf16 v[112:115], v[148:151], v[188:191], v[112:115]
	v_mfma_f32_16x16x32_bf16 v[108:111], v[156:159], v[188:191], v[108:111]
	v_mfma_f32_16x16x32_bf16 v[96:99], v[148:151], v[208:211], v[96:99]
	v_mfma_f32_16x16x32_bf16 v[92:95], v[156:159], v[208:211], v[92:95]
	v_mfma_f32_16x16x32_bf16 v[80:83], v[148:151], v[216:219], v[80:83]
	v_mfma_f32_16x16x32_bf16 v[76:79], v[156:159], v[216:219], v[76:79]
	v_mfma_f32_16x16x32_bf16 v[128:131], v[152:155], v[184:187], v[128:131]
	v_mfma_f32_16x16x32_bf16 v[124:127], v[160:163], v[184:187], v[124:127]
	v_mfma_f32_16x16x32_bf16 v[112:115], v[152:155], v[204:207], v[112:115]
	v_mfma_f32_16x16x32_bf16 v[108:111], v[160:163], v[204:207], v[108:111]
	v_mfma_f32_16x16x32_bf16 v[96:99], v[152:155], v[212:215], v[96:99]
	v_mfma_f32_16x16x32_bf16 v[92:95], v[160:163], v[212:215], v[92:95]
	v_mfma_f32_16x16x32_bf16 v[80:83], v[152:155], v[220:223], v[80:83]
	v_mfma_f32_16x16x32_bf16 v[76:79], v[160:163], v[220:223], v[76:79]
	s_setprio 0
	s_setprio 1
	v_mfma_f32_16x16x32_bf16 v[120:123], v[164:167], v[180:183], v[120:123]
	v_mfma_f32_16x16x32_bf16 v[116:119], v[172:175], v[180:183], v[116:119]
	v_mfma_f32_16x16x32_bf16 v[104:107], v[164:167], v[188:191], v[104:107]
	v_mfma_f32_16x16x32_bf16 v[100:103], v[172:175], v[188:191], v[100:103]
	v_mfma_f32_16x16x32_bf16 v[88:91], v[164:167], v[208:211], v[88:91]
	v_mfma_f32_16x16x32_bf16 v[84:87], v[172:175], v[208:211], v[84:87]
	v_mfma_f32_16x16x32_bf16 v[72:75], v[164:167], v[216:219], v[72:75]
	v_mfma_f32_16x16x32_bf16 v[68:71], v[172:175], v[216:219], v[68:71]
	v_mfma_f32_16x16x32_bf16 v[120:123], v[168:171], v[184:187], v[120:123]
	v_mfma_f32_16x16x32_bf16 v[116:119], v[176:179], v[184:187], v[116:119]
	v_mfma_f32_16x16x32_bf16 v[104:107], v[168:171], v[204:207], v[104:107]
	v_mfma_f32_16x16x32_bf16 v[100:103], v[176:179], v[204:207], v[100:103]
	v_mfma_f32_16x16x32_bf16 v[88:91], v[168:171], v[212:215], v[88:91]
	v_mfma_f32_16x16x32_bf16 v[84:87], v[176:179], v[212:215], v[84:87]
	v_mfma_f32_16x16x32_bf16 v[72:75], v[168:171], v[220:223], v[72:75]
	v_mfma_f32_16x16x32_bf16 v[68:71], v[176:179], v[220:223], v[68:71]
	s_setprio 0
	s_barrier
	s_add_i32 s60, s64, s34
	v_lshl_add_u64 v[142:143], s[62:63], 0, v[134:135]
	s_mov_b32 m0, s60
	ds_read_b128 v[180:183], v146 offset:16384
	ds_read_b128 v[184:187], v146 offset:17408
	ds_read_b128 v[188:191], v146 offset:18432
	ds_read_b128 v[204:207], v146 offset:19456
	ds_read_b128 v[208:211], v146 offset:20480
	ds_read_b128 v[212:215], v146 offset:21504
	ds_read_b128 v[216:219], v146 offset:22528
	ds_read_b128 v[220:223], v146 offset:23552
	global_load_lds_dwordx4 v[142:143], off
	s_add_i32 m0, s60, 0x2000
	s_add_u32 s60, s62, s8
	v_lshl_add_u64 v[196:197], s[62:63], 0, v[0:1]
	s_addc_u32 s61, s63, s9
	s_add_i32 s59, s59, s34
	global_load_lds_dwordx4 v[196:197], off
	v_lshl_add_u64 v[198:199], s[60:61], 0, v[134:135]
	s_mov_b32 m0, s59
	v_lshl_add_u64 v[200:201], s[60:61], 0, v[0:1]
	global_load_lds_dwordx4 v[198:199], off
	s_add_i32 m0, s59, 0x2000
	v_lshl_add_u64 v[228:229], s[24:25], 0, v[136:137]
	global_load_lds_dwordx4 v[200:201], off
	s_mov_b32 m0, s40
	v_lshl_add_u64 v[230:231], s[24:25], 0, v[132:133]
	global_load_lds_dwordx4 v[228:229], off
	s_mov_b32 m0, s41
	s_nop 0
	global_load_lds_dwordx4 v[230:231], off
	s_waitcnt vmcnt(8)
	s_waitcnt lgkmcnt(0)
	s_barrier
; #define PG8_STAGE(bufoff, gbase, voff) do { _Pragma("unroll") for (int _i = 0; _i < 2; ++_i) \
;         __builtin_amdgcn_global_load_lds((const unsigned*)((const char*)(gbase) + (voff)[_i]), (PG8_LAS unsigned*)(lds + (bufoff) + ldsw + _i * 8192), 16, 0, 0); } while (0)
; #define PG8_LDA(dst, b, h) do { _Pragma("unroll") for (int m = 0; m < 4; ++m) _Pragma("unroll") for (int k = 0; k < 2; ++k) dst[m][k] = *(const PG8_LAS bf16x8*)(lds + PG8_SA(b, h) + aoff + m * 2048 + k * 1024); } while (0)
; #define PG8_LDB(dst, b, h) do { _Pragma("unroll") for (int n = 0; n < 2; ++n) _Pragma("unroll") for (int k = 0; k < 2; ++k) dst[n][k] = *(const PG8_LAS bf16x8*)(lds + PG8_SB(b, h) + boff + n * 2048 + k * 1024); } while (0)
; #define PG8_MMA(ai, bj, At, Bt) do { __builtin_amdgcn_s_setprio(1); _Pragma("unroll") for (int m = 0; m < 4; ++m) _Pragma("unroll") for (int n = 0; n < 2; ++n) _Pragma("unroll") for (int k = 0; k < 2; ++k) \
;         acc[ai][bj][m][n] = __builtin_amdgcn_mfma_f32_16x16x32_bf16(Bt[n][k], At[m][k], acc[ai][bj][m][n], 0, 0, 0); __builtin_amdgcn_s_setprio(0); } while (0)
; #define PG8_WAIT_V(n) asm volatile("s_waitcnt vmcnt(" #n ")" ::: "memory")
; #define PG8_WAIT_L(n) asm volatile("s_waitcnt lgkmcnt(" #n ")" ::: "memory")
; #define PG8_BAR __builtin_amdgcn_s_barrier()
; #define PG8_SCHED __builtin_amdgcn_sched_barrier(0)
; template <class Epi, class Sched, bool ALIGN_EPI = false, bool SP2 = false>
; __device__ __forceinline__ void gemm_phase(PG8_LAS unsigned char* lds, const Gemm g, const Sched& S, const Epi& E, int tid_in) {
;     ...
;             PG8_WAIT_V(8); PG8_WAIT_L(0); PG8_BAR; PG8_MMA(1, 0, At, B0); PG8_MMA(1, 1, At, B1); PG8_BAR; PG8_SCHED;
;             PG8_LDB(B0, 1, 0); PG8_LDB(B1, 1, 1); PG8_SCHED; PG8_LDA(At, 1, 0); PG8_STAGE(PG8_SA(0, 1), a2 + hsA, voffA);
;             PG8_WAIT_V(8); PG8_WAIT_L(0); PG8_BAR; PG8_MMA(0, 0, At, B0); PG8_MMA(0, 1, At, B1); PG8_BAR; PG8_SCHED;
	s_setprio 1
	s_waitcnt lgkmcnt(0)
	v_mfma_f32_16x16x32_bf16 v[64:67], v[148:151], v[180:183], v[64:67]
	v_mfma_f32_16x16x32_bf16 v[60:63], v[156:159], v[180:183], v[60:63]
	v_mfma_f32_16x16x32_bf16 v[48:51], v[148:151], v[188:191], v[48:51]
	v_mfma_f32_16x16x32_bf16 v[44:47], v[156:159], v[188:191], v[44:47]
	v_mfma_f32_16x16x32_bf16 v[32:35], v[148:151], v[208:211], v[32:35]
	v_mfma_f32_16x16x32_bf16 v[28:31], v[156:159], v[208:211], v[28:31]
	v_mfma_f32_16x16x32_bf16 v[16:19], v[148:151], v[216:219], v[16:19]
	v_mfma_f32_16x16x32_bf16 v[12:15], v[156:159], v[216:219], v[12:15]
	v_mfma_f32_16x16x32_bf16 v[64:67], v[152:155], v[184:187], v[64:67]
	v_mfma_f32_16x16x32_bf16 v[60:63], v[160:163], v[184:187], v[60:63]
	v_mfma_f32_16x16x32_bf16 v[48:51], v[152:155], v[204:207], v[48:51]
	v_mfma_f32_16x16x32_bf16 v[44:47], v[160:163], v[204:207], v[44:47]
	v_mfma_f32_16x16x32_bf16 v[32:35], v[152:155], v[212:215], v[32:35]
	v_mfma_f32_16x16x32_bf16 v[28:31], v[160:163], v[212:215], v[28:31]
	v_mfma_f32_16x16x32_bf16 v[16:19], v[152:155], v[220:223], v[16:19]
	v_mfma_f32_16x16x32_bf16 v[12:15], v[160:163], v[220:223], v[12:15]
	s_setprio 0
	s_setprio 1
	v_mfma_f32_16x16x32_bf16 v[56:59], v[164:167], v[180:183], v[56:59]
	v_mfma_f32_16x16x32_bf16 v[52:55], v[172:175], v[180:183], v[52:55]
	v_mfma_f32_16x16x32_bf16 v[40:43], v[164:167], v[188:191], v[40:43]
	v_mfma_f32_16x16x32_bf16 v[36:39], v[172:175], v[188:191], v[36:39]
	v_mfma_f32_16x16x32_bf16 v[24:27], v[164:167], v[208:211], v[24:27]
	v_mfma_f32_16x16x32_bf16 v[20:23], v[172:175], v[208:211], v[20:23]
	v_mfma_f32_16x16x32_bf16 v[8:11], v[164:167], v[216:219], v[8:11]
	v_mfma_f32_16x16x32_bf16 v[4:7], v[172:175], v[216:219], v[4:7]
	v_mfma_f32_16x16x32_bf16 v[56:59], v[168:171], v[184:187], v[56:59]
	v_mfma_f32_16x16x32_bf16 v[52:55], v[176:179], v[184:187], v[52:55]
	v_mfma_f32_16x16x32_bf16 v[40:43], v[168:171], v[204:207], v[40:43]
	v_mfma_f32_16x16x32_bf16 v[36:39], v[176:179], v[204:207], v[36:39]
	v_mfma_f32_16x16x32_bf16 v[24:27], v[168:171], v[212:215], v[24:27]
	v_mfma_f32_16x16x32_bf16 v[20:23], v[176:179], v[212:215], v[20:23]
	v_mfma_f32_16x16x32_bf16 v[8:11], v[168:171], v[220:223], v[8:11]
	v_mfma_f32_16x16x32_bf16 v[4:7], v[176:179], v[220:223], v[4:7]
	s_setprio 0
	s_barrier
	s_add_i32 s59, 0, 0x18000
	v_add_u32_e32 v147, s59, v144
	s_add_i32 s60, 0, 0x1c000
	ds_read_b128 v[148:151], v147
	ds_read_b128 v[152:155], v147 offset:1024
	ds_read_b128 v[156:159], v147 offset:2048
	ds_read_b128 v[160:163], v147 offset:3072
	v_add_u32_e32 v147, s60, v144
	ds_read_b128 v[164:167], v147
	ds_read_b128 v[168:171], v147 offset:1024
	ds_read_b128 v[172:175], v147 offset:2048
	ds_read_b128 v[176:179], v147 offset:3072
	s_add_u32 s24, s24, s6
	s_addc_u32 s25, s25, s7
	s_mov_b32 m0, s42
	v_lshl_add_u64 v[232:233], s[24:25], 0, v[136:137]
	ds_read_b128 v[180:183], v146 offset:32768
	ds_read_b128 v[184:187], v146 offset:33792
	ds_read_b128 v[188:191], v146 offset:34816
	ds_read_b128 v[204:207], v146 offset:35840
	ds_read_b128 v[208:211], v146 offset:36864
	ds_read_b128 v[212:215], v146 offset:37888
	ds_read_b128 v[216:219], v146 offset:38912
	ds_read_b128 v[220:223], v146 offset:39936
	global_load_lds_dwordx4 v[232:233], off
	v_lshl_add_u64 v[232:233], s[24:25], 0, v[132:133]
	s_mov_b32 m0, s43
	s_nop 0
	global_load_lds_dwordx4 v[232:233], off
	s_waitcnt vmcnt(8)
	s_waitcnt lgkmcnt(0)
	s_barrier
	s_setprio 1
	s_waitcnt lgkmcnt(0)
	v_mfma_f32_16x16x32_bf16 v[128:131], v[148:151], v[180:183], v[128:131]
	v_mfma_f32_16x16x32_bf16 v[124:127], v[156:159], v[180:183], v[124:127]
	v_mfma_f32_16x16x32_bf16 v[112:115], v[148:151], v[188:191], v[112:115]
	v_mfma_f32_16x16x32_bf16 v[108:111], v[156:159], v[188:191], v[108:111]
	v_mfma_f32_16x16x32_bf16 v[96:99], v[148:151], v[208:211], v[96:99]
	v_mfma_f32_16x16x32_bf16 v[92:95], v[156:159], v[208:211], v[92:95]
	v_mfma_f32_16x16x32_bf16 v[80:83], v[148:151], v[216:219], v[80:83]
	v_mfma_f32_16x16x32_bf16 v[76:79], v[156:159], v[216:219], v[76:79]
	v_mfma_f32_16x16x32_bf16 v[128:131], v[152:155], v[184:187], v[128:131]
	v_mfma_f32_16x16x32_bf16 v[124:127], v[160:163], v[184:187], v[124:127]
	v_mfma_f32_16x16x32_bf16 v[112:115], v[152:155], v[204:207], v[112:115]
	v_mfma_f32_16x16x32_bf16 v[108:111], v[160:163], v[204:207], v[108:111]
	v_mfma_f32_16x16x32_bf16 v[96:99], v[152:155], v[212:215], v[96:99]
	v_mfma_f32_16x16x32_bf16 v[92:95], v[160:163], v[212:215], v[92:95]
	v_mfma_f32_16x16x32_bf16 v[80:83], v[152:155], v[220:223], v[80:83]
	v_mfma_f32_16x16x32_bf16 v[76:79], v[160:163], v[220:223], v[76:79]
	s_setprio 0
	s_setprio 1
	v_mfma_f32_16x16x32_bf16 v[120:123], v[164:167], v[180:183], v[120:123]
	v_mfma_f32_16x16x32_bf16 v[116:119], v[172:175], v[180:183], v[116:119]
	v_mfma_f32_16x16x32_bf16 v[104:107], v[164:167], v[188:191], v[104:107]
	v_mfma_f32_16x16x32_bf16 v[100:103], v[172:175], v[188:191], v[100:103]
	v_mfma_f32_16x16x32_bf16 v[88:91], v[164:167], v[208:211], v[88:91]
	v_mfma_f32_16x16x32_bf16 v[84:87], v[172:175], v[208:211], v[84:87]
	v_mfma_f32_16x16x32_bf16 v[72:75], v[164:167], v[216:219], v[72:75]
	v_mfma_f32_16x16x32_bf16 v[68:71], v[172:175], v[216:219], v[68:71]
	v_mfma_f32_16x16x32_bf16 v[120:123], v[168:171], v[184:187], v[120:123]
	v_mfma_f32_16x16x32_bf16 v[116:119], v[176:179], v[184:187], v[116:119]
	v_mfma_f32_16x16x32_bf16 v[104:107], v[168:171], v[204:207], v[104:107]
	v_mfma_f32_16x16x32_bf16 v[100:103], v[176:179], v[204:207], v[100:103]
	v_mfma_f32_16x16x32_bf16 v[88:91], v[168:171], v[212:215], v[88:91]
	v_mfma_f32_16x16x32_bf16 v[84:87], v[176:179], v[212:215], v[84:87]
	v_mfma_f32_16x16x32_bf16 v[72:75], v[168:171], v[220:223], v[72:75]
	v_mfma_f32_16x16x32_bf16 v[68:71], v[176:179], v[220:223], v[68:71]
	s_setprio 0
	s_barrier
; #define PG8_STAGE(bufoff, gbase, voff) do { _Pragma("unroll") for (int _i = 0; _i < 2; ++_i) \
;         __builtin_amdgcn_global_load_lds((const unsigned*)((const char*)(gbase) + (voff)[_i]), (PG8_LAS unsigned*)(lds + (bufoff) + ldsw + _i * 8192), 16, 0, 0); } while (0)
; #define PG8_LDA(dst, b, h) do { _Pragma("unroll") for (int m = 0; m < 4; ++m) _Pragma("unroll") for (int k = 0; k < 2; ++k) dst[m][k] = *(const PG8_LAS bf16x8*)(lds + PG8_SA(b, h) + aoff + m * 2048 + k * 1024); } while (0)
; #define PG8_MMA(ai, bj, At, Bt) do { __builtin_amdgcn_s_setprio(1); _Pragma("unroll") for (int m = 0; m < 4; ++m) _Pragma("unroll") for (int n = 0; n < 2; ++n) _Pragma("unroll") for (int k = 0; k < 2; ++k) \
;         acc[ai][bj][m][n] = __builtin_amdgcn_mfma_f32_16x16x32_bf16(Bt[n][k], At[m][k], acc[ai][bj][m][n], 0, 0, 0); __builtin_amdgcn_s_setprio(0); } while (0)
; #define PG8_WAIT_V(n) asm volatile("s_waitcnt vmcnt(" #n ")" ::: "memory")
; #define PG8_WAIT_L(n) asm volatile("s_waitcnt lgkmcnt(" #n ")" ::: "memory")
; #define PG8_BAR __builtin_amdgcn_s_barrier()
; #define PG8_SCHED __builtin_amdgcn_sched_barrier(0)
; template <class Epi, class Sched, bool ALIGN_EPI = false, bool SP2 = false>
; __device__ __forceinline__ void gemm_phase(PG8_LAS unsigned char* lds, const Gemm g, const Sched& S, const Epi& E, int tid_in) {
;     ...
;             PG8_LDA(At, 1, 1); PG8_STAGE(PG8_SB(1, 0), b3, voffB); PG8_STAGE(PG8_SB(1, 1), b3 + hsB, voffB); PG8_STAGE(PG8_SA(1, 0), a3, voffA);
;             PG8_WAIT_V(8); PG8_WAIT_L(0); PG8_BAR; PG8_MMA(1, 0, At, B0); PG8_MMA(1, 1, At, B1); PG8_BAR; PG8_SCHED;
	s_add_i32 s24, s59, s34
	v_lshl_add_u64 v[142:143], v[142:143], 0, s[80:81]
	s_mov_b32 m0, s24
	ds_read_b128 v[180:183], v146 offset:49152
	ds_read_b128 v[184:187], v146 offset:50176
	ds_read_b128 v[188:191], v146 offset:51200
	ds_read_b128 v[204:207], v146 offset:52224
	ds_read_b128 v[208:211], v146 offset:53248
	ds_read_b128 v[212:215], v146 offset:54272
	ds_read_b128 v[216:219], v146 offset:55296
	ds_read_b128 v[220:223], v146 offset:56320
	global_load_lds_dwordx4 v[142:143], off
	v_lshl_add_u64 v[142:143], v[196:197], 0, s[80:81]
	s_add_i32 m0, s24, 0x2000
	s_add_i32 s24, s60, s34
	global_load_lds_dwordx4 v[142:143], off
	v_lshl_add_u64 v[142:143], v[198:199], 0, s[80:81]
	s_mov_b32 m0, s24
	s_nop 0
	global_load_lds_dwordx4 v[142:143], off
	v_lshl_add_u64 v[142:143], v[200:201], 0, s[80:81]
	s_add_i32 m0, s24, 0x2000
	s_nop 0
	global_load_lds_dwordx4 v[142:143], off
	v_lshl_add_u64 v[142:143], v[228:229], 0, s[80:81]
	s_mov_b32 m0, s44
	s_nop 0
	global_load_lds_dwordx4 v[142:143], off
	v_lshl_add_u64 v[142:143], v[230:231], 0, s[80:81]
	s_mov_b32 m0, s45
	s_nop 0
	global_load_lds_dwordx4 v[142:143], off
	s_waitcnt vmcnt(8)
	s_waitcnt lgkmcnt(0)
	s_barrier
	s_setprio 1
	s_waitcnt lgkmcnt(0)
	s_nop 0
	v_mfma_f32_16x16x32_bf16 v[64:67], v[148:151], v[180:183], v[64:67]
	v_mfma_f32_16x16x32_bf16 v[60:63], v[156:159], v[180:183], v[60:63]
	v_mfma_f32_16x16x32_bf16 v[48:51], v[148:151], v[188:191], v[48:51]
	v_mfma_f32_16x16x32_bf16 v[44:47], v[156:159], v[188:191], v[44:47]
	v_mfma_f32_16x16x32_bf16 v[32:35], v[148:151], v[208:211], v[32:35]
	v_mfma_f32_16x16x32_bf16 v[28:31], v[156:159], v[208:211], v[28:31]
	v_mfma_f32_16x16x32_bf16 v[16:19], v[148:151], v[216:219], v[16:19]
	v_mfma_f32_16x16x32_bf16 v[12:15], v[156:159], v[216:219], v[12:15]
	v_mfma_f32_16x16x32_bf16 v[64:67], v[152:155], v[184:187], v[64:67]
	v_mfma_f32_16x16x32_bf16 v[60:63], v[160:163], v[184:187], v[60:63]
	v_mfma_f32_16x16x32_bf16 v[48:51], v[152:155], v[204:207], v[48:51]
	v_mfma_f32_16x16x32_bf16 v[44:47], v[160:163], v[204:207], v[44:47]
	v_mfma_f32_16x16x32_bf16 v[32:35], v[152:155], v[212:215], v[32:35]
	v_mfma_f32_16x16x32_bf16 v[28:31], v[160:163], v[212:215], v[28:31]
	v_mfma_f32_16x16x32_bf16 v[16:19], v[152:155], v[220:223], v[16:19]
	v_mfma_f32_16x16x32_bf16 v[12:15], v[160:163], v[220:223], v[12:15]
	s_setprio 0
	s_setprio 1
	v_mfma_f32_16x16x32_bf16 v[56:59], v[164:167], v[180:183], v[56:59]
	v_mfma_f32_16x16x32_bf16 v[52:55], v[172:175], v[180:183], v[52:55]
	v_mfma_f32_16x16x32_bf16 v[40:43], v[164:167], v[188:191], v[40:43]
	v_mfma_f32_16x16x32_bf16 v[36:39], v[172:175], v[188:191], v[36:39]
	v_mfma_f32_16x16x32_bf16 v[24:27], v[164:167], v[208:211], v[24:27]
	v_mfma_f32_16x16x32_bf16 v[20:23], v[172:175], v[208:211], v[20:23]
	v_mfma_f32_16x16x32_bf16 v[8:11], v[164:167], v[216:219], v[8:11]
	v_mfma_f32_16x16x32_bf16 v[4:7], v[172:175], v[216:219], v[4:7]
	v_mfma_f32_16x16x32_bf16 v[56:59], v[168:171], v[184:187], v[56:59]
	v_mfma_f32_16x16x32_bf16 v[52:55], v[176:179], v[184:187], v[52:55]
	v_mfma_f32_16x16x32_bf16 v[40:43], v[168:171], v[204:207], v[40:43]
	v_mfma_f32_16x16x32_bf16 v[36:39], v[176:179], v[204:207], v[36:39]
	v_mfma_f32_16x16x32_bf16 v[24:27], v[168:171], v[212:215], v[24:27]
	v_mfma_f32_16x16x32_bf16 v[20:23], v[176:179], v[212:215], v[20:23]
	v_mfma_f32_16x16x32_bf16 v[8:11], v[168:171], v[220:223], v[8:11]
	v_mfma_f32_16x16x32_bf16 v[4:7], v[176:179], v[220:223], v[4:7]
	s_setprio 0
	s_barrier
	s_add_i32 s24, s58, 2
	s_add_u32 s54, s54, 0x100
	s_addc_u32 s55, s55, 0
	s_add_u32 s22, s22, 0x100
	s_addc_u32 s23, s23, 0
	s_cmp_ge_i32 s58, s46
	s_mov_b32 s58, s24
	s_cbranch_scc0 .LBB0_924

; #define PG8_STAGE(bufoff, gbase, voff) do { _Pragma("unroll") for (int _i = 0; _i < 2; ++_i) \
;         __builtin_amdgcn_global_load_lds((const unsigned*)((const char*)(gbase) + (voff)[_i]), (PG8_LAS unsigned*)(lds + (bufoff) + ldsw + _i * 8192), 16, 0, 0); } while (0)
; #define PG8_LDA(dst, b, h) do { _Pragma("unroll") for (int m = 0; m < 4; ++m) _Pragma("unroll") for (int k = 0; k < 2; ++k) dst[m][k] = *(const PG8_LAS bf16x8*)(lds + PG8_SA(b, h) + aoff + m * 2048 + k * 1024); } while (0)
; #define PG8_LDB(dst, b, h) do { _Pragma("unroll") for (int n = 0; n < 2; ++n) _Pragma("unroll") for (int k = 0; k < 2; ++k) dst[n][k] = *(const PG8_LAS bf16x8*)(lds + PG8_SB(b, h) + boff + n * 2048 + k * 1024); } while (0)
; #define PG8_MMA(ai, bj, At, Bt) do { __builtin_amdgcn_s_setprio(1); _Pragma("unroll") for (int m = 0; m < 4; ++m) _Pragma("unroll") for (int n = 0; n < 2; ++n) _Pragma("unroll") for (int k = 0; k < 2; ++k) \
;         acc[ai][bj][m][n] = __builtin_amdgcn_mfma_f32_16x16x32_bf16(Bt[n][k], At[m][k], acc[ai][bj][m][n], 0, 0, 0); __builtin_amdgcn_s_setprio(0); } while (0)
; #define PG8_WAIT_V(n) asm volatile("s_waitcnt vmcnt(" #n ")" ::: "memory")
; template <class Epi, class Sched, bool ALIGN_EPI = false, bool SP2 = false>
; __device__ __forceinline__ void gemm_phase(PG8_LAS unsigned char* lds, const Gemm g, const Sched& S, const Epi& E, int tid_in) {
;     ...
;         for (int t = 0; t < nt; t += 2) {
;             const bool last = (t == nt - 2);
;             if constexpr (mid_hook<Epi>::value) { if (t == Epi::H1 || t == Epi::H2) E.mid(acc, cur, wr, wc, fr, fq, t == Epi::H2); }
;             const char* a1 = cA + (size_t)(t + 1) * kstep + (t >= jt ? jb : 0);
;             const char* a2 = last ? nA : cA + (size_t)(t + 2) * kstep + (t + 2 >= jt ? jb : 0); const char* b2 = last ? nB : cB + (size_t)(t + 2) * kstep;
;             const char* a3 = a2 + kstep; const char* b3 = b2 + kstep;
;             if (last && has_next) S.a_ready(nxt);
;             if constexpr (SP2) {
;             PG8_LDB(B0, 0, 0); PG8_LDB(B1, 0, 1); PG8_SCHED; PG8_LDA(At, 0, 0); PG8_STAGE(PG8_SA(1, 1), a1 + hsA, voffA);
;             PG8_WAIT_V(8); PG8_WAIT_L(0); PG8_BAR; PG8_MMA(0, 0, At, B0); PG8_MMA(0, 1, At, B1); PG8_BAR; PG8_SCHED;
;             PG8_LDA(At, 0, 1); PG8_STAGE(PG8_SB(0, 0), b2, voffB); PG8_STAGE(PG8_SB(0, 1), b2 + hsB, voffB); PG8_STAGE(PG8_SA(0, 0), a2, voffA);
.LBB0_994:
	s_cmp_ge_i32 s62, s37
	s_cselect_b32 s64, s38, 0
	s_cselect_b32 s65, s52, 0
	s_add_i32 s30, s62, 2
	s_cmp_ge_i32 s30, s37
	s_cselect_b32 s29, s38, 0
	s_cselect_b32 s28, s52, 0
	s_add_u32 s29, s26, s29
	s_addc_u32 s28, s27, s28
	s_add_u32 s31, s29, 0x80
	s_addc_u32 s28, s28, 0
	s_add_i32 s66, 0, 0x10000
	s_cmp_eq_u32 s53, s62
	s_cselect_b32 s29, s5, s28
	s_cselect_b32 s28, s4, s31
	v_add_u32_e32 v3, s66, v217
	s_cselect_b32 s63, s25, s61
	s_cselect_b32 s62, s24, s60
	s_add_i32 s31, 0, 0x14000
	ds_read_b128 v[134:137], v3
	ds_read_b128 v[138:141], v3 offset:1024
	ds_read_b128 v[142:145], v3 offset:2048
	ds_read_b128 v[146:149], v3 offset:3072
	v_add_u32_e32 v3, s31, v217
	ds_read_b128 v[150:153], v3
	ds_read_b128 v[154:157], v3 offset:1024
	ds_read_b128 v[158:161], v3 offset:2048
	ds_read_b128 v[162:165], v3 offset:3072
	v_lshl_add_u64 v[4:5], s[26:27], 0, v[182:183]
	v_lshl_add_u64 v[4:5], v[4:5], 0, s[64:65]
	s_add_i32 m0, s33, 0xc000
	ds_read_b128 v[166:169], v219
	ds_read_b128 v[170:173], v219 offset:1024
	ds_read_b128 v[220:223], v219 offset:2048
	ds_read_b128 v[238:241], v219 offset:3072
	ds_read_b128 v[242:245], v219 offset:4096
	ds_read_b128 v[246:249], v219 offset:5120
	ds_read_b128 v[250:253], v219 offset:6144
	ds_read_b128 v[230:233], v219 offset:7168
	global_load_lds_dwordx4 v[4:5], off
	v_lshl_add_u64 v[4:5], s[26:27], 0, v[180:181]
	v_lshl_add_u64 v[4:5], v[4:5], 0, s[64:65]
	s_add_i32 m0, s33, 0xe000
	s_nop 0
	global_load_lds_dwordx4 v[4:5], off
	s_waitcnt vmcnt(8)
	s_waitcnt lgkmcnt(0)
	s_barrier
	s_setprio 1
	s_waitcnt lgkmcnt(0)
	s_nop 0
	v_mfma_f32_16x16x32_bf16 v[126:129], v[134:137], v[166:169], v[126:129]
	v_mfma_f32_16x16x32_bf16 v[130:133], v[142:145], v[166:169], v[130:133]
	v_mfma_f32_16x16x32_bf16 v[114:117], v[134:137], v[220:223], v[114:117]
	v_mfma_f32_16x16x32_bf16 v[110:113], v[142:145], v[220:223], v[110:113]
	v_mfma_f32_16x16x32_bf16 v[98:101], v[134:137], v[242:245], v[98:101]
	v_mfma_f32_16x16x32_bf16 v[94:97], v[142:145], v[242:245], v[94:97]
	v_mfma_f32_16x16x32_bf16 v[82:85], v[134:137], v[250:253], v[82:85]
	v_mfma_f32_16x16x32_bf16 v[78:81], v[142:145], v[250:253], v[78:81]
	v_mfma_f32_16x16x32_bf16 v[126:129], v[138:141], v[170:173], v[126:129]
	v_mfma_f32_16x16x32_bf16 v[130:133], v[146:149], v[170:173], v[130:133]
	v_mfma_f32_16x16x32_bf16 v[114:117], v[138:141], v[238:241], v[114:117]
	v_mfma_f32_16x16x32_bf16 v[110:113], v[146:149], v[238:241], v[110:113]
	v_mfma_f32_16x16x32_bf16 v[98:101], v[138:141], v[246:249], v[98:101]
	v_mfma_f32_16x16x32_bf16 v[94:97], v[146:149], v[246:249], v[94:97]
	v_mfma_f32_16x16x32_bf16 v[82:85], v[138:141], v[230:233], v[82:85]
	v_mfma_f32_16x16x32_bf16 v[78:81], v[146:149], v[230:233], v[78:81]
	s_setprio 0
	s_setprio 1
	v_mfma_f32_16x16x32_bf16 v[122:125], v[150:153], v[166:169], v[122:125]
	v_mfma_f32_16x16x32_bf16 v[118:121], v[158:161], v[166:169], v[118:121]
	v_mfma_f32_16x16x32_bf16 v[106:109], v[150:153], v[220:223], v[106:109]
	v_mfma_f32_16x16x32_bf16 v[102:105], v[158:161], v[220:223], v[102:105]
	v_mfma_f32_16x16x32_bf16 v[90:93], v[150:153], v[242:245], v[90:93]
	v_mfma_f32_16x16x32_bf16 v[86:89], v[158:161], v[242:245], v[86:89]
	v_mfma_f32_16x16x32_bf16 v[74:77], v[150:153], v[250:253], v[74:77]
	v_mfma_f32_16x16x32_bf16 v[70:73], v[158:161], v[250:253], v[70:73]
	v_mfma_f32_16x16x32_bf16 v[122:125], v[154:157], v[170:173], v[122:125]
	v_mfma_f32_16x16x32_bf16 v[118:121], v[162:165], v[170:173], v[118:121]
	v_mfma_f32_16x16x32_bf16 v[106:109], v[154:157], v[238:241], v[106:109]
	v_mfma_f32_16x16x32_bf16 v[102:105], v[162:165], v[238:241], v[102:105]
	v_mfma_f32_16x16x32_bf16 v[90:93], v[154:157], v[246:249], v[90:93]
	v_mfma_f32_16x16x32_bf16 v[86:89], v[162:165], v[246:249], v[86:89]
	v_mfma_f32_16x16x32_bf16 v[74:77], v[154:157], v[230:233], v[74:77]
	v_mfma_f32_16x16x32_bf16 v[70:73], v[162:165], v[230:233], v[70:73]
	s_setprio 0
	s_barrier
	s_add_i32 s64, s66, s43
	v_lshl_add_u64 v[196:197], s[62:63], 0, v[176:177]
	s_mov_b32 m0, s64
	ds_read_b128 v[166:169], v219 offset:16384
	ds_read_b128 v[170:173], v219 offset:17408
	ds_read_b128 v[220:223], v219 offset:18432
	ds_read_b128 v[230:233], v219 offset:19456
	ds_read_b128 v[238:241], v219 offset:20480
	ds_read_b128 v[242:245], v219 offset:21504
	ds_read_b128 v[246:249], v219 offset:22528
	ds_read_b128 v[250:253], v219 offset:23552
	global_load_lds_dwordx4 v[196:197], off
	s_add_i32 m0, s64, 0x2000
	v_lshl_add_u64 v[198:199], s[62:63], 0, v[0:1]
	s_add_u32 s62, s62, s8
	s_addc_u32 s63, s63, s9
	s_add_i32 s31, s31, s43
	global_load_lds_dwordx4 v[198:199], off
	v_lshl_add_u64 v[200:201], s[62:63], 0, v[176:177]
	s_mov_b32 m0, s31
	v_lshl_add_u64 v[228:229], s[62:63], 0, v[0:1]
	global_load_lds_dwordx4 v[200:201], off
	s_add_i32 m0, s31, 0x2000
	v_lshl_add_u64 v[202:203], s[28:29], 0, v[178:179]
	global_load_lds_dwordx4 v[228:229], off
	s_mov_b32 m0, s33
	v_lshl_add_u64 v[192:193], s[28:29], 0, v[174:175]
	global_load_lds_dwordx4 v[202:203], off
	s_mov_b32 m0, s46
	s_nop 0
	global_load_lds_dwordx4 v[192:193], off
	s_waitcnt vmcnt(8)
	s_waitcnt lgkmcnt(0)
	s_barrier
; #define PG8_STAGE(bufoff, gbase, voff) do { _Pragma("unroll") for (int _i = 0; _i < 2; ++_i) \
;         __builtin_amdgcn_global_load_lds((const unsigned*)((const char*)(gbase) + (voff)[_i]), (PG8_LAS unsigned*)(lds + (bufoff) + ldsw + _i * 8192), 16, 0, 0); } while (0)
; #define PG8_LDA(dst, b, h) do { _Pragma("unroll") for (int m = 0; m < 4; ++m) _Pragma("unroll") for (int k = 0; k < 2; ++k) dst[m][k] = *(const PG8_LAS bf16x8*)(lds + PG8_SA(b, h) + aoff + m * 2048 + k * 1024); } while (0)
; #define PG8_LDB(dst, b, h) do { _Pragma("unroll") for (int n = 0; n < 2; ++n) _Pragma("unroll") for (int k = 0; k < 2; ++k) dst[n][k] = *(const PG8_LAS bf16x8*)(lds + PG8_SB(b, h) + boff + n * 2048 + k * 1024); } while (0)
; #define PG8_MMA(ai, bj, At, Bt) do { __builtin_amdgcn_s_setprio(1); _Pragma("unroll") for (int m = 0; m < 4; ++m) _Pragma("unroll") for (int n = 0; n < 2; ++n) _Pragma("unroll") for (int k = 0; k < 2; ++k) \
;         acc[ai][bj][m][n] = __builtin_amdgcn_mfma_f32_16x16x32_bf16(Bt[n][k], At[m][k], acc[ai][bj][m][n], 0, 0, 0); __builtin_amdgcn_s_setprio(0); } while (0)
; #define PG8_WAIT_V(n) asm volatile("s_waitcnt vmcnt(" #n ")" ::: "memory")
; #define PG8_WAIT_L(n) asm volatile("s_waitcnt lgkmcnt(" #n ")" ::: "memory")
; #define PG8_BAR __builtin_amdgcn_s_barrier()
; #define PG8_SCHED __builtin_amdgcn_sched_barrier(0)
; template <class Epi, class Sched, bool ALIGN_EPI = false, bool SP2 = false>
; __device__ __forceinline__ void gemm_phase(PG8_LAS unsigned char* lds, const Gemm g, const Sched& S, const Epi& E, int tid_in) {
;     ...
;             PG8_WAIT_V(8); PG8_WAIT_L(0); PG8_BAR; PG8_MMA(1, 0, At, B0); PG8_MMA(1, 1, At, B1); PG8_BAR; PG8_SCHED;
;             PG8_LDB(B0, 1, 0); PG8_LDB(B1, 1, 1); PG8_SCHED; PG8_LDA(At, 1, 0); PG8_STAGE(PG8_SA(0, 1), a2 + hsA, voffA);
;             PG8_WAIT_V(8); PG8_WAIT_L(0); PG8_BAR; PG8_MMA(0, 0, At, B0); PG8_MMA(0, 1, At, B1); PG8_BAR; PG8_SCHED;
	s_setprio 1
	s_waitcnt lgkmcnt(0)
	v_mfma_f32_16x16x32_bf16 v[66:69], v[134:137], v[166:169], v[66:69]
	v_mfma_f32_16x16x32_bf16 v[62:65], v[142:145], v[166:169], v[62:65]
	v_mfma_f32_16x16x32_bf16 v[50:53], v[134:137], v[220:223], v[50:53]
	v_mfma_f32_16x16x32_bf16 v[46:49], v[142:145], v[220:223], v[46:49]
	v_mfma_f32_16x16x32_bf16 v[34:37], v[134:137], v[238:241], v[34:37]
	v_mfma_f32_16x16x32_bf16 v[30:33], v[142:145], v[238:241], v[30:33]
	v_mfma_f32_16x16x32_bf16 v[18:21], v[134:137], v[246:249], v[18:21]
	v_mfma_f32_16x16x32_bf16 v[14:17], v[142:145], v[246:249], v[14:17]
	v_mfma_f32_16x16x32_bf16 v[66:69], v[138:141], v[170:173], v[66:69]
	v_mfma_f32_16x16x32_bf16 v[62:65], v[146:149], v[170:173], v[62:65]
	v_mfma_f32_16x16x32_bf16 v[50:53], v[138:141], v[230:233], v[50:53]
	v_mfma_f32_16x16x32_bf16 v[46:49], v[146:149], v[230:233], v[46:49]
	v_mfma_f32_16x16x32_bf16 v[34:37], v[138:141], v[242:245], v[34:37]
	v_mfma_f32_16x16x32_bf16 v[30:33], v[146:149], v[242:245], v[30:33]
	v_mfma_f32_16x16x32_bf16 v[18:21], v[138:141], v[250:253], v[18:21]
	v_mfma_f32_16x16x32_bf16 v[14:17], v[146:149], v[250:253], v[14:17]
	s_setprio 0
	s_setprio 1
	v_mfma_f32_16x16x32_bf16 v[58:61], v[150:153], v[166:169], v[58:61]
	v_mfma_f32_16x16x32_bf16 v[54:57], v[158:161], v[166:169], v[54:57]
	v_mfma_f32_16x16x32_bf16 v[42:45], v[150:153], v[220:223], v[42:45]
	v_mfma_f32_16x16x32_bf16 v[38:41], v[158:161], v[220:223], v[38:41]
	v_mfma_f32_16x16x32_bf16 v[26:29], v[150:153], v[238:241], v[26:29]
	v_mfma_f32_16x16x32_bf16 v[22:25], v[158:161], v[238:241], v[22:25]
	v_mfma_f32_16x16x32_bf16 v[10:13], v[150:153], v[246:249], v[10:13]
	v_mfma_f32_16x16x32_bf16 v[4:7], v[158:161], v[246:249], v[6:9]
	v_mfma_f32_16x16x32_bf16 v[58:61], v[154:157], v[170:173], v[58:61]
	v_mfma_f32_16x16x32_bf16 v[54:57], v[162:165], v[170:173], v[54:57]
	v_mfma_f32_16x16x32_bf16 v[42:45], v[154:157], v[230:233], v[42:45]
	v_mfma_f32_16x16x32_bf16 v[38:41], v[162:165], v[230:233], v[38:41]
	v_mfma_f32_16x16x32_bf16 v[26:29], v[154:157], v[242:245], v[26:29]
	v_mfma_f32_16x16x32_bf16 v[22:25], v[162:165], v[242:245], v[22:25]
	v_mfma_f32_16x16x32_bf16 v[10:13], v[154:157], v[250:253], v[10:13]
	v_mfma_f32_16x16x32_bf16 v[4:7], v[162:165], v[250:253], v[4:7]
	s_setprio 0
	s_barrier
	s_add_i32 s31, 0, 0x18000
	v_add_u32_e32 v3, s31, v217
	s_add_i32 s62, 0, 0x1c000
	ds_read_b128 v[134:137], v3
	ds_read_b128 v[138:141], v3 offset:1024
	ds_read_b128 v[142:145], v3 offset:2048
	ds_read_b128 v[146:149], v3 offset:3072
	v_add_u32_e32 v3, s62, v217
	ds_read_b128 v[150:153], v3
	ds_read_b128 v[154:157], v3 offset:1024
	ds_read_b128 v[158:161], v3 offset:2048
	ds_read_b128 v[162:165], v3 offset:3072
	s_add_u32 s28, s28, s6
	s_addc_u32 s29, s29, s7
	s_mov_b32 m0, s47
	v_lshl_add_u64 v[8:9], s[28:29], 0, v[178:179]
	ds_read_b128 v[166:169], v219 offset:32768
	ds_read_b128 v[170:173], v219 offset:33792
	ds_read_b128 v[220:223], v219 offset:34816
	ds_read_b128 v[230:233], v219 offset:35840
	ds_read_b128 v[238:241], v219 offset:36864
	ds_read_b128 v[242:245], v219 offset:37888
	ds_read_b128 v[246:249], v219 offset:38912
	ds_read_b128 v[250:253], v219 offset:39936
	global_load_lds_dwordx4 v[8:9], off
	v_lshl_add_u64 v[8:9], s[28:29], 0, v[174:175]
	s_mov_b32 m0, s48
	s_nop 0
	global_load_lds_dwordx4 v[8:9], off
	s_waitcnt vmcnt(8)
	s_waitcnt lgkmcnt(0)
	s_barrier
	s_setprio 1
	s_waitcnt lgkmcnt(0)
	v_mfma_f32_16x16x32_bf16 v[126:129], v[134:137], v[166:169], v[126:129]
	v_mfma_f32_16x16x32_bf16 v[130:133], v[142:145], v[166:169], v[130:133]
	v_mfma_f32_16x16x32_bf16 v[114:117], v[134:137], v[220:223], v[114:117]
	v_mfma_f32_16x16x32_bf16 v[110:113], v[142:145], v[220:223], v[110:113]
	v_mfma_f32_16x16x32_bf16 v[98:101], v[134:137], v[238:241], v[98:101]
	v_mfma_f32_16x16x32_bf16 v[94:97], v[142:145], v[238:241], v[94:97]
	v_mfma_f32_16x16x32_bf16 v[82:85], v[134:137], v[246:249], v[82:85]
	v_mfma_f32_16x16x32_bf16 v[78:81], v[142:145], v[246:249], v[78:81]
	v_mfma_f32_16x16x32_bf16 v[126:129], v[138:141], v[170:173], v[126:129]
	v_mfma_f32_16x16x32_bf16 v[130:133], v[146:149], v[170:173], v[130:133]
	v_mfma_f32_16x16x32_bf16 v[114:117], v[138:141], v[230:233], v[114:117]
	v_mfma_f32_16x16x32_bf16 v[110:113], v[146:149], v[230:233], v[110:113]
	v_mfma_f32_16x16x32_bf16 v[98:101], v[138:141], v[242:245], v[98:101]
	v_mfma_f32_16x16x32_bf16 v[94:97], v[146:149], v[242:245], v[94:97]
	v_mfma_f32_16x16x32_bf16 v[82:85], v[138:141], v[250:253], v[82:85]
	v_mfma_f32_16x16x32_bf16 v[78:81], v[146:149], v[250:253], v[78:81]
	s_setprio 0
	s_setprio 1
	v_mfma_f32_16x16x32_bf16 v[122:125], v[150:153], v[166:169], v[122:125]
	v_mfma_f32_16x16x32_bf16 v[118:121], v[158:161], v[166:169], v[118:121]
	v_mfma_f32_16x16x32_bf16 v[106:109], v[150:153], v[220:223], v[106:109]
	v_mfma_f32_16x16x32_bf16 v[102:105], v[158:161], v[220:223], v[102:105]
	v_mfma_f32_16x16x32_bf16 v[90:93], v[150:153], v[238:241], v[90:93]
	v_mfma_f32_16x16x32_bf16 v[86:89], v[158:161], v[238:241], v[86:89]
	v_mfma_f32_16x16x32_bf16 v[74:77], v[150:153], v[246:249], v[74:77]
	v_mfma_f32_16x16x32_bf16 v[70:73], v[158:161], v[246:249], v[70:73]
	v_mfma_f32_16x16x32_bf16 v[122:125], v[154:157], v[170:173], v[122:125]
	v_mfma_f32_16x16x32_bf16 v[118:121], v[162:165], v[170:173], v[118:121]
	v_mfma_f32_16x16x32_bf16 v[106:109], v[154:157], v[230:233], v[106:109]
	v_mfma_f32_16x16x32_bf16 v[102:105], v[162:165], v[230:233], v[102:105]
	v_mfma_f32_16x16x32_bf16 v[90:93], v[154:157], v[242:245], v[90:93]
	v_mfma_f32_16x16x32_bf16 v[86:89], v[162:165], v[242:245], v[86:89]
	v_mfma_f32_16x16x32_bf16 v[74:77], v[154:157], v[250:253], v[74:77]
	v_mfma_f32_16x16x32_bf16 v[70:73], v[162:165], v[250:253], v[70:73]
	s_setprio 0
	s_barrier
; #define PG8_STAGE(bufoff, gbase, voff) do { _Pragma("unroll") for (int _i = 0; _i < 2; ++_i) \
;         __builtin_amdgcn_global_load_lds((const unsigned*)((const char*)(gbase) + (voff)[_i]), (PG8_LAS unsigned*)(lds + (bufoff) + ldsw + _i * 8192), 16, 0, 0); } while (0)
; #define PG8_LDA(dst, b, h) do { _Pragma("unroll") for (int m = 0; m < 4; ++m) _Pragma("unroll") for (int k = 0; k < 2; ++k) dst[m][k] = *(const PG8_LAS bf16x8*)(lds + PG8_SA(b, h) + aoff + m * 2048 + k * 1024); } while (0)
; #define PG8_MMA(ai, bj, At, Bt) do { __builtin_amdgcn_s_setprio(1); _Pragma("unroll") for (int m = 0; m < 4; ++m) _Pragma("unroll") for (int n = 0; n < 2; ++n) _Pragma("unroll") for (int k = 0; k < 2; ++k) \
;         acc[ai][bj][m][n] = __builtin_amdgcn_mfma_f32_16x16x32_bf16(Bt[n][k], At[m][k], acc[ai][bj][m][n], 0, 0, 0); __builtin_amdgcn_s_setprio(0); } while (0)
; #define PG8_WAIT_V(n) asm volatile("s_waitcnt vmcnt(" #n ")" ::: "memory")
; #define PG8_WAIT_L(n) asm volatile("s_waitcnt lgkmcnt(" #n ")" ::: "memory")
; #define PG8_BAR __builtin_amdgcn_s_barrier()
; #define PG8_SCHED __builtin_amdgcn_sched_barrier(0)
; template <class Epi, class Sched, bool ALIGN_EPI = false, bool SP2 = false>
; __device__ __forceinline__ void gemm_phase(PG8_LAS unsigned char* lds, const Gemm g, const Sched& S, const Epi& E, int tid_in) {
;     ...
;             if constexpr (mid_hook<Epi>::value) { if (t == Epi::H1 || t == Epi::H2) E.mid(acc, cur, wr, wc, fr, fq, t == Epi::H2); }
;     ...
;             PG8_LDA(At, 1, 1); PG8_STAGE(PG8_SB(1, 0), b3, voffB); PG8_STAGE(PG8_SB(1, 1), b3 + hsB, voffB); PG8_STAGE(PG8_SA(1, 0), a3, voffA);
;             PG8_WAIT_V(8); PG8_WAIT_L(0); PG8_BAR; PG8_MMA(1, 0, At, B0); PG8_MMA(1, 1, At, B1); PG8_BAR; PG8_SCHED;
	s_add_i32 s28, s31, s43
	v_lshl_add_u64 v[8:9], v[196:197], 0, s[80:81]
	s_mov_b32 m0, s28
	ds_read_b128 v[166:169], v219 offset:49152
	ds_read_b128 v[170:173], v219 offset:50176
	ds_read_b128 v[220:223], v219 offset:51200
	ds_read_b128 v[230:233], v219 offset:52224
	ds_read_b128 v[238:241], v219 offset:53248
	ds_read_b128 v[242:245], v219 offset:54272
	ds_read_b128 v[246:249], v219 offset:55296
	ds_read_b128 v[250:253], v219 offset:56320
	global_load_lds_dwordx4 v[8:9], off
	v_lshl_add_u64 v[8:9], v[198:199], 0, s[80:81]
	s_add_i32 m0, s28, 0x2000
	s_add_i32 s28, s62, s43
	global_load_lds_dwordx4 v[8:9], off
	v_lshl_add_u64 v[8:9], v[200:201], 0, s[80:81]
	s_mov_b32 m0, s28
	s_nop 0
	global_load_lds_dwordx4 v[8:9], off
	v_lshl_add_u64 v[8:9], v[228:229], 0, s[80:81]
	s_add_i32 m0, s28, 0x2000
	s_nop 0
	global_load_lds_dwordx4 v[8:9], off
	v_lshl_add_u64 v[8:9], v[202:203], 0, s[80:81]
	s_mov_b32 m0, s49
	s_nop 0
	global_load_lds_dwordx4 v[8:9], off
	v_lshl_add_u64 v[8:9], v[192:193], 0, s[80:81]
	s_mov_b32 m0, s50
	s_nop 0
	global_load_lds_dwordx4 v[8:9], off
	s_waitcnt vmcnt(8)
	s_waitcnt lgkmcnt(0)
	s_barrier
	s_setprio 1
	s_waitcnt lgkmcnt(0)
	s_nop 0
	v_mfma_f32_16x16x32_bf16 v[66:69], v[134:137], v[166:169], v[66:69]
	v_mfma_f32_16x16x32_bf16 v[62:65], v[142:145], v[166:169], v[62:65]
	v_mfma_f32_16x16x32_bf16 v[50:53], v[134:137], v[220:223], v[50:53]
	v_mfma_f32_16x16x32_bf16 v[46:49], v[142:145], v[220:223], v[46:49]
	v_mfma_f32_16x16x32_bf16 v[34:37], v[134:137], v[238:241], v[34:37]
	v_mfma_f32_16x16x32_bf16 v[30:33], v[142:145], v[238:241], v[30:33]
	v_mfma_f32_16x16x32_bf16 v[18:21], v[134:137], v[246:249], v[18:21]
	v_mfma_f32_16x16x32_bf16 v[14:17], v[142:145], v[246:249], v[14:17]
	v_mfma_f32_16x16x32_bf16 v[66:69], v[138:141], v[170:173], v[66:69]
	v_mfma_f32_16x16x32_bf16 v[62:65], v[146:149], v[170:173], v[62:65]
	v_mfma_f32_16x16x32_bf16 v[50:53], v[138:141], v[230:233], v[50:53]
	v_mfma_f32_16x16x32_bf16 v[46:49], v[146:149], v[230:233], v[46:49]
	v_mfma_f32_16x16x32_bf16 v[34:37], v[138:141], v[242:245], v[34:37]
	v_mfma_f32_16x16x32_bf16 v[30:33], v[146:149], v[242:245], v[30:33]
	v_mfma_f32_16x16x32_bf16 v[18:21], v[138:141], v[250:253], v[18:21]
	v_mfma_f32_16x16x32_bf16 v[14:17], v[146:149], v[250:253], v[14:17]
	s_setprio 0
	s_setprio 1
	v_mfma_f32_16x16x32_bf16 v[58:61], v[150:153], v[166:169], v[58:61]
	v_mfma_f32_16x16x32_bf16 v[54:57], v[158:161], v[166:169], v[54:57]
	v_mfma_f32_16x16x32_bf16 v[42:45], v[150:153], v[220:223], v[42:45]
	v_mfma_f32_16x16x32_bf16 v[38:41], v[158:161], v[220:223], v[38:41]
	v_mfma_f32_16x16x32_bf16 v[26:29], v[150:153], v[238:241], v[26:29]
	v_mfma_f32_16x16x32_bf16 v[22:25], v[158:161], v[238:241], v[22:25]
	v_mfma_f32_16x16x32_bf16 v[8:11], v[150:153], v[246:249], v[10:13]
	v_mfma_f32_16x16x32_bf16 v[4:7], v[158:161], v[246:249], v[4:7]
	v_mfma_f32_16x16x32_bf16 v[58:61], v[154:157], v[170:173], v[58:61]
	v_mfma_f32_16x16x32_bf16 v[54:57], v[162:165], v[170:173], v[54:57]
	v_mfma_f32_16x16x32_bf16 v[42:45], v[154:157], v[230:233], v[42:45]
	v_mfma_f32_16x16x32_bf16 v[38:41], v[162:165], v[230:233], v[38:41]
	v_mfma_f32_16x16x32_bf16 v[26:29], v[154:157], v[242:245], v[26:29]
	v_mfma_f32_16x16x32_bf16 v[22:25], v[162:165], v[242:245], v[22:25]
	v_mfma_f32_16x16x32_bf16 v[10:13], v[154:157], v[250:253], v[8:11]
	v_mfma_f32_16x16x32_bf16 v[6:9], v[162:165], v[250:253], v[4:7]
	s_setprio 0
	s_barrier
	s_add_u32 s60, s60, 0x100
	s_addc_u32 s61, s61, 0
	s_add_u32 s26, s26, 0x100
	s_addc_u32 s27, s27, 0
	s_cmp_ge_i32 s30, s51
	s_cbranch_scc1 .LBB0_996
	s_mov_b32 s62, s30
	s_cmp_lt_i32 s62, 32
	s_cbranch_scc1 .LBB0_990
	s_branch .LBB0_989

; #define PG8_STAGE(bufoff, gbase, voff) do { _Pragma("unroll") for (int _i = 0; _i < 2; ++_i) \
;         __builtin_amdgcn_global_load_lds((const unsigned*)((const char*)(gbase) + (voff)[_i]), (PG8_LAS unsigned*)(lds + (bufoff) + ldsw + _i * 8192), 16, 0, 0); } while (0)
; #define PG8_LDA(dst, b, h) do { _Pragma("unroll") for (int m = 0; m < 4; ++m) _Pragma("unroll") for (int k = 0; k < 2; ++k) dst[m][k] = *(const PG8_LAS bf16x8*)(lds + PG8_SA(b, h) + aoff + m * 2048 + k * 1024); } while (0)
; #define PG8_LDB(dst, b, h) do { _Pragma("unroll") for (int n = 0; n < 2; ++n) _Pragma("unroll") for (int k = 0; k < 2; ++k) dst[n][k] = *(const PG8_LAS bf16x8*)(lds + PG8_SB(b, h) + boff + n * 2048 + k * 1024); } while (0)
; #define PG8_MMA(ai, bj, At, Bt) do { __builtin_amdgcn_s_setprio(1); _Pragma("unroll") for (int m = 0; m < 4; ++m) _Pragma("unroll") for (int n = 0; n < 2; ++n) _Pragma("unroll") for (int k = 0; k < 2; ++k) \
;         acc[ai][bj][m][n] = __builtin_amdgcn_mfma_f32_16x16x32_bf16(Bt[n][k], At[m][k], acc[ai][bj][m][n], 0, 0, 0); __builtin_amdgcn_s_setprio(0); } while (0)
; #define PG8_WAIT_V(n) asm volatile("s_waitcnt vmcnt(" #n ")" ::: "memory")
; template <class Epi, class Sched, bool ALIGN_EPI = false, bool SP2 = false>
; __device__ __forceinline__ void gemm_phase(PG8_LAS unsigned char* lds, const Gemm g, const Sched& S, const Epi& E, int tid_in) {
;     ...
;         for (int t = 0; t < nt; t += 2) {
;             const bool last = (t == nt - 2);
;             if constexpr (mid_hook<Epi>::value) { if (t == Epi::H1 || t == Epi::H2) E.mid(acc, cur, wr, wc, fr, fq, t == Epi::H2); }
;             const char* a1 = cA + (size_t)(t + 1) * kstep + (t >= jt ? jb : 0);
;             const char* a2 = last ? nA : cA + (size_t)(t + 2) * kstep + (t + 2 >= jt ? jb : 0); const char* b2 = last ? nB : cB + (size_t)(t + 2) * kstep;
;             const char* a3 = a2 + kstep; const char* b3 = b2 + kstep;
;             if (last && has_next) S.a_ready(nxt);
;             if constexpr (SP2) {
;             PG8_LDB(B0, 0, 0); PG8_LDB(B1, 0, 1); PG8_SCHED; PG8_LDA(At, 0, 0); PG8_STAGE(PG8_SA(1, 1), a1 + hsA, voffA);
;             PG8_WAIT_V(8); PG8_WAIT_L(0); PG8_BAR; PG8_MMA(0, 0, At, B0); PG8_MMA(0, 1, At, B1); PG8_BAR; PG8_SCHED;
;             PG8_LDA(At, 0, 1); PG8_STAGE(PG8_SB(0, 0), b2, voffB); PG8_STAGE(PG8_SB(0, 1), b2 + hsB, voffB); PG8_STAGE(PG8_SA(0, 0), a2, voffA);
.LBB0_1070:
	s_add_i32 s38, s40, -2
	s_cmp_ge_i32 s38, s46
	s_cselect_b32 s78, s47, 0
	s_cselect_b32 s79, s62, 0
	s_cmp_ge_i32 s40, s46
	s_cselect_b32 s39, s47, 0
	s_cselect_b32 s38, s62, 0
	s_add_u32 s39, s4, s39
	s_addc_u32 s38, s5, s38
	s_add_u32 s41, s39, 0x80
	s_addc_u32 s38, s38, 0
	s_add_i32 s77, 0, 0x10000
	s_cmp_eq_u32 s61, s40
	s_cselect_b32 s39, s35, s38
	s_cselect_b32 s38, s34, s41
	s_cselect_b32 s83, s37, s76
	s_cselect_b32 s82, s36, s75
	s_add_i32 s41, 0, 0x14000
	v_add_u32_e32 v144, s77, v217
	v_add_u32_e32 v170, s41, v217
	ds_read_b128 v[116:119], v144
	ds_read_b128 v[120:123], v144 offset:1024
	ds_read_b128 v[140:143], v144 offset:2048
	ds_read_b128 v[144:147], v144 offset:3072
	ds_read_b128 v[148:151], v170
	ds_read_b128 v[152:155], v170 offset:1024
	ds_read_b128 v[156:159], v170 offset:2048
	ds_read_b128 v[170:173], v170 offset:3072
	v_lshl_add_u64 v[190:191], s[4:5], 0, v[168:169]
	v_lshl_add_u64 v[190:191], v[190:191], 0, s[78:79]
	s_add_i32 m0, s51, 0xc000
	ds_read_b128 v[174:177], v219
	ds_read_b128 v[178:181], v219 offset:1024
	ds_read_b128 v[182:185], v219 offset:2048
	ds_read_b128 v[186:189], v219 offset:3072
	ds_read_b128 v[204:207], v219 offset:4096
	ds_read_b128 v[208:211], v219 offset:5120
	ds_read_b128 v[212:215], v219 offset:6144
	ds_read_b128 v[220:223], v219 offset:7168
	global_load_lds_dwordx4 v[190:191], off
	v_lshl_add_u64 v[190:191], s[4:5], 0, v[166:167]
	v_lshl_add_u64 v[190:191], v[190:191], 0, s[78:79]
	s_add_i32 m0, s51, 0xe000
	s_nop 0
	global_load_lds_dwordx4 v[190:191], off
	s_waitcnt vmcnt(8)
	s_waitcnt lgkmcnt(0)
	s_barrier
	s_setprio 1
	s_waitcnt lgkmcnt(0)
	v_mfma_f32_16x16x32_bf16 v[136:139], v[116:119], v[174:177], v[136:139]
	v_mfma_f32_16x16x32_bf16 v[132:135], v[140:143], v[174:177], v[132:135]
	v_mfma_f32_16x16x32_bf16 v[128:131], v[116:119], v[182:185], v[128:131]
	v_mfma_f32_16x16x32_bf16 v[124:127], v[140:143], v[182:185], v[124:127]
	v_mfma_f32_16x16x32_bf16 v[112:115], v[116:119], v[204:207], v[112:115]
	v_mfma_f32_16x16x32_bf16 v[108:111], v[140:143], v[204:207], v[108:111]
	v_mfma_f32_16x16x32_bf16 v[104:107], v[116:119], v[212:215], v[104:107]
	v_mfma_f32_16x16x32_bf16 v[100:103], v[140:143], v[212:215], v[100:103]
	v_mfma_f32_16x16x32_bf16 v[136:139], v[120:123], v[178:181], v[136:139]
	v_mfma_f32_16x16x32_bf16 v[132:135], v[144:147], v[178:181], v[132:135]
	v_mfma_f32_16x16x32_bf16 v[128:131], v[120:123], v[186:189], v[128:131]
	v_mfma_f32_16x16x32_bf16 v[124:127], v[144:147], v[186:189], v[124:127]
	v_mfma_f32_16x16x32_bf16 v[112:115], v[120:123], v[208:211], v[112:115]
	v_mfma_f32_16x16x32_bf16 v[108:111], v[144:147], v[208:211], v[108:111]
	v_mfma_f32_16x16x32_bf16 v[104:107], v[120:123], v[220:223], v[104:107]
	v_mfma_f32_16x16x32_bf16 v[100:103], v[144:147], v[220:223], v[100:103]
	s_setprio 0
	s_setprio 1
	v_mfma_f32_16x16x32_bf16 v[64:67], v[148:151], v[174:177], v[64:67]
	v_mfma_f32_16x16x32_bf16 v[56:59], v[156:159], v[174:177], v[56:59]
	v_mfma_f32_16x16x32_bf16 v[60:63], v[148:151], v[182:185], v[60:63]
	v_mfma_f32_16x16x32_bf16 v[52:55], v[156:159], v[182:185], v[52:55]
	v_mfma_f32_16x16x32_bf16 v[48:51], v[148:151], v[204:207], v[48:51]
	v_mfma_f32_16x16x32_bf16 v[40:43], v[156:159], v[204:207], v[40:43]
	v_mfma_f32_16x16x32_bf16 v[44:47], v[148:151], v[212:215], v[44:47]
	v_mfma_f32_16x16x32_bf16 v[36:39], v[156:159], v[212:215], v[36:39]
	v_mfma_f32_16x16x32_bf16 v[64:67], v[152:155], v[178:181], v[64:67]
	v_mfma_f32_16x16x32_bf16 v[56:59], v[170:173], v[178:181], v[56:59]
	v_mfma_f32_16x16x32_bf16 v[60:63], v[152:155], v[186:189], v[60:63]
	v_mfma_f32_16x16x32_bf16 v[52:55], v[170:173], v[186:189], v[52:55]
	v_mfma_f32_16x16x32_bf16 v[48:51], v[152:155], v[208:211], v[48:51]
	v_mfma_f32_16x16x32_bf16 v[40:43], v[170:173], v[208:211], v[40:43]
	v_mfma_f32_16x16x32_bf16 v[44:47], v[152:155], v[220:223], v[44:47]
	v_mfma_f32_16x16x32_bf16 v[36:39], v[170:173], v[220:223], v[36:39]
	s_setprio 0
	s_barrier
	s_add_i32 s77, s77, s50
	v_lshl_add_u64 v[190:191], s[82:83], 0, v[160:161]
	s_mov_b32 m0, s77
	ds_read_b128 v[174:177], v219 offset:16384
	ds_read_b128 v[178:181], v219 offset:17408
	ds_read_b128 v[182:185], v219 offset:18432
	ds_read_b128 v[186:189], v219 offset:19456
	ds_read_b128 v[204:207], v219 offset:20480
	ds_read_b128 v[208:211], v219 offset:21504
	ds_read_b128 v[212:215], v219 offset:22528
	ds_read_b128 v[220:223], v219 offset:23552
	global_load_lds_dwordx4 v[190:191], off
	s_add_i32 m0, s77, 0x2000
	s_add_u32 s78, s82, s12
	v_lshl_add_u64 v[192:193], s[82:83], 0, v[164:165]
	s_addc_u32 s79, s83, s13
	s_add_i32 s41, s41, s50
	global_load_lds_dwordx4 v[192:193], off
	v_lshl_add_u64 v[196:197], s[78:79], 0, v[160:161]
	s_mov_b32 m0, s41
	v_lshl_add_u64 v[198:199], s[78:79], 0, v[164:165]
	global_load_lds_dwordx4 v[196:197], off
	s_add_i32 m0, s41, 0x2000
	v_lshl_add_u64 v[200:201], s[38:39], 0, v[0:1]
	global_load_lds_dwordx4 v[198:199], off
	s_mov_b32 m0, s51
	v_lshl_add_u64 v[202:203], s[38:39], 0, v[162:163]
	global_load_lds_dwordx4 v[200:201], off
	s_mov_b32 m0, s52
	s_nop 0
	global_load_lds_dwordx4 v[202:203], off
	s_waitcnt vmcnt(8)
	s_waitcnt lgkmcnt(0)
	s_barrier
; #define PG8_STAGE(bufoff, gbase, voff) do { _Pragma("unroll") for (int _i = 0; _i < 2; ++_i) \
;         __builtin_amdgcn_global_load_lds((const unsigned*)((const char*)(gbase) + (voff)[_i]), (PG8_LAS unsigned*)(lds + (bufoff) + ldsw + _i * 8192), 16, 0, 0); } while (0)
; #define PG8_LDA(dst, b, h) do { _Pragma("unroll") for (int m = 0; m < 4; ++m) _Pragma("unroll") for (int k = 0; k < 2; ++k) dst[m][k] = *(const PG8_LAS bf16x8*)(lds + PG8_SA(b, h) + aoff + m * 2048 + k * 1024); } while (0)
; #define PG8_LDB(dst, b, h) do { _Pragma("unroll") for (int n = 0; n < 2; ++n) _Pragma("unroll") for (int k = 0; k < 2; ++k) dst[n][k] = *(const PG8_LAS bf16x8*)(lds + PG8_SB(b, h) + boff + n * 2048 + k * 1024); } while (0)
; #define PG8_MMA(ai, bj, At, Bt) do { __builtin_amdgcn_s_setprio(1); _Pragma("unroll") for (int m = 0; m < 4; ++m) _Pragma("unroll") for (int n = 0; n < 2; ++n) _Pragma("unroll") for (int k = 0; k < 2; ++k) \
;         acc[ai][bj][m][n] = __builtin_amdgcn_mfma_f32_16x16x32_bf16(Bt[n][k], At[m][k], acc[ai][bj][m][n], 0, 0, 0); __builtin_amdgcn_s_setprio(0); } while (0)
; #define PG8_WAIT_V(n) asm volatile("s_waitcnt vmcnt(" #n ")" ::: "memory")
; #define PG8_WAIT_L(n) asm volatile("s_waitcnt lgkmcnt(" #n ")" ::: "memory")
; #define PG8_BAR __builtin_amdgcn_s_barrier()
; #define PG8_SCHED __builtin_amdgcn_sched_barrier(0)
; template <class Epi, class Sched, bool ALIGN_EPI = false, bool SP2 = false>
; __device__ __forceinline__ void gemm_phase(PG8_LAS unsigned char* lds, const Gemm g, const Sched& S, const Epi& E, int tid_in) {
;     ...
;             PG8_WAIT_V(8); PG8_WAIT_L(0); PG8_BAR; PG8_MMA(1, 0, At, B0); PG8_MMA(1, 1, At, B1); PG8_BAR; PG8_SCHED;
;             PG8_LDB(B0, 1, 0); PG8_LDB(B1, 1, 1); PG8_SCHED; PG8_LDA(At, 1, 0); PG8_STAGE(PG8_SA(0, 1), a2 + hsA, voffA);
;             PG8_WAIT_V(8); PG8_WAIT_L(0); PG8_BAR; PG8_MMA(0, 0, At, B0); PG8_MMA(0, 1, At, B1); PG8_BAR; PG8_SCHED;
	s_setprio 1
	s_waitcnt lgkmcnt(0)
	v_mfma_f32_16x16x32_bf16 v[96:99], v[116:119], v[174:177], v[96:99]
	v_mfma_f32_16x16x32_bf16 v[92:95], v[140:143], v[174:177], v[92:95]
	v_mfma_f32_16x16x32_bf16 v[88:91], v[116:119], v[182:185], v[88:91]
	v_mfma_f32_16x16x32_bf16 v[84:87], v[140:143], v[182:185], v[84:87]
	v_mfma_f32_16x16x32_bf16 v[80:83], v[116:119], v[204:207], v[80:83]
	v_mfma_f32_16x16x32_bf16 v[76:79], v[140:143], v[204:207], v[76:79]
	v_mfma_f32_16x16x32_bf16 v[72:75], v[116:119], v[212:215], v[72:75]
	v_mfma_f32_16x16x32_bf16 v[68:71], v[140:143], v[212:215], v[68:71]
	v_mfma_f32_16x16x32_bf16 v[96:99], v[120:123], v[178:181], v[96:99]
	v_mfma_f32_16x16x32_bf16 v[92:95], v[144:147], v[178:181], v[92:95]
	v_mfma_f32_16x16x32_bf16 v[88:91], v[120:123], v[186:189], v[88:91]
	v_mfma_f32_16x16x32_bf16 v[84:87], v[144:147], v[186:189], v[84:87]
	v_mfma_f32_16x16x32_bf16 v[80:83], v[120:123], v[208:211], v[80:83]
	v_mfma_f32_16x16x32_bf16 v[76:79], v[144:147], v[208:211], v[76:79]
	v_mfma_f32_16x16x32_bf16 v[72:75], v[120:123], v[220:223], v[72:75]
	v_mfma_f32_16x16x32_bf16 v[68:71], v[144:147], v[220:223], v[68:71]
	s_setprio 0
	s_setprio 1
	v_mfma_f32_16x16x32_bf16 v[32:35], v[148:151], v[174:177], v[32:35]
	v_mfma_f32_16x16x32_bf16 v[28:31], v[156:159], v[174:177], v[28:31]
	v_mfma_f32_16x16x32_bf16 v[24:27], v[148:151], v[182:185], v[24:27]
	v_mfma_f32_16x16x32_bf16 v[12:15], v[156:159], v[182:185], v[12:15]
	v_mfma_f32_16x16x32_bf16 v[20:23], v[148:151], v[204:207], v[20:23]
	v_mfma_f32_16x16x32_bf16 v[8:11], v[156:159], v[204:207], v[8:11]
	v_mfma_f32_16x16x32_bf16 v[16:19], v[148:151], v[212:215], v[16:19]
	v_mfma_f32_16x16x32_bf16 v[4:7], v[156:159], v[212:215], v[4:7]
	v_mfma_f32_16x16x32_bf16 v[32:35], v[152:155], v[178:181], v[32:35]
	v_mfma_f32_16x16x32_bf16 v[28:31], v[170:173], v[178:181], v[28:31]
	v_mfma_f32_16x16x32_bf16 v[24:27], v[152:155], v[186:189], v[24:27]
	v_mfma_f32_16x16x32_bf16 v[12:15], v[170:173], v[186:189], v[12:15]
	v_mfma_f32_16x16x32_bf16 v[20:23], v[152:155], v[208:211], v[20:23]
	v_mfma_f32_16x16x32_bf16 v[8:11], v[170:173], v[208:211], v[8:11]
	v_mfma_f32_16x16x32_bf16 v[16:19], v[152:155], v[220:223], v[16:19]
	v_mfma_f32_16x16x32_bf16 v[4:7], v[170:173], v[220:223], v[4:7]
	s_setprio 0
	s_barrier
	s_add_i32 s41, 0, 0x18000
	s_add_i32 s77, 0, 0x1c000
	v_add_u32_e32 v144, s41, v217
	v_add_u32_e32 v170, s77, v217
	ds_read_b128 v[116:119], v144
	ds_read_b128 v[120:123], v144 offset:1024
	ds_read_b128 v[140:143], v144 offset:2048
	ds_read_b128 v[144:147], v144 offset:3072
	ds_read_b128 v[148:151], v170
	ds_read_b128 v[152:155], v170 offset:1024
	ds_read_b128 v[156:159], v170 offset:2048
	ds_read_b128 v[170:173], v170 offset:3072
	s_add_u32 s38, s38, s10
	s_addc_u32 s39, s39, s11
	s_mov_b32 m0, s53
	v_lshl_add_u64 v[228:229], s[38:39], 0, v[0:1]
	ds_read_b128 v[174:177], v219 offset:32768
	ds_read_b128 v[178:181], v219 offset:33792
	ds_read_b128 v[182:185], v219 offset:34816
	ds_read_b128 v[186:189], v219 offset:35840
	ds_read_b128 v[204:207], v219 offset:36864
	ds_read_b128 v[208:211], v219 offset:37888
	ds_read_b128 v[212:215], v219 offset:38912
	ds_read_b128 v[220:223], v219 offset:39936
	global_load_lds_dwordx4 v[228:229], off
	v_lshl_add_u64 v[228:229], s[38:39], 0, v[162:163]
	s_mov_b32 m0, s54
	s_nop 0
	global_load_lds_dwordx4 v[228:229], off
	s_waitcnt vmcnt(8)
	s_waitcnt lgkmcnt(0)
	s_barrier
	s_setprio 1
	s_waitcnt lgkmcnt(0)
	v_mfma_f32_16x16x32_bf16 v[136:139], v[116:119], v[174:177], v[136:139]
	v_mfma_f32_16x16x32_bf16 v[132:135], v[140:143], v[174:177], v[132:135]
	v_mfma_f32_16x16x32_bf16 v[128:131], v[116:119], v[182:185], v[128:131]
	v_mfma_f32_16x16x32_bf16 v[124:127], v[140:143], v[182:185], v[124:127]
	v_mfma_f32_16x16x32_bf16 v[112:115], v[116:119], v[204:207], v[112:115]
	v_mfma_f32_16x16x32_bf16 v[108:111], v[140:143], v[204:207], v[108:111]
	v_mfma_f32_16x16x32_bf16 v[104:107], v[116:119], v[212:215], v[104:107]
	v_mfma_f32_16x16x32_bf16 v[100:103], v[140:143], v[212:215], v[100:103]
	v_mfma_f32_16x16x32_bf16 v[136:139], v[120:123], v[178:181], v[136:139]
	v_mfma_f32_16x16x32_bf16 v[132:135], v[144:147], v[178:181], v[132:135]
	v_mfma_f32_16x16x32_bf16 v[128:131], v[120:123], v[186:189], v[128:131]
	v_mfma_f32_16x16x32_bf16 v[124:127], v[144:147], v[186:189], v[124:127]
	v_mfma_f32_16x16x32_bf16 v[112:115], v[120:123], v[208:211], v[112:115]
	v_mfma_f32_16x16x32_bf16 v[108:111], v[144:147], v[208:211], v[108:111]
	v_mfma_f32_16x16x32_bf16 v[104:107], v[120:123], v[220:223], v[104:107]
	v_mfma_f32_16x16x32_bf16 v[100:103], v[144:147], v[220:223], v[100:103]
	s_setprio 0
	s_setprio 1
	v_mfma_f32_16x16x32_bf16 v[64:67], v[148:151], v[174:177], v[64:67]
	v_mfma_f32_16x16x32_bf16 v[56:59], v[156:159], v[174:177], v[56:59]
	v_mfma_f32_16x16x32_bf16 v[60:63], v[148:151], v[182:185], v[60:63]
	v_mfma_f32_16x16x32_bf16 v[52:55], v[156:159], v[182:185], v[52:55]
	v_mfma_f32_16x16x32_bf16 v[48:51], v[148:151], v[204:207], v[48:51]
	v_mfma_f32_16x16x32_bf16 v[40:43], v[156:159], v[204:207], v[40:43]
	v_mfma_f32_16x16x32_bf16 v[44:47], v[148:151], v[212:215], v[44:47]
	v_mfma_f32_16x16x32_bf16 v[36:39], v[156:159], v[212:215], v[36:39]
	v_mfma_f32_16x16x32_bf16 v[64:67], v[152:155], v[178:181], v[64:67]
	v_mfma_f32_16x16x32_bf16 v[56:59], v[170:173], v[178:181], v[56:59]
	v_mfma_f32_16x16x32_bf16 v[60:63], v[152:155], v[186:189], v[60:63]
	v_mfma_f32_16x16x32_bf16 v[52:55], v[170:173], v[186:189], v[52:55]
	v_mfma_f32_16x16x32_bf16 v[48:51], v[152:155], v[208:211], v[48:51]
	v_mfma_f32_16x16x32_bf16 v[40:43], v[170:173], v[208:211], v[40:43]
	v_mfma_f32_16x16x32_bf16 v[44:47], v[152:155], v[220:223], v[44:47]
	v_mfma_f32_16x16x32_bf16 v[36:39], v[170:173], v[220:223], v[36:39]
	s_setprio 0
	s_barrier
; #define PG8_STAGE(bufoff, gbase, voff) do { _Pragma("unroll") for (int _i = 0; _i < 2; ++_i) \
;         __builtin_amdgcn_global_load_lds((const unsigned*)((const char*)(gbase) + (voff)[_i]), (PG8_LAS unsigned*)(lds + (bufoff) + ldsw + _i * 8192), 16, 0, 0); } while (0)
; #define PG8_LDA(dst, b, h) do { _Pragma("unroll") for (int m = 0; m < 4; ++m) _Pragma("unroll") for (int k = 0; k < 2; ++k) dst[m][k] = *(const PG8_LAS bf16x8*)(lds + PG8_SA(b, h) + aoff + m * 2048 + k * 1024); } while (0)
; #define PG8_MMA(ai, bj, At, Bt) do { __builtin_amdgcn_s_setprio(1); _Pragma("unroll") for (int m = 0; m < 4; ++m) _Pragma("unroll") for (int n = 0; n < 2; ++n) _Pragma("unroll") for (int k = 0; k < 2; ++k) \
;         acc[ai][bj][m][n] = __builtin_amdgcn_mfma_f32_16x16x32_bf16(Bt[n][k], At[m][k], acc[ai][bj][m][n], 0, 0, 0); __builtin_amdgcn_s_setprio(0); } while (0)
; #define PG8_WAIT_V(n) asm volatile("s_waitcnt vmcnt(" #n ")" ::: "memory")
; #define PG8_WAIT_L(n) asm volatile("s_waitcnt lgkmcnt(" #n ")" ::: "memory")
; #define PG8_BAR __builtin_amdgcn_s_barrier()
; #define PG8_SCHED __builtin_amdgcn_sched_barrier(0)
; template <class Epi, class Sched, bool ALIGN_EPI = false, bool SP2 = false>
; __device__ __forceinline__ void gemm_phase(PG8_LAS unsigned char* lds, const Gemm g, const Sched& S, const Epi& E, int tid_in) {
;     ...
;             PG8_LDA(At, 1, 1); PG8_STAGE(PG8_SB(1, 0), b3, voffB); PG8_STAGE(PG8_SB(1, 1), b3 + hsB, voffB); PG8_STAGE(PG8_SA(1, 0), a3, voffA);
;             PG8_WAIT_V(8); PG8_WAIT_L(0); PG8_BAR; PG8_MMA(1, 0, At, B0); PG8_MMA(1, 1, At, B1); PG8_BAR; PG8_SCHED;
	s_add_i32 s38, s41, s50
	v_lshl_add_u64 v[190:191], v[190:191], 0, s[80:81]
	s_mov_b32 m0, s38
	ds_read_b128 v[174:177], v219 offset:49152
	ds_read_b128 v[178:181], v219 offset:50176
	ds_read_b128 v[182:185], v219 offset:51200
	ds_read_b128 v[186:189], v219 offset:52224
	ds_read_b128 v[204:207], v219 offset:53248
	ds_read_b128 v[208:211], v219 offset:54272
	ds_read_b128 v[212:215], v219 offset:55296
	ds_read_b128 v[220:223], v219 offset:56320
	global_load_lds_dwordx4 v[190:191], off
	v_lshl_add_u64 v[190:191], v[192:193], 0, s[80:81]
	s_add_i32 m0, s38, 0x2000
	s_add_i32 s38, s77, s50
	global_load_lds_dwordx4 v[190:191], off
	v_lshl_add_u64 v[190:191], v[196:197], 0, s[80:81]
	s_mov_b32 m0, s38
	s_nop 0
	global_load_lds_dwordx4 v[190:191], off
	v_lshl_add_u64 v[190:191], v[198:199], 0, s[80:81]
	s_add_i32 m0, s38, 0x2000
	s_nop 0
	global_load_lds_dwordx4 v[190:191], off
	v_lshl_add_u64 v[190:191], v[200:201], 0, s[80:81]
	s_mov_b32 m0, s59
	s_nop 0
	global_load_lds_dwordx4 v[190:191], off
	v_lshl_add_u64 v[190:191], v[202:203], 0, s[80:81]
	s_mov_b32 m0, s60
	s_nop 0
	global_load_lds_dwordx4 v[190:191], off
	s_waitcnt vmcnt(8)
	s_waitcnt lgkmcnt(0)
	s_barrier
	s_setprio 1
	s_waitcnt lgkmcnt(0)
	s_nop 0
	v_mfma_f32_16x16x32_bf16 v[96:99], v[116:119], v[174:177], v[96:99]
	v_mfma_f32_16x16x32_bf16 v[92:95], v[140:143], v[174:177], v[92:95]
	v_mfma_f32_16x16x32_bf16 v[88:91], v[116:119], v[182:185], v[88:91]
	v_mfma_f32_16x16x32_bf16 v[84:87], v[140:143], v[182:185], v[84:87]
	v_mfma_f32_16x16x32_bf16 v[80:83], v[116:119], v[204:207], v[80:83]
	v_mfma_f32_16x16x32_bf16 v[76:79], v[140:143], v[204:207], v[76:79]
	v_mfma_f32_16x16x32_bf16 v[72:75], v[116:119], v[212:215], v[72:75]
	v_mfma_f32_16x16x32_bf16 v[68:71], v[140:143], v[212:215], v[68:71]
	v_mfma_f32_16x16x32_bf16 v[96:99], v[120:123], v[178:181], v[96:99]
	v_mfma_f32_16x16x32_bf16 v[92:95], v[144:147], v[178:181], v[92:95]
	v_mfma_f32_16x16x32_bf16 v[88:91], v[120:123], v[186:189], v[88:91]
	v_mfma_f32_16x16x32_bf16 v[84:87], v[144:147], v[186:189], v[84:87]
	v_mfma_f32_16x16x32_bf16 v[80:83], v[120:123], v[208:211], v[80:83]
	v_mfma_f32_16x16x32_bf16 v[76:79], v[144:147], v[208:211], v[76:79]
	v_mfma_f32_16x16x32_bf16 v[72:75], v[120:123], v[220:223], v[72:75]
	v_mfma_f32_16x16x32_bf16 v[68:71], v[144:147], v[220:223], v[68:71]
	s_setprio 0
	s_setprio 1
	v_mfma_f32_16x16x32_bf16 v[32:35], v[148:151], v[174:177], v[32:35]
	v_mfma_f32_16x16x32_bf16 v[28:31], v[156:159], v[174:177], v[28:31]
	v_mfma_f32_16x16x32_bf16 v[24:27], v[148:151], v[182:185], v[24:27]
	v_mfma_f32_16x16x32_bf16 v[12:15], v[156:159], v[182:185], v[12:15]
	v_mfma_f32_16x16x32_bf16 v[20:23], v[148:151], v[204:207], v[20:23]
	v_mfma_f32_16x16x32_bf16 v[8:11], v[156:159], v[204:207], v[8:11]
	v_mfma_f32_16x16x32_bf16 v[16:19], v[148:151], v[212:215], v[16:19]
	v_mfma_f32_16x16x32_bf16 v[4:7], v[156:159], v[212:215], v[4:7]
	v_mfma_f32_16x16x32_bf16 v[32:35], v[152:155], v[178:181], v[32:35]
	v_mfma_f32_16x16x32_bf16 v[28:31], v[170:173], v[178:181], v[28:31]
	v_mfma_f32_16x16x32_bf16 v[24:27], v[152:155], v[186:189], v[24:27]
	v_mfma_f32_16x16x32_bf16 v[12:15], v[170:173], v[186:189], v[12:15]
	v_mfma_f32_16x16x32_bf16 v[20:23], v[152:155], v[208:211], v[20:23]
	v_mfma_f32_16x16x32_bf16 v[8:11], v[170:173], v[208:211], v[8:11]
	v_mfma_f32_16x16x32_bf16 v[16:19], v[152:155], v[220:223], v[16:19]
	v_mfma_f32_16x16x32_bf16 v[4:7], v[170:173], v[220:223], v[4:7]
	s_setprio 0
	s_barrier
	s_add_i32 s38, s40, 2
	s_add_u32 s75, s75, 0x100
	s_addc_u32 s76, s76, 0
	s_add_u32 s4, s4, 0x100
	s_addc_u32 s5, s5, 0
	s_cmp_ge_i32 s40, s61
	s_mov_b32 s40, s38
	s_cbranch_scc0 .LBB0_1070
	s_movk_i32 s83, 0x3000

; #define PG8_STAGE(bufoff, gbase, voff) do { _Pragma("unroll") for (int _i = 0; _i < 2; ++_i) \
;         __builtin_amdgcn_global_load_lds((const unsigned*)((const char*)(gbase) + (voff)[_i]), (PG8_LAS unsigned*)(lds + (bufoff) + ldsw + _i * 8192), 16, 0, 0); } while (0)
; #define PG8_LDA(dst, b, h) do { _Pragma("unroll") for (int m = 0; m < 4; ++m) _Pragma("unroll") for (int k = 0; k < 2; ++k) dst[m][k] = *(const PG8_LAS bf16x8*)(lds + PG8_SA(b, h) + aoff + m * 2048 + k * 1024); } while (0)
; #define PG8_LDB(dst, b, h) do { _Pragma("unroll") for (int n = 0; n < 2; ++n) _Pragma("unroll") for (int k = 0; k < 2; ++k) dst[n][k] = *(const PG8_LAS bf16x8*)(lds + PG8_SB(b, h) + boff + n * 2048 + k * 1024); } while (0)
; #define PG8_MMA(ai, bj, At, Bt) do { __builtin_amdgcn_s_setprio(1); _Pragma("unroll") for (int m = 0; m < 4; ++m) _Pragma("unroll") for (int n = 0; n < 2; ++n) _Pragma("unroll") for (int k = 0; k < 2; ++k) \
;         acc[ai][bj][m][n] = __builtin_amdgcn_mfma_f32_16x16x32_bf16(Bt[n][k], At[m][k], acc[ai][bj][m][n], 0, 0, 0); __builtin_amdgcn_s_setprio(0); } while (0)
; #define PG8_WAIT_V(n) asm volatile("s_waitcnt vmcnt(" #n ")" ::: "memory")
; template <class Epi, class Sched, bool ALIGN_EPI = false, bool SP2 = false>
; __device__ __forceinline__ void gemm_phase(PG8_LAS unsigned char* lds, const Gemm g, const Sched& S, const Epi& E, int tid_in) {
;     ...
;         for (int t = 0; t < nt; t += 2) {
;             const bool last = (t == nt - 2);
;             if constexpr (mid_hook<Epi>::value) { if (t == Epi::H1 || t == Epi::H2) E.mid(acc, cur, wr, wc, fr, fq, t == Epi::H2); }
;             const char* a1 = cA + (size_t)(t + 1) * kstep + (t >= jt ? jb : 0);
;             const char* a2 = last ? nA : cA + (size_t)(t + 2) * kstep + (t + 2 >= jt ? jb : 0); const char* b2 = last ? nB : cB + (size_t)(t + 2) * kstep;
;             const char* a3 = a2 + kstep; const char* b3 = b2 + kstep;
;             if (last && has_next) S.a_ready(nxt);
;             if constexpr (SP2) {
;             PG8_LDB(B0, 0, 0); PG8_LDB(B1, 0, 1); PG8_SCHED; PG8_LDA(At, 0, 0); PG8_STAGE(PG8_SA(1, 1), a1 + hsA, voffA);
;             PG8_WAIT_V(8); PG8_WAIT_L(0); PG8_BAR; PG8_MMA(0, 0, At, B0); PG8_MMA(0, 1, At, B1); PG8_BAR; PG8_SCHED;
;             PG8_LDA(At, 0, 1); PG8_STAGE(PG8_SB(0, 0), b2, voffB); PG8_STAGE(PG8_SB(0, 1), b2 + hsB, voffB); PG8_STAGE(PG8_SA(0, 0), a2, voffA);
.LBB0_1102:
	s_add_i32 s26, s55, -2
	s_cmp_ge_i32 s26, s28
	s_cselect_b32 s58, s29, 0
	s_cselect_b32 s59, s49, 0
	s_cmp_ge_i32 s55, s28
	s_cselect_b32 s27, s29, 0
	s_cselect_b32 s26, s49, 0
	s_add_u32 s27, s24, s27
	s_addc_u32 s26, s25, s26
	s_add_u32 s60, s27, 0x80
	s_addc_u32 s26, s26, 0
	s_add_i32 s62, 0, 0x10000
	s_cmp_eq_u32 s48, s55
	s_cselect_b32 s27, s5, s26
	s_cselect_b32 s26, s4, s60
	s_cselect_b32 s61, s23, s21
	s_cselect_b32 s60, s22, s17
	s_add_i32 s63, 0, 0x14000
	v_add_u32_e32 v160, s62, v3
	v_add_u32_e32 v176, s63, v3
	ds_read_b128 v[148:151], v160
	ds_read_b128 v[152:155], v160 offset:1024
	ds_read_b128 v[156:159], v160 offset:2048
	ds_read_b128 v[160:163], v160 offset:3072
	ds_read_b128 v[164:167], v176
	ds_read_b128 v[168:171], v176 offset:1024
	ds_read_b128 v[172:175], v176 offset:2048
	ds_read_b128 v[176:179], v176 offset:3072
	v_lshl_add_u64 v[192:193], s[24:25], 0, v[140:141]
	v_lshl_add_u64 v[192:193], v[192:193], 0, s[58:59]
	s_add_i32 m0, s35, 0xc000
	ds_read_b128 v[180:183], v147
	ds_read_b128 v[184:187], v147 offset:1024
	ds_read_b128 v[188:191], v147 offset:2048
	ds_read_b128 v[204:207], v147 offset:3072
	ds_read_b128 v[208:211], v147 offset:4096
	ds_read_b128 v[212:215], v147 offset:5120
	ds_read_b128 v[216:219], v147 offset:6144
	ds_read_b128 v[220:223], v147 offset:7168
	global_load_lds_dwordx4 v[192:193], off
	v_lshl_add_u64 v[192:193], s[24:25], 0, v[138:139]
	v_lshl_add_u64 v[192:193], v[192:193], 0, s[58:59]
	s_add_i32 m0, s35, 0xe000
	s_nop 0
	global_load_lds_dwordx4 v[192:193], off
	s_waitcnt vmcnt(8)
	s_waitcnt lgkmcnt(0)
	s_barrier
	s_setprio 1
	s_waitcnt lgkmcnt(0)
	s_nop 0
	v_mfma_f32_16x16x32_bf16 v[124:127], v[148:151], v[180:183], v[124:127]
	v_mfma_f32_16x16x32_bf16 v[128:131], v[156:159], v[180:183], v[128:131]
	v_mfma_f32_16x16x32_bf16 v[112:115], v[148:151], v[188:191], v[112:115]
	v_mfma_f32_16x16x32_bf16 v[108:111], v[156:159], v[188:191], v[108:111]
	v_mfma_f32_16x16x32_bf16 v[96:99], v[148:151], v[208:211], v[96:99]
	v_mfma_f32_16x16x32_bf16 v[92:95], v[156:159], v[208:211], v[92:95]
	v_mfma_f32_16x16x32_bf16 v[80:83], v[148:151], v[216:219], v[80:83]
	v_mfma_f32_16x16x32_bf16 v[76:79], v[156:159], v[216:219], v[76:79]
	v_mfma_f32_16x16x32_bf16 v[124:127], v[152:155], v[184:187], v[124:127]
	v_mfma_f32_16x16x32_bf16 v[128:131], v[160:163], v[184:187], v[128:131]
	v_mfma_f32_16x16x32_bf16 v[112:115], v[152:155], v[204:207], v[112:115]
	v_mfma_f32_16x16x32_bf16 v[108:111], v[160:163], v[204:207], v[108:111]
	v_mfma_f32_16x16x32_bf16 v[96:99], v[152:155], v[212:215], v[96:99]
	v_mfma_f32_16x16x32_bf16 v[92:95], v[160:163], v[212:215], v[92:95]
	v_mfma_f32_16x16x32_bf16 v[80:83], v[152:155], v[220:223], v[80:83]
	v_mfma_f32_16x16x32_bf16 v[76:79], v[160:163], v[220:223], v[76:79]
	s_setprio 0
	s_setprio 1
	v_mfma_f32_16x16x32_bf16 v[120:123], v[164:167], v[180:183], v[120:123]
	v_mfma_f32_16x16x32_bf16 v[116:119], v[172:175], v[180:183], v[116:119]
	v_mfma_f32_16x16x32_bf16 v[104:107], v[164:167], v[188:191], v[104:107]
	v_mfma_f32_16x16x32_bf16 v[100:103], v[172:175], v[188:191], v[100:103]
	v_mfma_f32_16x16x32_bf16 v[88:91], v[164:167], v[208:211], v[88:91]
	v_mfma_f32_16x16x32_bf16 v[84:87], v[172:175], v[208:211], v[84:87]
	v_mfma_f32_16x16x32_bf16 v[72:75], v[164:167], v[216:219], v[72:75]
	v_mfma_f32_16x16x32_bf16 v[68:71], v[172:175], v[216:219], v[68:71]
	v_mfma_f32_16x16x32_bf16 v[120:123], v[168:171], v[184:187], v[120:123]
	v_mfma_f32_16x16x32_bf16 v[116:119], v[176:179], v[184:187], v[116:119]
	v_mfma_f32_16x16x32_bf16 v[104:107], v[168:171], v[204:207], v[104:107]
	v_mfma_f32_16x16x32_bf16 v[100:103], v[176:179], v[204:207], v[100:103]
	v_mfma_f32_16x16x32_bf16 v[88:91], v[168:171], v[212:215], v[88:91]
	v_mfma_f32_16x16x32_bf16 v[84:87], v[176:179], v[212:215], v[84:87]
	v_mfma_f32_16x16x32_bf16 v[72:75], v[168:171], v[220:223], v[72:75]
	v_mfma_f32_16x16x32_bf16 v[68:71], v[176:179], v[220:223], v[68:71]
	s_setprio 0
	s_barrier
	s_add_i32 s58, s62, s33
	v_lshl_add_u64 v[192:193], s[60:61], 0, v[134:135]
	s_mov_b32 m0, s58
	ds_read_b128 v[180:183], v147 offset:16384
	ds_read_b128 v[184:187], v147 offset:17408
	ds_read_b128 v[188:191], v147 offset:18432
	ds_read_b128 v[204:207], v147 offset:19456
	ds_read_b128 v[208:211], v147 offset:20480
	ds_read_b128 v[212:215], v147 offset:21504
	ds_read_b128 v[216:219], v147 offset:22528
	ds_read_b128 v[220:223], v147 offset:23552
	global_load_lds_dwordx4 v[192:193], off
	s_add_i32 m0, s58, 0x2000
	s_add_u32 s58, s60, s8
	v_lshl_add_u64 v[196:197], s[60:61], 0, v[0:1]
	s_addc_u32 s59, s61, s9
	s_add_i32 s60, s63, s33
	global_load_lds_dwordx4 v[196:197], off
	v_lshl_add_u64 v[198:199], s[58:59], 0, v[134:135]
	s_mov_b32 m0, s60
	v_lshl_add_u64 v[200:201], s[58:59], 0, v[0:1]
	global_load_lds_dwordx4 v[198:199], off
	s_add_i32 m0, s60, 0x2000
	v_lshl_add_u64 v[202:203], s[26:27], 0, v[136:137]
	global_load_lds_dwordx4 v[200:201], off
	s_mov_b32 m0, s35
	v_lshl_add_u64 v[228:229], s[26:27], 0, v[132:133]
	global_load_lds_dwordx4 v[202:203], off
	s_mov_b32 m0, s36
	s_nop 0
	global_load_lds_dwordx4 v[228:229], off
	s_waitcnt vmcnt(8)
	s_waitcnt lgkmcnt(0)
	s_barrier
; #define PG8_STAGE(bufoff, gbase, voff) do { _Pragma("unroll") for (int _i = 0; _i < 2; ++_i) \
;         __builtin_amdgcn_global_load_lds((const unsigned*)((const char*)(gbase) + (voff)[_i]), (PG8_LAS unsigned*)(lds + (bufoff) + ldsw + _i * 8192), 16, 0, 0); } while (0)
; #define PG8_LDA(dst, b, h) do { _Pragma("unroll") for (int m = 0; m < 4; ++m) _Pragma("unroll") for (int k = 0; k < 2; ++k) dst[m][k] = *(const PG8_LAS bf16x8*)(lds + PG8_SA(b, h) + aoff + m * 2048 + k * 1024); } while (0)
; #define PG8_LDB(dst, b, h) do { _Pragma("unroll") for (int n = 0; n < 2; ++n) _Pragma("unroll") for (int k = 0; k < 2; ++k) dst[n][k] = *(const PG8_LAS bf16x8*)(lds + PG8_SB(b, h) + boff + n * 2048 + k * 1024); } while (0)
; #define PG8_MMA(ai, bj, At, Bt) do { __builtin_amdgcn_s_setprio(1); _Pragma("unroll") for (int m = 0; m < 4; ++m) _Pragma("unroll") for (int n = 0; n < 2; ++n) _Pragma("unroll") for (int k = 0; k < 2; ++k) \
;         acc[ai][bj][m][n] = __builtin_amdgcn_mfma_f32_16x16x32_bf16(Bt[n][k], At[m][k], acc[ai][bj][m][n], 0, 0, 0); __builtin_amdgcn_s_setprio(0); } while (0)
; #define PG8_WAIT_V(n) asm volatile("s_waitcnt vmcnt(" #n ")" ::: "memory")
; #define PG8_WAIT_L(n) asm volatile("s_waitcnt lgkmcnt(" #n ")" ::: "memory")
; #define PG8_BAR __builtin_amdgcn_s_barrier()
; #define PG8_SCHED __builtin_amdgcn_sched_barrier(0)
; template <class Epi, class Sched, bool ALIGN_EPI = false, bool SP2 = false>
; __device__ __forceinline__ void gemm_phase(PG8_LAS unsigned char* lds, const Gemm g, const Sched& S, const Epi& E, int tid_in) {
;     ...
;             PG8_WAIT_V(8); PG8_WAIT_L(0); PG8_BAR; PG8_MMA(1, 0, At, B0); PG8_MMA(1, 1, At, B1); PG8_BAR; PG8_SCHED;
;             PG8_LDB(B0, 1, 0); PG8_LDB(B1, 1, 1); PG8_SCHED; PG8_LDA(At, 1, 0); PG8_STAGE(PG8_SA(0, 1), a2 + hsA, voffA);
;             PG8_WAIT_V(8); PG8_WAIT_L(0); PG8_BAR; PG8_MMA(0, 0, At, B0); PG8_MMA(0, 1, At, B1); PG8_BAR; PG8_SCHED;
	s_setprio 1
	s_waitcnt lgkmcnt(0)
	v_mfma_f32_16x16x32_bf16 v[64:67], v[148:151], v[180:183], v[64:67]
	v_mfma_f32_16x16x32_bf16 v[60:63], v[156:159], v[180:183], v[60:63]
	v_mfma_f32_16x16x32_bf16 v[48:51], v[148:151], v[188:191], v[48:51]
	v_mfma_f32_16x16x32_bf16 v[44:47], v[156:159], v[188:191], v[44:47]
	v_mfma_f32_16x16x32_bf16 v[32:35], v[148:151], v[208:211], v[32:35]
	v_mfma_f32_16x16x32_bf16 v[28:31], v[156:159], v[208:211], v[28:31]
	v_mfma_f32_16x16x32_bf16 v[16:19], v[148:151], v[216:219], v[16:19]
	v_mfma_f32_16x16x32_bf16 v[12:15], v[156:159], v[216:219], v[12:15]
	v_mfma_f32_16x16x32_bf16 v[64:67], v[152:155], v[184:187], v[64:67]
	v_mfma_f32_16x16x32_bf16 v[60:63], v[160:163], v[184:187], v[60:63]
	v_mfma_f32_16x16x32_bf16 v[48:51], v[152:155], v[204:207], v[48:51]
	v_mfma_f32_16x16x32_bf16 v[44:47], v[160:163], v[204:207], v[44:47]
	v_mfma_f32_16x16x32_bf16 v[32:35], v[152:155], v[212:215], v[32:35]
	v_mfma_f32_16x16x32_bf16 v[28:31], v[160:163], v[212:215], v[28:31]
	v_mfma_f32_16x16x32_bf16 v[16:19], v[152:155], v[220:223], v[16:19]
	v_mfma_f32_16x16x32_bf16 v[12:15], v[160:163], v[220:223], v[12:15]
	s_setprio 0
	s_setprio 1
	v_mfma_f32_16x16x32_bf16 v[56:59], v[164:167], v[180:183], v[56:59]
	v_mfma_f32_16x16x32_bf16 v[52:55], v[172:175], v[180:183], v[52:55]
	v_mfma_f32_16x16x32_bf16 v[40:43], v[164:167], v[188:191], v[40:43]
	v_mfma_f32_16x16x32_bf16 v[36:39], v[172:175], v[188:191], v[36:39]
	v_mfma_f32_16x16x32_bf16 v[24:27], v[164:167], v[208:211], v[24:27]
	v_mfma_f32_16x16x32_bf16 v[20:23], v[172:175], v[208:211], v[20:23]
	v_mfma_f32_16x16x32_bf16 v[8:11], v[164:167], v[216:219], v[8:11]
	v_mfma_f32_16x16x32_bf16 v[4:7], v[172:175], v[216:219], v[4:7]
	v_mfma_f32_16x16x32_bf16 v[56:59], v[168:171], v[184:187], v[56:59]
	v_mfma_f32_16x16x32_bf16 v[52:55], v[176:179], v[184:187], v[52:55]
	v_mfma_f32_16x16x32_bf16 v[40:43], v[168:171], v[204:207], v[40:43]
	v_mfma_f32_16x16x32_bf16 v[36:39], v[176:179], v[204:207], v[36:39]
	v_mfma_f32_16x16x32_bf16 v[24:27], v[168:171], v[212:215], v[24:27]
	v_mfma_f32_16x16x32_bf16 v[20:23], v[176:179], v[212:215], v[20:23]
	v_mfma_f32_16x16x32_bf16 v[8:11], v[168:171], v[220:223], v[8:11]
	v_mfma_f32_16x16x32_bf16 v[4:7], v[176:179], v[220:223], v[4:7]
	s_setprio 0
	s_barrier
	s_add_i32 s58, 0, 0x18000
	s_add_i32 s59, 0, 0x1c000
	v_add_u32_e32 v160, s58, v3
	v_add_u32_e32 v176, s59, v3
	ds_read_b128 v[148:151], v160
	ds_read_b128 v[152:155], v160 offset:1024
	ds_read_b128 v[156:159], v160 offset:2048
	ds_read_b128 v[160:163], v160 offset:3072
	ds_read_b128 v[164:167], v176
	ds_read_b128 v[168:171], v176 offset:1024
	ds_read_b128 v[172:175], v176 offset:2048
	ds_read_b128 v[176:179], v176 offset:3072
	s_add_u32 s26, s26, s6
	s_addc_u32 s27, s27, s7
	s_mov_b32 m0, s37
	v_lshl_add_u64 v[230:231], s[26:27], 0, v[136:137]
	ds_read_b128 v[180:183], v147 offset:32768
	ds_read_b128 v[184:187], v147 offset:33792
	ds_read_b128 v[188:191], v147 offset:34816
	ds_read_b128 v[204:207], v147 offset:35840
	ds_read_b128 v[208:211], v147 offset:36864
	ds_read_b128 v[212:215], v147 offset:37888
	ds_read_b128 v[216:219], v147 offset:38912
	ds_read_b128 v[220:223], v147 offset:39936
	global_load_lds_dwordx4 v[230:231], off
	v_lshl_add_u64 v[230:231], s[26:27], 0, v[132:133]
	s_mov_b32 m0, s38
	s_nop 0
	global_load_lds_dwordx4 v[230:231], off
	s_waitcnt vmcnt(8)
	s_waitcnt lgkmcnt(0)
	s_barrier
	s_setprio 1
	s_waitcnt lgkmcnt(0)
	v_mfma_f32_16x16x32_bf16 v[124:127], v[148:151], v[180:183], v[124:127]
	v_mfma_f32_16x16x32_bf16 v[128:131], v[156:159], v[180:183], v[128:131]
	v_mfma_f32_16x16x32_bf16 v[112:115], v[148:151], v[188:191], v[112:115]
	v_mfma_f32_16x16x32_bf16 v[108:111], v[156:159], v[188:191], v[108:111]
	v_mfma_f32_16x16x32_bf16 v[96:99], v[148:151], v[208:211], v[96:99]
	v_mfma_f32_16x16x32_bf16 v[92:95], v[156:159], v[208:211], v[92:95]
	v_mfma_f32_16x16x32_bf16 v[80:83], v[148:151], v[216:219], v[80:83]
	v_mfma_f32_16x16x32_bf16 v[76:79], v[156:159], v[216:219], v[76:79]
	v_mfma_f32_16x16x32_bf16 v[124:127], v[152:155], v[184:187], v[124:127]
	v_mfma_f32_16x16x32_bf16 v[128:131], v[160:163], v[184:187], v[128:131]
	v_mfma_f32_16x16x32_bf16 v[112:115], v[152:155], v[204:207], v[112:115]
	v_mfma_f32_16x16x32_bf16 v[108:111], v[160:163], v[204:207], v[108:111]
	v_mfma_f32_16x16x32_bf16 v[96:99], v[152:155], v[212:215], v[96:99]
	v_mfma_f32_16x16x32_bf16 v[92:95], v[160:163], v[212:215], v[92:95]
	v_mfma_f32_16x16x32_bf16 v[80:83], v[152:155], v[220:223], v[80:83]
	v_mfma_f32_16x16x32_bf16 v[76:79], v[160:163], v[220:223], v[76:79]
	s_setprio 0
	s_setprio 1
	v_mfma_f32_16x16x32_bf16 v[120:123], v[164:167], v[180:183], v[120:123]
	v_mfma_f32_16x16x32_bf16 v[116:119], v[172:175], v[180:183], v[116:119]
	v_mfma_f32_16x16x32_bf16 v[104:107], v[164:167], v[188:191], v[104:107]
	v_mfma_f32_16x16x32_bf16 v[100:103], v[172:175], v[188:191], v[100:103]
	v_mfma_f32_16x16x32_bf16 v[88:91], v[164:167], v[208:211], v[88:91]
	v_mfma_f32_16x16x32_bf16 v[84:87], v[172:175], v[208:211], v[84:87]
	v_mfma_f32_16x16x32_bf16 v[72:75], v[164:167], v[216:219], v[72:75]
	v_mfma_f32_16x16x32_bf16 v[68:71], v[172:175], v[216:219], v[68:71]
	v_mfma_f32_16x16x32_bf16 v[120:123], v[168:171], v[184:187], v[120:123]
	v_mfma_f32_16x16x32_bf16 v[116:119], v[176:179], v[184:187], v[116:119]
	v_mfma_f32_16x16x32_bf16 v[104:107], v[168:171], v[204:207], v[104:107]
	v_mfma_f32_16x16x32_bf16 v[100:103], v[176:179], v[204:207], v[100:103]
	v_mfma_f32_16x16x32_bf16 v[88:91], v[168:171], v[212:215], v[88:91]
	v_mfma_f32_16x16x32_bf16 v[84:87], v[176:179], v[212:215], v[84:87]
	v_mfma_f32_16x16x32_bf16 v[72:75], v[168:171], v[220:223], v[72:75]
	v_mfma_f32_16x16x32_bf16 v[68:71], v[176:179], v[220:223], v[68:71]
	s_setprio 0
	s_barrier
; #define PG8_STAGE(bufoff, gbase, voff) do { _Pragma("unroll") for (int _i = 0; _i < 2; ++_i) \
;         __builtin_amdgcn_global_load_lds((const unsigned*)((const char*)(gbase) + (voff)[_i]), (PG8_LAS unsigned*)(lds + (bufoff) + ldsw + _i * 8192), 16, 0, 0); } while (0)
; #define PG8_LDA(dst, b, h) do { _Pragma("unroll") for (int m = 0; m < 4; ++m) _Pragma("unroll") for (int k = 0; k < 2; ++k) dst[m][k] = *(const PG8_LAS bf16x8*)(lds + PG8_SA(b, h) + aoff + m * 2048 + k * 1024); } while (0)
; #define PG8_MMA(ai, bj, At, Bt) do { __builtin_amdgcn_s_setprio(1); _Pragma("unroll") for (int m = 0; m < 4; ++m) _Pragma("unroll") for (int n = 0; n < 2; ++n) _Pragma("unroll") for (int k = 0; k < 2; ++k) \
;         acc[ai][bj][m][n] = __builtin_amdgcn_mfma_f32_16x16x32_bf16(Bt[n][k], At[m][k], acc[ai][bj][m][n], 0, 0, 0); __builtin_amdgcn_s_setprio(0); } while (0)
; #define PG8_WAIT_V(n) asm volatile("s_waitcnt vmcnt(" #n ")" ::: "memory")
; #define PG8_WAIT_L(n) asm volatile("s_waitcnt lgkmcnt(" #n ")" ::: "memory")
; #define PG8_BAR __builtin_amdgcn_s_barrier()
; #define PG8_SCHED __builtin_amdgcn_sched_barrier(0)
; template <class Epi, class Sched, bool ALIGN_EPI = false, bool SP2 = false>
; __device__ __forceinline__ void gemm_phase(PG8_LAS unsigned char* lds, const Gemm g, const Sched& S, const Epi& E, int tid_in) {
;     ...
;             PG8_LDA(At, 1, 1); PG8_STAGE(PG8_SB(1, 0), b3, voffB); PG8_STAGE(PG8_SB(1, 1), b3 + hsB, voffB); PG8_STAGE(PG8_SA(1, 0), a3, voffA);
;             PG8_WAIT_V(8); PG8_WAIT_L(0); PG8_BAR; PG8_MMA(1, 0, At, B0); PG8_MMA(1, 1, At, B1); PG8_BAR; PG8_SCHED;
	s_add_i32 s26, s58, s33
	v_lshl_add_u64 v[192:193], v[192:193], 0, s[80:81]
	s_mov_b32 m0, s26
	ds_read_b128 v[180:183], v147 offset:49152
	ds_read_b128 v[184:187], v147 offset:50176
	ds_read_b128 v[188:191], v147 offset:51200
	ds_read_b128 v[204:207], v147 offset:52224
	ds_read_b128 v[208:211], v147 offset:53248
	ds_read_b128 v[212:215], v147 offset:54272
	ds_read_b128 v[216:219], v147 offset:55296
	ds_read_b128 v[220:223], v147 offset:56320
	global_load_lds_dwordx4 v[192:193], off
	v_lshl_add_u64 v[192:193], v[196:197], 0, s[80:81]
	s_add_i32 m0, s26, 0x2000
	s_add_i32 s26, s59, s33
	global_load_lds_dwordx4 v[192:193], off
	v_lshl_add_u64 v[192:193], v[198:199], 0, s[80:81]
	s_mov_b32 m0, s26
	s_nop 0
	global_load_lds_dwordx4 v[192:193], off
	v_lshl_add_u64 v[192:193], v[200:201], 0, s[80:81]
	s_add_i32 m0, s26, 0x2000
	s_nop 0
	global_load_lds_dwordx4 v[192:193], off
	v_lshl_add_u64 v[192:193], v[202:203], 0, s[80:81]
	s_mov_b32 m0, s41
	s_nop 0
	global_load_lds_dwordx4 v[192:193], off
	v_lshl_add_u64 v[192:193], v[228:229], 0, s[80:81]
	s_mov_b32 m0, s46
	s_nop 0
	global_load_lds_dwordx4 v[192:193], off
	s_waitcnt vmcnt(8)
	s_waitcnt lgkmcnt(0)
	s_barrier
	s_setprio 1
	s_waitcnt lgkmcnt(0)
	s_nop 0
	v_mfma_f32_16x16x32_bf16 v[64:67], v[148:151], v[180:183], v[64:67]
	v_mfma_f32_16x16x32_bf16 v[60:63], v[156:159], v[180:183], v[60:63]
	v_mfma_f32_16x16x32_bf16 v[48:51], v[148:151], v[188:191], v[48:51]
	v_mfma_f32_16x16x32_bf16 v[44:47], v[156:159], v[188:191], v[44:47]
	v_mfma_f32_16x16x32_bf16 v[32:35], v[148:151], v[208:211], v[32:35]
	v_mfma_f32_16x16x32_bf16 v[28:31], v[156:159], v[208:211], v[28:31]
	v_mfma_f32_16x16x32_bf16 v[16:19], v[148:151], v[216:219], v[16:19]
	v_mfma_f32_16x16x32_bf16 v[12:15], v[156:159], v[216:219], v[12:15]
	v_mfma_f32_16x16x32_bf16 v[64:67], v[152:155], v[184:187], v[64:67]
	v_mfma_f32_16x16x32_bf16 v[60:63], v[160:163], v[184:187], v[60:63]
	v_mfma_f32_16x16x32_bf16 v[48:51], v[152:155], v[204:207], v[48:51]
	v_mfma_f32_16x16x32_bf16 v[44:47], v[160:163], v[204:207], v[44:47]
	v_mfma_f32_16x16x32_bf16 v[32:35], v[152:155], v[212:215], v[32:35]
	v_mfma_f32_16x16x32_bf16 v[28:31], v[160:163], v[212:215], v[28:31]
	v_mfma_f32_16x16x32_bf16 v[16:19], v[152:155], v[220:223], v[16:19]
	v_mfma_f32_16x16x32_bf16 v[12:15], v[160:163], v[220:223], v[12:15]
	s_setprio 0
	s_setprio 1
	v_mfma_f32_16x16x32_bf16 v[56:59], v[164:167], v[180:183], v[56:59]
	v_mfma_f32_16x16x32_bf16 v[52:55], v[172:175], v[180:183], v[52:55]
	v_mfma_f32_16x16x32_bf16 v[40:43], v[164:167], v[188:191], v[40:43]
	v_mfma_f32_16x16x32_bf16 v[36:39], v[172:175], v[188:191], v[36:39]
	v_mfma_f32_16x16x32_bf16 v[24:27], v[164:167], v[208:211], v[24:27]
	v_mfma_f32_16x16x32_bf16 v[20:23], v[172:175], v[208:211], v[20:23]
	v_mfma_f32_16x16x32_bf16 v[8:11], v[164:167], v[216:219], v[8:11]
	v_mfma_f32_16x16x32_bf16 v[4:7], v[172:175], v[216:219], v[4:7]
	v_mfma_f32_16x16x32_bf16 v[56:59], v[168:171], v[184:187], v[56:59]
	v_mfma_f32_16x16x32_bf16 v[52:55], v[176:179], v[184:187], v[52:55]
	v_mfma_f32_16x16x32_bf16 v[40:43], v[168:171], v[204:207], v[40:43]
	v_mfma_f32_16x16x32_bf16 v[36:39], v[176:179], v[204:207], v[36:39]
	v_mfma_f32_16x16x32_bf16 v[24:27], v[168:171], v[212:215], v[24:27]
	v_mfma_f32_16x16x32_bf16 v[20:23], v[176:179], v[212:215], v[20:23]
	v_mfma_f32_16x16x32_bf16 v[8:11], v[168:171], v[220:223], v[8:11]
	v_mfma_f32_16x16x32_bf16 v[4:7], v[176:179], v[220:223], v[4:7]
	s_setprio 0
	s_barrier
	s_add_i32 s26, s55, 2
	s_add_u32 s17, s17, 0x100
	s_addc_u32 s21, s21, 0
	s_add_u32 s24, s24, 0x100
	s_addc_u32 s25, s25, 0
	s_cmp_ge_i32 s55, s48
	s_mov_b32 s55, s26
	s_cbranch_scc0 .LBB0_1102

; #define PG8_STAGE(bufoff, gbase, voff) do { _Pragma("unroll") for (int _i = 0; _i < 2; ++_i) \
;         __builtin_amdgcn_global_load_lds((const unsigned*)((const char*)(gbase) + (voff)[_i]), (PG8_LAS unsigned*)(lds + (bufoff) + ldsw + _i * 8192), 16, 0, 0); } while (0)
; #define PG8_LDA(dst, b, h) do { _Pragma("unroll") for (int m = 0; m < 4; ++m) _Pragma("unroll") for (int k = 0; k < 2; ++k) dst[m][k] = *(const PG8_LAS bf16x8*)(lds + PG8_SA(b, h) + aoff + m * 2048 + k * 1024); } while (0)
; #define PG8_LDB(dst, b, h) do { _Pragma("unroll") for (int n = 0; n < 2; ++n) _Pragma("unroll") for (int k = 0; k < 2; ++k) dst[n][k] = *(const PG8_LAS bf16x8*)(lds + PG8_SB(b, h) + boff + n * 2048 + k * 1024); } while (0)
; #define PG8_MMA(ai, bj, At, Bt) do { __builtin_amdgcn_s_setprio(1); _Pragma("unroll") for (int m = 0; m < 4; ++m) _Pragma("unroll") for (int n = 0; n < 2; ++n) _Pragma("unroll") for (int k = 0; k < 2; ++k) \
;         acc[ai][bj][m][n] = __builtin_amdgcn_mfma_f32_16x16x32_bf16(Bt[n][k], At[m][k], acc[ai][bj][m][n], 0, 0, 0); __builtin_amdgcn_s_setprio(0); } while (0)
; #define PG8_WAIT_V(n) asm volatile("s_waitcnt vmcnt(" #n ")" ::: "memory")
; template <class Epi, class Sched, bool ALIGN_EPI = false, bool SP2 = false>
; __device__ __forceinline__ void gemm_phase(PG8_LAS unsigned char* lds, const Gemm g, const Sched& S, const Epi& E, int tid_in) {
;     ...
;         for (int t = 0; t < nt; t += 2) {
;             const bool last = (t == nt - 2);
;             if constexpr (mid_hook<Epi>::value) { if (t == Epi::H1 || t == Epi::H2) E.mid(acc, cur, wr, wc, fr, fq, t == Epi::H2); }
;             const char* a1 = cA + (size_t)(t + 1) * kstep + (t >= jt ? jb : 0);
;             const char* a2 = last ? nA : cA + (size_t)(t + 2) * kstep + (t + 2 >= jt ? jb : 0); const char* b2 = last ? nB : cB + (size_t)(t + 2) * kstep;
;             const char* a3 = a2 + kstep; const char* b3 = b2 + kstep;
;             if (last && has_next) S.a_ready(nxt);
;             if constexpr (SP2) {
;             PG8_LDB(B0, 0, 0); PG8_LDB(B1, 0, 1); PG8_SCHED; PG8_LDA(At, 0, 0); PG8_STAGE(PG8_SA(1, 1), a1 + hsA, voffA);
;             PG8_WAIT_V(8); PG8_WAIT_L(0); PG8_BAR; PG8_MMA(0, 0, At, B0); PG8_MMA(0, 1, At, B1); PG8_BAR; PG8_SCHED;
;             PG8_LDA(At, 0, 1); PG8_STAGE(PG8_SB(0, 0), b2, voffB); PG8_STAGE(PG8_SB(0, 1), b2 + hsB, voffB); PG8_STAGE(PG8_SA(0, 0), a2, voffA);
.LBB0_1255:
	s_add_i32 s24, s58, -2
	s_cmp_ge_i32 s24, s29
	s_cselect_b32 s60, s30, 0
	s_cselect_b32 s61, s47, 0
	s_cmp_ge_i32 s58, s29
	s_cselect_b32 s25, s30, 0
	s_cselect_b32 s24, s47, 0
	s_add_u32 s25, s22, s25
	s_addc_u32 s24, s23, s24
	s_add_u32 s59, s25, 0x80
	s_addc_u32 s24, s24, 0
	s_add_i32 s64, 0, 0x10000
	s_cmp_eq_u32 s46, s58
	s_cselect_b32 s25, s5, s24
	s_cselect_b32 s24, s4, s59
	s_cselect_b32 s63, s21, s55
	s_cselect_b32 s62, s20, s54
	s_add_i32 s59, 0, 0x14000
	v_add_u32_e32 v160, s64, v142
	v_add_u32_e32 v176, s59, v142
	ds_read_b128 v[148:151], v160
	ds_read_b128 v[152:155], v160 offset:1024
	ds_read_b128 v[156:159], v160 offset:2048
	ds_read_b128 v[160:163], v160 offset:3072
	ds_read_b128 v[164:167], v176
	ds_read_b128 v[168:171], v176 offset:1024
	ds_read_b128 v[172:175], v176 offset:2048
	ds_read_b128 v[176:179], v176 offset:3072
	v_lshl_add_u64 v[192:193], s[22:23], 0, v[140:141]
	v_lshl_add_u64 v[192:193], v[192:193], 0, s[60:61]
	s_add_i32 m0, s40, 0xc000
	ds_read_b128 v[180:183], v147
	ds_read_b128 v[184:187], v147 offset:1024
	ds_read_b128 v[188:191], v147 offset:2048
	ds_read_b128 v[204:207], v147 offset:3072
	ds_read_b128 v[208:211], v147 offset:4096
	ds_read_b128 v[212:215], v147 offset:5120
	ds_read_b128 v[216:219], v147 offset:6144
	ds_read_b128 v[220:223], v147 offset:7168
	global_load_lds_dwordx4 v[192:193], off
	v_lshl_add_u64 v[192:193], s[22:23], 0, v[138:139]
	v_lshl_add_u64 v[192:193], v[192:193], 0, s[60:61]
	s_add_i32 m0, s40, 0xe000
	s_nop 0
	global_load_lds_dwordx4 v[192:193], off
	s_waitcnt vmcnt(8)
	s_waitcnt lgkmcnt(0)
	s_barrier
	s_setprio 1
	s_waitcnt lgkmcnt(0)
	s_nop 0
	v_mfma_f32_16x16x32_bf16 v[124:127], v[148:151], v[180:183], v[124:127]
	v_mfma_f32_16x16x32_bf16 v[120:123], v[156:159], v[180:183], v[120:123]
	v_mfma_f32_16x16x32_bf16 v[112:115], v[148:151], v[188:191], v[112:115]
	v_mfma_f32_16x16x32_bf16 v[104:107], v[156:159], v[188:191], v[104:107]
	v_mfma_f32_16x16x32_bf16 v[96:99], v[148:151], v[208:211], v[96:99]
	v_mfma_f32_16x16x32_bf16 v[88:91], v[156:159], v[208:211], v[88:91]
	v_mfma_f32_16x16x32_bf16 v[80:83], v[148:151], v[216:219], v[80:83]
	v_mfma_f32_16x16x32_bf16 v[72:75], v[156:159], v[216:219], v[72:75]
	v_mfma_f32_16x16x32_bf16 v[124:127], v[152:155], v[184:187], v[124:127]
	v_mfma_f32_16x16x32_bf16 v[120:123], v[160:163], v[184:187], v[120:123]
	v_mfma_f32_16x16x32_bf16 v[112:115], v[152:155], v[204:207], v[112:115]
	v_mfma_f32_16x16x32_bf16 v[104:107], v[160:163], v[204:207], v[104:107]
	v_mfma_f32_16x16x32_bf16 v[96:99], v[152:155], v[212:215], v[96:99]
	v_mfma_f32_16x16x32_bf16 v[88:91], v[160:163], v[212:215], v[88:91]
	v_mfma_f32_16x16x32_bf16 v[80:83], v[152:155], v[220:223], v[80:83]
	v_mfma_f32_16x16x32_bf16 v[72:75], v[160:163], v[220:223], v[72:75]
	s_setprio 0
	s_setprio 1
	v_mfma_f32_16x16x32_bf16 v[128:131], v[164:167], v[180:183], v[128:131]
	v_mfma_f32_16x16x32_bf16 v[116:119], v[172:175], v[180:183], v[116:119]
	v_mfma_f32_16x16x32_bf16 v[108:111], v[164:167], v[188:191], v[108:111]
	v_mfma_f32_16x16x32_bf16 v[100:103], v[172:175], v[188:191], v[100:103]
	v_mfma_f32_16x16x32_bf16 v[92:95], v[164:167], v[208:211], v[92:95]
	v_mfma_f32_16x16x32_bf16 v[84:87], v[172:175], v[208:211], v[84:87]
	v_mfma_f32_16x16x32_bf16 v[76:79], v[164:167], v[216:219], v[76:79]
	v_mfma_f32_16x16x32_bf16 v[68:71], v[172:175], v[216:219], v[68:71]
	v_mfma_f32_16x16x32_bf16 v[128:131], v[168:171], v[184:187], v[128:131]
	v_mfma_f32_16x16x32_bf16 v[116:119], v[176:179], v[184:187], v[116:119]
	v_mfma_f32_16x16x32_bf16 v[108:111], v[168:171], v[204:207], v[108:111]
	v_mfma_f32_16x16x32_bf16 v[100:103], v[176:179], v[204:207], v[100:103]
	v_mfma_f32_16x16x32_bf16 v[92:95], v[168:171], v[212:215], v[92:95]
	v_mfma_f32_16x16x32_bf16 v[84:87], v[176:179], v[212:215], v[84:87]
	v_mfma_f32_16x16x32_bf16 v[76:79], v[168:171], v[220:223], v[76:79]
	v_mfma_f32_16x16x32_bf16 v[68:71], v[176:179], v[220:223], v[68:71]
	s_setprio 0
	s_barrier
	s_add_i32 s60, s64, s36
	v_lshl_add_u64 v[192:193], s[62:63], 0, v[134:135]
	s_mov_b32 m0, s60
	ds_read_b128 v[180:183], v147 offset:16384
	ds_read_b128 v[184:187], v147 offset:17408
	ds_read_b128 v[188:191], v147 offset:18432
	ds_read_b128 v[204:207], v147 offset:19456
	ds_read_b128 v[208:211], v147 offset:20480
	ds_read_b128 v[212:215], v147 offset:21504
	ds_read_b128 v[216:219], v147 offset:22528
	ds_read_b128 v[220:223], v147 offset:23552
	global_load_lds_dwordx4 v[192:193], off
	s_add_i32 m0, s60, 0x2000
	s_add_u32 s60, s62, s6
	v_lshl_add_u64 v[196:197], s[62:63], 0, v[0:1]
	s_addc_u32 s61, s63, s7
	s_add_i32 s59, s59, s36
	global_load_lds_dwordx4 v[196:197], off
	v_lshl_add_u64 v[198:199], s[60:61], 0, v[134:135]
	s_mov_b32 m0, s59
	v_lshl_add_u64 v[200:201], s[60:61], 0, v[0:1]
	global_load_lds_dwordx4 v[198:199], off
	s_add_i32 m0, s59, 0x2000
	v_lshl_add_u64 v[202:203], s[24:25], 0, v[136:137]
	global_load_lds_dwordx4 v[200:201], off
	s_mov_b32 m0, s40
	v_lshl_add_u64 v[228:229], s[24:25], 0, v[132:133]
	global_load_lds_dwordx4 v[202:203], off
	s_mov_b32 m0, s41
	s_nop 0
	global_load_lds_dwordx4 v[228:229], off
	s_waitcnt vmcnt(8)
	s_waitcnt lgkmcnt(0)
	s_barrier
; #define PG8_STAGE(bufoff, gbase, voff) do { _Pragma("unroll") for (int _i = 0; _i < 2; ++_i) \
;         __builtin_amdgcn_global_load_lds((const unsigned*)((const char*)(gbase) + (voff)[_i]), (PG8_LAS unsigned*)(lds + (bufoff) + ldsw + _i * 8192), 16, 0, 0); } while (0)
; #define PG8_LDA(dst, b, h) do { _Pragma("unroll") for (int m = 0; m < 4; ++m) _Pragma("unroll") for (int k = 0; k < 2; ++k) dst[m][k] = *(const PG8_LAS bf16x8*)(lds + PG8_SA(b, h) + aoff + m * 2048 + k * 1024); } while (0)
; #define PG8_LDB(dst, b, h) do { _Pragma("unroll") for (int n = 0; n < 2; ++n) _Pragma("unroll") for (int k = 0; k < 2; ++k) dst[n][k] = *(const PG8_LAS bf16x8*)(lds + PG8_SB(b, h) + boff + n * 2048 + k * 1024); } while (0)
; #define PG8_MMA(ai, bj, At, Bt) do { __builtin_amdgcn_s_setprio(1); _Pragma("unroll") for (int m = 0; m < 4; ++m) _Pragma("unroll") for (int n = 0; n < 2; ++n) _Pragma("unroll") for (int k = 0; k < 2; ++k) \
;         acc[ai][bj][m][n] = __builtin_amdgcn_mfma_f32_16x16x32_bf16(Bt[n][k], At[m][k], acc[ai][bj][m][n], 0, 0, 0); __builtin_amdgcn_s_setprio(0); } while (0)
; #define PG8_WAIT_V(n) asm volatile("s_waitcnt vmcnt(" #n ")" ::: "memory")
; #define PG8_WAIT_L(n) asm volatile("s_waitcnt lgkmcnt(" #n ")" ::: "memory")
; #define PG8_BAR __builtin_amdgcn_s_barrier()
; #define PG8_SCHED __builtin_amdgcn_sched_barrier(0)
; template <class Epi, class Sched, bool ALIGN_EPI = false, bool SP2 = false>
; __device__ __forceinline__ void gemm_phase(PG8_LAS unsigned char* lds, const Gemm g, const Sched& S, const Epi& E, int tid_in) {
;     ...
;             PG8_WAIT_V(8); PG8_WAIT_L(0); PG8_BAR; PG8_MMA(1, 0, At, B0); PG8_MMA(1, 1, At, B1); PG8_BAR; PG8_SCHED;
;             PG8_LDB(B0, 1, 0); PG8_LDB(B1, 1, 1); PG8_SCHED; PG8_LDA(At, 1, 0); PG8_STAGE(PG8_SA(0, 1), a2 + hsA, voffA);
;             PG8_WAIT_V(8); PG8_WAIT_L(0); PG8_BAR; PG8_MMA(0, 0, At, B0); PG8_MMA(0, 1, At, B1); PG8_BAR; PG8_SCHED;
	s_setprio 1
	s_waitcnt lgkmcnt(0)
	v_mfma_f32_16x16x32_bf16 v[64:67], v[148:151], v[180:183], v[64:67]
	v_mfma_f32_16x16x32_bf16 v[56:59], v[156:159], v[180:183], v[56:59]
	v_mfma_f32_16x16x32_bf16 v[48:51], v[148:151], v[188:191], v[48:51]
	v_mfma_f32_16x16x32_bf16 v[40:43], v[156:159], v[188:191], v[40:43]
	v_mfma_f32_16x16x32_bf16 v[32:35], v[148:151], v[208:211], v[32:35]
	v_mfma_f32_16x16x32_bf16 v[24:27], v[156:159], v[208:211], v[24:27]
	v_mfma_f32_16x16x32_bf16 v[16:19], v[148:151], v[216:219], v[16:19]
	v_mfma_f32_16x16x32_bf16 v[8:11], v[156:159], v[216:219], v[8:11]
	v_mfma_f32_16x16x32_bf16 v[64:67], v[152:155], v[184:187], v[64:67]
	v_mfma_f32_16x16x32_bf16 v[56:59], v[160:163], v[184:187], v[56:59]
	v_mfma_f32_16x16x32_bf16 v[48:51], v[152:155], v[204:207], v[48:51]
	v_mfma_f32_16x16x32_bf16 v[40:43], v[160:163], v[204:207], v[40:43]
	v_mfma_f32_16x16x32_bf16 v[32:35], v[152:155], v[212:215], v[32:35]
	v_mfma_f32_16x16x32_bf16 v[24:27], v[160:163], v[212:215], v[24:27]
	v_mfma_f32_16x16x32_bf16 v[16:19], v[152:155], v[220:223], v[16:19]
	v_mfma_f32_16x16x32_bf16 v[8:11], v[160:163], v[220:223], v[8:11]
	s_setprio 0
	s_setprio 1
	v_mfma_f32_16x16x32_bf16 v[60:63], v[164:167], v[180:183], v[60:63]
	v_mfma_f32_16x16x32_bf16 v[52:55], v[172:175], v[180:183], v[52:55]
	v_mfma_f32_16x16x32_bf16 v[44:47], v[164:167], v[188:191], v[44:47]
	v_mfma_f32_16x16x32_bf16 v[36:39], v[172:175], v[188:191], v[36:39]
	v_mfma_f32_16x16x32_bf16 v[28:31], v[164:167], v[208:211], v[28:31]
	v_mfma_f32_16x16x32_bf16 v[20:23], v[172:175], v[208:211], v[20:23]
	v_mfma_f32_16x16x32_bf16 v[12:15], v[164:167], v[216:219], v[12:15]
	v_mfma_f32_16x16x32_bf16 v[4:7], v[172:175], v[216:219], v[4:7]
	v_mfma_f32_16x16x32_bf16 v[60:63], v[168:171], v[184:187], v[60:63]
	v_mfma_f32_16x16x32_bf16 v[52:55], v[176:179], v[184:187], v[52:55]
	v_mfma_f32_16x16x32_bf16 v[44:47], v[168:171], v[204:207], v[44:47]
	v_mfma_f32_16x16x32_bf16 v[36:39], v[176:179], v[204:207], v[36:39]
	v_mfma_f32_16x16x32_bf16 v[28:31], v[168:171], v[212:215], v[28:31]
	v_mfma_f32_16x16x32_bf16 v[20:23], v[176:179], v[212:215], v[20:23]
	v_mfma_f32_16x16x32_bf16 v[12:15], v[168:171], v[220:223], v[12:15]
	v_mfma_f32_16x16x32_bf16 v[4:7], v[176:179], v[220:223], v[4:7]
	s_setprio 0
	s_barrier
	s_add_i32 s59, 0, 0x18000
	s_add_i32 s60, 0, 0x1c000
	v_add_u32_e32 v160, s59, v142
	v_add_u32_e32 v176, s60, v142
	ds_read_b128 v[148:151], v160
	ds_read_b128 v[152:155], v160 offset:1024
	ds_read_b128 v[156:159], v160 offset:2048
	ds_read_b128 v[160:163], v160 offset:3072
	ds_read_b128 v[164:167], v176
	ds_read_b128 v[168:171], v176 offset:1024
	ds_read_b128 v[172:175], v176 offset:2048
	ds_read_b128 v[176:179], v176 offset:3072
	s_add_u32 s24, s24, s0
	s_addc_u32 s25, s25, s1
	s_mov_b32 m0, s42
	v_lshl_add_u64 v[230:231], s[24:25], 0, v[136:137]
	ds_read_b128 v[180:183], v147 offset:32768
	ds_read_b128 v[184:187], v147 offset:33792
	ds_read_b128 v[188:191], v147 offset:34816
	ds_read_b128 v[204:207], v147 offset:35840
	ds_read_b128 v[208:211], v147 offset:36864
	ds_read_b128 v[212:215], v147 offset:37888
	ds_read_b128 v[216:219], v147 offset:38912
	ds_read_b128 v[220:223], v147 offset:39936
	global_load_lds_dwordx4 v[230:231], off
	v_lshl_add_u64 v[230:231], s[24:25], 0, v[132:133]
	s_mov_b32 m0, s43
	s_nop 0
	global_load_lds_dwordx4 v[230:231], off
	s_waitcnt vmcnt(8)
	s_waitcnt lgkmcnt(0)
	s_barrier
	s_setprio 1
	s_waitcnt lgkmcnt(0)
	v_mfma_f32_16x16x32_bf16 v[124:127], v[148:151], v[180:183], v[124:127]
	v_mfma_f32_16x16x32_bf16 v[120:123], v[156:159], v[180:183], v[120:123]
	v_mfma_f32_16x16x32_bf16 v[112:115], v[148:151], v[188:191], v[112:115]
	v_mfma_f32_16x16x32_bf16 v[104:107], v[156:159], v[188:191], v[104:107]
	v_mfma_f32_16x16x32_bf16 v[96:99], v[148:151], v[208:211], v[96:99]
	v_mfma_f32_16x16x32_bf16 v[88:91], v[156:159], v[208:211], v[88:91]
	v_mfma_f32_16x16x32_bf16 v[80:83], v[148:151], v[216:219], v[80:83]
	v_mfma_f32_16x16x32_bf16 v[72:75], v[156:159], v[216:219], v[72:75]
	v_mfma_f32_16x16x32_bf16 v[124:127], v[152:155], v[184:187], v[124:127]
	v_mfma_f32_16x16x32_bf16 v[120:123], v[160:163], v[184:187], v[120:123]
	v_mfma_f32_16x16x32_bf16 v[112:115], v[152:155], v[204:207], v[112:115]
	v_mfma_f32_16x16x32_bf16 v[104:107], v[160:163], v[204:207], v[104:107]
	v_mfma_f32_16x16x32_bf16 v[96:99], v[152:155], v[212:215], v[96:99]
	v_mfma_f32_16x16x32_bf16 v[88:91], v[160:163], v[212:215], v[88:91]
	v_mfma_f32_16x16x32_bf16 v[80:83], v[152:155], v[220:223], v[80:83]
	v_mfma_f32_16x16x32_bf16 v[72:75], v[160:163], v[220:223], v[72:75]
	s_setprio 0
	s_setprio 1
	v_mfma_f32_16x16x32_bf16 v[128:131], v[164:167], v[180:183], v[128:131]
	v_mfma_f32_16x16x32_bf16 v[116:119], v[172:175], v[180:183], v[116:119]
	v_mfma_f32_16x16x32_bf16 v[108:111], v[164:167], v[188:191], v[108:111]
	v_mfma_f32_16x16x32_bf16 v[100:103], v[172:175], v[188:191], v[100:103]
	v_mfma_f32_16x16x32_bf16 v[92:95], v[164:167], v[208:211], v[92:95]
	v_mfma_f32_16x16x32_bf16 v[84:87], v[172:175], v[208:211], v[84:87]
	v_mfma_f32_16x16x32_bf16 v[76:79], v[164:167], v[216:219], v[76:79]
	v_mfma_f32_16x16x32_bf16 v[68:71], v[172:175], v[216:219], v[68:71]
	v_mfma_f32_16x16x32_bf16 v[128:131], v[168:171], v[184:187], v[128:131]
	v_mfma_f32_16x16x32_bf16 v[116:119], v[176:179], v[184:187], v[116:119]
	v_mfma_f32_16x16x32_bf16 v[108:111], v[168:171], v[204:207], v[108:111]
	v_mfma_f32_16x16x32_bf16 v[100:103], v[176:179], v[204:207], v[100:103]
	v_mfma_f32_16x16x32_bf16 v[92:95], v[168:171], v[212:215], v[92:95]
	v_mfma_f32_16x16x32_bf16 v[84:87], v[176:179], v[212:215], v[84:87]
	v_mfma_f32_16x16x32_bf16 v[76:79], v[168:171], v[220:223], v[76:79]
	v_mfma_f32_16x16x32_bf16 v[68:71], v[176:179], v[220:223], v[68:71]
	s_setprio 0
	s_barrier
; #define PG8_STAGE(bufoff, gbase, voff) do { _Pragma("unroll") for (int _i = 0; _i < 2; ++_i) \
;         __builtin_amdgcn_global_load_lds((const unsigned*)((const char*)(gbase) + (voff)[_i]), (PG8_LAS unsigned*)(lds + (bufoff) + ldsw + _i * 8192), 16, 0, 0); } while (0)
; #define PG8_LDA(dst, b, h) do { _Pragma("unroll") for (int m = 0; m < 4; ++m) _Pragma("unroll") for (int k = 0; k < 2; ++k) dst[m][k] = *(const PG8_LAS bf16x8*)(lds + PG8_SA(b, h) + aoff + m * 2048 + k * 1024); } while (0)
; #define PG8_MMA(ai, bj, At, Bt) do { __builtin_amdgcn_s_setprio(1); _Pragma("unroll") for (int m = 0; m < 4; ++m) _Pragma("unroll") for (int n = 0; n < 2; ++n) _Pragma("unroll") for (int k = 0; k < 2; ++k) \
;         acc[ai][bj][m][n] = __builtin_amdgcn_mfma_f32_16x16x32_bf16(Bt[n][k], At[m][k], acc[ai][bj][m][n], 0, 0, 0); __builtin_amdgcn_s_setprio(0); } while (0)
; #define PG8_WAIT_V(n) asm volatile("s_waitcnt vmcnt(" #n ")" ::: "memory")
; #define PG8_WAIT_L(n) asm volatile("s_waitcnt lgkmcnt(" #n ")" ::: "memory")
; #define PG8_BAR __builtin_amdgcn_s_barrier()
; #define PG8_SCHED __builtin_amdgcn_sched_barrier(0)
; template <class Epi, class Sched, bool ALIGN_EPI = false, bool SP2 = false>
; __device__ __forceinline__ void gemm_phase(PG8_LAS unsigned char* lds, const Gemm g, const Sched& S, const Epi& E, int tid_in) {
;     ...
;             PG8_LDA(At, 1, 1); PG8_STAGE(PG8_SB(1, 0), b3, voffB); PG8_STAGE(PG8_SB(1, 1), b3 + hsB, voffB); PG8_STAGE(PG8_SA(1, 0), a3, voffA);
;             PG8_WAIT_V(8); PG8_WAIT_L(0); PG8_BAR; PG8_MMA(1, 0, At, B0); PG8_MMA(1, 1, At, B1); PG8_BAR; PG8_SCHED;
	s_add_i32 s24, s59, s36
	v_lshl_add_u64 v[192:193], v[192:193], 0, s[80:81]
	s_mov_b32 m0, s24
	ds_read_b128 v[180:183], v147 offset:49152
	ds_read_b128 v[184:187], v147 offset:50176
	ds_read_b128 v[188:191], v147 offset:51200
	ds_read_b128 v[204:207], v147 offset:52224
	ds_read_b128 v[208:211], v147 offset:53248
	ds_read_b128 v[212:215], v147 offset:54272
	ds_read_b128 v[216:219], v147 offset:55296
	ds_read_b128 v[220:223], v147 offset:56320
	global_load_lds_dwordx4 v[192:193], off
	v_lshl_add_u64 v[192:193], v[196:197], 0, s[80:81]
	s_add_i32 m0, s24, 0x2000
	s_add_i32 s24, s60, s36
	global_load_lds_dwordx4 v[192:193], off
	v_lshl_add_u64 v[192:193], v[198:199], 0, s[80:81]
	s_mov_b32 m0, s24
	s_nop 0
	global_load_lds_dwordx4 v[192:193], off
	v_lshl_add_u64 v[192:193], v[200:201], 0, s[80:81]
	s_add_i32 m0, s24, 0x2000
	s_nop 0
	global_load_lds_dwordx4 v[192:193], off
	v_lshl_add_u64 v[192:193], v[202:203], 0, s[80:81]
	s_mov_b32 m0, s44
	s_nop 0
	global_load_lds_dwordx4 v[192:193], off
	v_lshl_add_u64 v[192:193], v[228:229], 0, s[80:81]
	s_mov_b32 m0, s45
	s_nop 0
	global_load_lds_dwordx4 v[192:193], off
	s_waitcnt vmcnt(8)
	s_waitcnt lgkmcnt(0)
	s_barrier
	s_setprio 1
	s_waitcnt lgkmcnt(0)
	s_nop 0
	v_mfma_f32_16x16x32_bf16 v[64:67], v[148:151], v[180:183], v[64:67]
	v_mfma_f32_16x16x32_bf16 v[56:59], v[156:159], v[180:183], v[56:59]
	v_mfma_f32_16x16x32_bf16 v[48:51], v[148:151], v[188:191], v[48:51]
	v_mfma_f32_16x16x32_bf16 v[40:43], v[156:159], v[188:191], v[40:43]
	v_mfma_f32_16x16x32_bf16 v[32:35], v[148:151], v[208:211], v[32:35]
	v_mfma_f32_16x16x32_bf16 v[24:27], v[156:159], v[208:211], v[24:27]
	v_mfma_f32_16x16x32_bf16 v[16:19], v[148:151], v[216:219], v[16:19]
	v_mfma_f32_16x16x32_bf16 v[8:11], v[156:159], v[216:219], v[8:11]
	v_mfma_f32_16x16x32_bf16 v[64:67], v[152:155], v[184:187], v[64:67]
	v_mfma_f32_16x16x32_bf16 v[56:59], v[160:163], v[184:187], v[56:59]
	v_mfma_f32_16x16x32_bf16 v[48:51], v[152:155], v[204:207], v[48:51]
	v_mfma_f32_16x16x32_bf16 v[40:43], v[160:163], v[204:207], v[40:43]
	v_mfma_f32_16x16x32_bf16 v[32:35], v[152:155], v[212:215], v[32:35]
	v_mfma_f32_16x16x32_bf16 v[24:27], v[160:163], v[212:215], v[24:27]
	v_mfma_f32_16x16x32_bf16 v[16:19], v[152:155], v[220:223], v[16:19]
	v_mfma_f32_16x16x32_bf16 v[8:11], v[160:163], v[220:223], v[8:11]
	s_setprio 0
	s_setprio 1
	v_mfma_f32_16x16x32_bf16 v[60:63], v[164:167], v[180:183], v[60:63]
	v_mfma_f32_16x16x32_bf16 v[52:55], v[172:175], v[180:183], v[52:55]
	v_mfma_f32_16x16x32_bf16 v[44:47], v[164:167], v[188:191], v[44:47]
	v_mfma_f32_16x16x32_bf16 v[36:39], v[172:175], v[188:191], v[36:39]
	v_mfma_f32_16x16x32_bf16 v[28:31], v[164:167], v[208:211], v[28:31]
	v_mfma_f32_16x16x32_bf16 v[20:23], v[172:175], v[208:211], v[20:23]
	v_mfma_f32_16x16x32_bf16 v[12:15], v[164:167], v[216:219], v[12:15]
	v_mfma_f32_16x16x32_bf16 v[4:7], v[172:175], v[216:219], v[4:7]
	v_mfma_f32_16x16x32_bf16 v[60:63], v[168:171], v[184:187], v[60:63]
	v_mfma_f32_16x16x32_bf16 v[52:55], v[176:179], v[184:187], v[52:55]
	v_mfma_f32_16x16x32_bf16 v[44:47], v[168:171], v[204:207], v[44:47]
	v_mfma_f32_16x16x32_bf16 v[36:39], v[176:179], v[204:207], v[36:39]
	v_mfma_f32_16x16x32_bf16 v[28:31], v[168:171], v[212:215], v[28:31]
	v_mfma_f32_16x16x32_bf16 v[20:23], v[176:179], v[212:215], v[20:23]
	v_mfma_f32_16x16x32_bf16 v[12:15], v[168:171], v[220:223], v[12:15]
	v_mfma_f32_16x16x32_bf16 v[4:7], v[176:179], v[220:223], v[4:7]
	s_setprio 0
	s_barrier
	s_add_i32 s24, s58, 2
	s_add_u32 s54, s54, 0x100
	s_addc_u32 s55, s55, 0
	s_add_u32 s22, s22, 0x100
	s_addc_u32 s23, s23, 0
	s_cmp_ge_i32 s58, s46
	s_mov_b32 s58, s24
	s_cbranch_scc0 .LBB0_1255

; #define PG8_STAGE(bufoff, gbase, voff) do { _Pragma("unroll") for (int _i = 0; _i < 2; ++_i) \
;         __builtin_amdgcn_global_load_lds((const unsigned*)((const char*)(gbase) + (voff)[_i]), (PG8_LAS unsigned*)(lds + (bufoff) + ldsw + _i * 8192), 16, 0, 0); } while (0)
; #define PG8_LDA(dst, b, h) do { _Pragma("unroll") for (int m = 0; m < 4; ++m) _Pragma("unroll") for (int k = 0; k < 2; ++k) dst[m][k] = *(const PG8_LAS bf16x8*)(lds + PG8_SA(b, h) + aoff + m * 2048 + k * 1024); } while (0)
; #define PG8_LDB(dst, b, h) do { _Pragma("unroll") for (int n = 0; n < 2; ++n) _Pragma("unroll") for (int k = 0; k < 2; ++k) dst[n][k] = *(const PG8_LAS bf16x8*)(lds + PG8_SB(b, h) + boff + n * 2048 + k * 1024); } while (0)
; #define PG8_MMA(ai, bj, At, Bt) do { __builtin_amdgcn_s_setprio(1); _Pragma("unroll") for (int m = 0; m < 4; ++m) _Pragma("unroll") for (int n = 0; n < 2; ++n) _Pragma("unroll") for (int k = 0; k < 2; ++k) \
;         acc[ai][bj][m][n] = __builtin_amdgcn_mfma_f32_16x16x32_bf16(Bt[n][k], At[m][k], acc[ai][bj][m][n], 0, 0, 0); __builtin_amdgcn_s_setprio(0); } while (0)
; #define PG8_WAIT_V(n) asm volatile("s_waitcnt vmcnt(" #n ")" ::: "memory")
; template <class Epi, class Sched, bool ALIGN_EPI = false, bool SP2 = false>
; __device__ __forceinline__ void gemm_phase(PG8_LAS unsigned char* lds, const Gemm g, const Sched& S, const Epi& E, int tid_in) {
;     ...
;         for (int t = 0; t < nt; t += 2) {
;             const bool last = (t == nt - 2);
;             if constexpr (mid_hook<Epi>::value) { if (t == Epi::H1 || t == Epi::H2) E.mid(acc, cur, wr, wc, fr, fq, t == Epi::H2); }
;             const char* a1 = cA + (size_t)(t + 1) * kstep + (t >= jt ? jb : 0);
;             const char* a2 = last ? nA : cA + (size_t)(t + 2) * kstep + (t + 2 >= jt ? jb : 0); const char* b2 = last ? nB : cB + (size_t)(t + 2) * kstep;
;             const char* a3 = a2 + kstep; const char* b3 = b2 + kstep;
;             if (last && has_next) S.a_ready(nxt);
;             if constexpr (SP2) {
;             PG8_LDB(B0, 0, 0); PG8_LDB(B1, 0, 1); PG8_SCHED; PG8_LDA(At, 0, 0); PG8_STAGE(PG8_SA(1, 1), a1 + hsA, voffA);
;             PG8_WAIT_V(8); PG8_WAIT_L(0); PG8_BAR; PG8_MMA(0, 0, At, B0); PG8_MMA(0, 1, At, B1); PG8_BAR; PG8_SCHED;
;             PG8_LDA(At, 0, 1); PG8_STAGE(PG8_SB(0, 0), b2, voffB); PG8_STAGE(PG8_SB(0, 1), b2 + hsB, voffB); PG8_STAGE(PG8_SA(0, 0), a2, voffA);
.LBB0_1331:
	s_add_i32 s38, s40, -2
	s_cmp_ge_i32 s38, s33
	s_cselect_b32 s76, s46, 0
	s_cselect_b32 s77, s61, 0
	s_cmp_ge_i32 s40, s33
	s_cselect_b32 s39, s46, 0
	s_cselect_b32 s38, s61, 0
	s_add_u32 s39, s4, s39
	s_addc_u32 s38, s5, s38
	s_add_u32 s41, s39, 0x80
	s_addc_u32 s38, s38, 0
	s_add_i32 s82, 0, 0x10000
	s_cmp_eq_u32 s60, s40
	s_cselect_b32 s39, s35, s38
	s_cselect_b32 s38, s34, s41
	s_cselect_b32 s79, s37, s75
	s_cselect_b32 s78, s36, s74
	s_add_i32 s41, 0, 0x14000
	v_add_u32_e32 v144, s82, v217
	v_add_u32_e32 v170, s41, v217
	ds_read_b128 v[132:135], v144
	ds_read_b128 v[136:139], v144 offset:1024
	ds_read_b128 v[140:143], v144 offset:2048
	ds_read_b128 v[144:147], v144 offset:3072
	ds_read_b128 v[148:151], v170
	ds_read_b128 v[162:165], v170 offset:1024
	ds_read_b128 v[166:169], v170 offset:2048
	ds_read_b128 v[170:173], v170 offset:3072
	v_lshl_add_u64 v[190:191], s[4:5], 0, v[160:161]
	v_lshl_add_u64 v[190:191], v[190:191], 0, s[76:77]
	s_add_i32 m0, s50, 0xc000
	ds_read_b128 v[174:177], v219
	ds_read_b128 v[178:181], v219 offset:1024
	ds_read_b128 v[182:185], v219 offset:2048
	ds_read_b128 v[186:189], v219 offset:3072
	ds_read_b128 v[204:207], v219 offset:4096
	ds_read_b128 v[208:211], v219 offset:5120
	ds_read_b128 v[212:215], v219 offset:6144
	ds_read_b128 v[220:223], v219 offset:7168
	global_load_lds_dwordx4 v[190:191], off
	v_lshl_add_u64 v[190:191], s[4:5], 0, v[158:159]
	v_lshl_add_u64 v[190:191], v[190:191], 0, s[76:77]
	s_add_i32 m0, s50, 0xe000
	s_nop 0
	global_load_lds_dwordx4 v[190:191], off
	s_waitcnt vmcnt(8)
	s_waitcnt lgkmcnt(0)
	s_barrier
	s_setprio 1
	s_waitcnt lgkmcnt(0)
	v_mfma_f32_16x16x32_bf16 v[128:131], v[132:135], v[174:177], v[128:131]
	v_mfma_f32_16x16x32_bf16 v[124:127], v[140:143], v[174:177], v[124:127]
	v_mfma_f32_16x16x32_bf16 v[120:123], v[132:135], v[182:185], v[120:123]
	v_mfma_f32_16x16x32_bf16 v[116:119], v[140:143], v[182:185], v[116:119]
	v_mfma_f32_16x16x32_bf16 v[112:115], v[132:135], v[204:207], v[112:115]
	v_mfma_f32_16x16x32_bf16 v[108:111], v[140:143], v[204:207], v[108:111]
	v_mfma_f32_16x16x32_bf16 v[104:107], v[132:135], v[212:215], v[104:107]
	v_mfma_f32_16x16x32_bf16 v[100:103], v[140:143], v[212:215], v[100:103]
	v_mfma_f32_16x16x32_bf16 v[128:131], v[136:139], v[178:181], v[128:131]
	v_mfma_f32_16x16x32_bf16 v[124:127], v[144:147], v[178:181], v[124:127]
	v_mfma_f32_16x16x32_bf16 v[120:123], v[136:139], v[186:189], v[120:123]
	v_mfma_f32_16x16x32_bf16 v[116:119], v[144:147], v[186:189], v[116:119]
	v_mfma_f32_16x16x32_bf16 v[112:115], v[136:139], v[208:211], v[112:115]
	v_mfma_f32_16x16x32_bf16 v[108:111], v[144:147], v[208:211], v[108:111]
	v_mfma_f32_16x16x32_bf16 v[104:107], v[136:139], v[220:223], v[104:107]
	v_mfma_f32_16x16x32_bf16 v[100:103], v[144:147], v[220:223], v[100:103]
	s_setprio 0
	s_setprio 1
	v_mfma_f32_16x16x32_bf16 v[64:67], v[148:151], v[174:177], v[64:67]
	v_mfma_f32_16x16x32_bf16 v[56:59], v[166:169], v[174:177], v[56:59]
	v_mfma_f32_16x16x32_bf16 v[60:63], v[148:151], v[182:185], v[60:63]
	v_mfma_f32_16x16x32_bf16 v[52:55], v[166:169], v[182:185], v[52:55]
	v_mfma_f32_16x16x32_bf16 v[48:51], v[148:151], v[204:207], v[48:51]
	v_mfma_f32_16x16x32_bf16 v[40:43], v[166:169], v[204:207], v[40:43]
	v_mfma_f32_16x16x32_bf16 v[44:47], v[148:151], v[212:215], v[44:47]
	v_mfma_f32_16x16x32_bf16 v[36:39], v[166:169], v[212:215], v[36:39]
	v_mfma_f32_16x16x32_bf16 v[64:67], v[162:165], v[178:181], v[64:67]
	v_mfma_f32_16x16x32_bf16 v[56:59], v[170:173], v[178:181], v[56:59]
	v_mfma_f32_16x16x32_bf16 v[60:63], v[162:165], v[186:189], v[60:63]
	v_mfma_f32_16x16x32_bf16 v[52:55], v[170:173], v[186:189], v[52:55]
	v_mfma_f32_16x16x32_bf16 v[48:51], v[162:165], v[208:211], v[48:51]
	v_mfma_f32_16x16x32_bf16 v[40:43], v[170:173], v[208:211], v[40:43]
	v_mfma_f32_16x16x32_bf16 v[44:47], v[162:165], v[220:223], v[44:47]
	v_mfma_f32_16x16x32_bf16 v[36:39], v[170:173], v[220:223], v[36:39]
	s_setprio 0
	s_barrier
	s_add_i32 s76, s82, s49
	v_lshl_add_u64 v[190:191], s[78:79], 0, v[152:153]
	s_mov_b32 m0, s76
	ds_read_b128 v[174:177], v219 offset:16384
	ds_read_b128 v[178:181], v219 offset:17408
	ds_read_b128 v[182:185], v219 offset:18432
	ds_read_b128 v[186:189], v219 offset:19456
	ds_read_b128 v[204:207], v219 offset:20480
	ds_read_b128 v[208:211], v219 offset:21504
	ds_read_b128 v[212:215], v219 offset:22528
	ds_read_b128 v[220:223], v219 offset:23552
	global_load_lds_dwordx4 v[190:191], off
	s_add_i32 m0, s76, 0x2000
	s_add_u32 s76, s78, s12
	v_lshl_add_u64 v[192:193], s[78:79], 0, v[156:157]
	s_addc_u32 s77, s79, s13
	s_add_i32 s41, s41, s49
	global_load_lds_dwordx4 v[192:193], off
	v_lshl_add_u64 v[196:197], s[76:77], 0, v[152:153]
	s_mov_b32 m0, s41
	v_lshl_add_u64 v[198:199], s[76:77], 0, v[156:157]
	global_load_lds_dwordx4 v[196:197], off
	s_add_i32 m0, s41, 0x2000
	v_lshl_add_u64 v[200:201], s[38:39], 0, v[0:1]
	global_load_lds_dwordx4 v[198:199], off
	s_mov_b32 m0, s50
	v_lshl_add_u64 v[202:203], s[38:39], 0, v[154:155]
	global_load_lds_dwordx4 v[200:201], off
	s_mov_b32 m0, s51
	s_nop 0
	global_load_lds_dwordx4 v[202:203], off
	s_waitcnt vmcnt(8)
	s_waitcnt lgkmcnt(0)
	s_barrier
; #define PG8_STAGE(bufoff, gbase, voff) do { _Pragma("unroll") for (int _i = 0; _i < 2; ++_i) \
;         __builtin_amdgcn_global_load_lds((const unsigned*)((const char*)(gbase) + (voff)[_i]), (PG8_LAS unsigned*)(lds + (bufoff) + ldsw + _i * 8192), 16, 0, 0); } while (0)
; #define PG8_LDA(dst, b, h) do { _Pragma("unroll") for (int m = 0; m < 4; ++m) _Pragma("unroll") for (int k = 0; k < 2; ++k) dst[m][k] = *(const PG8_LAS bf16x8*)(lds + PG8_SA(b, h) + aoff + m * 2048 + k * 1024); } while (0)
; #define PG8_LDB(dst, b, h) do { _Pragma("unroll") for (int n = 0; n < 2; ++n) _Pragma("unroll") for (int k = 0; k < 2; ++k) dst[n][k] = *(const PG8_LAS bf16x8*)(lds + PG8_SB(b, h) + boff + n * 2048 + k * 1024); } while (0)
; #define PG8_MMA(ai, bj, At, Bt) do { __builtin_amdgcn_s_setprio(1); _Pragma("unroll") for (int m = 0; m < 4; ++m) _Pragma("unroll") for (int n = 0; n < 2; ++n) _Pragma("unroll") for (int k = 0; k < 2; ++k) \
;         acc[ai][bj][m][n] = __builtin_amdgcn_mfma_f32_16x16x32_bf16(Bt[n][k], At[m][k], acc[ai][bj][m][n], 0, 0, 0); __builtin_amdgcn_s_setprio(0); } while (0)
; #define PG8_WAIT_V(n) asm volatile("s_waitcnt vmcnt(" #n ")" ::: "memory")
; #define PG8_WAIT_L(n) asm volatile("s_waitcnt lgkmcnt(" #n ")" ::: "memory")
; #define PG8_BAR __builtin_amdgcn_s_barrier()
; #define PG8_SCHED __builtin_amdgcn_sched_barrier(0)
; template <class Epi, class Sched, bool ALIGN_EPI = false, bool SP2 = false>
; __device__ __forceinline__ void gemm_phase(PG8_LAS unsigned char* lds, const Gemm g, const Sched& S, const Epi& E, int tid_in) {
;     ...
;             PG8_WAIT_V(8); PG8_WAIT_L(0); PG8_BAR; PG8_MMA(1, 0, At, B0); PG8_MMA(1, 1, At, B1); PG8_BAR; PG8_SCHED;
;             PG8_LDB(B0, 1, 0); PG8_LDB(B1, 1, 1); PG8_SCHED; PG8_LDA(At, 1, 0); PG8_STAGE(PG8_SA(0, 1), a2 + hsA, voffA);
;             PG8_WAIT_V(8); PG8_WAIT_L(0); PG8_BAR; PG8_MMA(0, 0, At, B0); PG8_MMA(0, 1, At, B1); PG8_BAR; PG8_SCHED;
	s_setprio 1
	s_waitcnt lgkmcnt(0)
	v_mfma_f32_16x16x32_bf16 v[96:99], v[132:135], v[174:177], v[96:99]
	v_mfma_f32_16x16x32_bf16 v[92:95], v[140:143], v[174:177], v[92:95]
	v_mfma_f32_16x16x32_bf16 v[88:91], v[132:135], v[182:185], v[88:91]
	v_mfma_f32_16x16x32_bf16 v[84:87], v[140:143], v[182:185], v[84:87]
	v_mfma_f32_16x16x32_bf16 v[80:83], v[132:135], v[204:207], v[80:83]
	v_mfma_f32_16x16x32_bf16 v[76:79], v[140:143], v[204:207], v[76:79]
	v_mfma_f32_16x16x32_bf16 v[72:75], v[132:135], v[212:215], v[72:75]
	v_mfma_f32_16x16x32_bf16 v[68:71], v[140:143], v[212:215], v[68:71]
	v_mfma_f32_16x16x32_bf16 v[96:99], v[136:139], v[178:181], v[96:99]
	v_mfma_f32_16x16x32_bf16 v[92:95], v[144:147], v[178:181], v[92:95]
	v_mfma_f32_16x16x32_bf16 v[88:91], v[136:139], v[186:189], v[88:91]
	v_mfma_f32_16x16x32_bf16 v[84:87], v[144:147], v[186:189], v[84:87]
	v_mfma_f32_16x16x32_bf16 v[80:83], v[136:139], v[208:211], v[80:83]
	v_mfma_f32_16x16x32_bf16 v[76:79], v[144:147], v[208:211], v[76:79]
	v_mfma_f32_16x16x32_bf16 v[72:75], v[136:139], v[220:223], v[72:75]
	v_mfma_f32_16x16x32_bf16 v[68:71], v[144:147], v[220:223], v[68:71]
	s_setprio 0
	s_setprio 1
	v_mfma_f32_16x16x32_bf16 v[32:35], v[148:151], v[174:177], v[32:35]
	v_mfma_f32_16x16x32_bf16 v[28:31], v[166:169], v[174:177], v[28:31]
	v_mfma_f32_16x16x32_bf16 v[24:27], v[148:151], v[182:185], v[24:27]
	v_mfma_f32_16x16x32_bf16 v[12:15], v[166:169], v[182:185], v[12:15]
	v_mfma_f32_16x16x32_bf16 v[20:23], v[148:151], v[204:207], v[20:23]
	v_mfma_f32_16x16x32_bf16 v[8:11], v[166:169], v[204:207], v[8:11]
	v_mfma_f32_16x16x32_bf16 v[16:19], v[148:151], v[212:215], v[16:19]
	v_mfma_f32_16x16x32_bf16 v[4:7], v[166:169], v[212:215], v[4:7]
	v_mfma_f32_16x16x32_bf16 v[32:35], v[162:165], v[178:181], v[32:35]
	v_mfma_f32_16x16x32_bf16 v[28:31], v[170:173], v[178:181], v[28:31]
	v_mfma_f32_16x16x32_bf16 v[24:27], v[162:165], v[186:189], v[24:27]
	v_mfma_f32_16x16x32_bf16 v[12:15], v[170:173], v[186:189], v[12:15]
	v_mfma_f32_16x16x32_bf16 v[20:23], v[162:165], v[208:211], v[20:23]
	v_mfma_f32_16x16x32_bf16 v[8:11], v[170:173], v[208:211], v[8:11]
	v_mfma_f32_16x16x32_bf16 v[16:19], v[162:165], v[220:223], v[16:19]
	v_mfma_f32_16x16x32_bf16 v[4:7], v[170:173], v[220:223], v[4:7]
	s_setprio 0
	s_barrier
	s_add_i32 s41, 0, 0x18000
	s_add_i32 s76, 0, 0x1c000
	v_add_u32_e32 v144, s41, v217
	v_add_u32_e32 v170, s76, v217
	ds_read_b128 v[132:135], v144
	ds_read_b128 v[136:139], v144 offset:1024
	ds_read_b128 v[140:143], v144 offset:2048
	ds_read_b128 v[144:147], v144 offset:3072
	ds_read_b128 v[148:151], v170
	ds_read_b128 v[162:165], v170 offset:1024
	ds_read_b128 v[166:169], v170 offset:2048
	ds_read_b128 v[170:173], v170 offset:3072
	s_add_u32 s38, s38, s10
	s_addc_u32 s39, s39, s11
	s_mov_b32 m0, s52
	v_lshl_add_u64 v[228:229], s[38:39], 0, v[0:1]
	ds_read_b128 v[174:177], v219 offset:32768
	ds_read_b128 v[178:181], v219 offset:33792
	ds_read_b128 v[182:185], v219 offset:34816
	ds_read_b128 v[186:189], v219 offset:35840
	ds_read_b128 v[204:207], v219 offset:36864
	ds_read_b128 v[208:211], v219 offset:37888
	ds_read_b128 v[212:215], v219 offset:38912
	ds_read_b128 v[220:223], v219 offset:39936
	global_load_lds_dwordx4 v[228:229], off
	v_lshl_add_u64 v[228:229], s[38:39], 0, v[154:155]
	s_mov_b32 m0, s53
	s_nop 0
	global_load_lds_dwordx4 v[228:229], off
	s_waitcnt vmcnt(8)
	s_waitcnt lgkmcnt(0)
	s_barrier
	s_setprio 1
	s_waitcnt lgkmcnt(0)
	v_mfma_f32_16x16x32_bf16 v[128:131], v[132:135], v[174:177], v[128:131]
	v_mfma_f32_16x16x32_bf16 v[124:127], v[140:143], v[174:177], v[124:127]
	v_mfma_f32_16x16x32_bf16 v[120:123], v[132:135], v[182:185], v[120:123]
	v_mfma_f32_16x16x32_bf16 v[116:119], v[140:143], v[182:185], v[116:119]
	v_mfma_f32_16x16x32_bf16 v[112:115], v[132:135], v[204:207], v[112:115]
	v_mfma_f32_16x16x32_bf16 v[108:111], v[140:143], v[204:207], v[108:111]
	v_mfma_f32_16x16x32_bf16 v[104:107], v[132:135], v[212:215], v[104:107]
	v_mfma_f32_16x16x32_bf16 v[100:103], v[140:143], v[212:215], v[100:103]
	v_mfma_f32_16x16x32_bf16 v[128:131], v[136:139], v[178:181], v[128:131]
	v_mfma_f32_16x16x32_bf16 v[124:127], v[144:147], v[178:181], v[124:127]
	v_mfma_f32_16x16x32_bf16 v[120:123], v[136:139], v[186:189], v[120:123]
	v_mfma_f32_16x16x32_bf16 v[116:119], v[144:147], v[186:189], v[116:119]
	v_mfma_f32_16x16x32_bf16 v[112:115], v[136:139], v[208:211], v[112:115]
	v_mfma_f32_16x16x32_bf16 v[108:111], v[144:147], v[208:211], v[108:111]
	v_mfma_f32_16x16x32_bf16 v[104:107], v[136:139], v[220:223], v[104:107]
	v_mfma_f32_16x16x32_bf16 v[100:103], v[144:147], v[220:223], v[100:103]
	s_setprio 0
	s_setprio 1
	v_mfma_f32_16x16x32_bf16 v[64:67], v[148:151], v[174:177], v[64:67]
	v_mfma_f32_16x16x32_bf16 v[56:59], v[166:169], v[174:177], v[56:59]
	v_mfma_f32_16x16x32_bf16 v[60:63], v[148:151], v[182:185], v[60:63]
	v_mfma_f32_16x16x32_bf16 v[52:55], v[166:169], v[182:185], v[52:55]
	v_mfma_f32_16x16x32_bf16 v[48:51], v[148:151], v[204:207], v[48:51]
	v_mfma_f32_16x16x32_bf16 v[40:43], v[166:169], v[204:207], v[40:43]
	v_mfma_f32_16x16x32_bf16 v[44:47], v[148:151], v[212:215], v[44:47]
	v_mfma_f32_16x16x32_bf16 v[36:39], v[166:169], v[212:215], v[36:39]
	v_mfma_f32_16x16x32_bf16 v[64:67], v[162:165], v[178:181], v[64:67]
	v_mfma_f32_16x16x32_bf16 v[56:59], v[170:173], v[178:181], v[56:59]
	v_mfma_f32_16x16x32_bf16 v[60:63], v[162:165], v[186:189], v[60:63]
	v_mfma_f32_16x16x32_bf16 v[52:55], v[170:173], v[186:189], v[52:55]
	v_mfma_f32_16x16x32_bf16 v[48:51], v[162:165], v[208:211], v[48:51]
	v_mfma_f32_16x16x32_bf16 v[40:43], v[170:173], v[208:211], v[40:43]
	v_mfma_f32_16x16x32_bf16 v[44:47], v[162:165], v[220:223], v[44:47]
	v_mfma_f32_16x16x32_bf16 v[36:39], v[170:173], v[220:223], v[36:39]
	s_setprio 0
	s_barrier
; #define PG8_STAGE(bufoff, gbase, voff) do { _Pragma("unroll") for (int _i = 0; _i < 2; ++_i) \
;         __builtin_amdgcn_global_load_lds((const unsigned*)((const char*)(gbase) + (voff)[_i]), (PG8_LAS unsigned*)(lds + (bufoff) + ldsw + _i * 8192), 16, 0, 0); } while (0)
; #define PG8_LDA(dst, b, h) do { _Pragma("unroll") for (int m = 0; m < 4; ++m) _Pragma("unroll") for (int k = 0; k < 2; ++k) dst[m][k] = *(const PG8_LAS bf16x8*)(lds + PG8_SA(b, h) + aoff + m * 2048 + k * 1024); } while (0)
; #define PG8_MMA(ai, bj, At, Bt) do { __builtin_amdgcn_s_setprio(1); _Pragma("unroll") for (int m = 0; m < 4; ++m) _Pragma("unroll") for (int n = 0; n < 2; ++n) _Pragma("unroll") for (int k = 0; k < 2; ++k) \
;         acc[ai][bj][m][n] = __builtin_amdgcn_mfma_f32_16x16x32_bf16(Bt[n][k], At[m][k], acc[ai][bj][m][n], 0, 0, 0); __builtin_amdgcn_s_setprio(0); } while (0)
; #define PG8_WAIT_V(n) asm volatile("s_waitcnt vmcnt(" #n ")" ::: "memory")
; #define PG8_WAIT_L(n) asm volatile("s_waitcnt lgkmcnt(" #n ")" ::: "memory")
; #define PG8_BAR __builtin_amdgcn_s_barrier()
; #define PG8_SCHED __builtin_amdgcn_sched_barrier(0)
; template <class Epi, class Sched, bool ALIGN_EPI = false, bool SP2 = false>
; __device__ __forceinline__ void gemm_phase(PG8_LAS unsigned char* lds, const Gemm g, const Sched& S, const Epi& E, int tid_in) {
;     ...
;             PG8_LDA(At, 1, 1); PG8_STAGE(PG8_SB(1, 0), b3, voffB); PG8_STAGE(PG8_SB(1, 1), b3 + hsB, voffB); PG8_STAGE(PG8_SA(1, 0), a3, voffA);
;             PG8_WAIT_V(8); PG8_WAIT_L(0); PG8_BAR; PG8_MMA(1, 0, At, B0); PG8_MMA(1, 1, At, B1); PG8_BAR; PG8_SCHED;
	s_add_i32 s38, s41, s49
	v_lshl_add_u64 v[190:191], v[190:191], 0, s[80:81]
	s_mov_b32 m0, s38
	ds_read_b128 v[174:177], v219 offset:49152
	ds_read_b128 v[178:181], v219 offset:50176
	ds_read_b128 v[182:185], v219 offset:51200
	ds_read_b128 v[186:189], v219 offset:52224
	ds_read_b128 v[204:207], v219 offset:53248
	ds_read_b128 v[208:211], v219 offset:54272
	ds_read_b128 v[212:215], v219 offset:55296
	ds_read_b128 v[220:223], v219 offset:56320
	global_load_lds_dwordx4 v[190:191], off
	v_lshl_add_u64 v[190:191], v[192:193], 0, s[80:81]
	s_add_i32 m0, s38, 0x2000
	s_add_i32 s38, s76, s49
	global_load_lds_dwordx4 v[190:191], off
	v_lshl_add_u64 v[190:191], v[196:197], 0, s[80:81]
	s_mov_b32 m0, s38
	s_nop 0
	global_load_lds_dwordx4 v[190:191], off
	v_lshl_add_u64 v[190:191], v[198:199], 0, s[80:81]
	s_add_i32 m0, s38, 0x2000
	s_nop 0
	global_load_lds_dwordx4 v[190:191], off
	v_lshl_add_u64 v[190:191], v[200:201], 0, s[80:81]
	s_mov_b32 m0, s58
	s_nop 0
	global_load_lds_dwordx4 v[190:191], off
	v_lshl_add_u64 v[190:191], v[202:203], 0, s[80:81]
	s_mov_b32 m0, s59
	s_nop 0
	global_load_lds_dwordx4 v[190:191], off
	s_waitcnt vmcnt(8)
	s_waitcnt lgkmcnt(0)
	s_barrier
	s_setprio 1
	s_waitcnt lgkmcnt(0)
	s_nop 0
	v_mfma_f32_16x16x32_bf16 v[96:99], v[132:135], v[174:177], v[96:99]
	v_mfma_f32_16x16x32_bf16 v[92:95], v[140:143], v[174:177], v[92:95]
	v_mfma_f32_16x16x32_bf16 v[88:91], v[132:135], v[182:185], v[88:91]
	v_mfma_f32_16x16x32_bf16 v[84:87], v[140:143], v[182:185], v[84:87]
	v_mfma_f32_16x16x32_bf16 v[80:83], v[132:135], v[204:207], v[80:83]
	v_mfma_f32_16x16x32_bf16 v[76:79], v[140:143], v[204:207], v[76:79]
	v_mfma_f32_16x16x32_bf16 v[72:75], v[132:135], v[212:215], v[72:75]
	v_mfma_f32_16x16x32_bf16 v[68:71], v[140:143], v[212:215], v[68:71]
	v_mfma_f32_16x16x32_bf16 v[96:99], v[136:139], v[178:181], v[96:99]
	v_mfma_f32_16x16x32_bf16 v[92:95], v[144:147], v[178:181], v[92:95]
	v_mfma_f32_16x16x32_bf16 v[88:91], v[136:139], v[186:189], v[88:91]
	v_mfma_f32_16x16x32_bf16 v[84:87], v[144:147], v[186:189], v[84:87]
	v_mfma_f32_16x16x32_bf16 v[80:83], v[136:139], v[208:211], v[80:83]
	v_mfma_f32_16x16x32_bf16 v[76:79], v[144:147], v[208:211], v[76:79]
	v_mfma_f32_16x16x32_bf16 v[72:75], v[136:139], v[220:223], v[72:75]
	v_mfma_f32_16x16x32_bf16 v[68:71], v[144:147], v[220:223], v[68:71]
	s_setprio 0
	s_setprio 1
	v_mfma_f32_16x16x32_bf16 v[32:35], v[148:151], v[174:177], v[32:35]
	v_mfma_f32_16x16x32_bf16 v[28:31], v[166:169], v[174:177], v[28:31]
	v_mfma_f32_16x16x32_bf16 v[24:27], v[148:151], v[182:185], v[24:27]
	v_mfma_f32_16x16x32_bf16 v[12:15], v[166:169], v[182:185], v[12:15]
	v_mfma_f32_16x16x32_bf16 v[20:23], v[148:151], v[204:207], v[20:23]
	v_mfma_f32_16x16x32_bf16 v[8:11], v[166:169], v[204:207], v[8:11]
	v_mfma_f32_16x16x32_bf16 v[16:19], v[148:151], v[212:215], v[16:19]
	v_mfma_f32_16x16x32_bf16 v[4:7], v[166:169], v[212:215], v[4:7]
	v_mfma_f32_16x16x32_bf16 v[32:35], v[162:165], v[178:181], v[32:35]
	v_mfma_f32_16x16x32_bf16 v[28:31], v[170:173], v[178:181], v[28:31]
	v_mfma_f32_16x16x32_bf16 v[24:27], v[162:165], v[186:189], v[24:27]
	v_mfma_f32_16x16x32_bf16 v[12:15], v[170:173], v[186:189], v[12:15]
	v_mfma_f32_16x16x32_bf16 v[20:23], v[162:165], v[208:211], v[20:23]
	v_mfma_f32_16x16x32_bf16 v[8:11], v[170:173], v[208:211], v[8:11]
	v_mfma_f32_16x16x32_bf16 v[16:19], v[162:165], v[220:223], v[16:19]
	v_mfma_f32_16x16x32_bf16 v[4:7], v[170:173], v[220:223], v[4:7]
	s_setprio 0
	s_barrier
	s_add_i32 s38, s40, 2
	s_add_u32 s74, s74, 0x100
	s_addc_u32 s75, s75, 0
	s_add_u32 s4, s4, 0x100
	s_addc_u32 s5, s5, 0
	s_cmp_ge_i32 s40, s60
	s_mov_b32 s40, s38
	s_cbranch_scc0 .LBB0_1331
	s_movk_i32 s74, 0x2c00

; #define PG8_STAGE(bufoff, gbase, voff) do { _Pragma("unroll") for (int _i = 0; _i < 2; ++_i) \
;         __builtin_amdgcn_global_load_lds((const unsigned*)((const char*)(gbase) + (voff)[_i]), (PG8_LAS unsigned*)(lds + (bufoff) + ldsw + _i * 8192), 16, 0, 0); } while (0)
; #define PG8_LDA(dst, b, h) do { _Pragma("unroll") for (int m = 0; m < 4; ++m) _Pragma("unroll") for (int k = 0; k < 2; ++k) dst[m][k] = *(const PG8_LAS bf16x8*)(lds + PG8_SA(b, h) + aoff + m * 2048 + k * 1024); } while (0)
; #define PG8_LDB(dst, b, h) do { _Pragma("unroll") for (int n = 0; n < 2; ++n) _Pragma("unroll") for (int k = 0; k < 2; ++k) dst[n][k] = *(const PG8_LAS bf16x8*)(lds + PG8_SB(b, h) + boff + n * 2048 + k * 1024); } while (0)
; #define PG8_MMA(ai, bj, At, Bt) do { __builtin_amdgcn_s_setprio(1); _Pragma("unroll") for (int m = 0; m < 4; ++m) _Pragma("unroll") for (int n = 0; n < 2; ++n) _Pragma("unroll") for (int k = 0; k < 2; ++k) \
;         acc[ai][bj][m][n] = __builtin_amdgcn_mfma_f32_16x16x32_bf16(Bt[n][k], At[m][k], acc[ai][bj][m][n], 0, 0, 0); __builtin_amdgcn_s_setprio(0); } while (0)
; #define PG8_WAIT_V(n) asm volatile("s_waitcnt vmcnt(" #n ")" ::: "memory")
; template <class Epi, class Sched, bool ALIGN_EPI = false, bool SP2 = false>
; __device__ __forceinline__ void gemm_phase(PG8_LAS unsigned char* lds, const Gemm g, const Sched& S, const Epi& E, int tid_in) {
;     ...
;         for (int t = 0; t < nt; t += 2) {
;             const bool last = (t == nt - 2);
;             if constexpr (mid_hook<Epi>::value) { if (t == Epi::H1 || t == Epi::H2) E.mid(acc, cur, wr, wc, fr, fq, t == Epi::H2); }
;             const char* a1 = cA + (size_t)(t + 1) * kstep + (t >= jt ? jb : 0);
;             const char* a2 = last ? nA : cA + (size_t)(t + 2) * kstep + (t + 2 >= jt ? jb : 0); const char* b2 = last ? nB : cB + (size_t)(t + 2) * kstep;
;             const char* a3 = a2 + kstep; const char* b3 = b2 + kstep;
;             if (last && has_next) S.a_ready(nxt);
;             if constexpr (SP2) {
;             PG8_LDB(B0, 0, 0); PG8_LDB(B1, 0, 1); PG8_SCHED; PG8_LDA(At, 0, 0); PG8_STAGE(PG8_SA(1, 1), a1 + hsA, voffA);
;             PG8_WAIT_V(8); PG8_WAIT_L(0); PG8_BAR; PG8_MMA(0, 0, At, B0); PG8_MMA(0, 1, At, B1); PG8_BAR; PG8_SCHED;
;             PG8_LDA(At, 0, 1); PG8_STAGE(PG8_SB(0, 0), b2, voffB); PG8_STAGE(PG8_SB(0, 1), b2 + hsB, voffB); PG8_STAGE(PG8_SA(0, 0), a2, voffA);
.LBB0_1362:
	s_add_i32 s24, s55, -2
	s_cmp_ge_i32 s24, s26
	s_cselect_b32 s58, s27, 0
	s_cselect_b32 s59, s47, 0
	s_cmp_ge_i32 s55, s26
	s_cselect_b32 s25, s27, 0
	s_cselect_b32 s24, s47, 0
	s_add_u32 s25, s22, s25
	s_addc_u32 s24, s23, s24
	s_add_u32 s60, s25, 0x80
	s_addc_u32 s24, s24, 0
	s_add_i32 s62, 0, 0x10000
	s_cmp_eq_u32 s46, s55
	s_cselect_b32 s25, s5, s24
	s_cselect_b32 s24, s4, s60
	s_cselect_b32 s61, s21, s54
	s_cselect_b32 s60, s20, s53
	s_add_i32 s63, 0, 0x14000
	v_add_u32_e32 v160, s62, v3
	v_add_u32_e32 v176, s63, v3
	ds_read_b128 v[148:151], v160
	ds_read_b128 v[152:155], v160 offset:1024
	ds_read_b128 v[156:159], v160 offset:2048
	ds_read_b128 v[160:163], v160 offset:3072
	ds_read_b128 v[164:167], v176
	ds_read_b128 v[168:171], v176 offset:1024
	ds_read_b128 v[172:175], v176 offset:2048
	ds_read_b128 v[176:179], v176 offset:3072
	v_lshl_add_u64 v[192:193], s[22:23], 0, v[140:141]
	v_lshl_add_u64 v[192:193], v[192:193], 0, s[58:59]
	s_add_i32 m0, s33, 0xc000
	ds_read_b128 v[180:183], v147
	ds_read_b128 v[184:187], v147 offset:1024
	ds_read_b128 v[188:191], v147 offset:2048
	ds_read_b128 v[204:207], v147 offset:3072
	ds_read_b128 v[208:211], v147 offset:4096
	ds_read_b128 v[212:215], v147 offset:5120
	ds_read_b128 v[216:219], v147 offset:6144
	ds_read_b128 v[220:223], v147 offset:7168
	global_load_lds_dwordx4 v[192:193], off
	v_lshl_add_u64 v[192:193], s[22:23], 0, v[138:139]
	v_lshl_add_u64 v[192:193], v[192:193], 0, s[58:59]
	s_add_i32 m0, s33, 0xe000
	s_nop 0
	global_load_lds_dwordx4 v[192:193], off
	s_waitcnt vmcnt(8)
	s_waitcnt lgkmcnt(0)
	s_barrier
	s_setprio 1
	s_waitcnt lgkmcnt(0)
	s_nop 0
	v_mfma_f32_16x16x32_bf16 v[124:127], v[148:151], v[180:183], v[124:127]
	v_mfma_f32_16x16x32_bf16 v[128:131], v[156:159], v[180:183], v[128:131]
	v_mfma_f32_16x16x32_bf16 v[112:115], v[148:151], v[188:191], v[112:115]
	v_mfma_f32_16x16x32_bf16 v[108:111], v[156:159], v[188:191], v[108:111]
	v_mfma_f32_16x16x32_bf16 v[96:99], v[148:151], v[208:211], v[96:99]
	v_mfma_f32_16x16x32_bf16 v[92:95], v[156:159], v[208:211], v[92:95]
	v_mfma_f32_16x16x32_bf16 v[80:83], v[148:151], v[216:219], v[80:83]
	v_mfma_f32_16x16x32_bf16 v[76:79], v[156:159], v[216:219], v[76:79]
	v_mfma_f32_16x16x32_bf16 v[124:127], v[152:155], v[184:187], v[124:127]
	v_mfma_f32_16x16x32_bf16 v[128:131], v[160:163], v[184:187], v[128:131]
	v_mfma_f32_16x16x32_bf16 v[112:115], v[152:155], v[204:207], v[112:115]
	v_mfma_f32_16x16x32_bf16 v[108:111], v[160:163], v[204:207], v[108:111]
	v_mfma_f32_16x16x32_bf16 v[96:99], v[152:155], v[212:215], v[96:99]
	v_mfma_f32_16x16x32_bf16 v[92:95], v[160:163], v[212:215], v[92:95]
	v_mfma_f32_16x16x32_bf16 v[80:83], v[152:155], v[220:223], v[80:83]
	v_mfma_f32_16x16x32_bf16 v[76:79], v[160:163], v[220:223], v[76:79]
	s_setprio 0
	s_setprio 1
	v_mfma_f32_16x16x32_bf16 v[120:123], v[164:167], v[180:183], v[120:123]
	v_mfma_f32_16x16x32_bf16 v[116:119], v[172:175], v[180:183], v[116:119]
	v_mfma_f32_16x16x32_bf16 v[104:107], v[164:167], v[188:191], v[104:107]
	v_mfma_f32_16x16x32_bf16 v[100:103], v[172:175], v[188:191], v[100:103]
	v_mfma_f32_16x16x32_bf16 v[88:91], v[164:167], v[208:211], v[88:91]
	v_mfma_f32_16x16x32_bf16 v[84:87], v[172:175], v[208:211], v[84:87]
	v_mfma_f32_16x16x32_bf16 v[72:75], v[164:167], v[216:219], v[72:75]
	v_mfma_f32_16x16x32_bf16 v[68:71], v[172:175], v[216:219], v[68:71]
	v_mfma_f32_16x16x32_bf16 v[120:123], v[168:171], v[184:187], v[120:123]
	v_mfma_f32_16x16x32_bf16 v[116:119], v[176:179], v[184:187], v[116:119]
	v_mfma_f32_16x16x32_bf16 v[104:107], v[168:171], v[204:207], v[104:107]
	v_mfma_f32_16x16x32_bf16 v[100:103], v[176:179], v[204:207], v[100:103]
	v_mfma_f32_16x16x32_bf16 v[88:91], v[168:171], v[212:215], v[88:91]
	v_mfma_f32_16x16x32_bf16 v[84:87], v[176:179], v[212:215], v[84:87]
	v_mfma_f32_16x16x32_bf16 v[72:75], v[168:171], v[220:223], v[72:75]
	v_mfma_f32_16x16x32_bf16 v[68:71], v[176:179], v[220:223], v[68:71]
	s_setprio 0
	s_barrier
	s_add_i32 s58, s62, s30
	v_lshl_add_u64 v[192:193], s[60:61], 0, v[134:135]
	s_mov_b32 m0, s58
	ds_read_b128 v[180:183], v147 offset:16384
	ds_read_b128 v[184:187], v147 offset:17408
	ds_read_b128 v[188:191], v147 offset:18432
	ds_read_b128 v[204:207], v147 offset:19456
	ds_read_b128 v[208:211], v147 offset:20480
	ds_read_b128 v[212:215], v147 offset:21504
	ds_read_b128 v[216:219], v147 offset:22528
	ds_read_b128 v[220:223], v147 offset:23552
	global_load_lds_dwordx4 v[192:193], off
	s_add_i32 m0, s58, 0x2000
	s_add_u32 s58, s60, s8
	v_lshl_add_u64 v[196:197], s[60:61], 0, v[0:1]
	s_addc_u32 s59, s61, s9
	s_add_i32 s60, s63, s30
	global_load_lds_dwordx4 v[196:197], off
	v_lshl_add_u64 v[198:199], s[58:59], 0, v[134:135]
	s_mov_b32 m0, s60
	v_lshl_add_u64 v[200:201], s[58:59], 0, v[0:1]
	global_load_lds_dwordx4 v[198:199], off
	s_add_i32 m0, s60, 0x2000
	v_lshl_add_u64 v[202:203], s[24:25], 0, v[136:137]
	global_load_lds_dwordx4 v[200:201], off
	s_mov_b32 m0, s33
	v_lshl_add_u64 v[228:229], s[24:25], 0, v[132:133]
	global_load_lds_dwordx4 v[202:203], off
	s_mov_b32 m0, s34
	s_nop 0
	global_load_lds_dwordx4 v[228:229], off
	s_waitcnt vmcnt(8)
	s_waitcnt lgkmcnt(0)
	s_barrier
; #define PG8_STAGE(bufoff, gbase, voff) do { _Pragma("unroll") for (int _i = 0; _i < 2; ++_i) \
;         __builtin_amdgcn_global_load_lds((const unsigned*)((const char*)(gbase) + (voff)[_i]), (PG8_LAS unsigned*)(lds + (bufoff) + ldsw + _i * 8192), 16, 0, 0); } while (0)
; #define PG8_LDA(dst, b, h) do { _Pragma("unroll") for (int m = 0; m < 4; ++m) _Pragma("unroll") for (int k = 0; k < 2; ++k) dst[m][k] = *(const PG8_LAS bf16x8*)(lds + PG8_SA(b, h) + aoff + m * 2048 + k * 1024); } while (0)
; #define PG8_LDB(dst, b, h) do { _Pragma("unroll") for (int n = 0; n < 2; ++n) _Pragma("unroll") for (int k = 0; k < 2; ++k) dst[n][k] = *(const PG8_LAS bf16x8*)(lds + PG8_SB(b, h) + boff + n * 2048 + k * 1024); } while (0)
; #define PG8_MMA(ai, bj, At, Bt) do { __builtin_amdgcn_s_setprio(1); _Pragma("unroll") for (int m = 0; m < 4; ++m) _Pragma("unroll") for (int n = 0; n < 2; ++n) _Pragma("unroll") for (int k = 0; k < 2; ++k) \
;         acc[ai][bj][m][n] = __builtin_amdgcn_mfma_f32_16x16x32_bf16(Bt[n][k], At[m][k], acc[ai][bj][m][n], 0, 0, 0); __builtin_amdgcn_s_setprio(0); } while (0)
; #define PG8_WAIT_V(n) asm volatile("s_waitcnt vmcnt(" #n ")" ::: "memory")
; #define PG8_WAIT_L(n) asm volatile("s_waitcnt lgkmcnt(" #n ")" ::: "memory")
; #define PG8_BAR __builtin_amdgcn_s_barrier()
; #define PG8_SCHED __builtin_amdgcn_sched_barrier(0)
; template <class Epi, class Sched, bool ALIGN_EPI = false, bool SP2 = false>
; __device__ __forceinline__ void gemm_phase(PG8_LAS unsigned char* lds, const Gemm g, const Sched& S, const Epi& E, int tid_in) {
;     ...
;             PG8_WAIT_V(8); PG8_WAIT_L(0); PG8_BAR; PG8_MMA(1, 0, At, B0); PG8_MMA(1, 1, At, B1); PG8_BAR; PG8_SCHED;
;             PG8_LDB(B0, 1, 0); PG8_LDB(B1, 1, 1); PG8_SCHED; PG8_LDA(At, 1, 0); PG8_STAGE(PG8_SA(0, 1), a2 + hsA, voffA);
;             PG8_WAIT_V(8); PG8_WAIT_L(0); PG8_BAR; PG8_MMA(0, 0, At, B0); PG8_MMA(0, 1, At, B1); PG8_BAR; PG8_SCHED;
	s_setprio 1
	s_waitcnt lgkmcnt(0)
	v_mfma_f32_16x16x32_bf16 v[64:67], v[148:151], v[180:183], v[64:67]
	v_mfma_f32_16x16x32_bf16 v[60:63], v[156:159], v[180:183], v[60:63]
	v_mfma_f32_16x16x32_bf16 v[48:51], v[148:151], v[188:191], v[48:51]
	v_mfma_f32_16x16x32_bf16 v[44:47], v[156:159], v[188:191], v[44:47]
	v_mfma_f32_16x16x32_bf16 v[32:35], v[148:151], v[208:211], v[32:35]
	v_mfma_f32_16x16x32_bf16 v[28:31], v[156:159], v[208:211], v[28:31]
	v_mfma_f32_16x16x32_bf16 v[16:19], v[148:151], v[216:219], v[16:19]
	v_mfma_f32_16x16x32_bf16 v[12:15], v[156:159], v[216:219], v[12:15]
	v_mfma_f32_16x16x32_bf16 v[64:67], v[152:155], v[184:187], v[64:67]
	v_mfma_f32_16x16x32_bf16 v[60:63], v[160:163], v[184:187], v[60:63]
	v_mfma_f32_16x16x32_bf16 v[48:51], v[152:155], v[204:207], v[48:51]
	v_mfma_f32_16x16x32_bf16 v[44:47], v[160:163], v[204:207], v[44:47]
	v_mfma_f32_16x16x32_bf16 v[32:35], v[152:155], v[212:215], v[32:35]
	v_mfma_f32_16x16x32_bf16 v[28:31], v[160:163], v[212:215], v[28:31]
	v_mfma_f32_16x16x32_bf16 v[16:19], v[152:155], v[220:223], v[16:19]
	v_mfma_f32_16x16x32_bf16 v[12:15], v[160:163], v[220:223], v[12:15]
	s_setprio 0
	s_setprio 1
	v_mfma_f32_16x16x32_bf16 v[56:59], v[164:167], v[180:183], v[56:59]
	v_mfma_f32_16x16x32_bf16 v[52:55], v[172:175], v[180:183], v[52:55]
	v_mfma_f32_16x16x32_bf16 v[40:43], v[164:167], v[188:191], v[40:43]
	v_mfma_f32_16x16x32_bf16 v[36:39], v[172:175], v[188:191], v[36:39]
	v_mfma_f32_16x16x32_bf16 v[24:27], v[164:167], v[208:211], v[24:27]
	v_mfma_f32_16x16x32_bf16 v[20:23], v[172:175], v[208:211], v[20:23]
	v_mfma_f32_16x16x32_bf16 v[8:11], v[164:167], v[216:219], v[8:11]
	v_mfma_f32_16x16x32_bf16 v[4:7], v[172:175], v[216:219], v[4:7]
	v_mfma_f32_16x16x32_bf16 v[56:59], v[168:171], v[184:187], v[56:59]
	v_mfma_f32_16x16x32_bf16 v[52:55], v[176:179], v[184:187], v[52:55]
	v_mfma_f32_16x16x32_bf16 v[40:43], v[168:171], v[204:207], v[40:43]
	v_mfma_f32_16x16x32_bf16 v[36:39], v[176:179], v[204:207], v[36:39]
	v_mfma_f32_16x16x32_bf16 v[24:27], v[168:171], v[212:215], v[24:27]
	v_mfma_f32_16x16x32_bf16 v[20:23], v[176:179], v[212:215], v[20:23]
	v_mfma_f32_16x16x32_bf16 v[8:11], v[168:171], v[220:223], v[8:11]
	v_mfma_f32_16x16x32_bf16 v[4:7], v[176:179], v[220:223], v[4:7]
	s_setprio 0
	s_barrier
	s_add_i32 s58, 0, 0x18000
	s_add_i32 s59, 0, 0x1c000
	v_add_u32_e32 v160, s58, v3
	v_add_u32_e32 v176, s59, v3
	ds_read_b128 v[148:151], v160
	ds_read_b128 v[152:155], v160 offset:1024
	ds_read_b128 v[156:159], v160 offset:2048
	ds_read_b128 v[160:163], v160 offset:3072
	ds_read_b128 v[164:167], v176
	ds_read_b128 v[168:171], v176 offset:1024
	ds_read_b128 v[172:175], v176 offset:2048
	ds_read_b128 v[176:179], v176 offset:3072
	s_add_u32 s24, s24, s6
	s_addc_u32 s25, s25, s7
	s_mov_b32 m0, s35
	v_lshl_add_u64 v[230:231], s[24:25], 0, v[136:137]
	ds_read_b128 v[180:183], v147 offset:32768
	ds_read_b128 v[184:187], v147 offset:33792
	ds_read_b128 v[188:191], v147 offset:34816
	ds_read_b128 v[204:207], v147 offset:35840
	ds_read_b128 v[208:211], v147 offset:36864
	ds_read_b128 v[212:215], v147 offset:37888
	ds_read_b128 v[216:219], v147 offset:38912
	ds_read_b128 v[220:223], v147 offset:39936
	global_load_lds_dwordx4 v[230:231], off
	v_lshl_add_u64 v[230:231], s[24:25], 0, v[132:133]
	s_mov_b32 m0, s36
	s_nop 0
	global_load_lds_dwordx4 v[230:231], off
	s_waitcnt vmcnt(8)
	s_waitcnt lgkmcnt(0)
	s_barrier
	s_setprio 1
	s_waitcnt lgkmcnt(0)
	v_mfma_f32_16x16x32_bf16 v[124:127], v[148:151], v[180:183], v[124:127]
	v_mfma_f32_16x16x32_bf16 v[128:131], v[156:159], v[180:183], v[128:131]
	v_mfma_f32_16x16x32_bf16 v[112:115], v[148:151], v[188:191], v[112:115]
	v_mfma_f32_16x16x32_bf16 v[108:111], v[156:159], v[188:191], v[108:111]
	v_mfma_f32_16x16x32_bf16 v[96:99], v[148:151], v[208:211], v[96:99]
	v_mfma_f32_16x16x32_bf16 v[92:95], v[156:159], v[208:211], v[92:95]
	v_mfma_f32_16x16x32_bf16 v[80:83], v[148:151], v[216:219], v[80:83]
	v_mfma_f32_16x16x32_bf16 v[76:79], v[156:159], v[216:219], v[76:79]
	v_mfma_f32_16x16x32_bf16 v[124:127], v[152:155], v[184:187], v[124:127]
	v_mfma_f32_16x16x32_bf16 v[128:131], v[160:163], v[184:187], v[128:131]
	v_mfma_f32_16x16x32_bf16 v[112:115], v[152:155], v[204:207], v[112:115]
	v_mfma_f32_16x16x32_bf16 v[108:111], v[160:163], v[204:207], v[108:111]
	v_mfma_f32_16x16x32_bf16 v[96:99], v[152:155], v[212:215], v[96:99]
	v_mfma_f32_16x16x32_bf16 v[92:95], v[160:163], v[212:215], v[92:95]
	v_mfma_f32_16x16x32_bf16 v[80:83], v[152:155], v[220:223], v[80:83]
	v_mfma_f32_16x16x32_bf16 v[76:79], v[160:163], v[220:223], v[76:79]
	s_setprio 0
	s_setprio 1
	v_mfma_f32_16x16x32_bf16 v[120:123], v[164:167], v[180:183], v[120:123]
	v_mfma_f32_16x16x32_bf16 v[116:119], v[172:175], v[180:183], v[116:119]
	v_mfma_f32_16x16x32_bf16 v[104:107], v[164:167], v[188:191], v[104:107]
	v_mfma_f32_16x16x32_bf16 v[100:103], v[172:175], v[188:191], v[100:103]
	v_mfma_f32_16x16x32_bf16 v[88:91], v[164:167], v[208:211], v[88:91]
	v_mfma_f32_16x16x32_bf16 v[84:87], v[172:175], v[208:211], v[84:87]
	v_mfma_f32_16x16x32_bf16 v[72:75], v[164:167], v[216:219], v[72:75]
	v_mfma_f32_16x16x32_bf16 v[68:71], v[172:175], v[216:219], v[68:71]
	v_mfma_f32_16x16x32_bf16 v[120:123], v[168:171], v[184:187], v[120:123]
	v_mfma_f32_16x16x32_bf16 v[116:119], v[176:179], v[184:187], v[116:119]
	v_mfma_f32_16x16x32_bf16 v[104:107], v[168:171], v[204:207], v[104:107]
	v_mfma_f32_16x16x32_bf16 v[100:103], v[176:179], v[204:207], v[100:103]
	v_mfma_f32_16x16x32_bf16 v[88:91], v[168:171], v[212:215], v[88:91]
	v_mfma_f32_16x16x32_bf16 v[84:87], v[176:179], v[212:215], v[84:87]
	v_mfma_f32_16x16x32_bf16 v[72:75], v[168:171], v[220:223], v[72:75]
	v_mfma_f32_16x16x32_bf16 v[68:71], v[176:179], v[220:223], v[68:71]
	s_setprio 0
	s_barrier
; #define PG8_STAGE(bufoff, gbase, voff) do { _Pragma("unroll") for (int _i = 0; _i < 2; ++_i) \
;         __builtin_amdgcn_global_load_lds((const unsigned*)((const char*)(gbase) + (voff)[_i]), (PG8_LAS unsigned*)(lds + (bufoff) + ldsw + _i * 8192), 16, 0, 0); } while (0)
; #define PG8_LDA(dst, b, h) do { _Pragma("unroll") for (int m = 0; m < 4; ++m) _Pragma("unroll") for (int k = 0; k < 2; ++k) dst[m][k] = *(const PG8_LAS bf16x8*)(lds + PG8_SA(b, h) + aoff + m * 2048 + k * 1024); } while (0)
; #define PG8_MMA(ai, bj, At, Bt) do { __builtin_amdgcn_s_setprio(1); _Pragma("unroll") for (int m = 0; m < 4; ++m) _Pragma("unroll") for (int n = 0; n < 2; ++n) _Pragma("unroll") for (int k = 0; k < 2; ++k) \
;         acc[ai][bj][m][n] = __builtin_amdgcn_mfma_f32_16x16x32_bf16(Bt[n][k], At[m][k], acc[ai][bj][m][n], 0, 0, 0); __builtin_amdgcn_s_setprio(0); } while (0)
; #define PG8_WAIT_V(n) asm volatile("s_waitcnt vmcnt(" #n ")" ::: "memory")
; #define PG8_WAIT_L(n) asm volatile("s_waitcnt lgkmcnt(" #n ")" ::: "memory")
; #define PG8_BAR __builtin_amdgcn_s_barrier()
; #define PG8_SCHED __builtin_amdgcn_sched_barrier(0)
; template <class Epi, class Sched, bool ALIGN_EPI = false, bool SP2 = false>
; __device__ __forceinline__ void gemm_phase(PG8_LAS unsigned char* lds, const Gemm g, const Sched& S, const Epi& E, int tid_in) {
;     ...
;             PG8_LDA(At, 1, 1); PG8_STAGE(PG8_SB(1, 0), b3, voffB); PG8_STAGE(PG8_SB(1, 1), b3 + hsB, voffB); PG8_STAGE(PG8_SA(1, 0), a3, voffA);
;             PG8_WAIT_V(8); PG8_WAIT_L(0); PG8_BAR; PG8_MMA(1, 0, At, B0); PG8_MMA(1, 1, At, B1); PG8_BAR; PG8_SCHED;
	s_add_i32 s24, s58, s30
	v_lshl_add_u64 v[192:193], v[192:193], 0, s[80:81]
	s_mov_b32 m0, s24
	ds_read_b128 v[180:183], v147 offset:49152
	ds_read_b128 v[184:187], v147 offset:50176
	ds_read_b128 v[188:191], v147 offset:51200
	ds_read_b128 v[204:207], v147 offset:52224
	ds_read_b128 v[208:211], v147 offset:53248
	ds_read_b128 v[212:215], v147 offset:54272
	ds_read_b128 v[216:219], v147 offset:55296
	ds_read_b128 v[220:223], v147 offset:56320
	global_load_lds_dwordx4 v[192:193], off
	v_lshl_add_u64 v[192:193], v[196:197], 0, s[80:81]
	s_add_i32 m0, s24, 0x2000
	s_add_i32 s24, s59, s30
	global_load_lds_dwordx4 v[192:193], off
	v_lshl_add_u64 v[192:193], v[198:199], 0, s[80:81]
	s_mov_b32 m0, s24
	s_nop 0
	global_load_lds_dwordx4 v[192:193], off
	v_lshl_add_u64 v[192:193], v[200:201], 0, s[80:81]
	s_add_i32 m0, s24, 0x2000
	s_nop 0
	global_load_lds_dwordx4 v[192:193], off
	v_lshl_add_u64 v[192:193], v[202:203], 0, s[80:81]
	s_mov_b32 m0, s39
	s_nop 0
	global_load_lds_dwordx4 v[192:193], off
	v_lshl_add_u64 v[192:193], v[228:229], 0, s[80:81]
	s_mov_b32 m0, s40
	s_nop 0
	global_load_lds_dwordx4 v[192:193], off
	s_waitcnt vmcnt(8)
	s_waitcnt lgkmcnt(0)
	s_barrier
	s_setprio 1
	s_waitcnt lgkmcnt(0)
	s_nop 0
	v_mfma_f32_16x16x32_bf16 v[64:67], v[148:151], v[180:183], v[64:67]
	v_mfma_f32_16x16x32_bf16 v[60:63], v[156:159], v[180:183], v[60:63]
	v_mfma_f32_16x16x32_bf16 v[48:51], v[148:151], v[188:191], v[48:51]
	v_mfma_f32_16x16x32_bf16 v[44:47], v[156:159], v[188:191], v[44:47]
	v_mfma_f32_16x16x32_bf16 v[32:35], v[148:151], v[208:211], v[32:35]
	v_mfma_f32_16x16x32_bf16 v[28:31], v[156:159], v[208:211], v[28:31]
	v_mfma_f32_16x16x32_bf16 v[16:19], v[148:151], v[216:219], v[16:19]
	v_mfma_f32_16x16x32_bf16 v[12:15], v[156:159], v[216:219], v[12:15]
	v_mfma_f32_16x16x32_bf16 v[64:67], v[152:155], v[184:187], v[64:67]
	v_mfma_f32_16x16x32_bf16 v[60:63], v[160:163], v[184:187], v[60:63]
	v_mfma_f32_16x16x32_bf16 v[48:51], v[152:155], v[204:207], v[48:51]
	v_mfma_f32_16x16x32_bf16 v[44:47], v[160:163], v[204:207], v[44:47]
	v_mfma_f32_16x16x32_bf16 v[32:35], v[152:155], v[212:215], v[32:35]
	v_mfma_f32_16x16x32_bf16 v[28:31], v[160:163], v[212:215], v[28:31]
	v_mfma_f32_16x16x32_bf16 v[16:19], v[152:155], v[220:223], v[16:19]
	v_mfma_f32_16x16x32_bf16 v[12:15], v[160:163], v[220:223], v[12:15]
	s_setprio 0
	s_setprio 1
	v_mfma_f32_16x16x32_bf16 v[56:59], v[164:167], v[180:183], v[56:59]
	v_mfma_f32_16x16x32_bf16 v[52:55], v[172:175], v[180:183], v[52:55]
	v_mfma_f32_16x16x32_bf16 v[40:43], v[164:167], v[188:191], v[40:43]
	v_mfma_f32_16x16x32_bf16 v[36:39], v[172:175], v[188:191], v[36:39]
	v_mfma_f32_16x16x32_bf16 v[24:27], v[164:167], v[208:211], v[24:27]
	v_mfma_f32_16x16x32_bf16 v[20:23], v[172:175], v[208:211], v[20:23]
	v_mfma_f32_16x16x32_bf16 v[8:11], v[164:167], v[216:219], v[8:11]
	v_mfma_f32_16x16x32_bf16 v[4:7], v[172:175], v[216:219], v[4:7]
	v_mfma_f32_16x16x32_bf16 v[56:59], v[168:171], v[184:187], v[56:59]
	v_mfma_f32_16x16x32_bf16 v[52:55], v[176:179], v[184:187], v[52:55]
	v_mfma_f32_16x16x32_bf16 v[40:43], v[168:171], v[204:207], v[40:43]
	v_mfma_f32_16x16x32_bf16 v[36:39], v[176:179], v[204:207], v[36:39]
	v_mfma_f32_16x16x32_bf16 v[24:27], v[168:171], v[212:215], v[24:27]
	v_mfma_f32_16x16x32_bf16 v[20:23], v[176:179], v[212:215], v[20:23]
	v_mfma_f32_16x16x32_bf16 v[8:11], v[168:171], v[220:223], v[8:11]
	v_mfma_f32_16x16x32_bf16 v[4:7], v[176:179], v[220:223], v[4:7]
	s_setprio 0
	s_barrier
	s_add_i32 s24, s55, 2
	s_add_u32 s53, s53, 0x100
	s_addc_u32 s54, s54, 0
	s_add_u32 s22, s22, 0x100
	s_addc_u32 s23, s23, 0
	s_cmp_ge_i32 s55, s46
	s_mov_b32 s55, s24
	s_cbranch_scc0 .LBB0_1362
